# K-loops: the load-segment barrier is issued after the first 4 MFMAs of the following MFMA segment (same rendezvous order)
# baseline (speedup 1.0000x reference)
; #define PG8_STAGEA(bufoff, gbase) PG8_STAGE_(bufoff, gbase, voffA)
; #define PG8_STAGEB(bufoff, gbase) PG8_STAGE_(bufoff, gbase, voffB)
; #define PG8_LDA(dst, b, h) do { _Pragma("unroll") for (int m = 0; m < 4; ++m) _Pragma("unroll") for (int k = 0; k < 2; ++k) dst[m][k] = *(const LAS bf16x8*)(lds + PG8_SA(b, h) + aoff + m * 2048 + k * 1024); } while (0)
; #define PG8_LDB(dst, b, h) do { _Pragma("unroll") for (int n = 0; n < 2; ++n) _Pragma("unroll") for (int k = 0; k < 2; ++k) dst[n][k] = *(const LAS bf16x8*)(lds + PG8_SB(b, h) + boff + n * 2048 + k * 1024); } while (0)
; #define PG8_MMA(ai, bj, At, Bt_) do { __builtin_amdgcn_s_setprio(1); _Pragma("unroll") for (int m = 0; m < 4; ++m) _Pragma("unroll") for (int n = 0; n < 2; ++n) _Pragma("unroll") for (int k = 0; k < 2; ++k) \
;         acc[ai][bj][m][n] = __builtin_amdgcn_mfma_f32_16x16x32_bf16(Bt_[n][k], At[m][k], acc[ai][bj][m][n], 0, 0, 0); __builtin_amdgcn_s_setprio(0); } while (0)
; #define PG8_WAIT_V(n) asm volatile("s_waitcnt vmcnt(" #n ")" ::: "memory")
; #define PG8_WAIT_L(n) asm volatile("s_waitcnt lgkmcnt(" #n ")" ::: "memory")
; #define PG8_BAR __builtin_amdgcn_s_barrier()
; template <int EK, int SK = -1>
; __device__ __forceinline__ void gemm_phase(LAS unsigned char* lds, const bf16_t* A, const bf16_t* Bt, int nM, int N, int K, const EpiArgs& E) {
;     ...
;         const bool has_next = S.next(ui + 1, nxt);
;         const char* nA = has_next ? (const char*)A + (size_t)nxt.pm * tstep : cA; const char* nB = has_next ? (const char*)Bt + (size_t)nxt.pn * tstep : cB;
;         for (int t = 0; t < nt; t += 2) {
;             const bool last = (t == nt - 2);
;             const char* a1 = cA + (size_t)(t + 1) * kstep;
;             const char* a2 = last ? nA : cA + (size_t)(t + 2) * kstep; const char* b2 = last ? nB : cB + (size_t)(t + 2) * kstep;
;             const char* a3 = a2 + kstep; const char* b3 = b2 + kstep;
;             PG8_LDB(B0, 0, 0); PG8_LDB(B1, 0, 1); PG8_SCHED; PG8_LDA(At, 0, 0); PG8_STAGEA(PG8_SA(1, 1), a1 + hstep);
;             PG8_WAIT_V(8); PG8_WAIT_L(0); PG8_BAR; PG8_MMA(0, 0, At, B0); PG8_MMA(0, 1, At, B1); PG8_BAR; PG8_SCHED;
;             PG8_LDA(At, 0, 1); PG8_STAGEB(PG8_SB(0, 0), b2); PG8_STAGEB(PG8_SB(0, 1), b2 + hstep); PG8_STAGEA(PG8_SA(0, 0), a2);
;             PG8_WAIT_V(8); PG8_WAIT_L(0); PG8_BAR; PG8_MMA(1, 0, At, B0); PG8_MMA(1, 1, At, B1); PG8_BAR; PG8_SCHED;
.LBB0_197:
	s_add_u32 s58, s78, 0x100
	s_addc_u32 s59, s79, 0
	s_ashr_i32 s75, s74, 31
	s_lshl_b64 s[76:77], s[74:75], 19
	s_add_u32 s80, s62, s76
	s_addc_u32 s81, s63, s77
	s_and_b64 s[76:77], s[6:7], exec
	s_cselect_b32 s75, s81, s71
	s_cselect_b32 s90, s80, s70
	s_ashr_i32 s73, s72, 31
	s_lshl_b64 s[76:77], s[72:73], 19
	s_add_u32 s76, s30, s76
	s_addc_u32 s77, s31, s77
	s_and_b64 s[82:83], s[6:7], exec
	s_cselect_b32 s73, s77, s79
	s_cselect_b32 s91, s76, s78
	v_lshl_add_u64 v[146:147], s[70:71], 0, v[138:139]
	v_lshl_add_u64 v[148:149], s[70:71], 0, v[140:141]
	s_mov_b32 s92, -2
	s_mov_b64 s[78:79], 0
	v_add_u32_e32 v150, s54, v152
	ds_read_b128 v[156:159], v150
	ds_read_b128 v[160:163], v150 offset:1024
	ds_read_b128 v[164:167], v150 offset:2048
	ds_read_b128 v[168:171], v150 offset:3072
	v_add_u32_e32 v150, s55, v152
	s_add_u32 s82, s70, s78
	ds_read_b128 v[172:175], v150
	ds_read_b128 v[176:179], v150 offset:1024
	ds_read_b128 v[180:183], v150 offset:2048
	ds_read_b128 v[184:187], v150 offset:3072
	s_addc_u32 s83, s71, s79
	s_add_u32 s82, s82, 0x100
	s_addc_u32 s83, s83, 0
	s_add_u32 s93, s58, s78
	s_addc_u32 s94, s59, s79
	s_cmpk_eq_i32 s78, 0x700
	s_cselect_b32 s85, s75, s83
	s_cselect_b32 s84, s90, s82
	s_cselect_b32 s83, s73, s94
	s_cselect_b32 s82, s91, s93
	v_lshl_add_u64 v[150:151], v[146:147], 0, s[78:79]
	s_add_i32 m0, s67, 0xc000
	ds_read_b128 v[188:191], v155
	ds_read_b128 v[192:195], v155 offset:1024
	ds_read_b128 v[196:199], v155 offset:2048
	ds_read_b128 v[200:203], v155 offset:3072
	ds_read_b128 v[204:207], v155 offset:4096
	ds_read_b128 v[208:211], v155 offset:5120
	ds_read_b128 v[212:215], v155 offset:6144
	ds_read_b128 v[216:219], v155 offset:7168
	global_load_lds_dwordx4 v[150:151], off
	v_lshl_add_u64 v[150:151], v[148:149], 0, s[78:79]
	s_add_i32 m0, s67, 0xe000
	s_nop 0
	global_load_lds_dwordx4 v[150:151], off
	s_waitcnt vmcnt(8)
	s_waitcnt lgkmcnt(0)
	s_waitcnt lgkmcnt(0)
	v_mfma_f32_16x16x32_bf16 v[110:113], v[156:159], v[188:191], 0
	v_mfma_f32_16x16x32_bf16 v[106:109], v[164:167], v[188:191], 0
	v_mfma_f32_16x16x32_bf16 v[102:105], v[156:159], v[196:199], 0
	v_mfma_f32_16x16x32_bf16 v[98:101], v[164:167], v[196:199], 0
	s_barrier
	v_mfma_f32_16x16x32_bf16 v[94:97], v[156:159], v[204:207], 0
	v_mfma_f32_16x16x32_bf16 v[90:93], v[164:167], v[204:207], 0
	v_mfma_f32_16x16x32_bf16 v[86:89], v[156:159], v[212:215], 0
	v_mfma_f32_16x16x32_bf16 v[82:85], v[164:167], v[212:215], 0
	v_mfma_f32_16x16x32_bf16 v[110:113], v[160:163], v[192:195], v[110:113]
	v_mfma_f32_16x16x32_bf16 v[106:109], v[168:171], v[192:195], v[106:109]
	v_mfma_f32_16x16x32_bf16 v[102:105], v[160:163], v[200:203], v[102:105]
	v_mfma_f32_16x16x32_bf16 v[98:101], v[168:171], v[200:203], v[98:101]
	v_mfma_f32_16x16x32_bf16 v[94:97], v[160:163], v[208:211], v[94:97]
	v_mfma_f32_16x16x32_bf16 v[90:93], v[168:171], v[208:211], v[90:93]
	v_mfma_f32_16x16x32_bf16 v[86:89], v[160:163], v[216:219], v[86:89]
	v_mfma_f32_16x16x32_bf16 v[82:85], v[168:171], v[216:219], v[82:85]
	v_mfma_f32_16x16x32_bf16 v[78:81], v[172:175], v[188:191], 0
	v_mfma_f32_16x16x32_bf16 v[74:77], v[180:183], v[188:191], 0
	v_mfma_f32_16x16x32_bf16 v[70:73], v[172:175], v[196:199], 0
	v_mfma_f32_16x16x32_bf16 v[66:69], v[180:183], v[196:199], 0
	v_mfma_f32_16x16x32_bf16 v[62:65], v[172:175], v[204:207], 0
	v_mfma_f32_16x16x32_bf16 v[58:61], v[180:183], v[204:207], 0
	v_mfma_f32_16x16x32_bf16 v[54:57], v[172:175], v[212:215], 0
	v_mfma_f32_16x16x32_bf16 v[50:53], v[180:183], v[212:215], 0
	v_mfma_f32_16x16x32_bf16 v[78:81], v[176:179], v[192:195], v[78:81]
	v_mfma_f32_16x16x32_bf16 v[74:77], v[184:187], v[192:195], v[74:77]
	v_mfma_f32_16x16x32_bf16 v[70:73], v[176:179], v[200:203], v[70:73]
	v_mfma_f32_16x16x32_bf16 v[66:69], v[184:187], v[200:203], v[66:69]
	v_mfma_f32_16x16x32_bf16 v[62:65], v[176:179], v[208:211], v[62:65]
	v_mfma_f32_16x16x32_bf16 v[58:61], v[184:187], v[208:211], v[58:61]
	v_mfma_f32_16x16x32_bf16 v[54:57], v[176:179], v[216:219], v[54:57]
	v_mfma_f32_16x16x32_bf16 v[50:53], v[184:187], v[216:219], v[50:53]
	s_barrier
	s_add_i32 s93, s54, s87
	v_lshl_add_u64 v[150:151], s[82:83], 0, v[132:133]
	s_mov_b32 m0, s93
	ds_read_b128 v[188:191], v155 offset:16384
	ds_read_b128 v[192:195], v155 offset:17408
	ds_read_b128 v[196:199], v155 offset:18432
	ds_read_b128 v[200:203], v155 offset:19456
	ds_read_b128 v[204:207], v155 offset:20480
	ds_read_b128 v[208:211], v155 offset:21504
	ds_read_b128 v[212:215], v155 offset:22528
	ds_read_b128 v[216:219], v155 offset:23552
	global_load_lds_dwordx4 v[150:151], off
	s_add_i32 m0, s93, 0x2000
	s_add_u32 s94, s82, 0x40000
	v_lshl_add_u64 v[220:221], s[82:83], 0, v[136:137]
	s_addc_u32 s95, s83, 0
	s_add_i32 s93, s55, s87
	global_load_lds_dwordx4 v[220:221], off
	v_lshl_add_u64 v[222:223], s[94:95], 0, v[132:133]
	s_mov_b32 m0, s93
	v_lshl_add_u64 v[224:225], s[84:85], 0, v[134:135]
	global_load_lds_dwordx4 v[222:223], off
	v_lshl_add_u64 v[222:223], s[94:95], 0, v[136:137]
	s_add_i32 m0, s93, 0x2000
	s_nop 0
	global_load_lds_dwordx4 v[222:223], off
	v_lshl_add_u64 v[222:223], s[84:85], 0, v[130:131]
	s_mov_b32 m0, s67
	s_nop 0
	global_load_lds_dwordx4 v[222:223], off
	s_mov_b32 m0, s69
	s_nop 0
	global_load_lds_dwordx4 v[224:225], off
	s_waitcnt vmcnt(8)
	s_waitcnt lgkmcnt(0)
	s_waitcnt lgkmcnt(0)
	v_mfma_f32_16x16x32_bf16 v[46:49], v[156:159], v[188:191], 0
	v_mfma_f32_16x16x32_bf16 v[42:45], v[164:167], v[188:191], 0
	v_mfma_f32_16x16x32_bf16 v[38:41], v[156:159], v[196:199], 0
	v_mfma_f32_16x16x32_bf16 v[34:37], v[164:167], v[196:199], 0
	s_barrier
; #define PG8_STAGEA(bufoff, gbase) PG8_STAGE_(bufoff, gbase, voffA)
; #define PG8_LDA(dst, b, h) do { _Pragma("unroll") for (int m = 0; m < 4; ++m) _Pragma("unroll") for (int k = 0; k < 2; ++k) dst[m][k] = *(const LAS bf16x8*)(lds + PG8_SA(b, h) + aoff + m * 2048 + k * 1024); } while (0)
; #define PG8_LDB(dst, b, h) do { _Pragma("unroll") for (int n = 0; n < 2; ++n) _Pragma("unroll") for (int k = 0; k < 2; ++k) dst[n][k] = *(const LAS bf16x8*)(lds + PG8_SB(b, h) + boff + n * 2048 + k * 1024); } while (0)
; #define PG8_MMA(ai, bj, At, Bt_) do { __builtin_amdgcn_s_setprio(1); _Pragma("unroll") for (int m = 0; m < 4; ++m) _Pragma("unroll") for (int n = 0; n < 2; ++n) _Pragma("unroll") for (int k = 0; k < 2; ++k) \
;         acc[ai][bj][m][n] = __builtin_amdgcn_mfma_f32_16x16x32_bf16(Bt_[n][k], At[m][k], acc[ai][bj][m][n], 0, 0, 0); __builtin_amdgcn_s_setprio(0); } while (0)
; #define PG8_WAIT_V(n) asm volatile("s_waitcnt vmcnt(" #n ")" ::: "memory")
; #define PG8_WAIT_L(n) asm volatile("s_waitcnt lgkmcnt(" #n ")" ::: "memory")
; #define PG8_BAR __builtin_amdgcn_s_barrier()
; #define PG8_SCHED __builtin_amdgcn_sched_barrier(0)
; template <int EK, int SK = -1>
; __device__ __forceinline__ void gemm_phase(LAS unsigned char* lds, const bf16_t* A, const bf16_t* Bt, int nM, int N, int K, const EpiArgs& E) {
;     ...
;             PG8_WAIT_V(8); PG8_WAIT_L(0); PG8_BAR; PG8_MMA(1, 0, At, B0); PG8_MMA(1, 1, At, B1); PG8_BAR; PG8_SCHED;
;             PG8_LDB(B0, 1, 0); PG8_LDB(B1, 1, 1); PG8_SCHED; PG8_LDA(At, 1, 0); PG8_STAGEA(PG8_SA(0, 1), a2 + hstep);
;             PG8_WAIT_V(8); PG8_WAIT_L(0); PG8_BAR; PG8_MMA(0, 0, At, B0); PG8_MMA(0, 1, At, B1); PG8_BAR; PG8_SCHED;
	v_mfma_f32_16x16x32_bf16 v[30:33], v[156:159], v[204:207], 0
	v_mfma_f32_16x16x32_bf16 v[26:29], v[164:167], v[204:207], 0
	v_mfma_f32_16x16x32_bf16 v[22:25], v[156:159], v[212:215], 0
	v_mfma_f32_16x16x32_bf16 v[18:21], v[164:167], v[212:215], 0
	v_mfma_f32_16x16x32_bf16 v[46:49], v[160:163], v[192:195], v[46:49]
	v_mfma_f32_16x16x32_bf16 v[42:45], v[168:171], v[192:195], v[42:45]
	v_mfma_f32_16x16x32_bf16 v[38:41], v[160:163], v[200:203], v[38:41]
	v_mfma_f32_16x16x32_bf16 v[34:37], v[168:171], v[200:203], v[34:37]
	v_mfma_f32_16x16x32_bf16 v[30:33], v[160:163], v[208:211], v[30:33]
	v_mfma_f32_16x16x32_bf16 v[26:29], v[168:171], v[208:211], v[26:29]
	v_mfma_f32_16x16x32_bf16 v[22:25], v[160:163], v[216:219], v[22:25]
	v_mfma_f32_16x16x32_bf16 v[18:21], v[168:171], v[216:219], v[18:21]
	v_mfma_f32_16x16x32_bf16 v[14:17], v[172:175], v[188:191], 0
	v_mfma_f32_16x16x32_bf16 v[10:13], v[180:183], v[188:191], 0
	v_mfma_f32_16x16x32_bf16 v[6:9], v[172:175], v[196:199], 0
	v_mfma_f32_16x16x32_bf16 v[2:5], v[180:183], v[196:199], 0
	v_mfma_f32_16x16x32_bf16 v[114:117], v[172:175], v[204:207], 0
	v_mfma_f32_16x16x32_bf16 v[118:121], v[180:183], v[204:207], 0
	v_mfma_f32_16x16x32_bf16 v[122:125], v[172:175], v[212:215], 0
	v_mfma_f32_16x16x32_bf16 v[126:129], v[180:183], v[212:215], 0
	v_mfma_f32_16x16x32_bf16 v[14:17], v[176:179], v[192:195], v[14:17]
	v_mfma_f32_16x16x32_bf16 v[10:13], v[184:187], v[192:195], v[10:13]
	v_mfma_f32_16x16x32_bf16 v[6:9], v[176:179], v[200:203], v[6:9]
	v_mfma_f32_16x16x32_bf16 v[2:5], v[184:187], v[200:203], v[2:5]
	v_mfma_f32_16x16x32_bf16 v[114:117], v[176:179], v[208:211], v[114:117]
	v_mfma_f32_16x16x32_bf16 v[118:121], v[184:187], v[208:211], v[118:121]
	v_mfma_f32_16x16x32_bf16 v[122:125], v[176:179], v[216:219], v[122:125]
	v_mfma_f32_16x16x32_bf16 v[126:129], v[184:187], v[216:219], v[126:129]
	s_barrier
	s_add_i32 s93, 0, 0x18000
	s_add_i32 s94, 0, 0x1c000
	v_add_u32_e32 v168, s93, v152
	v_add_u32_e32 v184, s94, v152
	ds_read_b128 v[156:159], v168
	ds_read_b128 v[160:163], v168 offset:1024
	ds_read_b128 v[164:167], v168 offset:2048
	ds_read_b128 v[168:171], v168 offset:3072
	ds_read_b128 v[172:175], v184
	ds_read_b128 v[176:179], v184 offset:1024
	ds_read_b128 v[180:183], v184 offset:2048
	ds_read_b128 v[184:187], v184 offset:3072
	s_add_u32 s84, s84, 0x40000
	s_addc_u32 s85, s85, 0
	s_mov_b32 m0, s88
	v_lshl_add_u64 v[226:227], s[84:85], 0, v[130:131]
	ds_read_b128 v[188:191], v155 offset:32768
	ds_read_b128 v[192:195], v155 offset:33792
	ds_read_b128 v[196:199], v155 offset:34816
	ds_read_b128 v[200:203], v155 offset:35840
	ds_read_b128 v[204:207], v155 offset:36864
	ds_read_b128 v[208:211], v155 offset:37888
	ds_read_b128 v[212:215], v155 offset:38912
	ds_read_b128 v[216:219], v155 offset:39936
	global_load_lds_dwordx4 v[226:227], off
	v_lshl_add_u64 v[226:227], s[84:85], 0, v[134:135]
	s_mov_b32 m0, s89
	s_nop 0
	global_load_lds_dwordx4 v[226:227], off
	s_waitcnt vmcnt(8)
	s_waitcnt lgkmcnt(0)
	s_waitcnt lgkmcnt(0)
	v_mfma_f32_16x16x32_bf16 v[110:113], v[156:159], v[188:191], v[110:113]
	v_mfma_f32_16x16x32_bf16 v[106:109], v[164:167], v[188:191], v[106:109]
	v_mfma_f32_16x16x32_bf16 v[102:105], v[156:159], v[196:199], v[102:105]
	v_mfma_f32_16x16x32_bf16 v[98:101], v[164:167], v[196:199], v[98:101]
	s_barrier
	v_mfma_f32_16x16x32_bf16 v[94:97], v[156:159], v[204:207], v[94:97]
	v_mfma_f32_16x16x32_bf16 v[90:93], v[164:167], v[204:207], v[90:93]
	v_mfma_f32_16x16x32_bf16 v[86:89], v[156:159], v[212:215], v[86:89]
	v_mfma_f32_16x16x32_bf16 v[82:85], v[164:167], v[212:215], v[82:85]
	v_mfma_f32_16x16x32_bf16 v[110:113], v[160:163], v[192:195], v[110:113]
	v_mfma_f32_16x16x32_bf16 v[106:109], v[168:171], v[192:195], v[106:109]
	v_mfma_f32_16x16x32_bf16 v[102:105], v[160:163], v[200:203], v[102:105]
	v_mfma_f32_16x16x32_bf16 v[98:101], v[168:171], v[200:203], v[98:101]
	v_mfma_f32_16x16x32_bf16 v[94:97], v[160:163], v[208:211], v[94:97]
	v_mfma_f32_16x16x32_bf16 v[90:93], v[168:171], v[208:211], v[90:93]
	v_mfma_f32_16x16x32_bf16 v[86:89], v[160:163], v[216:219], v[86:89]
	v_mfma_f32_16x16x32_bf16 v[82:85], v[168:171], v[216:219], v[82:85]
	v_mfma_f32_16x16x32_bf16 v[78:81], v[172:175], v[188:191], v[78:81]
	v_mfma_f32_16x16x32_bf16 v[74:77], v[180:183], v[188:191], v[74:77]
	v_mfma_f32_16x16x32_bf16 v[70:73], v[172:175], v[196:199], v[70:73]
	v_mfma_f32_16x16x32_bf16 v[66:69], v[180:183], v[196:199], v[66:69]
	v_mfma_f32_16x16x32_bf16 v[62:65], v[172:175], v[204:207], v[62:65]
	v_mfma_f32_16x16x32_bf16 v[58:61], v[180:183], v[204:207], v[58:61]
	v_mfma_f32_16x16x32_bf16 v[54:57], v[172:175], v[212:215], v[54:57]
	v_mfma_f32_16x16x32_bf16 v[50:53], v[180:183], v[212:215], v[50:53]
	v_mfma_f32_16x16x32_bf16 v[78:81], v[176:179], v[192:195], v[78:81]
	v_mfma_f32_16x16x32_bf16 v[74:77], v[184:187], v[192:195], v[74:77]
	v_mfma_f32_16x16x32_bf16 v[70:73], v[176:179], v[200:203], v[70:73]
	v_mfma_f32_16x16x32_bf16 v[66:69], v[184:187], v[200:203], v[66:69]
	v_mfma_f32_16x16x32_bf16 v[62:65], v[176:179], v[208:211], v[62:65]
	v_mfma_f32_16x16x32_bf16 v[58:61], v[184:187], v[208:211], v[58:61]
	v_mfma_f32_16x16x32_bf16 v[54:57], v[176:179], v[216:219], v[54:57]
	v_mfma_f32_16x16x32_bf16 v[50:53], v[184:187], v[216:219], v[50:53]
	s_barrier
; #define PG8_STAGEA(bufoff, gbase) PG8_STAGE_(bufoff, gbase, voffA)
; #define PG8_STAGEB(bufoff, gbase) PG8_STAGE_(bufoff, gbase, voffB)
; #define PG8_LDA(dst, b, h) do { _Pragma("unroll") for (int m = 0; m < 4; ++m) _Pragma("unroll") for (int k = 0; k < 2; ++k) dst[m][k] = *(const LAS bf16x8*)(lds + PG8_SA(b, h) + aoff + m * 2048 + k * 1024); } while (0)
; #define PG8_LDB(dst, b, h) do { _Pragma("unroll") for (int n = 0; n < 2; ++n) _Pragma("unroll") for (int k = 0; k < 2; ++k) dst[n][k] = *(const LAS bf16x8*)(lds + PG8_SB(b, h) + boff + n * 2048 + k * 1024); } while (0)
; #define PG8_MMA(ai, bj, At, Bt_) do { __builtin_amdgcn_s_setprio(1); _Pragma("unroll") for (int m = 0; m < 4; ++m) _Pragma("unroll") for (int n = 0; n < 2; ++n) _Pragma("unroll") for (int k = 0; k < 2; ++k) \
;         acc[ai][bj][m][n] = __builtin_amdgcn_mfma_f32_16x16x32_bf16(Bt_[n][k], At[m][k], acc[ai][bj][m][n], 0, 0, 0); __builtin_amdgcn_s_setprio(0); } while (0)
; #define PG8_WAIT_V(n) asm volatile("s_waitcnt vmcnt(" #n ")" ::: "memory")
; #define PG8_WAIT_L(n) asm volatile("s_waitcnt lgkmcnt(" #n ")" ::: "memory")
; #define PG8_BAR __builtin_amdgcn_s_barrier()
; #define PG8_SCHED __builtin_amdgcn_sched_barrier(0)
; template <int EK, int SK = -1>
; __device__ __forceinline__ void gemm_phase(LAS unsigned char* lds, const bf16_t* A, const bf16_t* Bt, int nM, int N, int K, const EpiArgs& E) {
;     ...
;             PG8_LDB(B0, 0, 0); PG8_LDB(B1, 0, 1); PG8_SCHED; PG8_LDA(At, 0, 0); PG8_STAGEA(PG8_SA(1, 1), a1 + hstep);
;             PG8_WAIT_V(8); PG8_WAIT_L(0); PG8_BAR; PG8_MMA(0, 0, At, B0); PG8_MMA(0, 1, At, B1); PG8_BAR; PG8_SCHED;
;     ...
;             PG8_LDA(At, 1, 1); PG8_STAGEB(PG8_SB(1, 0), b3); PG8_STAGEB(PG8_SB(1, 1), b3 + hstep); PG8_STAGEA(PG8_SA(1, 0), a3);
;             PG8_WAIT_V(8); PG8_WAIT_L(0); PG8_BAR; PG8_MMA(1, 0, At, B0); PG8_MMA(1, 1, At, B1); PG8_BAR; PG8_SCHED;
	s_add_i32 s84, s93, s87
	v_lshl_add_u64 v[150:151], v[150:151], 0, s[10:11]
	s_mov_b32 m0, s84
	ds_read_b128 v[188:191], v155 offset:49152
	ds_read_b128 v[192:195], v155 offset:50176
	ds_read_b128 v[196:199], v155 offset:51200
	ds_read_b128 v[200:203], v155 offset:52224
	ds_read_b128 v[204:207], v155 offset:53248
	ds_read_b128 v[208:211], v155 offset:54272
	ds_read_b128 v[212:215], v155 offset:55296
	ds_read_b128 v[216:219], v155 offset:56320
	global_load_lds_dwordx4 v[150:151], off
	s_add_i32 m0, s84, 0x2000
	s_add_u32 s82, s82, 0x40080
	v_lshl_add_u64 v[150:151], v[220:221], 0, s[10:11]
	s_addc_u32 s83, s83, 0
	s_add_i32 s84, s94, s87
	global_load_lds_dwordx4 v[150:151], off
	v_lshl_add_u64 v[150:151], s[82:83], 0, v[132:133]
	s_mov_b32 m0, s84
	s_nop 0
	global_load_lds_dwordx4 v[150:151], off
	v_lshl_add_u64 v[150:151], s[82:83], 0, v[136:137]
	s_add_i32 m0, s84, 0x2000
	s_nop 0
	global_load_lds_dwordx4 v[150:151], off
	v_lshl_add_u64 v[150:151], v[222:223], 0, s[10:11]
	s_mov_b32 m0, s52
	s_nop 0
	global_load_lds_dwordx4 v[150:151], off
	v_lshl_add_u64 v[150:151], v[224:225], 0, s[10:11]
	s_mov_b32 m0, s53
	s_nop 0
	global_load_lds_dwordx4 v[150:151], off
	s_waitcnt vmcnt(8)
	s_waitcnt lgkmcnt(0)
	s_waitcnt lgkmcnt(0)
	v_mfma_f32_16x16x32_bf16 v[46:49], v[156:159], v[188:191], v[46:49]
	v_mfma_f32_16x16x32_bf16 v[42:45], v[164:167], v[188:191], v[42:45]
	v_mfma_f32_16x16x32_bf16 v[38:41], v[156:159], v[196:199], v[38:41]
	v_mfma_f32_16x16x32_bf16 v[34:37], v[164:167], v[196:199], v[34:37]
	s_barrier
	v_mfma_f32_16x16x32_bf16 v[30:33], v[156:159], v[204:207], v[30:33]
	v_mfma_f32_16x16x32_bf16 v[26:29], v[164:167], v[204:207], v[26:29]
	v_mfma_f32_16x16x32_bf16 v[22:25], v[156:159], v[212:215], v[22:25]
	v_mfma_f32_16x16x32_bf16 v[18:21], v[164:167], v[212:215], v[18:21]
	v_mfma_f32_16x16x32_bf16 v[46:49], v[160:163], v[192:195], v[46:49]
	v_mfma_f32_16x16x32_bf16 v[42:45], v[168:171], v[192:195], v[42:45]
	v_mfma_f32_16x16x32_bf16 v[38:41], v[160:163], v[200:203], v[38:41]
	v_mfma_f32_16x16x32_bf16 v[34:37], v[168:171], v[200:203], v[34:37]
	v_mfma_f32_16x16x32_bf16 v[30:33], v[160:163], v[208:211], v[30:33]
	v_mfma_f32_16x16x32_bf16 v[26:29], v[168:171], v[208:211], v[26:29]
	v_mfma_f32_16x16x32_bf16 v[22:25], v[160:163], v[216:219], v[22:25]
	v_mfma_f32_16x16x32_bf16 v[18:21], v[168:171], v[216:219], v[18:21]
	v_mfma_f32_16x16x32_bf16 v[14:17], v[172:175], v[188:191], v[14:17]
	v_mfma_f32_16x16x32_bf16 v[10:13], v[180:183], v[188:191], v[10:13]
	v_mfma_f32_16x16x32_bf16 v[6:9], v[172:175], v[196:199], v[6:9]
	v_mfma_f32_16x16x32_bf16 v[2:5], v[180:183], v[196:199], v[2:5]
	v_mfma_f32_16x16x32_bf16 v[114:117], v[172:175], v[204:207], v[114:117]
	v_mfma_f32_16x16x32_bf16 v[118:121], v[180:183], v[204:207], v[118:121]
	v_mfma_f32_16x16x32_bf16 v[122:125], v[172:175], v[212:215], v[122:125]
	v_mfma_f32_16x16x32_bf16 v[126:129], v[180:183], v[212:215], v[126:129]
	v_mfma_f32_16x16x32_bf16 v[14:17], v[176:179], v[192:195], v[14:17]
	v_mfma_f32_16x16x32_bf16 v[10:13], v[184:187], v[192:195], v[10:13]
	v_mfma_f32_16x16x32_bf16 v[6:9], v[176:179], v[200:203], v[6:9]
	v_mfma_f32_16x16x32_bf16 v[2:5], v[184:187], v[200:203], v[2:5]
	v_mfma_f32_16x16x32_bf16 v[114:117], v[176:179], v[208:211], v[114:117]
	v_mfma_f32_16x16x32_bf16 v[118:121], v[184:187], v[208:211], v[118:121]
	v_mfma_f32_16x16x32_bf16 v[122:125], v[176:179], v[216:219], v[122:125]
	v_mfma_f32_16x16x32_bf16 v[126:129], v[184:187], v[216:219], v[126:129]
	s_barrier
	s_add_i32 s92, s92, 2
	s_add_u32 s78, s78, 0x100
	s_addc_u32 s79, s79, 0
	s_cmp_gt_u32 s92, 13
	s_cbranch_scc0 .LBB0_198
	s_branch .Lmy_kexit_0
.LBB0_198:
	v_add_u32_e32 v150, s54, v152
	ds_read_b128 v[156:159], v150
	ds_read_b128 v[160:163], v150 offset:1024
	ds_read_b128 v[164:167], v150 offset:2048
	ds_read_b128 v[168:171], v150 offset:3072
	v_add_u32_e32 v150, s55, v152
	s_add_u32 s82, s70, s78
	ds_read_b128 v[172:175], v150
	ds_read_b128 v[176:179], v150 offset:1024
	ds_read_b128 v[180:183], v150 offset:2048
	ds_read_b128 v[184:187], v150 offset:3072
	s_addc_u32 s83, s71, s79
	s_add_u32 s82, s82, 0x100
	s_addc_u32 s83, s83, 0
	s_add_u32 s93, s58, s78
	s_addc_u32 s94, s59, s79
	s_cmpk_eq_i32 s78, 0x700
	s_cselect_b32 s85, s75, s83
	s_cselect_b32 s84, s90, s82
	s_cselect_b32 s83, s73, s94
	s_cselect_b32 s82, s91, s93
	v_lshl_add_u64 v[150:151], v[146:147], 0, s[78:79]
	s_add_i32 m0, s67, 0xc000
	ds_read_b128 v[188:191], v155
	ds_read_b128 v[192:195], v155 offset:1024
	ds_read_b128 v[196:199], v155 offset:2048
	ds_read_b128 v[200:203], v155 offset:3072
	ds_read_b128 v[204:207], v155 offset:4096
	ds_read_b128 v[208:211], v155 offset:5120
	ds_read_b128 v[212:215], v155 offset:6144
	ds_read_b128 v[216:219], v155 offset:7168
	global_load_lds_dwordx4 v[150:151], off
	v_lshl_add_u64 v[150:151], v[148:149], 0, s[78:79]
	s_add_i32 m0, s67, 0xe000
	s_nop 0
	global_load_lds_dwordx4 v[150:151], off
	s_waitcnt vmcnt(8)
	s_waitcnt lgkmcnt(0)
	s_waitcnt lgkmcnt(0)
	v_mfma_f32_16x16x32_bf16 v[110:113], v[156:159], v[188:191], v[110:113]
	v_mfma_f32_16x16x32_bf16 v[106:109], v[164:167], v[188:191], v[106:109]
	v_mfma_f32_16x16x32_bf16 v[102:105], v[156:159], v[196:199], v[102:105]
	v_mfma_f32_16x16x32_bf16 v[98:101], v[164:167], v[196:199], v[98:101]
	s_barrier
; #define PG8_STAGEA(bufoff, gbase) PG8_STAGE_(bufoff, gbase, voffA)
; #define PG8_STAGEB(bufoff, gbase) PG8_STAGE_(bufoff, gbase, voffB)
; #define PG8_LDA(dst, b, h) do { _Pragma("unroll") for (int m = 0; m < 4; ++m) _Pragma("unroll") for (int k = 0; k < 2; ++k) dst[m][k] = *(const LAS bf16x8*)(lds + PG8_SA(b, h) + aoff + m * 2048 + k * 1024); } while (0)
; #define PG8_MMA(ai, bj, At, Bt_) do { __builtin_amdgcn_s_setprio(1); _Pragma("unroll") for (int m = 0; m < 4; ++m) _Pragma("unroll") for (int n = 0; n < 2; ++n) _Pragma("unroll") for (int k = 0; k < 2; ++k) \
;         acc[ai][bj][m][n] = __builtin_amdgcn_mfma_f32_16x16x32_bf16(Bt_[n][k], At[m][k], acc[ai][bj][m][n], 0, 0, 0); __builtin_amdgcn_s_setprio(0); } while (0)
; #define PG8_WAIT_V(n) asm volatile("s_waitcnt vmcnt(" #n ")" ::: "memory")
; #define PG8_WAIT_L(n) asm volatile("s_waitcnt lgkmcnt(" #n ")" ::: "memory")
; #define PG8_BAR __builtin_amdgcn_s_barrier()
; #define PG8_SCHED __builtin_amdgcn_sched_barrier(0)
; template <int EK, int SK = -1>
; __device__ __forceinline__ void gemm_phase(LAS unsigned char* lds, const bf16_t* A, const bf16_t* Bt, int nM, int N, int K, const EpiArgs& E) {
;     ...
;             PG8_WAIT_V(8); PG8_WAIT_L(0); PG8_BAR; PG8_MMA(0, 0, At, B0); PG8_MMA(0, 1, At, B1); PG8_BAR; PG8_SCHED;
;             PG8_LDA(At, 0, 1); PG8_STAGEB(PG8_SB(0, 0), b2); PG8_STAGEB(PG8_SB(0, 1), b2 + hstep); PG8_STAGEA(PG8_SA(0, 0), a2);
;             PG8_WAIT_V(8); PG8_WAIT_L(0); PG8_BAR; PG8_MMA(1, 0, At, B0); PG8_MMA(1, 1, At, B1); PG8_BAR; PG8_SCHED;
	v_mfma_f32_16x16x32_bf16 v[94:97], v[156:159], v[204:207], v[94:97]
	v_mfma_f32_16x16x32_bf16 v[90:93], v[164:167], v[204:207], v[90:93]
	v_mfma_f32_16x16x32_bf16 v[86:89], v[156:159], v[212:215], v[86:89]
	v_mfma_f32_16x16x32_bf16 v[82:85], v[164:167], v[212:215], v[82:85]
	v_mfma_f32_16x16x32_bf16 v[110:113], v[160:163], v[192:195], v[110:113]
	v_mfma_f32_16x16x32_bf16 v[106:109], v[168:171], v[192:195], v[106:109]
	v_mfma_f32_16x16x32_bf16 v[102:105], v[160:163], v[200:203], v[102:105]
	v_mfma_f32_16x16x32_bf16 v[98:101], v[168:171], v[200:203], v[98:101]
	v_mfma_f32_16x16x32_bf16 v[94:97], v[160:163], v[208:211], v[94:97]
	v_mfma_f32_16x16x32_bf16 v[90:93], v[168:171], v[208:211], v[90:93]
	v_mfma_f32_16x16x32_bf16 v[86:89], v[160:163], v[216:219], v[86:89]
	v_mfma_f32_16x16x32_bf16 v[82:85], v[168:171], v[216:219], v[82:85]
	v_mfma_f32_16x16x32_bf16 v[78:81], v[172:175], v[188:191], v[78:81]
	v_mfma_f32_16x16x32_bf16 v[74:77], v[180:183], v[188:191], v[74:77]
	v_mfma_f32_16x16x32_bf16 v[70:73], v[172:175], v[196:199], v[70:73]
	v_mfma_f32_16x16x32_bf16 v[66:69], v[180:183], v[196:199], v[66:69]
	v_mfma_f32_16x16x32_bf16 v[62:65], v[172:175], v[204:207], v[62:65]
	v_mfma_f32_16x16x32_bf16 v[58:61], v[180:183], v[204:207], v[58:61]
	v_mfma_f32_16x16x32_bf16 v[54:57], v[172:175], v[212:215], v[54:57]
	v_mfma_f32_16x16x32_bf16 v[50:53], v[180:183], v[212:215], v[50:53]
	v_mfma_f32_16x16x32_bf16 v[78:81], v[176:179], v[192:195], v[78:81]
	v_mfma_f32_16x16x32_bf16 v[74:77], v[184:187], v[192:195], v[74:77]
	v_mfma_f32_16x16x32_bf16 v[70:73], v[176:179], v[200:203], v[70:73]
	v_mfma_f32_16x16x32_bf16 v[66:69], v[184:187], v[200:203], v[66:69]
	v_mfma_f32_16x16x32_bf16 v[62:65], v[176:179], v[208:211], v[62:65]
	v_mfma_f32_16x16x32_bf16 v[58:61], v[184:187], v[208:211], v[58:61]
	v_mfma_f32_16x16x32_bf16 v[54:57], v[176:179], v[216:219], v[54:57]
	v_mfma_f32_16x16x32_bf16 v[50:53], v[184:187], v[216:219], v[50:53]
	s_barrier
	s_add_i32 s93, s54, s87
	v_lshl_add_u64 v[150:151], s[82:83], 0, v[132:133]
	s_mov_b32 m0, s93
	ds_read_b128 v[188:191], v155 offset:16384
	ds_read_b128 v[192:195], v155 offset:17408
	ds_read_b128 v[196:199], v155 offset:18432
	ds_read_b128 v[200:203], v155 offset:19456
	ds_read_b128 v[204:207], v155 offset:20480
	ds_read_b128 v[208:211], v155 offset:21504
	ds_read_b128 v[212:215], v155 offset:22528
	ds_read_b128 v[216:219], v155 offset:23552
	global_load_lds_dwordx4 v[150:151], off
	s_add_i32 m0, s93, 0x2000
	s_add_u32 s94, s82, 0x40000
	v_lshl_add_u64 v[220:221], s[82:83], 0, v[136:137]
	s_addc_u32 s95, s83, 0
	s_add_i32 s93, s55, s87
	global_load_lds_dwordx4 v[220:221], off
	v_lshl_add_u64 v[222:223], s[94:95], 0, v[132:133]
	s_mov_b32 m0, s93
	v_lshl_add_u64 v[224:225], s[84:85], 0, v[134:135]
	global_load_lds_dwordx4 v[222:223], off
	v_lshl_add_u64 v[222:223], s[94:95], 0, v[136:137]
	s_add_i32 m0, s93, 0x2000
	s_nop 0
	global_load_lds_dwordx4 v[222:223], off
	v_lshl_add_u64 v[222:223], s[84:85], 0, v[130:131]
	s_mov_b32 m0, s67
	s_nop 0
	global_load_lds_dwordx4 v[222:223], off
	s_mov_b32 m0, s69
	s_nop 0
	global_load_lds_dwordx4 v[224:225], off
	s_waitcnt vmcnt(8)
	s_waitcnt lgkmcnt(0)
	s_waitcnt lgkmcnt(0)
	v_mfma_f32_16x16x32_bf16 v[46:49], v[156:159], v[188:191], v[46:49]
	v_mfma_f32_16x16x32_bf16 v[42:45], v[164:167], v[188:191], v[42:45]
	v_mfma_f32_16x16x32_bf16 v[38:41], v[156:159], v[196:199], v[38:41]
	v_mfma_f32_16x16x32_bf16 v[34:37], v[164:167], v[196:199], v[34:37]
	s_barrier
	v_mfma_f32_16x16x32_bf16 v[30:33], v[156:159], v[204:207], v[30:33]
	v_mfma_f32_16x16x32_bf16 v[26:29], v[164:167], v[204:207], v[26:29]
	v_mfma_f32_16x16x32_bf16 v[22:25], v[156:159], v[212:215], v[22:25]
	v_mfma_f32_16x16x32_bf16 v[18:21], v[164:167], v[212:215], v[18:21]
	v_mfma_f32_16x16x32_bf16 v[46:49], v[160:163], v[192:195], v[46:49]
	v_mfma_f32_16x16x32_bf16 v[42:45], v[168:171], v[192:195], v[42:45]
	v_mfma_f32_16x16x32_bf16 v[38:41], v[160:163], v[200:203], v[38:41]
	v_mfma_f32_16x16x32_bf16 v[34:37], v[168:171], v[200:203], v[34:37]
	v_mfma_f32_16x16x32_bf16 v[30:33], v[160:163], v[208:211], v[30:33]
	v_mfma_f32_16x16x32_bf16 v[26:29], v[168:171], v[208:211], v[26:29]
	v_mfma_f32_16x16x32_bf16 v[22:25], v[160:163], v[216:219], v[22:25]
	v_mfma_f32_16x16x32_bf16 v[18:21], v[168:171], v[216:219], v[18:21]
	v_mfma_f32_16x16x32_bf16 v[14:17], v[172:175], v[188:191], v[14:17]
	v_mfma_f32_16x16x32_bf16 v[10:13], v[180:183], v[188:191], v[10:13]
	v_mfma_f32_16x16x32_bf16 v[6:9], v[172:175], v[196:199], v[6:9]
	v_mfma_f32_16x16x32_bf16 v[2:5], v[180:183], v[196:199], v[2:5]
	v_mfma_f32_16x16x32_bf16 v[114:117], v[172:175], v[204:207], v[114:117]
	v_mfma_f32_16x16x32_bf16 v[118:121], v[180:183], v[204:207], v[118:121]
	v_mfma_f32_16x16x32_bf16 v[122:125], v[172:175], v[212:215], v[122:125]
	v_mfma_f32_16x16x32_bf16 v[126:129], v[180:183], v[212:215], v[126:129]
	v_mfma_f32_16x16x32_bf16 v[14:17], v[176:179], v[192:195], v[14:17]
	v_mfma_f32_16x16x32_bf16 v[10:13], v[184:187], v[192:195], v[10:13]
	v_mfma_f32_16x16x32_bf16 v[6:9], v[176:179], v[200:203], v[6:9]
	v_mfma_f32_16x16x32_bf16 v[2:5], v[184:187], v[200:203], v[2:5]
	v_mfma_f32_16x16x32_bf16 v[114:117], v[176:179], v[208:211], v[114:117]
	v_mfma_f32_16x16x32_bf16 v[118:121], v[184:187], v[208:211], v[118:121]
	v_mfma_f32_16x16x32_bf16 v[122:125], v[176:179], v[216:219], v[122:125]
	v_mfma_f32_16x16x32_bf16 v[126:129], v[184:187], v[216:219], v[126:129]
	s_barrier
; #define PG8_STAGEA(bufoff, gbase) PG8_STAGE_(bufoff, gbase, voffA)
; #define PG8_STAGEB(bufoff, gbase) PG8_STAGE_(bufoff, gbase, voffB)
; #define PG8_LDA(dst, b, h) do { _Pragma("unroll") for (int m = 0; m < 4; ++m) _Pragma("unroll") for (int k = 0; k < 2; ++k) dst[m][k] = *(const LAS bf16x8*)(lds + PG8_SA(b, h) + aoff + m * 2048 + k * 1024); } while (0)
; #define PG8_LDB(dst, b, h) do { _Pragma("unroll") for (int n = 0; n < 2; ++n) _Pragma("unroll") for (int k = 0; k < 2; ++k) dst[n][k] = *(const LAS bf16x8*)(lds + PG8_SB(b, h) + boff + n * 2048 + k * 1024); } while (0)
; #define PG8_MMA(ai, bj, At, Bt_) do { __builtin_amdgcn_s_setprio(1); _Pragma("unroll") for (int m = 0; m < 4; ++m) _Pragma("unroll") for (int n = 0; n < 2; ++n) _Pragma("unroll") for (int k = 0; k < 2; ++k) \
;         acc[ai][bj][m][n] = __builtin_amdgcn_mfma_f32_16x16x32_bf16(Bt_[n][k], At[m][k], acc[ai][bj][m][n], 0, 0, 0); __builtin_amdgcn_s_setprio(0); } while (0)
; #define PG8_WAIT_V(n) asm volatile("s_waitcnt vmcnt(" #n ")" ::: "memory")
; #define PG8_WAIT_L(n) asm volatile("s_waitcnt lgkmcnt(" #n ")" ::: "memory")
; #define PG8_BAR __builtin_amdgcn_s_barrier()
; #define PG8_SCHED __builtin_amdgcn_sched_barrier(0)
; template <int EK, int SK = -1>
; __device__ __forceinline__ void gemm_phase(LAS unsigned char* lds, const bf16_t* A, const bf16_t* Bt, int nM, int N, int K, const EpiArgs& E) {
;     ...
;             PG8_LDB(B0, 1, 0); PG8_LDB(B1, 1, 1); PG8_SCHED; PG8_LDA(At, 1, 0); PG8_STAGEA(PG8_SA(0, 1), a2 + hstep);
;             PG8_WAIT_V(8); PG8_WAIT_L(0); PG8_BAR; PG8_MMA(0, 0, At, B0); PG8_MMA(0, 1, At, B1); PG8_BAR; PG8_SCHED;
;             PG8_LDA(At, 1, 1); PG8_STAGEB(PG8_SB(1, 0), b3); PG8_STAGEB(PG8_SB(1, 1), b3 + hstep); PG8_STAGEA(PG8_SA(1, 0), a3);
;             PG8_WAIT_V(8); PG8_WAIT_L(0); PG8_BAR; PG8_MMA(1, 0, At, B0); PG8_MMA(1, 1, At, B1); PG8_BAR; PG8_SCHED;
	s_add_i32 s93, 0, 0x18000
	s_add_i32 s94, 0, 0x1c000
	v_add_u32_e32 v168, s93, v152
	v_add_u32_e32 v184, s94, v152
	ds_read_b128 v[156:159], v168
	ds_read_b128 v[160:163], v168 offset:1024
	ds_read_b128 v[164:167], v168 offset:2048
	ds_read_b128 v[168:171], v168 offset:3072
	ds_read_b128 v[172:175], v184
	ds_read_b128 v[176:179], v184 offset:1024
	ds_read_b128 v[180:183], v184 offset:2048
	ds_read_b128 v[184:187], v184 offset:3072
	s_add_u32 s84, s84, 0x40000
	s_addc_u32 s85, s85, 0
	s_mov_b32 m0, s88
	v_lshl_add_u64 v[226:227], s[84:85], 0, v[130:131]
	ds_read_b128 v[188:191], v155 offset:32768
	ds_read_b128 v[192:195], v155 offset:33792
	ds_read_b128 v[196:199], v155 offset:34816
	ds_read_b128 v[200:203], v155 offset:35840
	ds_read_b128 v[204:207], v155 offset:36864
	ds_read_b128 v[208:211], v155 offset:37888
	ds_read_b128 v[212:215], v155 offset:38912
	ds_read_b128 v[216:219], v155 offset:39936
	global_load_lds_dwordx4 v[226:227], off
	v_lshl_add_u64 v[226:227], s[84:85], 0, v[134:135]
	s_mov_b32 m0, s89
	s_nop 0
	global_load_lds_dwordx4 v[226:227], off
	s_waitcnt vmcnt(8)
	s_waitcnt lgkmcnt(0)
	s_waitcnt lgkmcnt(0)
	v_mfma_f32_16x16x32_bf16 v[110:113], v[156:159], v[188:191], v[110:113]
	v_mfma_f32_16x16x32_bf16 v[106:109], v[164:167], v[188:191], v[106:109]
	v_mfma_f32_16x16x32_bf16 v[102:105], v[156:159], v[196:199], v[102:105]
	v_mfma_f32_16x16x32_bf16 v[98:101], v[164:167], v[196:199], v[98:101]
	s_barrier
	v_mfma_f32_16x16x32_bf16 v[94:97], v[156:159], v[204:207], v[94:97]
	v_mfma_f32_16x16x32_bf16 v[90:93], v[164:167], v[204:207], v[90:93]
	v_mfma_f32_16x16x32_bf16 v[86:89], v[156:159], v[212:215], v[86:89]
	v_mfma_f32_16x16x32_bf16 v[82:85], v[164:167], v[212:215], v[82:85]
	v_mfma_f32_16x16x32_bf16 v[110:113], v[160:163], v[192:195], v[110:113]
	v_mfma_f32_16x16x32_bf16 v[106:109], v[168:171], v[192:195], v[106:109]
	v_mfma_f32_16x16x32_bf16 v[102:105], v[160:163], v[200:203], v[102:105]
	v_mfma_f32_16x16x32_bf16 v[98:101], v[168:171], v[200:203], v[98:101]
	v_mfma_f32_16x16x32_bf16 v[94:97], v[160:163], v[208:211], v[94:97]
	v_mfma_f32_16x16x32_bf16 v[90:93], v[168:171], v[208:211], v[90:93]
	v_mfma_f32_16x16x32_bf16 v[86:89], v[160:163], v[216:219], v[86:89]
	v_mfma_f32_16x16x32_bf16 v[82:85], v[168:171], v[216:219], v[82:85]
	v_mfma_f32_16x16x32_bf16 v[78:81], v[172:175], v[188:191], v[78:81]
	v_mfma_f32_16x16x32_bf16 v[74:77], v[180:183], v[188:191], v[74:77]
	v_mfma_f32_16x16x32_bf16 v[70:73], v[172:175], v[196:199], v[70:73]
	v_mfma_f32_16x16x32_bf16 v[66:69], v[180:183], v[196:199], v[66:69]
	v_mfma_f32_16x16x32_bf16 v[62:65], v[172:175], v[204:207], v[62:65]
	v_mfma_f32_16x16x32_bf16 v[58:61], v[180:183], v[204:207], v[58:61]
	v_mfma_f32_16x16x32_bf16 v[54:57], v[172:175], v[212:215], v[54:57]
	v_mfma_f32_16x16x32_bf16 v[50:53], v[180:183], v[212:215], v[50:53]
	v_mfma_f32_16x16x32_bf16 v[78:81], v[176:179], v[192:195], v[78:81]
	v_mfma_f32_16x16x32_bf16 v[74:77], v[184:187], v[192:195], v[74:77]
	v_mfma_f32_16x16x32_bf16 v[70:73], v[176:179], v[200:203], v[70:73]
	v_mfma_f32_16x16x32_bf16 v[66:69], v[184:187], v[200:203], v[66:69]
	v_mfma_f32_16x16x32_bf16 v[62:65], v[176:179], v[208:211], v[62:65]
	v_mfma_f32_16x16x32_bf16 v[58:61], v[184:187], v[208:211], v[58:61]
	v_mfma_f32_16x16x32_bf16 v[54:57], v[176:179], v[216:219], v[54:57]
	v_mfma_f32_16x16x32_bf16 v[50:53], v[184:187], v[216:219], v[50:53]
	s_barrier
	s_add_i32 s84, s93, s87
	v_lshl_add_u64 v[150:151], v[150:151], 0, s[10:11]
	s_mov_b32 m0, s84
	ds_read_b128 v[188:191], v155 offset:49152
	ds_read_b128 v[192:195], v155 offset:50176
	ds_read_b128 v[196:199], v155 offset:51200
	ds_read_b128 v[200:203], v155 offset:52224
	ds_read_b128 v[204:207], v155 offset:53248
	ds_read_b128 v[208:211], v155 offset:54272
	ds_read_b128 v[212:215], v155 offset:55296
	ds_read_b128 v[216:219], v155 offset:56320
	global_load_lds_dwordx4 v[150:151], off
	s_add_i32 m0, s84, 0x2000
	s_add_u32 s82, s82, 0x40080
	v_lshl_add_u64 v[150:151], v[220:221], 0, s[10:11]
	s_addc_u32 s83, s83, 0
	s_add_i32 s84, s94, s87
	global_load_lds_dwordx4 v[150:151], off
	v_lshl_add_u64 v[150:151], s[82:83], 0, v[132:133]
	s_mov_b32 m0, s84
	s_nop 0
	global_load_lds_dwordx4 v[150:151], off
	v_lshl_add_u64 v[150:151], s[82:83], 0, v[136:137]
	s_add_i32 m0, s84, 0x2000
	s_nop 0
	global_load_lds_dwordx4 v[150:151], off
	v_lshl_add_u64 v[150:151], v[222:223], 0, s[10:11]
	s_mov_b32 m0, s52
	s_nop 0
	global_load_lds_dwordx4 v[150:151], off
	v_lshl_add_u64 v[150:151], v[224:225], 0, s[10:11]
	s_mov_b32 m0, s53
	s_nop 0
	global_load_lds_dwordx4 v[150:151], off
	s_waitcnt vmcnt(8)
	s_waitcnt lgkmcnt(0)
	s_waitcnt lgkmcnt(0)
	v_mfma_f32_16x16x32_bf16 v[46:49], v[156:159], v[188:191], v[46:49]
	v_mfma_f32_16x16x32_bf16 v[42:45], v[164:167], v[188:191], v[42:45]
	v_mfma_f32_16x16x32_bf16 v[38:41], v[156:159], v[196:199], v[38:41]
	v_mfma_f32_16x16x32_bf16 v[34:37], v[164:167], v[196:199], v[34:37]
	s_barrier
	v_mfma_f32_16x16x32_bf16 v[30:33], v[156:159], v[204:207], v[30:33]
	v_mfma_f32_16x16x32_bf16 v[26:29], v[164:167], v[204:207], v[26:29]
	v_mfma_f32_16x16x32_bf16 v[22:25], v[156:159], v[212:215], v[22:25]
	v_mfma_f32_16x16x32_bf16 v[18:21], v[164:167], v[212:215], v[18:21]
	v_mfma_f32_16x16x32_bf16 v[46:49], v[160:163], v[192:195], v[46:49]
	v_mfma_f32_16x16x32_bf16 v[42:45], v[168:171], v[192:195], v[42:45]
	v_mfma_f32_16x16x32_bf16 v[38:41], v[160:163], v[200:203], v[38:41]
	v_mfma_f32_16x16x32_bf16 v[34:37], v[168:171], v[200:203], v[34:37]
	v_mfma_f32_16x16x32_bf16 v[30:33], v[160:163], v[208:211], v[30:33]
	v_mfma_f32_16x16x32_bf16 v[26:29], v[168:171], v[208:211], v[26:29]
	v_mfma_f32_16x16x32_bf16 v[22:25], v[160:163], v[216:219], v[22:25]
	v_mfma_f32_16x16x32_bf16 v[18:21], v[168:171], v[216:219], v[18:21]
	v_mfma_f32_16x16x32_bf16 v[14:17], v[172:175], v[188:191], v[14:17]
	v_mfma_f32_16x16x32_bf16 v[10:13], v[180:183], v[188:191], v[10:13]
	v_mfma_f32_16x16x32_bf16 v[6:9], v[172:175], v[196:199], v[6:9]
	v_mfma_f32_16x16x32_bf16 v[2:5], v[180:183], v[196:199], v[2:5]
	v_mfma_f32_16x16x32_bf16 v[114:117], v[172:175], v[204:207], v[114:117]
	v_mfma_f32_16x16x32_bf16 v[118:121], v[180:183], v[204:207], v[118:121]
	v_mfma_f32_16x16x32_bf16 v[122:125], v[172:175], v[212:215], v[122:125]
	v_mfma_f32_16x16x32_bf16 v[126:129], v[180:183], v[212:215], v[126:129]
	v_mfma_f32_16x16x32_bf16 v[14:17], v[176:179], v[192:195], v[14:17]
	v_mfma_f32_16x16x32_bf16 v[10:13], v[184:187], v[192:195], v[10:13]
	v_mfma_f32_16x16x32_bf16 v[6:9], v[176:179], v[200:203], v[6:9]
	v_mfma_f32_16x16x32_bf16 v[2:5], v[184:187], v[200:203], v[2:5]
	v_mfma_f32_16x16x32_bf16 v[114:117], v[176:179], v[208:211], v[114:117]
	v_mfma_f32_16x16x32_bf16 v[118:121], v[184:187], v[208:211], v[118:121]
	v_mfma_f32_16x16x32_bf16 v[122:125], v[176:179], v[216:219], v[122:125]
	v_mfma_f32_16x16x32_bf16 v[126:129], v[184:187], v[216:219], v[126:129]
	s_barrier
	s_add_i32 s92, s92, 2
	s_add_u32 s78, s78, 0x100
	s_addc_u32 s79, s79, 0
	s_cmp_gt_u32 s92, 13
	s_cbranch_scc0 .LBB0_198

; #define PG8_STAGEA(bufoff, gbase) PG8_STAGE_(bufoff, gbase, voffA)
; #define PG8_STAGEB(bufoff, gbase) PG8_STAGE_(bufoff, gbase, voffB)
; #define PG8_LDA(dst, b, h) do { _Pragma("unroll") for (int m = 0; m < 4; ++m) _Pragma("unroll") for (int k = 0; k < 2; ++k) dst[m][k] = *(const LAS bf16x8*)(lds + PG8_SA(b, h) + aoff + m * 2048 + k * 1024); } while (0)
; #define PG8_LDB(dst, b, h) do { _Pragma("unroll") for (int n = 0; n < 2; ++n) _Pragma("unroll") for (int k = 0; k < 2; ++k) dst[n][k] = *(const LAS bf16x8*)(lds + PG8_SB(b, h) + boff + n * 2048 + k * 1024); } while (0)
; #define PG8_MMA(ai, bj, At, Bt_) do { __builtin_amdgcn_s_setprio(1); _Pragma("unroll") for (int m = 0; m < 4; ++m) _Pragma("unroll") for (int n = 0; n < 2; ++n) _Pragma("unroll") for (int k = 0; k < 2; ++k) \
;         acc[ai][bj][m][n] = __builtin_amdgcn_mfma_f32_16x16x32_bf16(Bt_[n][k], At[m][k], acc[ai][bj][m][n], 0, 0, 0); __builtin_amdgcn_s_setprio(0); } while (0)
; #define PG8_WAIT_V(n) asm volatile("s_waitcnt vmcnt(" #n ")" ::: "memory")
; #define PG8_WAIT_L(n) asm volatile("s_waitcnt lgkmcnt(" #n ")" ::: "memory")
; #define PG8_BAR __builtin_amdgcn_s_barrier()
; template <int EK, int SK = -1>
; __device__ __forceinline__ void gemm_phase(LAS unsigned char* lds, const bf16_t* A, const bf16_t* Bt, int nM, int N, int K, const EpiArgs& E) {
;     ...
;         const bool has_next = S.next(ui + 1, nxt);
;         const char* nA = has_next ? (const char*)A + (size_t)nxt.pm * tstep : cA; const char* nB = has_next ? (const char*)Bt + (size_t)nxt.pn * tstep : cB;
;         for (int t = 0; t < nt; t += 2) {
;             const bool last = (t == nt - 2);
;             const char* a1 = cA + (size_t)(t + 1) * kstep;
;             const char* a2 = last ? nA : cA + (size_t)(t + 2) * kstep; const char* b2 = last ? nB : cB + (size_t)(t + 2) * kstep;
;             const char* a3 = a2 + kstep; const char* b3 = b2 + kstep;
;             PG8_LDB(B0, 0, 0); PG8_LDB(B1, 0, 1); PG8_SCHED; PG8_LDA(At, 0, 0); PG8_STAGEA(PG8_SA(1, 1), a1 + hstep);
;             PG8_WAIT_V(8); PG8_WAIT_L(0); PG8_BAR; PG8_MMA(0, 0, At, B0); PG8_MMA(0, 1, At, B1); PG8_BAR; PG8_SCHED;
;             PG8_LDA(At, 0, 1); PG8_STAGEB(PG8_SB(0, 0), b2); PG8_STAGEB(PG8_SB(0, 1), b2 + hstep); PG8_STAGEA(PG8_SA(0, 0), a2);
;             PG8_WAIT_V(8); PG8_WAIT_L(0); PG8_BAR; PG8_MMA(1, 0, At, B0); PG8_MMA(1, 1, At, B1); PG8_BAR; PG8_SCHED;
.LBB0_412:
	s_add_u32 s53, s80, 0x100
	s_addc_u32 s54, s81, 0
	s_ashr_i32 s75, s74, 31
	s_lshl_b64 s[56:57], s[74:75], 19
	s_add_u32 s78, s66, s56
	s_addc_u32 s79, s67, s57
	s_and_b64 s[56:57], s[8:9], exec
	s_cselect_b32 s40, s79, s19
	s_cselect_b32 s55, s78, s18
	s_ashr_i32 s73, s72, 31
	s_lshl_b64 s[56:57], s[72:73], 19
	s_add_u32 s76, s86, s56
	s_addc_u32 s77, s87, s57
	s_and_b64 s[56:57], s[8:9], exec
	s_cselect_b32 s56, s77, s81
	s_cselect_b32 s57, s76, s80
	v_lshl_add_u64 v[146:147], s[18:19], 0, v[138:139]
	v_lshl_add_u64 v[148:149], s[18:19], 0, v[140:141]
	s_mov_b32 s58, -2
	s_mov_b64 s[80:81], 0
	v_add_u32_e32 v150, s95, v152
	ds_read_b128 v[156:159], v150
	ds_read_b128 v[160:163], v150 offset:1024
	ds_read_b128 v[164:167], v150 offset:2048
	ds_read_b128 v[168:171], v150 offset:3072
	v_add_u32_e32 v150, s96, v152
	s_add_u32 s59, s18, s80
	ds_read_b128 v[172:175], v150
	ds_read_b128 v[176:179], v150 offset:1024
	ds_read_b128 v[180:183], v150 offset:2048
	ds_read_b128 v[184:187], v150 offset:3072
	s_addc_u32 s73, s19, s81
	s_add_u32 s59, s59, 0x100
	s_addc_u32 s73, s73, 0
	s_add_u32 s75, s53, s80
	s_addc_u32 s82, s54, s81
	s_cmpk_eq_i32 s80, 0x700
	s_cselect_b32 s85, s40, s73
	s_cselect_b32 s84, s55, s59
	s_cselect_b32 s83, s56, s82
	s_cselect_b32 s82, s57, s75
	v_lshl_add_u64 v[150:151], v[146:147], 0, s[80:81]
	s_add_i32 m0, s15, 0xc000
	ds_read_b128 v[188:191], v154
	ds_read_b128 v[192:195], v154 offset:1024
	ds_read_b128 v[196:199], v154 offset:2048
	ds_read_b128 v[200:203], v154 offset:3072
	ds_read_b128 v[204:207], v154 offset:4096
	ds_read_b128 v[208:211], v154 offset:5120
	ds_read_b128 v[212:215], v154 offset:6144
	ds_read_b128 v[216:219], v154 offset:7168
	global_load_lds_dwordx4 v[150:151], off
	v_lshl_add_u64 v[150:151], v[148:149], 0, s[80:81]
	s_add_i32 m0, s15, 0xe000
	s_nop 0
	global_load_lds_dwordx4 v[150:151], off
	s_waitcnt vmcnt(8)
	s_waitcnt lgkmcnt(0)
	s_waitcnt lgkmcnt(0)
	v_mfma_f32_16x16x32_bf16 v[126:129], v[156:159], v[188:191], 0
	v_mfma_f32_16x16x32_bf16 v[122:125], v[164:167], v[188:191], 0
	v_mfma_f32_16x16x32_bf16 v[118:121], v[156:159], v[196:199], 0
	v_mfma_f32_16x16x32_bf16 v[114:117], v[164:167], v[196:199], 0
	s_barrier
	v_mfma_f32_16x16x32_bf16 v[110:113], v[156:159], v[204:207], 0
	v_mfma_f32_16x16x32_bf16 v[106:109], v[164:167], v[204:207], 0
	v_mfma_f32_16x16x32_bf16 v[102:105], v[156:159], v[212:215], 0
	v_mfma_f32_16x16x32_bf16 v[98:101], v[164:167], v[212:215], 0
	v_mfma_f32_16x16x32_bf16 v[126:129], v[160:163], v[192:195], v[126:129]
	v_mfma_f32_16x16x32_bf16 v[122:125], v[168:171], v[192:195], v[122:125]
	v_mfma_f32_16x16x32_bf16 v[118:121], v[160:163], v[200:203], v[118:121]
	v_mfma_f32_16x16x32_bf16 v[114:117], v[168:171], v[200:203], v[114:117]
	v_mfma_f32_16x16x32_bf16 v[110:113], v[160:163], v[208:211], v[110:113]
	v_mfma_f32_16x16x32_bf16 v[106:109], v[168:171], v[208:211], v[106:109]
	v_mfma_f32_16x16x32_bf16 v[102:105], v[160:163], v[216:219], v[102:105]
	v_mfma_f32_16x16x32_bf16 v[98:101], v[168:171], v[216:219], v[98:101]
	v_mfma_f32_16x16x32_bf16 v[94:97], v[172:175], v[188:191], 0
	v_mfma_f32_16x16x32_bf16 v[90:93], v[180:183], v[188:191], 0
	v_mfma_f32_16x16x32_bf16 v[86:89], v[172:175], v[196:199], 0
	v_mfma_f32_16x16x32_bf16 v[82:85], v[180:183], v[196:199], 0
	v_mfma_f32_16x16x32_bf16 v[78:81], v[172:175], v[204:207], 0
	v_mfma_f32_16x16x32_bf16 v[74:77], v[180:183], v[204:207], 0
	v_mfma_f32_16x16x32_bf16 v[70:73], v[172:175], v[212:215], 0
	v_mfma_f32_16x16x32_bf16 v[66:69], v[180:183], v[212:215], 0
	v_mfma_f32_16x16x32_bf16 v[94:97], v[176:179], v[192:195], v[94:97]
	v_mfma_f32_16x16x32_bf16 v[90:93], v[184:187], v[192:195], v[90:93]
	v_mfma_f32_16x16x32_bf16 v[86:89], v[176:179], v[200:203], v[86:89]
	v_mfma_f32_16x16x32_bf16 v[82:85], v[184:187], v[200:203], v[82:85]
	v_mfma_f32_16x16x32_bf16 v[78:81], v[176:179], v[208:211], v[78:81]
	v_mfma_f32_16x16x32_bf16 v[74:77], v[184:187], v[208:211], v[74:77]
	v_mfma_f32_16x16x32_bf16 v[70:73], v[176:179], v[216:219], v[70:73]
	v_mfma_f32_16x16x32_bf16 v[66:69], v[184:187], v[216:219], v[66:69]
	s_barrier
	s_add_i32 s59, s95, s88
	v_lshl_add_u64 v[150:151], s[82:83], 0, v[132:133]
	s_mov_b32 m0, s59
	ds_read_b128 v[188:191], v154 offset:16384
	ds_read_b128 v[192:195], v154 offset:17408
	ds_read_b128 v[196:199], v154 offset:18432
	ds_read_b128 v[200:203], v154 offset:19456
	ds_read_b128 v[204:207], v154 offset:20480
	ds_read_b128 v[208:211], v154 offset:21504
	ds_read_b128 v[212:215], v154 offset:22528
	ds_read_b128 v[216:219], v154 offset:23552
	global_load_lds_dwordx4 v[150:151], off
	s_add_i32 m0, s59, 0x2000
	s_add_u32 vcc_lo, s82, 0x40000
	v_lshl_add_u64 v[220:221], s[82:83], 0, v[136:137]
	s_addc_u32 vcc_hi, s83, 0
	s_add_i32 s59, s96, s88
	global_load_lds_dwordx4 v[220:221], off
	v_lshl_add_u64 v[222:223], vcc, 0, v[132:133]
	s_mov_b32 m0, s59
	v_lshl_add_u64 v[224:225], s[84:85], 0, v[134:135]
	global_load_lds_dwordx4 v[222:223], off
	v_lshl_add_u64 v[222:223], vcc, 0, v[136:137]
	s_add_i32 m0, s59, 0x2000
	s_nop 0
	global_load_lds_dwordx4 v[222:223], off
	v_lshl_add_u64 v[222:223], s[84:85], 0, v[130:131]
	s_mov_b32 m0, s15
	s_nop 0
	global_load_lds_dwordx4 v[222:223], off
	s_mov_b32 m0, s17
	s_nop 0
	global_load_lds_dwordx4 v[224:225], off
	s_waitcnt vmcnt(8)
	s_waitcnt lgkmcnt(0)
	s_waitcnt lgkmcnt(0)
	v_mfma_f32_16x16x32_bf16 v[62:65], v[156:159], v[188:191], 0
	v_mfma_f32_16x16x32_bf16 v[58:61], v[164:167], v[188:191], 0
	v_mfma_f32_16x16x32_bf16 v[54:57], v[156:159], v[196:199], 0
	v_mfma_f32_16x16x32_bf16 v[50:53], v[164:167], v[196:199], 0
	s_barrier
; #define PG8_STAGEA(bufoff, gbase) PG8_STAGE_(bufoff, gbase, voffA)
; #define PG8_LDA(dst, b, h) do { _Pragma("unroll") for (int m = 0; m < 4; ++m) _Pragma("unroll") for (int k = 0; k < 2; ++k) dst[m][k] = *(const LAS bf16x8*)(lds + PG8_SA(b, h) + aoff + m * 2048 + k * 1024); } while (0)
; #define PG8_LDB(dst, b, h) do { _Pragma("unroll") for (int n = 0; n < 2; ++n) _Pragma("unroll") for (int k = 0; k < 2; ++k) dst[n][k] = *(const LAS bf16x8*)(lds + PG8_SB(b, h) + boff + n * 2048 + k * 1024); } while (0)
; #define PG8_MMA(ai, bj, At, Bt_) do { __builtin_amdgcn_s_setprio(1); _Pragma("unroll") for (int m = 0; m < 4; ++m) _Pragma("unroll") for (int n = 0; n < 2; ++n) _Pragma("unroll") for (int k = 0; k < 2; ++k) \
;         acc[ai][bj][m][n] = __builtin_amdgcn_mfma_f32_16x16x32_bf16(Bt_[n][k], At[m][k], acc[ai][bj][m][n], 0, 0, 0); __builtin_amdgcn_s_setprio(0); } while (0)
; #define PG8_WAIT_V(n) asm volatile("s_waitcnt vmcnt(" #n ")" ::: "memory")
; #define PG8_WAIT_L(n) asm volatile("s_waitcnt lgkmcnt(" #n ")" ::: "memory")
; #define PG8_BAR __builtin_amdgcn_s_barrier()
; #define PG8_SCHED __builtin_amdgcn_sched_barrier(0)
; template <int EK, int SK = -1>
; __device__ __forceinline__ void gemm_phase(LAS unsigned char* lds, const bf16_t* A, const bf16_t* Bt, int nM, int N, int K, const EpiArgs& E) {
;     ...
;             PG8_WAIT_V(8); PG8_WAIT_L(0); PG8_BAR; PG8_MMA(1, 0, At, B0); PG8_MMA(1, 1, At, B1); PG8_BAR; PG8_SCHED;
;             PG8_LDB(B0, 1, 0); PG8_LDB(B1, 1, 1); PG8_SCHED; PG8_LDA(At, 1, 0); PG8_STAGEA(PG8_SA(0, 1), a2 + hstep);
;             PG8_WAIT_V(8); PG8_WAIT_L(0); PG8_BAR; PG8_MMA(0, 0, At, B0); PG8_MMA(0, 1, At, B1); PG8_BAR; PG8_SCHED;
	v_mfma_f32_16x16x32_bf16 v[46:49], v[156:159], v[204:207], 0
	v_mfma_f32_16x16x32_bf16 v[42:45], v[164:167], v[204:207], 0
	v_mfma_f32_16x16x32_bf16 v[38:41], v[156:159], v[212:215], 0
	v_mfma_f32_16x16x32_bf16 v[34:37], v[164:167], v[212:215], 0
	v_mfma_f32_16x16x32_bf16 v[62:65], v[160:163], v[192:195], v[62:65]
	v_mfma_f32_16x16x32_bf16 v[58:61], v[168:171], v[192:195], v[58:61]
	v_mfma_f32_16x16x32_bf16 v[54:57], v[160:163], v[200:203], v[54:57]
	v_mfma_f32_16x16x32_bf16 v[50:53], v[168:171], v[200:203], v[50:53]
	v_mfma_f32_16x16x32_bf16 v[46:49], v[160:163], v[208:211], v[46:49]
	v_mfma_f32_16x16x32_bf16 v[42:45], v[168:171], v[208:211], v[42:45]
	v_mfma_f32_16x16x32_bf16 v[38:41], v[160:163], v[216:219], v[38:41]
	v_mfma_f32_16x16x32_bf16 v[34:37], v[168:171], v[216:219], v[34:37]
	v_mfma_f32_16x16x32_bf16 v[30:33], v[172:175], v[188:191], 0
	v_mfma_f32_16x16x32_bf16 v[26:29], v[180:183], v[188:191], 0
	v_mfma_f32_16x16x32_bf16 v[22:25], v[172:175], v[196:199], 0
	v_mfma_f32_16x16x32_bf16 v[18:21], v[180:183], v[196:199], 0
	v_mfma_f32_16x16x32_bf16 v[14:17], v[172:175], v[204:207], 0
	v_mfma_f32_16x16x32_bf16 v[10:13], v[180:183], v[204:207], 0
	v_mfma_f32_16x16x32_bf16 v[6:9], v[172:175], v[212:215], 0
	v_mfma_f32_16x16x32_bf16 v[2:5], v[180:183], v[212:215], 0
	v_mfma_f32_16x16x32_bf16 v[30:33], v[176:179], v[192:195], v[30:33]
	v_mfma_f32_16x16x32_bf16 v[26:29], v[184:187], v[192:195], v[26:29]
	v_mfma_f32_16x16x32_bf16 v[22:25], v[176:179], v[200:203], v[22:25]
	v_mfma_f32_16x16x32_bf16 v[18:21], v[184:187], v[200:203], v[18:21]
	v_mfma_f32_16x16x32_bf16 v[14:17], v[176:179], v[208:211], v[14:17]
	v_mfma_f32_16x16x32_bf16 v[10:13], v[184:187], v[208:211], v[10:13]
	v_mfma_f32_16x16x32_bf16 v[6:9], v[176:179], v[216:219], v[6:9]
	v_mfma_f32_16x16x32_bf16 v[2:5], v[184:187], v[216:219], v[2:5]
	s_barrier
	s_add_i32 s59, 0, 0x18000
	s_add_i32 s73, 0, 0x1c000
	v_add_u32_e32 v168, s59, v152
	v_add_u32_e32 v184, s73, v152
	ds_read_b128 v[156:159], v168
	ds_read_b128 v[160:163], v168 offset:1024
	ds_read_b128 v[164:167], v168 offset:2048
	ds_read_b128 v[168:171], v168 offset:3072
	ds_read_b128 v[172:175], v184
	ds_read_b128 v[176:179], v184 offset:1024
	ds_read_b128 v[180:183], v184 offset:2048
	ds_read_b128 v[184:187], v184 offset:3072
	s_add_u32 s84, s84, 0x40000
	s_addc_u32 s85, s85, 0
	s_mov_b32 m0, s89
	v_lshl_add_u64 v[226:227], s[84:85], 0, v[130:131]
	ds_read_b128 v[188:191], v154 offset:32768
	ds_read_b128 v[192:195], v154 offset:33792
	ds_read_b128 v[196:199], v154 offset:34816
	ds_read_b128 v[200:203], v154 offset:35840
	ds_read_b128 v[204:207], v154 offset:36864
	ds_read_b128 v[208:211], v154 offset:37888
	ds_read_b128 v[212:215], v154 offset:38912
	ds_read_b128 v[216:219], v154 offset:39936
	global_load_lds_dwordx4 v[226:227], off
	v_lshl_add_u64 v[226:227], s[84:85], 0, v[134:135]
	s_mov_b32 m0, s90
	s_nop 0
	global_load_lds_dwordx4 v[226:227], off
	s_waitcnt vmcnt(8)
	s_waitcnt lgkmcnt(0)
	s_waitcnt lgkmcnt(0)
	v_mfma_f32_16x16x32_bf16 v[126:129], v[156:159], v[188:191], v[126:129]
	v_mfma_f32_16x16x32_bf16 v[122:125], v[164:167], v[188:191], v[122:125]
	v_mfma_f32_16x16x32_bf16 v[118:121], v[156:159], v[196:199], v[118:121]
	v_mfma_f32_16x16x32_bf16 v[114:117], v[164:167], v[196:199], v[114:117]
	s_barrier
	v_mfma_f32_16x16x32_bf16 v[110:113], v[156:159], v[204:207], v[110:113]
	v_mfma_f32_16x16x32_bf16 v[106:109], v[164:167], v[204:207], v[106:109]
	v_mfma_f32_16x16x32_bf16 v[102:105], v[156:159], v[212:215], v[102:105]
	v_mfma_f32_16x16x32_bf16 v[98:101], v[164:167], v[212:215], v[98:101]
	v_mfma_f32_16x16x32_bf16 v[126:129], v[160:163], v[192:195], v[126:129]
	v_mfma_f32_16x16x32_bf16 v[122:125], v[168:171], v[192:195], v[122:125]
	v_mfma_f32_16x16x32_bf16 v[118:121], v[160:163], v[200:203], v[118:121]
	v_mfma_f32_16x16x32_bf16 v[114:117], v[168:171], v[200:203], v[114:117]
	v_mfma_f32_16x16x32_bf16 v[110:113], v[160:163], v[208:211], v[110:113]
	v_mfma_f32_16x16x32_bf16 v[106:109], v[168:171], v[208:211], v[106:109]
	v_mfma_f32_16x16x32_bf16 v[102:105], v[160:163], v[216:219], v[102:105]
	v_mfma_f32_16x16x32_bf16 v[98:101], v[168:171], v[216:219], v[98:101]
	v_mfma_f32_16x16x32_bf16 v[94:97], v[172:175], v[188:191], v[94:97]
	v_mfma_f32_16x16x32_bf16 v[90:93], v[180:183], v[188:191], v[90:93]
	v_mfma_f32_16x16x32_bf16 v[86:89], v[172:175], v[196:199], v[86:89]
	v_mfma_f32_16x16x32_bf16 v[82:85], v[180:183], v[196:199], v[82:85]
	v_mfma_f32_16x16x32_bf16 v[78:81], v[172:175], v[204:207], v[78:81]
	v_mfma_f32_16x16x32_bf16 v[74:77], v[180:183], v[204:207], v[74:77]
	v_mfma_f32_16x16x32_bf16 v[70:73], v[172:175], v[212:215], v[70:73]
	v_mfma_f32_16x16x32_bf16 v[66:69], v[180:183], v[212:215], v[66:69]
	v_mfma_f32_16x16x32_bf16 v[94:97], v[176:179], v[192:195], v[94:97]
	v_mfma_f32_16x16x32_bf16 v[90:93], v[184:187], v[192:195], v[90:93]
	v_mfma_f32_16x16x32_bf16 v[86:89], v[176:179], v[200:203], v[86:89]
	v_mfma_f32_16x16x32_bf16 v[82:85], v[184:187], v[200:203], v[82:85]
	v_mfma_f32_16x16x32_bf16 v[78:81], v[176:179], v[208:211], v[78:81]
	v_mfma_f32_16x16x32_bf16 v[74:77], v[184:187], v[208:211], v[74:77]
	v_mfma_f32_16x16x32_bf16 v[70:73], v[176:179], v[216:219], v[70:73]
	v_mfma_f32_16x16x32_bf16 v[66:69], v[184:187], v[216:219], v[66:69]
	s_barrier
; #define PG8_STAGEA(bufoff, gbase) PG8_STAGE_(bufoff, gbase, voffA)
; #define PG8_STAGEB(bufoff, gbase) PG8_STAGE_(bufoff, gbase, voffB)
; #define PG8_LDA(dst, b, h) do { _Pragma("unroll") for (int m = 0; m < 4; ++m) _Pragma("unroll") for (int k = 0; k < 2; ++k) dst[m][k] = *(const LAS bf16x8*)(lds + PG8_SA(b, h) + aoff + m * 2048 + k * 1024); } while (0)
; #define PG8_LDB(dst, b, h) do { _Pragma("unroll") for (int n = 0; n < 2; ++n) _Pragma("unroll") for (int k = 0; k < 2; ++k) dst[n][k] = *(const LAS bf16x8*)(lds + PG8_SB(b, h) + boff + n * 2048 + k * 1024); } while (0)
; #define PG8_MMA(ai, bj, At, Bt_) do { __builtin_amdgcn_s_setprio(1); _Pragma("unroll") for (int m = 0; m < 4; ++m) _Pragma("unroll") for (int n = 0; n < 2; ++n) _Pragma("unroll") for (int k = 0; k < 2; ++k) \
;         acc[ai][bj][m][n] = __builtin_amdgcn_mfma_f32_16x16x32_bf16(Bt_[n][k], At[m][k], acc[ai][bj][m][n], 0, 0, 0); __builtin_amdgcn_s_setprio(0); } while (0)
; #define PG8_WAIT_V(n) asm volatile("s_waitcnt vmcnt(" #n ")" ::: "memory")
; #define PG8_WAIT_L(n) asm volatile("s_waitcnt lgkmcnt(" #n ")" ::: "memory")
; #define PG8_BAR __builtin_amdgcn_s_barrier()
; #define PG8_SCHED __builtin_amdgcn_sched_barrier(0)
; template <int EK, int SK = -1>
; __device__ __forceinline__ void gemm_phase(LAS unsigned char* lds, const bf16_t* A, const bf16_t* Bt, int nM, int N, int K, const EpiArgs& E) {
;     ...
;             PG8_LDB(B0, 0, 0); PG8_LDB(B1, 0, 1); PG8_SCHED; PG8_LDA(At, 0, 0); PG8_STAGEA(PG8_SA(1, 1), a1 + hstep);
;             PG8_WAIT_V(8); PG8_WAIT_L(0); PG8_BAR; PG8_MMA(0, 0, At, B0); PG8_MMA(0, 1, At, B1); PG8_BAR; PG8_SCHED;
;     ...
;             PG8_LDA(At, 1, 1); PG8_STAGEB(PG8_SB(1, 0), b3); PG8_STAGEB(PG8_SB(1, 1), b3 + hstep); PG8_STAGEA(PG8_SA(1, 0), a3);
;             PG8_WAIT_V(8); PG8_WAIT_L(0); PG8_BAR; PG8_MMA(1, 0, At, B0); PG8_MMA(1, 1, At, B1); PG8_BAR; PG8_SCHED;
	s_add_i32 s59, s59, s88
	v_lshl_add_u64 v[150:151], v[150:151], 0, s[68:69]
	s_mov_b32 m0, s59
	ds_read_b128 v[188:191], v154 offset:49152
	ds_read_b128 v[192:195], v154 offset:50176
	ds_read_b128 v[196:199], v154 offset:51200
	ds_read_b128 v[200:203], v154 offset:52224
	ds_read_b128 v[204:207], v154 offset:53248
	ds_read_b128 v[208:211], v154 offset:54272
	ds_read_b128 v[212:215], v154 offset:55296
	ds_read_b128 v[216:219], v154 offset:56320
	global_load_lds_dwordx4 v[150:151], off
	s_add_i32 m0, s59, 0x2000
	s_add_u32 s82, s82, 0x40080
	v_lshl_add_u64 v[150:151], v[220:221], 0, s[68:69]
	s_addc_u32 s83, s83, 0
	s_add_i32 s59, s73, s88
	global_load_lds_dwordx4 v[150:151], off
	v_lshl_add_u64 v[150:151], s[82:83], 0, v[132:133]
	s_mov_b32 m0, s59
	s_nop 0
	global_load_lds_dwordx4 v[150:151], off
	v_lshl_add_u64 v[150:151], s[82:83], 0, v[136:137]
	s_add_i32 m0, s59, 0x2000
	s_nop 0
	global_load_lds_dwordx4 v[150:151], off
	v_lshl_add_u64 v[150:151], v[222:223], 0, s[68:69]
	s_mov_b32 m0, s93
	s_nop 0
	global_load_lds_dwordx4 v[150:151], off
	v_lshl_add_u64 v[150:151], v[224:225], 0, s[68:69]
	s_mov_b32 m0, s94
	s_nop 0
	global_load_lds_dwordx4 v[150:151], off
	s_waitcnt vmcnt(8)
	s_waitcnt lgkmcnt(0)
	s_waitcnt lgkmcnt(0)
	v_mfma_f32_16x16x32_bf16 v[62:65], v[156:159], v[188:191], v[62:65]
	v_mfma_f32_16x16x32_bf16 v[58:61], v[164:167], v[188:191], v[58:61]
	v_mfma_f32_16x16x32_bf16 v[54:57], v[156:159], v[196:199], v[54:57]
	v_mfma_f32_16x16x32_bf16 v[50:53], v[164:167], v[196:199], v[50:53]
	s_barrier
	v_mfma_f32_16x16x32_bf16 v[46:49], v[156:159], v[204:207], v[46:49]
	v_mfma_f32_16x16x32_bf16 v[42:45], v[164:167], v[204:207], v[42:45]
	v_mfma_f32_16x16x32_bf16 v[38:41], v[156:159], v[212:215], v[38:41]
	v_mfma_f32_16x16x32_bf16 v[34:37], v[164:167], v[212:215], v[34:37]
	v_mfma_f32_16x16x32_bf16 v[62:65], v[160:163], v[192:195], v[62:65]
	v_mfma_f32_16x16x32_bf16 v[58:61], v[168:171], v[192:195], v[58:61]
	v_mfma_f32_16x16x32_bf16 v[54:57], v[160:163], v[200:203], v[54:57]
	v_mfma_f32_16x16x32_bf16 v[50:53], v[168:171], v[200:203], v[50:53]
	v_mfma_f32_16x16x32_bf16 v[46:49], v[160:163], v[208:211], v[46:49]
	v_mfma_f32_16x16x32_bf16 v[42:45], v[168:171], v[208:211], v[42:45]
	v_mfma_f32_16x16x32_bf16 v[38:41], v[160:163], v[216:219], v[38:41]
	v_mfma_f32_16x16x32_bf16 v[34:37], v[168:171], v[216:219], v[34:37]
	v_mfma_f32_16x16x32_bf16 v[30:33], v[172:175], v[188:191], v[30:33]
	v_mfma_f32_16x16x32_bf16 v[26:29], v[180:183], v[188:191], v[26:29]
	v_mfma_f32_16x16x32_bf16 v[22:25], v[172:175], v[196:199], v[22:25]
	v_mfma_f32_16x16x32_bf16 v[18:21], v[180:183], v[196:199], v[18:21]
	v_mfma_f32_16x16x32_bf16 v[14:17], v[172:175], v[204:207], v[14:17]
	v_mfma_f32_16x16x32_bf16 v[10:13], v[180:183], v[204:207], v[10:13]
	v_mfma_f32_16x16x32_bf16 v[6:9], v[172:175], v[212:215], v[6:9]
	v_mfma_f32_16x16x32_bf16 v[2:5], v[180:183], v[212:215], v[2:5]
	v_mfma_f32_16x16x32_bf16 v[30:33], v[176:179], v[192:195], v[30:33]
	v_mfma_f32_16x16x32_bf16 v[26:29], v[184:187], v[192:195], v[26:29]
	v_mfma_f32_16x16x32_bf16 v[22:25], v[176:179], v[200:203], v[22:25]
	v_mfma_f32_16x16x32_bf16 v[18:21], v[184:187], v[200:203], v[18:21]
	v_mfma_f32_16x16x32_bf16 v[14:17], v[176:179], v[208:211], v[14:17]
	v_mfma_f32_16x16x32_bf16 v[10:13], v[184:187], v[208:211], v[10:13]
	v_mfma_f32_16x16x32_bf16 v[6:9], v[176:179], v[216:219], v[6:9]
	v_mfma_f32_16x16x32_bf16 v[2:5], v[184:187], v[216:219], v[2:5]
	s_barrier
	s_add_i32 s58, s58, 2
	s_add_u32 s80, s80, 0x100
	s_addc_u32 s81, s81, 0
	s_cmp_gt_u32 s58, 13
	s_cbranch_scc0 .LBB0_413
	s_branch .Lmy_kexit_1
.LBB0_413:
	v_add_u32_e32 v150, s95, v152
	ds_read_b128 v[156:159], v150
	ds_read_b128 v[160:163], v150 offset:1024
	ds_read_b128 v[164:167], v150 offset:2048
	ds_read_b128 v[168:171], v150 offset:3072
	v_add_u32_e32 v150, s96, v152
	s_add_u32 s59, s18, s80
	ds_read_b128 v[172:175], v150
	ds_read_b128 v[176:179], v150 offset:1024
	ds_read_b128 v[180:183], v150 offset:2048
	ds_read_b128 v[184:187], v150 offset:3072
	s_addc_u32 s73, s19, s81
	s_add_u32 s59, s59, 0x100
	s_addc_u32 s73, s73, 0
	s_add_u32 s75, s53, s80
	s_addc_u32 s82, s54, s81
	s_cmpk_eq_i32 s80, 0x700
	s_cselect_b32 s85, s40, s73
	s_cselect_b32 s84, s55, s59
	s_cselect_b32 s83, s56, s82
	s_cselect_b32 s82, s57, s75
	v_lshl_add_u64 v[150:151], v[146:147], 0, s[80:81]
	s_add_i32 m0, s15, 0xc000
	ds_read_b128 v[188:191], v154
	ds_read_b128 v[192:195], v154 offset:1024
	ds_read_b128 v[196:199], v154 offset:2048
	ds_read_b128 v[200:203], v154 offset:3072
	ds_read_b128 v[204:207], v154 offset:4096
	ds_read_b128 v[208:211], v154 offset:5120
	ds_read_b128 v[212:215], v154 offset:6144
	ds_read_b128 v[216:219], v154 offset:7168
	global_load_lds_dwordx4 v[150:151], off
	v_lshl_add_u64 v[150:151], v[148:149], 0, s[80:81]
	s_add_i32 m0, s15, 0xe000
	s_nop 0
	global_load_lds_dwordx4 v[150:151], off
	s_waitcnt vmcnt(8)
	s_waitcnt lgkmcnt(0)
	s_waitcnt lgkmcnt(0)
	v_mfma_f32_16x16x32_bf16 v[126:129], v[156:159], v[188:191], v[126:129]
	v_mfma_f32_16x16x32_bf16 v[122:125], v[164:167], v[188:191], v[122:125]
	v_mfma_f32_16x16x32_bf16 v[118:121], v[156:159], v[196:199], v[118:121]
	v_mfma_f32_16x16x32_bf16 v[114:117], v[164:167], v[196:199], v[114:117]
	s_barrier
; #define PG8_STAGEA(bufoff, gbase) PG8_STAGE_(bufoff, gbase, voffA)
; #define PG8_STAGEB(bufoff, gbase) PG8_STAGE_(bufoff, gbase, voffB)
; #define PG8_LDA(dst, b, h) do { _Pragma("unroll") for (int m = 0; m < 4; ++m) _Pragma("unroll") for (int k = 0; k < 2; ++k) dst[m][k] = *(const LAS bf16x8*)(lds + PG8_SA(b, h) + aoff + m * 2048 + k * 1024); } while (0)
; #define PG8_MMA(ai, bj, At, Bt_) do { __builtin_amdgcn_s_setprio(1); _Pragma("unroll") for (int m = 0; m < 4; ++m) _Pragma("unroll") for (int n = 0; n < 2; ++n) _Pragma("unroll") for (int k = 0; k < 2; ++k) \
;         acc[ai][bj][m][n] = __builtin_amdgcn_mfma_f32_16x16x32_bf16(Bt_[n][k], At[m][k], acc[ai][bj][m][n], 0, 0, 0); __builtin_amdgcn_s_setprio(0); } while (0)
; #define PG8_WAIT_V(n) asm volatile("s_waitcnt vmcnt(" #n ")" ::: "memory")
; #define PG8_WAIT_L(n) asm volatile("s_waitcnt lgkmcnt(" #n ")" ::: "memory")
; #define PG8_BAR __builtin_amdgcn_s_barrier()
; #define PG8_SCHED __builtin_amdgcn_sched_barrier(0)
; template <int EK, int SK = -1>
; __device__ __forceinline__ void gemm_phase(LAS unsigned char* lds, const bf16_t* A, const bf16_t* Bt, int nM, int N, int K, const EpiArgs& E) {
;     ...
;             PG8_WAIT_V(8); PG8_WAIT_L(0); PG8_BAR; PG8_MMA(0, 0, At, B0); PG8_MMA(0, 1, At, B1); PG8_BAR; PG8_SCHED;
;             PG8_LDA(At, 0, 1); PG8_STAGEB(PG8_SB(0, 0), b2); PG8_STAGEB(PG8_SB(0, 1), b2 + hstep); PG8_STAGEA(PG8_SA(0, 0), a2);
;             PG8_WAIT_V(8); PG8_WAIT_L(0); PG8_BAR; PG8_MMA(1, 0, At, B0); PG8_MMA(1, 1, At, B1); PG8_BAR; PG8_SCHED;
	v_mfma_f32_16x16x32_bf16 v[110:113], v[156:159], v[204:207], v[110:113]
	v_mfma_f32_16x16x32_bf16 v[106:109], v[164:167], v[204:207], v[106:109]
	v_mfma_f32_16x16x32_bf16 v[102:105], v[156:159], v[212:215], v[102:105]
	v_mfma_f32_16x16x32_bf16 v[98:101], v[164:167], v[212:215], v[98:101]
	v_mfma_f32_16x16x32_bf16 v[126:129], v[160:163], v[192:195], v[126:129]
	v_mfma_f32_16x16x32_bf16 v[122:125], v[168:171], v[192:195], v[122:125]
	v_mfma_f32_16x16x32_bf16 v[118:121], v[160:163], v[200:203], v[118:121]
	v_mfma_f32_16x16x32_bf16 v[114:117], v[168:171], v[200:203], v[114:117]
	v_mfma_f32_16x16x32_bf16 v[110:113], v[160:163], v[208:211], v[110:113]
	v_mfma_f32_16x16x32_bf16 v[106:109], v[168:171], v[208:211], v[106:109]
	v_mfma_f32_16x16x32_bf16 v[102:105], v[160:163], v[216:219], v[102:105]
	v_mfma_f32_16x16x32_bf16 v[98:101], v[168:171], v[216:219], v[98:101]
	v_mfma_f32_16x16x32_bf16 v[94:97], v[172:175], v[188:191], v[94:97]
	v_mfma_f32_16x16x32_bf16 v[90:93], v[180:183], v[188:191], v[90:93]
	v_mfma_f32_16x16x32_bf16 v[86:89], v[172:175], v[196:199], v[86:89]
	v_mfma_f32_16x16x32_bf16 v[82:85], v[180:183], v[196:199], v[82:85]
	v_mfma_f32_16x16x32_bf16 v[78:81], v[172:175], v[204:207], v[78:81]
	v_mfma_f32_16x16x32_bf16 v[74:77], v[180:183], v[204:207], v[74:77]
	v_mfma_f32_16x16x32_bf16 v[70:73], v[172:175], v[212:215], v[70:73]
	v_mfma_f32_16x16x32_bf16 v[66:69], v[180:183], v[212:215], v[66:69]
	v_mfma_f32_16x16x32_bf16 v[94:97], v[176:179], v[192:195], v[94:97]
	v_mfma_f32_16x16x32_bf16 v[90:93], v[184:187], v[192:195], v[90:93]
	v_mfma_f32_16x16x32_bf16 v[86:89], v[176:179], v[200:203], v[86:89]
	v_mfma_f32_16x16x32_bf16 v[82:85], v[184:187], v[200:203], v[82:85]
	v_mfma_f32_16x16x32_bf16 v[78:81], v[176:179], v[208:211], v[78:81]
	v_mfma_f32_16x16x32_bf16 v[74:77], v[184:187], v[208:211], v[74:77]
	v_mfma_f32_16x16x32_bf16 v[70:73], v[176:179], v[216:219], v[70:73]
	v_mfma_f32_16x16x32_bf16 v[66:69], v[184:187], v[216:219], v[66:69]
	s_barrier
	s_add_i32 s59, s95, s88
	v_lshl_add_u64 v[150:151], s[82:83], 0, v[132:133]
	s_mov_b32 m0, s59
	ds_read_b128 v[188:191], v154 offset:16384
	ds_read_b128 v[192:195], v154 offset:17408
	ds_read_b128 v[196:199], v154 offset:18432
	ds_read_b128 v[200:203], v154 offset:19456
	ds_read_b128 v[204:207], v154 offset:20480
	ds_read_b128 v[208:211], v154 offset:21504
	ds_read_b128 v[212:215], v154 offset:22528
	ds_read_b128 v[216:219], v154 offset:23552
	global_load_lds_dwordx4 v[150:151], off
	s_add_i32 m0, s59, 0x2000
	s_add_u32 vcc_lo, s82, 0x40000
	v_lshl_add_u64 v[220:221], s[82:83], 0, v[136:137]
	s_addc_u32 vcc_hi, s83, 0
	s_add_i32 s59, s96, s88
	global_load_lds_dwordx4 v[220:221], off
	v_lshl_add_u64 v[222:223], vcc, 0, v[132:133]
	s_mov_b32 m0, s59
	v_lshl_add_u64 v[224:225], s[84:85], 0, v[134:135]
	global_load_lds_dwordx4 v[222:223], off
	v_lshl_add_u64 v[222:223], vcc, 0, v[136:137]
	s_add_i32 m0, s59, 0x2000
	s_nop 0
	global_load_lds_dwordx4 v[222:223], off
	v_lshl_add_u64 v[222:223], s[84:85], 0, v[130:131]
	s_mov_b32 m0, s15
	s_nop 0
	global_load_lds_dwordx4 v[222:223], off
	s_mov_b32 m0, s17
	s_nop 0
	global_load_lds_dwordx4 v[224:225], off
	s_waitcnt vmcnt(8)
	s_waitcnt lgkmcnt(0)
	s_waitcnt lgkmcnt(0)
	v_mfma_f32_16x16x32_bf16 v[62:65], v[156:159], v[188:191], v[62:65]
	v_mfma_f32_16x16x32_bf16 v[58:61], v[164:167], v[188:191], v[58:61]
	v_mfma_f32_16x16x32_bf16 v[54:57], v[156:159], v[196:199], v[54:57]
	v_mfma_f32_16x16x32_bf16 v[50:53], v[164:167], v[196:199], v[50:53]
	s_barrier
	v_mfma_f32_16x16x32_bf16 v[46:49], v[156:159], v[204:207], v[46:49]
	v_mfma_f32_16x16x32_bf16 v[42:45], v[164:167], v[204:207], v[42:45]
	v_mfma_f32_16x16x32_bf16 v[38:41], v[156:159], v[212:215], v[38:41]
	v_mfma_f32_16x16x32_bf16 v[34:37], v[164:167], v[212:215], v[34:37]
	v_mfma_f32_16x16x32_bf16 v[62:65], v[160:163], v[192:195], v[62:65]
	v_mfma_f32_16x16x32_bf16 v[58:61], v[168:171], v[192:195], v[58:61]
	v_mfma_f32_16x16x32_bf16 v[54:57], v[160:163], v[200:203], v[54:57]
	v_mfma_f32_16x16x32_bf16 v[50:53], v[168:171], v[200:203], v[50:53]
	v_mfma_f32_16x16x32_bf16 v[46:49], v[160:163], v[208:211], v[46:49]
	v_mfma_f32_16x16x32_bf16 v[42:45], v[168:171], v[208:211], v[42:45]
	v_mfma_f32_16x16x32_bf16 v[38:41], v[160:163], v[216:219], v[38:41]
	v_mfma_f32_16x16x32_bf16 v[34:37], v[168:171], v[216:219], v[34:37]
	v_mfma_f32_16x16x32_bf16 v[30:33], v[172:175], v[188:191], v[30:33]
	v_mfma_f32_16x16x32_bf16 v[26:29], v[180:183], v[188:191], v[26:29]
	v_mfma_f32_16x16x32_bf16 v[22:25], v[172:175], v[196:199], v[22:25]
	v_mfma_f32_16x16x32_bf16 v[18:21], v[180:183], v[196:199], v[18:21]
	v_mfma_f32_16x16x32_bf16 v[14:17], v[172:175], v[204:207], v[14:17]
	v_mfma_f32_16x16x32_bf16 v[10:13], v[180:183], v[204:207], v[10:13]
	v_mfma_f32_16x16x32_bf16 v[6:9], v[172:175], v[212:215], v[6:9]
	v_mfma_f32_16x16x32_bf16 v[2:5], v[180:183], v[212:215], v[2:5]
	v_mfma_f32_16x16x32_bf16 v[30:33], v[176:179], v[192:195], v[30:33]
	v_mfma_f32_16x16x32_bf16 v[26:29], v[184:187], v[192:195], v[26:29]
	v_mfma_f32_16x16x32_bf16 v[22:25], v[176:179], v[200:203], v[22:25]
	v_mfma_f32_16x16x32_bf16 v[18:21], v[184:187], v[200:203], v[18:21]
	v_mfma_f32_16x16x32_bf16 v[14:17], v[176:179], v[208:211], v[14:17]
	v_mfma_f32_16x16x32_bf16 v[10:13], v[184:187], v[208:211], v[10:13]
	v_mfma_f32_16x16x32_bf16 v[6:9], v[176:179], v[216:219], v[6:9]
	v_mfma_f32_16x16x32_bf16 v[2:5], v[184:187], v[216:219], v[2:5]
	s_barrier
; #define PG8_STAGEA(bufoff, gbase) PG8_STAGE_(bufoff, gbase, voffA)
; #define PG8_STAGEB(bufoff, gbase) PG8_STAGE_(bufoff, gbase, voffB)
; #define PG8_LDA(dst, b, h) do { _Pragma("unroll") for (int m = 0; m < 4; ++m) _Pragma("unroll") for (int k = 0; k < 2; ++k) dst[m][k] = *(const LAS bf16x8*)(lds + PG8_SA(b, h) + aoff + m * 2048 + k * 1024); } while (0)
; #define PG8_LDB(dst, b, h) do { _Pragma("unroll") for (int n = 0; n < 2; ++n) _Pragma("unroll") for (int k = 0; k < 2; ++k) dst[n][k] = *(const LAS bf16x8*)(lds + PG8_SB(b, h) + boff + n * 2048 + k * 1024); } while (0)
; #define PG8_MMA(ai, bj, At, Bt_) do { __builtin_amdgcn_s_setprio(1); _Pragma("unroll") for (int m = 0; m < 4; ++m) _Pragma("unroll") for (int n = 0; n < 2; ++n) _Pragma("unroll") for (int k = 0; k < 2; ++k) \
;         acc[ai][bj][m][n] = __builtin_amdgcn_mfma_f32_16x16x32_bf16(Bt_[n][k], At[m][k], acc[ai][bj][m][n], 0, 0, 0); __builtin_amdgcn_s_setprio(0); } while (0)
; #define PG8_WAIT_V(n) asm volatile("s_waitcnt vmcnt(" #n ")" ::: "memory")
; #define PG8_WAIT_L(n) asm volatile("s_waitcnt lgkmcnt(" #n ")" ::: "memory")
; #define PG8_BAR __builtin_amdgcn_s_barrier()
; #define PG8_SCHED __builtin_amdgcn_sched_barrier(0)
; template <int EK, int SK = -1>
; __device__ __forceinline__ void gemm_phase(LAS unsigned char* lds, const bf16_t* A, const bf16_t* Bt, int nM, int N, int K, const EpiArgs& E) {
;     ...
;             PG8_LDB(B0, 1, 0); PG8_LDB(B1, 1, 1); PG8_SCHED; PG8_LDA(At, 1, 0); PG8_STAGEA(PG8_SA(0, 1), a2 + hstep);
;             PG8_WAIT_V(8); PG8_WAIT_L(0); PG8_BAR; PG8_MMA(0, 0, At, B0); PG8_MMA(0, 1, At, B1); PG8_BAR; PG8_SCHED;
;             PG8_LDA(At, 1, 1); PG8_STAGEB(PG8_SB(1, 0), b3); PG8_STAGEB(PG8_SB(1, 1), b3 + hstep); PG8_STAGEA(PG8_SA(1, 0), a3);
;             PG8_WAIT_V(8); PG8_WAIT_L(0); PG8_BAR; PG8_MMA(1, 0, At, B0); PG8_MMA(1, 1, At, B1); PG8_BAR; PG8_SCHED;
	s_add_i32 s59, 0, 0x18000
	s_add_i32 s73, 0, 0x1c000
	v_add_u32_e32 v168, s59, v152
	v_add_u32_e32 v184, s73, v152
	ds_read_b128 v[156:159], v168
	ds_read_b128 v[160:163], v168 offset:1024
	ds_read_b128 v[164:167], v168 offset:2048
	ds_read_b128 v[168:171], v168 offset:3072
	ds_read_b128 v[172:175], v184
	ds_read_b128 v[176:179], v184 offset:1024
	ds_read_b128 v[180:183], v184 offset:2048
	ds_read_b128 v[184:187], v184 offset:3072
	s_add_u32 s84, s84, 0x40000
	s_addc_u32 s85, s85, 0
	s_mov_b32 m0, s89
	v_lshl_add_u64 v[226:227], s[84:85], 0, v[130:131]
	ds_read_b128 v[188:191], v154 offset:32768
	ds_read_b128 v[192:195], v154 offset:33792
	ds_read_b128 v[196:199], v154 offset:34816
	ds_read_b128 v[200:203], v154 offset:35840
	ds_read_b128 v[204:207], v154 offset:36864
	ds_read_b128 v[208:211], v154 offset:37888
	ds_read_b128 v[212:215], v154 offset:38912
	ds_read_b128 v[216:219], v154 offset:39936
	global_load_lds_dwordx4 v[226:227], off
	v_lshl_add_u64 v[226:227], s[84:85], 0, v[134:135]
	s_mov_b32 m0, s90
	s_nop 0
	global_load_lds_dwordx4 v[226:227], off
	s_waitcnt vmcnt(8)
	s_waitcnt lgkmcnt(0)
	s_waitcnt lgkmcnt(0)
	v_mfma_f32_16x16x32_bf16 v[126:129], v[156:159], v[188:191], v[126:129]
	v_mfma_f32_16x16x32_bf16 v[122:125], v[164:167], v[188:191], v[122:125]
	v_mfma_f32_16x16x32_bf16 v[118:121], v[156:159], v[196:199], v[118:121]
	v_mfma_f32_16x16x32_bf16 v[114:117], v[164:167], v[196:199], v[114:117]
	s_barrier
	v_mfma_f32_16x16x32_bf16 v[110:113], v[156:159], v[204:207], v[110:113]
	v_mfma_f32_16x16x32_bf16 v[106:109], v[164:167], v[204:207], v[106:109]
	v_mfma_f32_16x16x32_bf16 v[102:105], v[156:159], v[212:215], v[102:105]
	v_mfma_f32_16x16x32_bf16 v[98:101], v[164:167], v[212:215], v[98:101]
	v_mfma_f32_16x16x32_bf16 v[126:129], v[160:163], v[192:195], v[126:129]
	v_mfma_f32_16x16x32_bf16 v[122:125], v[168:171], v[192:195], v[122:125]
	v_mfma_f32_16x16x32_bf16 v[118:121], v[160:163], v[200:203], v[118:121]
	v_mfma_f32_16x16x32_bf16 v[114:117], v[168:171], v[200:203], v[114:117]
	v_mfma_f32_16x16x32_bf16 v[110:113], v[160:163], v[208:211], v[110:113]
	v_mfma_f32_16x16x32_bf16 v[106:109], v[168:171], v[208:211], v[106:109]
	v_mfma_f32_16x16x32_bf16 v[102:105], v[160:163], v[216:219], v[102:105]
	v_mfma_f32_16x16x32_bf16 v[98:101], v[168:171], v[216:219], v[98:101]
	v_mfma_f32_16x16x32_bf16 v[94:97], v[172:175], v[188:191], v[94:97]
	v_mfma_f32_16x16x32_bf16 v[90:93], v[180:183], v[188:191], v[90:93]
	v_mfma_f32_16x16x32_bf16 v[86:89], v[172:175], v[196:199], v[86:89]
	v_mfma_f32_16x16x32_bf16 v[82:85], v[180:183], v[196:199], v[82:85]
	v_mfma_f32_16x16x32_bf16 v[78:81], v[172:175], v[204:207], v[78:81]
	v_mfma_f32_16x16x32_bf16 v[74:77], v[180:183], v[204:207], v[74:77]
	v_mfma_f32_16x16x32_bf16 v[70:73], v[172:175], v[212:215], v[70:73]
	v_mfma_f32_16x16x32_bf16 v[66:69], v[180:183], v[212:215], v[66:69]
	v_mfma_f32_16x16x32_bf16 v[94:97], v[176:179], v[192:195], v[94:97]
	v_mfma_f32_16x16x32_bf16 v[90:93], v[184:187], v[192:195], v[90:93]
	v_mfma_f32_16x16x32_bf16 v[86:89], v[176:179], v[200:203], v[86:89]
	v_mfma_f32_16x16x32_bf16 v[82:85], v[184:187], v[200:203], v[82:85]
	v_mfma_f32_16x16x32_bf16 v[78:81], v[176:179], v[208:211], v[78:81]
	v_mfma_f32_16x16x32_bf16 v[74:77], v[184:187], v[208:211], v[74:77]
	v_mfma_f32_16x16x32_bf16 v[70:73], v[176:179], v[216:219], v[70:73]
	v_mfma_f32_16x16x32_bf16 v[66:69], v[184:187], v[216:219], v[66:69]
	s_barrier
	s_add_i32 s59, s59, s88
	v_lshl_add_u64 v[150:151], v[150:151], 0, s[68:69]
	s_mov_b32 m0, s59
	ds_read_b128 v[188:191], v154 offset:49152
	ds_read_b128 v[192:195], v154 offset:50176
	ds_read_b128 v[196:199], v154 offset:51200
	ds_read_b128 v[200:203], v154 offset:52224
	ds_read_b128 v[204:207], v154 offset:53248
	ds_read_b128 v[208:211], v154 offset:54272
	ds_read_b128 v[212:215], v154 offset:55296
	ds_read_b128 v[216:219], v154 offset:56320
	global_load_lds_dwordx4 v[150:151], off
	s_add_i32 m0, s59, 0x2000
	s_add_u32 s82, s82, 0x40080
	v_lshl_add_u64 v[150:151], v[220:221], 0, s[68:69]
	s_addc_u32 s83, s83, 0
	s_add_i32 s59, s73, s88
	global_load_lds_dwordx4 v[150:151], off
	v_lshl_add_u64 v[150:151], s[82:83], 0, v[132:133]
	s_mov_b32 m0, s59
	s_nop 0
	global_load_lds_dwordx4 v[150:151], off
	v_lshl_add_u64 v[150:151], s[82:83], 0, v[136:137]
	s_add_i32 m0, s59, 0x2000
	s_nop 0
	global_load_lds_dwordx4 v[150:151], off
	v_lshl_add_u64 v[150:151], v[222:223], 0, s[68:69]
	s_mov_b32 m0, s93
	s_nop 0
	global_load_lds_dwordx4 v[150:151], off
	v_lshl_add_u64 v[150:151], v[224:225], 0, s[68:69]
	s_mov_b32 m0, s94
	s_nop 0
	global_load_lds_dwordx4 v[150:151], off
	s_waitcnt vmcnt(8)
	s_waitcnt lgkmcnt(0)
	s_waitcnt lgkmcnt(0)
	v_mfma_f32_16x16x32_bf16 v[62:65], v[156:159], v[188:191], v[62:65]
	v_mfma_f32_16x16x32_bf16 v[58:61], v[164:167], v[188:191], v[58:61]
	v_mfma_f32_16x16x32_bf16 v[54:57], v[156:159], v[196:199], v[54:57]
	v_mfma_f32_16x16x32_bf16 v[50:53], v[164:167], v[196:199], v[50:53]
	s_barrier
	v_mfma_f32_16x16x32_bf16 v[46:49], v[156:159], v[204:207], v[46:49]
	v_mfma_f32_16x16x32_bf16 v[42:45], v[164:167], v[204:207], v[42:45]
	v_mfma_f32_16x16x32_bf16 v[38:41], v[156:159], v[212:215], v[38:41]
	v_mfma_f32_16x16x32_bf16 v[34:37], v[164:167], v[212:215], v[34:37]
	v_mfma_f32_16x16x32_bf16 v[62:65], v[160:163], v[192:195], v[62:65]
	v_mfma_f32_16x16x32_bf16 v[58:61], v[168:171], v[192:195], v[58:61]
	v_mfma_f32_16x16x32_bf16 v[54:57], v[160:163], v[200:203], v[54:57]
	v_mfma_f32_16x16x32_bf16 v[50:53], v[168:171], v[200:203], v[50:53]
	v_mfma_f32_16x16x32_bf16 v[46:49], v[160:163], v[208:211], v[46:49]
	v_mfma_f32_16x16x32_bf16 v[42:45], v[168:171], v[208:211], v[42:45]
	v_mfma_f32_16x16x32_bf16 v[38:41], v[160:163], v[216:219], v[38:41]
	v_mfma_f32_16x16x32_bf16 v[34:37], v[168:171], v[216:219], v[34:37]
	v_mfma_f32_16x16x32_bf16 v[30:33], v[172:175], v[188:191], v[30:33]
	v_mfma_f32_16x16x32_bf16 v[26:29], v[180:183], v[188:191], v[26:29]
	v_mfma_f32_16x16x32_bf16 v[22:25], v[172:175], v[196:199], v[22:25]
	v_mfma_f32_16x16x32_bf16 v[18:21], v[180:183], v[196:199], v[18:21]
	v_mfma_f32_16x16x32_bf16 v[14:17], v[172:175], v[204:207], v[14:17]
	v_mfma_f32_16x16x32_bf16 v[10:13], v[180:183], v[204:207], v[10:13]
	v_mfma_f32_16x16x32_bf16 v[6:9], v[172:175], v[212:215], v[6:9]
	v_mfma_f32_16x16x32_bf16 v[2:5], v[180:183], v[212:215], v[2:5]
	v_mfma_f32_16x16x32_bf16 v[30:33], v[176:179], v[192:195], v[30:33]
	v_mfma_f32_16x16x32_bf16 v[26:29], v[184:187], v[192:195], v[26:29]
	v_mfma_f32_16x16x32_bf16 v[22:25], v[176:179], v[200:203], v[22:25]
	v_mfma_f32_16x16x32_bf16 v[18:21], v[184:187], v[200:203], v[18:21]
	v_mfma_f32_16x16x32_bf16 v[14:17], v[176:179], v[208:211], v[14:17]
	v_mfma_f32_16x16x32_bf16 v[10:13], v[184:187], v[208:211], v[10:13]
	v_mfma_f32_16x16x32_bf16 v[6:9], v[176:179], v[216:219], v[6:9]
	v_mfma_f32_16x16x32_bf16 v[2:5], v[184:187], v[216:219], v[2:5]
	s_barrier
	s_add_i32 s58, s58, 2
	s_add_u32 s80, s80, 0x100
	s_addc_u32 s81, s81, 0
	s_cmp_gt_u32 s58, 13
	s_cbranch_scc0 .LBB0_413

; #define PG8_STAGEA(bufoff, gbase) PG8_STAGE_(bufoff, gbase, voffA)
; #define PG8_STAGEB(bufoff, gbase) PG8_STAGE_(bufoff, gbase, voffB)
; #define PG8_LDA(dst, b, h) do { _Pragma("unroll") for (int m = 0; m < 4; ++m) _Pragma("unroll") for (int k = 0; k < 2; ++k) dst[m][k] = *(const LAS bf16x8*)(lds + PG8_SA(b, h) + aoff + m * 2048 + k * 1024); } while (0)
; #define PG8_LDB(dst, b, h) do { _Pragma("unroll") for (int n = 0; n < 2; ++n) _Pragma("unroll") for (int k = 0; k < 2; ++k) dst[n][k] = *(const LAS bf16x8*)(lds + PG8_SB(b, h) + boff + n * 2048 + k * 1024); } while (0)
; #define PG8_MMA(ai, bj, At, Bt_) do { __builtin_amdgcn_s_setprio(1); _Pragma("unroll") for (int m = 0; m < 4; ++m) _Pragma("unroll") for (int n = 0; n < 2; ++n) _Pragma("unroll") for (int k = 0; k < 2; ++k) \
;         acc[ai][bj][m][n] = __builtin_amdgcn_mfma_f32_16x16x32_bf16(Bt_[n][k], At[m][k], acc[ai][bj][m][n], 0, 0, 0); __builtin_amdgcn_s_setprio(0); } while (0)
; #define PG8_WAIT_V(n) asm volatile("s_waitcnt vmcnt(" #n ")" ::: "memory")
; #define PG8_WAIT_L(n) asm volatile("s_waitcnt lgkmcnt(" #n ")" ::: "memory")
; #define PG8_BAR __builtin_amdgcn_s_barrier()
; template <int EK, int SK = -1>
; __device__ __forceinline__ void gemm_phase(LAS unsigned char* lds, const bf16_t* A, const bf16_t* Bt, int nM, int N, int K, const EpiArgs& E) {
;     ...
;         const bool has_next = S.next(ui + 1, nxt);
;         const char* nA = has_next ? (const char*)A + (size_t)nxt.pm * tstep : cA; const char* nB = has_next ? (const char*)Bt + (size_t)nxt.pn * tstep : cB;
;         for (int t = 0; t < nt; t += 2) {
;             const bool last = (t == nt - 2);
;             const char* a1 = cA + (size_t)(t + 1) * kstep;
;             const char* a2 = last ? nA : cA + (size_t)(t + 2) * kstep; const char* b2 = last ? nB : cB + (size_t)(t + 2) * kstep;
;             const char* a3 = a2 + kstep; const char* b3 = b2 + kstep;
;             PG8_LDB(B0, 0, 0); PG8_LDB(B1, 0, 1); PG8_SCHED; PG8_LDA(At, 0, 0); PG8_STAGEA(PG8_SA(1, 1), a1 + hstep);
;             PG8_WAIT_V(8); PG8_WAIT_L(0); PG8_BAR; PG8_MMA(0, 0, At, B0); PG8_MMA(0, 1, At, B1); PG8_BAR; PG8_SCHED;
;             PG8_LDA(At, 0, 1); PG8_STAGEB(PG8_SB(0, 0), b2); PG8_STAGEB(PG8_SB(0, 1), b2 + hstep); PG8_STAGEA(PG8_SA(0, 0), a2);
;             PG8_WAIT_V(8); PG8_WAIT_L(0); PG8_BAR; PG8_MMA(1, 0, At, B0); PG8_MMA(1, 1, At, B1); PG8_BAR; PG8_SCHED;
.LBB0_537:
	s_add_u32 s54, s74, 0x100
	s_addc_u32 s55, s75, 0
	s_ashr_i32 s69, s68, 31
	s_lshl_b64 s[56:57], s[68:69], 19
	s_add_u32 s72, s62, s56
	s_addc_u32 s73, s63, s57
	s_and_b64 s[56:57], s[6:7], exec
	s_cselect_b32 s56, s73, s39
	s_cselect_b32 s57, s72, s38
	s_ashr_i32 s41, s40, 31
	s_lshl_b64 s[58:59], s[40:41], 19
	s_add_u32 s70, s81, s58
	s_addc_u32 s71, s82, s59
	s_and_b64 s[58:59], s[6:7], exec
	s_cselect_b32 s41, s71, s75
	s_cselect_b32 s58, s70, s74
	v_lshl_add_u64 v[146:147], s[38:39], 0, v[138:139]
	v_lshl_add_u64 v[148:149], s[38:39], 0, v[140:141]
	s_mov_b32 s59, -2
	s_mov_b64 s[74:75], 0
	v_add_u32_e32 v154, s88, v159
	ds_read_b128 v[150:153], v154
	ds_read_b128 v[164:167], v154 offset:1024
	ds_read_b128 v[168:171], v154 offset:2048
	ds_read_b128 v[172:175], v154 offset:3072
	v_add_u32_e32 v154, s89, v159
	s_add_u32 s69, s38, s74
	ds_read_b128 v[176:179], v154
	ds_read_b128 v[180:183], v154 offset:1024
	ds_read_b128 v[184:187], v154 offset:2048
	ds_read_b128 v[188:191], v154 offset:3072
	s_addc_u32 s76, s39, s75
	s_add_u32 s69, s69, 0x100
	s_addc_u32 s76, s76, 0
	s_add_u32 s91, s54, s74
	s_addc_u32 s77, s55, s75
	s_cmpk_eq_i32 s74, 0x700
	s_cselect_b32 s79, s56, s76
	s_cselect_b32 s78, s57, s69
	s_cselect_b32 s77, s41, s77
	s_cselect_b32 s76, s58, s91
	v_lshl_add_u64 v[154:155], v[146:147], 0, s[74:75]
	s_add_i32 m0, s15, 0xc000
	ds_read_b128 v[192:195], v162
	ds_read_b128 v[196:199], v162 offset:1024
	ds_read_b128 v[200:203], v162 offset:2048
	ds_read_b128 v[204:207], v162 offset:3072
	ds_read_b128 v[208:211], v162 offset:4096
	ds_read_b128 v[212:215], v162 offset:5120
	ds_read_b128 v[216:219], v162 offset:6144
	ds_read_b128 v[220:223], v162 offset:7168
	global_load_lds_dwordx4 v[154:155], off
	v_lshl_add_u64 v[154:155], v[148:149], 0, s[74:75]
	s_add_i32 m0, s15, 0xe000
	s_nop 0
	global_load_lds_dwordx4 v[154:155], off
	s_waitcnt vmcnt(8)
	s_waitcnt lgkmcnt(0)
	s_waitcnt lgkmcnt(0)
	v_mfma_f32_16x16x32_bf16 v[110:113], v[150:153], v[192:195], 0
	v_mfma_f32_16x16x32_bf16 v[106:109], v[168:171], v[192:195], 0
	v_mfma_f32_16x16x32_bf16 v[102:105], v[150:153], v[200:203], 0
	v_mfma_f32_16x16x32_bf16 v[98:101], v[168:171], v[200:203], 0
	s_barrier
	v_mfma_f32_16x16x32_bf16 v[94:97], v[150:153], v[208:211], 0
	v_mfma_f32_16x16x32_bf16 v[90:93], v[168:171], v[208:211], 0
	v_mfma_f32_16x16x32_bf16 v[86:89], v[150:153], v[216:219], 0
	v_mfma_f32_16x16x32_bf16 v[82:85], v[168:171], v[216:219], 0
	v_mfma_f32_16x16x32_bf16 v[110:113], v[164:167], v[196:199], v[110:113]
	v_mfma_f32_16x16x32_bf16 v[106:109], v[172:175], v[196:199], v[106:109]
	v_mfma_f32_16x16x32_bf16 v[102:105], v[164:167], v[204:207], v[102:105]
	v_mfma_f32_16x16x32_bf16 v[98:101], v[172:175], v[204:207], v[98:101]
	v_mfma_f32_16x16x32_bf16 v[94:97], v[164:167], v[212:215], v[94:97]
	v_mfma_f32_16x16x32_bf16 v[90:93], v[172:175], v[212:215], v[90:93]
	v_mfma_f32_16x16x32_bf16 v[86:89], v[164:167], v[220:223], v[86:89]
	v_mfma_f32_16x16x32_bf16 v[82:85], v[172:175], v[220:223], v[82:85]
	v_mfma_f32_16x16x32_bf16 v[78:81], v[176:179], v[192:195], 0
	v_mfma_f32_16x16x32_bf16 v[74:77], v[184:187], v[192:195], 0
	v_mfma_f32_16x16x32_bf16 v[70:73], v[176:179], v[200:203], 0
	v_mfma_f32_16x16x32_bf16 v[66:69], v[184:187], v[200:203], 0
	v_mfma_f32_16x16x32_bf16 v[62:65], v[176:179], v[208:211], 0
	v_mfma_f32_16x16x32_bf16 v[58:61], v[184:187], v[208:211], 0
	v_mfma_f32_16x16x32_bf16 v[54:57], v[176:179], v[216:219], 0
	v_mfma_f32_16x16x32_bf16 v[50:53], v[184:187], v[216:219], 0
	v_mfma_f32_16x16x32_bf16 v[78:81], v[180:183], v[196:199], v[78:81]
	v_mfma_f32_16x16x32_bf16 v[74:77], v[188:191], v[196:199], v[74:77]
	v_mfma_f32_16x16x32_bf16 v[70:73], v[180:183], v[204:207], v[70:73]
	v_mfma_f32_16x16x32_bf16 v[66:69], v[188:191], v[204:207], v[66:69]
	v_mfma_f32_16x16x32_bf16 v[62:65], v[180:183], v[212:215], v[62:65]
	v_mfma_f32_16x16x32_bf16 v[58:61], v[188:191], v[212:215], v[58:61]
	v_mfma_f32_16x16x32_bf16 v[54:57], v[180:183], v[220:223], v[54:57]
	v_mfma_f32_16x16x32_bf16 v[50:53], v[188:191], v[220:223], v[50:53]
	s_barrier
	s_add_i32 s69, s88, s83
	v_lshl_add_u64 v[154:155], s[76:77], 0, v[132:133]
	s_mov_b32 m0, s69
	ds_read_b128 v[192:195], v162 offset:16384
	ds_read_b128 v[196:199], v162 offset:17408
	ds_read_b128 v[200:203], v162 offset:18432
	ds_read_b128 v[204:207], v162 offset:19456
	ds_read_b128 v[208:211], v162 offset:20480
	ds_read_b128 v[212:215], v162 offset:21504
	ds_read_b128 v[216:219], v162 offset:22528
	ds_read_b128 v[220:223], v162 offset:23552
	global_load_lds_dwordx4 v[154:155], off
	s_add_i32 m0, s69, 0x2000
	s_add_u32 s92, s76, 0x40000
	v_lshl_add_u64 v[224:225], s[76:77], 0, v[136:137]
	s_addc_u32 s93, s77, 0
	s_add_i32 s69, s89, s83
	global_load_lds_dwordx4 v[224:225], off
	v_lshl_add_u64 v[226:227], s[92:93], 0, v[132:133]
	s_mov_b32 m0, s69
	v_lshl_add_u64 v[228:229], s[78:79], 0, v[134:135]
	global_load_lds_dwordx4 v[226:227], off
	v_lshl_add_u64 v[226:227], s[92:93], 0, v[136:137]
	s_add_i32 m0, s69, 0x2000
	s_nop 0
	global_load_lds_dwordx4 v[226:227], off
	v_lshl_add_u64 v[226:227], s[78:79], 0, v[130:131]
	s_mov_b32 m0, s15
	s_nop 0
	global_load_lds_dwordx4 v[226:227], off
	s_mov_b32 m0, s17
	s_nop 0
	global_load_lds_dwordx4 v[228:229], off
	s_waitcnt vmcnt(8)
	s_waitcnt lgkmcnt(0)
	s_waitcnt lgkmcnt(0)
	v_mfma_f32_16x16x32_bf16 v[46:49], v[150:153], v[192:195], 0
	v_mfma_f32_16x16x32_bf16 v[42:45], v[168:171], v[192:195], 0
	v_mfma_f32_16x16x32_bf16 v[38:41], v[150:153], v[200:203], 0
	v_mfma_f32_16x16x32_bf16 v[34:37], v[168:171], v[200:203], 0
	s_barrier
; #define PG8_STAGEA(bufoff, gbase) PG8_STAGE_(bufoff, gbase, voffA)
; #define PG8_STAGEB(bufoff, gbase) PG8_STAGE_(bufoff, gbase, voffB)
; #define PG8_LDA(dst, b, h) do { _Pragma("unroll") for (int m = 0; m < 4; ++m) _Pragma("unroll") for (int k = 0; k < 2; ++k) dst[m][k] = *(const LAS bf16x8*)(lds + PG8_SA(b, h) + aoff + m * 2048 + k * 1024); } while (0)
; #define PG8_LDB(dst, b, h) do { _Pragma("unroll") for (int n = 0; n < 2; ++n) _Pragma("unroll") for (int k = 0; k < 2; ++k) dst[n][k] = *(const LAS bf16x8*)(lds + PG8_SB(b, h) + boff + n * 2048 + k * 1024); } while (0)
; #define PG8_MMA(ai, bj, At, Bt_) do { __builtin_amdgcn_s_setprio(1); _Pragma("unroll") for (int m = 0; m < 4; ++m) _Pragma("unroll") for (int n = 0; n < 2; ++n) _Pragma("unroll") for (int k = 0; k < 2; ++k) \
;         acc[ai][bj][m][n] = __builtin_amdgcn_mfma_f32_16x16x32_bf16(Bt_[n][k], At[m][k], acc[ai][bj][m][n], 0, 0, 0); __builtin_amdgcn_s_setprio(0); } while (0)
; #define PG8_WAIT_V(n) asm volatile("s_waitcnt vmcnt(" #n ")" ::: "memory")
; #define PG8_WAIT_L(n) asm volatile("s_waitcnt lgkmcnt(" #n ")" ::: "memory")
; #define PG8_BAR __builtin_amdgcn_s_barrier()
; #define PG8_SCHED __builtin_amdgcn_sched_barrier(0)
; template <int EK, int SK = -1>
; __device__ __forceinline__ void gemm_phase(LAS unsigned char* lds, const bf16_t* A, const bf16_t* Bt, int nM, int N, int K, const EpiArgs& E) {
;     ...
;             PG8_WAIT_V(8); PG8_WAIT_L(0); PG8_BAR; PG8_MMA(0, 0, At, B0); PG8_MMA(0, 1, At, B1); PG8_BAR; PG8_SCHED;
;             PG8_LDA(At, 0, 1); PG8_STAGEB(PG8_SB(0, 0), b2); PG8_STAGEB(PG8_SB(0, 1), b2 + hstep); PG8_STAGEA(PG8_SA(0, 0), a2);
;             PG8_WAIT_V(8); PG8_WAIT_L(0); PG8_BAR; PG8_MMA(1, 0, At, B0); PG8_MMA(1, 1, At, B1); PG8_BAR; PG8_SCHED;
;             PG8_LDB(B0, 1, 0); PG8_LDB(B1, 1, 1); PG8_SCHED; PG8_LDA(At, 1, 0); PG8_STAGEA(PG8_SA(0, 1), a2 + hstep);
;             PG8_WAIT_V(8); PG8_WAIT_L(0); PG8_BAR; PG8_MMA(0, 0, At, B0); PG8_MMA(0, 1, At, B1); PG8_BAR; PG8_SCHED;
	v_mfma_f32_16x16x32_bf16 v[30:33], v[150:153], v[208:211], 0
	v_mfma_f32_16x16x32_bf16 v[26:29], v[168:171], v[208:211], 0
	v_mfma_f32_16x16x32_bf16 v[22:25], v[150:153], v[216:219], 0
	v_mfma_f32_16x16x32_bf16 v[18:21], v[168:171], v[216:219], 0
	v_mfma_f32_16x16x32_bf16 v[46:49], v[164:167], v[196:199], v[46:49]
	v_mfma_f32_16x16x32_bf16 v[42:45], v[172:175], v[196:199], v[42:45]
	v_mfma_f32_16x16x32_bf16 v[38:41], v[164:167], v[204:207], v[38:41]
	v_mfma_f32_16x16x32_bf16 v[34:37], v[172:175], v[204:207], v[34:37]
	v_mfma_f32_16x16x32_bf16 v[30:33], v[164:167], v[212:215], v[30:33]
	v_mfma_f32_16x16x32_bf16 v[26:29], v[172:175], v[212:215], v[26:29]
	v_mfma_f32_16x16x32_bf16 v[22:25], v[164:167], v[220:223], v[22:25]
	v_mfma_f32_16x16x32_bf16 v[18:21], v[172:175], v[220:223], v[18:21]
	v_mfma_f32_16x16x32_bf16 v[14:17], v[176:179], v[192:195], 0
	v_mfma_f32_16x16x32_bf16 v[10:13], v[184:187], v[192:195], 0
	v_mfma_f32_16x16x32_bf16 v[6:9], v[176:179], v[200:203], 0
	v_mfma_f32_16x16x32_bf16 v[2:5], v[184:187], v[200:203], 0
	v_mfma_f32_16x16x32_bf16 v[114:117], v[176:179], v[208:211], 0
	v_mfma_f32_16x16x32_bf16 v[118:121], v[184:187], v[208:211], 0
	v_mfma_f32_16x16x32_bf16 v[122:125], v[176:179], v[216:219], 0
	v_mfma_f32_16x16x32_bf16 v[126:129], v[184:187], v[216:219], 0
	v_mfma_f32_16x16x32_bf16 v[14:17], v[180:183], v[196:199], v[14:17]
	v_mfma_f32_16x16x32_bf16 v[10:13], v[188:191], v[196:199], v[10:13]
	v_mfma_f32_16x16x32_bf16 v[6:9], v[180:183], v[204:207], v[6:9]
	v_mfma_f32_16x16x32_bf16 v[2:5], v[188:191], v[204:207], v[2:5]
	v_mfma_f32_16x16x32_bf16 v[114:117], v[180:183], v[212:215], v[114:117]
	v_mfma_f32_16x16x32_bf16 v[118:121], v[188:191], v[212:215], v[118:121]
	v_mfma_f32_16x16x32_bf16 v[122:125], v[180:183], v[220:223], v[122:125]
	v_mfma_f32_16x16x32_bf16 v[126:129], v[188:191], v[220:223], v[126:129]
	s_barrier
	s_add_i32 s69, 0, 0x18000
	v_add_u32_e32 v163, s69, v159
	s_add_i32 s91, 0, 0x1c000
	ds_read_b128 v[150:153], v163
	ds_read_b128 v[164:167], v163 offset:1024
	ds_read_b128 v[168:171], v163 offset:2048
	ds_read_b128 v[172:175], v163 offset:3072
	v_add_u32_e32 v163, s91, v159
	ds_read_b128 v[176:179], v163
	ds_read_b128 v[180:183], v163 offset:1024
	ds_read_b128 v[184:187], v163 offset:2048
	ds_read_b128 v[188:191], v163 offset:3072
	s_add_u32 s78, s78, 0x40000
	s_addc_u32 s79, s79, 0
	s_mov_b32 m0, s84
	v_lshl_add_u64 v[230:231], s[78:79], 0, v[130:131]
	ds_read_b128 v[192:195], v162 offset:32768
	ds_read_b128 v[196:199], v162 offset:33792
	ds_read_b128 v[200:203], v162 offset:34816
	ds_read_b128 v[204:207], v162 offset:35840
	ds_read_b128 v[208:211], v162 offset:36864
	ds_read_b128 v[212:215], v162 offset:37888
	ds_read_b128 v[216:219], v162 offset:38912
	ds_read_b128 v[220:223], v162 offset:39936
	global_load_lds_dwordx4 v[230:231], off
	v_lshl_add_u64 v[230:231], s[78:79], 0, v[134:135]
	s_mov_b32 m0, s85
	s_nop 0
	global_load_lds_dwordx4 v[230:231], off
	s_waitcnt vmcnt(8)
	s_waitcnt lgkmcnt(0)
	s_waitcnt lgkmcnt(0)
	v_mfma_f32_16x16x32_bf16 v[110:113], v[150:153], v[192:195], v[110:113]
	v_mfma_f32_16x16x32_bf16 v[106:109], v[168:171], v[192:195], v[106:109]
	v_mfma_f32_16x16x32_bf16 v[102:105], v[150:153], v[200:203], v[102:105]
	v_mfma_f32_16x16x32_bf16 v[98:101], v[168:171], v[200:203], v[98:101]
	s_barrier
	v_mfma_f32_16x16x32_bf16 v[94:97], v[150:153], v[208:211], v[94:97]
	v_mfma_f32_16x16x32_bf16 v[90:93], v[168:171], v[208:211], v[90:93]
	v_mfma_f32_16x16x32_bf16 v[86:89], v[150:153], v[216:219], v[86:89]
	v_mfma_f32_16x16x32_bf16 v[82:85], v[168:171], v[216:219], v[82:85]
	v_mfma_f32_16x16x32_bf16 v[110:113], v[164:167], v[196:199], v[110:113]
	v_mfma_f32_16x16x32_bf16 v[106:109], v[172:175], v[196:199], v[106:109]
	v_mfma_f32_16x16x32_bf16 v[102:105], v[164:167], v[204:207], v[102:105]
	v_mfma_f32_16x16x32_bf16 v[98:101], v[172:175], v[204:207], v[98:101]
	v_mfma_f32_16x16x32_bf16 v[94:97], v[164:167], v[212:215], v[94:97]
	v_mfma_f32_16x16x32_bf16 v[90:93], v[172:175], v[212:215], v[90:93]
	v_mfma_f32_16x16x32_bf16 v[86:89], v[164:167], v[220:223], v[86:89]
	v_mfma_f32_16x16x32_bf16 v[82:85], v[172:175], v[220:223], v[82:85]
	v_mfma_f32_16x16x32_bf16 v[78:81], v[176:179], v[192:195], v[78:81]
	v_mfma_f32_16x16x32_bf16 v[74:77], v[184:187], v[192:195], v[74:77]
	v_mfma_f32_16x16x32_bf16 v[70:73], v[176:179], v[200:203], v[70:73]
	v_mfma_f32_16x16x32_bf16 v[66:69], v[184:187], v[200:203], v[66:69]
	v_mfma_f32_16x16x32_bf16 v[62:65], v[176:179], v[208:211], v[62:65]
	v_mfma_f32_16x16x32_bf16 v[58:61], v[184:187], v[208:211], v[58:61]
	v_mfma_f32_16x16x32_bf16 v[54:57], v[176:179], v[216:219], v[54:57]
	v_mfma_f32_16x16x32_bf16 v[50:53], v[184:187], v[216:219], v[50:53]
	v_mfma_f32_16x16x32_bf16 v[78:81], v[180:183], v[196:199], v[78:81]
	v_mfma_f32_16x16x32_bf16 v[74:77], v[188:191], v[196:199], v[74:77]
	v_mfma_f32_16x16x32_bf16 v[70:73], v[180:183], v[204:207], v[70:73]
	v_mfma_f32_16x16x32_bf16 v[66:69], v[188:191], v[204:207], v[66:69]
	v_mfma_f32_16x16x32_bf16 v[62:65], v[180:183], v[212:215], v[62:65]
	v_mfma_f32_16x16x32_bf16 v[58:61], v[188:191], v[212:215], v[58:61]
	v_mfma_f32_16x16x32_bf16 v[54:57], v[180:183], v[220:223], v[54:57]
	v_mfma_f32_16x16x32_bf16 v[50:53], v[188:191], v[220:223], v[50:53]
	s_barrier
; #define PG8_STAGEA(bufoff, gbase) PG8_STAGE_(bufoff, gbase, voffA)
; #define PG8_STAGEB(bufoff, gbase) PG8_STAGE_(bufoff, gbase, voffB)
; #define PG8_LDA(dst, b, h) do { _Pragma("unroll") for (int m = 0; m < 4; ++m) _Pragma("unroll") for (int k = 0; k < 2; ++k) dst[m][k] = *(const LAS bf16x8*)(lds + PG8_SA(b, h) + aoff + m * 2048 + k * 1024); } while (0)
; #define PG8_LDB(dst, b, h) do { _Pragma("unroll") for (int n = 0; n < 2; ++n) _Pragma("unroll") for (int k = 0; k < 2; ++k) dst[n][k] = *(const LAS bf16x8*)(lds + PG8_SB(b, h) + boff + n * 2048 + k * 1024); } while (0)
; #define PG8_WAIT_V(n) asm volatile("s_waitcnt vmcnt(" #n ")" ::: "memory")
; #define PG8_WAIT_L(n) asm volatile("s_waitcnt lgkmcnt(" #n ")" ::: "memory")
; #define PG8_BAR __builtin_amdgcn_s_barrier()
; #define PG8_SCHED __builtin_amdgcn_sched_barrier(0)
; template <int EK, int SK = -1>
; __device__ __forceinline__ void gemm_phase(LAS unsigned char* lds, const bf16_t* A, const bf16_t* Bt, int nM, int N, int K, const EpiArgs& E) {
;     ...
;         for (int t = 0; t < nt; t += 2) {
;             const bool last = (t == nt - 2);
;             const char* a1 = cA + (size_t)(t + 1) * kstep;
;             const char* a2 = last ? nA : cA + (size_t)(t + 2) * kstep; const char* b2 = last ? nB : cB + (size_t)(t + 2) * kstep;
;             const char* a3 = a2 + kstep; const char* b3 = b2 + kstep;
;             PG8_LDB(B0, 0, 0); PG8_LDB(B1, 0, 1); PG8_SCHED; PG8_LDA(At, 0, 0); PG8_STAGEA(PG8_SA(1, 1), a1 + hstep);
;             PG8_WAIT_V(8); PG8_WAIT_L(0); PG8_BAR; PG8_MMA(0, 0, At, B0); PG8_MMA(0, 1, At, B1); PG8_BAR; PG8_SCHED;
;             PG8_LDA(At, 0, 1); PG8_STAGEB(PG8_SB(0, 0), b2); PG8_STAGEB(PG8_SB(0, 1), b2 + hstep); PG8_STAGEA(PG8_SA(0, 0), a2);
;             PG8_WAIT_V(8); PG8_WAIT_L(0); PG8_BAR; PG8_MMA(1, 0, At, B0); PG8_MMA(1, 1, At, B1); PG8_BAR; PG8_SCHED;
;             PG8_LDB(B0, 1, 0); PG8_LDB(B1, 1, 1); PG8_SCHED; PG8_LDA(At, 1, 0); PG8_STAGEA(PG8_SA(0, 1), a2 + hstep);
;             PG8_WAIT_V(8); PG8_WAIT_L(0); PG8_BAR; PG8_MMA(0, 0, At, B0); PG8_MMA(0, 1, At, B1); PG8_BAR; PG8_SCHED;
;             PG8_LDA(At, 1, 1); PG8_STAGEB(PG8_SB(1, 0), b3); PG8_STAGEB(PG8_SB(1, 1), b3 + hstep); PG8_STAGEA(PG8_SA(1, 0), a3);
;             PG8_WAIT_V(8); PG8_WAIT_L(0); PG8_BAR; PG8_MMA(1, 0, At, B0); PG8_MMA(1, 1, At, B1); PG8_BAR; PG8_SCHED;
	s_add_i32 s69, s69, s83
	v_lshl_add_u64 v[154:155], v[154:155], 0, s[10:11]
	s_mov_b32 m0, s69
	ds_read_b128 v[192:195], v162 offset:49152
	ds_read_b128 v[196:199], v162 offset:50176
	ds_read_b128 v[200:203], v162 offset:51200
	ds_read_b128 v[204:207], v162 offset:52224
	ds_read_b128 v[208:211], v162 offset:53248
	ds_read_b128 v[212:215], v162 offset:54272
	ds_read_b128 v[216:219], v162 offset:55296
	ds_read_b128 v[220:223], v162 offset:56320
	global_load_lds_dwordx4 v[154:155], off
	s_add_i32 m0, s69, 0x2000
	s_add_u32 s76, s76, 0x40080
	v_lshl_add_u64 v[154:155], v[224:225], 0, s[10:11]
	s_addc_u32 s77, s77, 0
	s_add_i32 s69, s91, s83
	global_load_lds_dwordx4 v[154:155], off
	v_lshl_add_u64 v[154:155], s[76:77], 0, v[132:133]
	s_mov_b32 m0, s69
	s_nop 0
	global_load_lds_dwordx4 v[154:155], off
	v_lshl_add_u64 v[154:155], s[76:77], 0, v[136:137]
	s_add_i32 m0, s69, 0x2000
	s_nop 0
	global_load_lds_dwordx4 v[154:155], off
	v_lshl_add_u64 v[154:155], v[226:227], 0, s[10:11]
	s_mov_b32 m0, s86
	s_nop 0
	global_load_lds_dwordx4 v[154:155], off
	v_lshl_add_u64 v[154:155], v[228:229], 0, s[10:11]
	s_mov_b32 m0, s87
	s_nop 0
	global_load_lds_dwordx4 v[154:155], off
	s_waitcnt vmcnt(8)
	s_waitcnt lgkmcnt(0)
	s_waitcnt lgkmcnt(0)
	v_mfma_f32_16x16x32_bf16 v[46:49], v[150:153], v[192:195], v[46:49]
	v_mfma_f32_16x16x32_bf16 v[42:45], v[168:171], v[192:195], v[42:45]
	v_mfma_f32_16x16x32_bf16 v[38:41], v[150:153], v[200:203], v[38:41]
	v_mfma_f32_16x16x32_bf16 v[34:37], v[168:171], v[200:203], v[34:37]
	s_barrier
	v_mfma_f32_16x16x32_bf16 v[30:33], v[150:153], v[208:211], v[30:33]
	v_mfma_f32_16x16x32_bf16 v[26:29], v[168:171], v[208:211], v[26:29]
	v_mfma_f32_16x16x32_bf16 v[22:25], v[150:153], v[216:219], v[22:25]
	v_mfma_f32_16x16x32_bf16 v[18:21], v[168:171], v[216:219], v[18:21]
	v_mfma_f32_16x16x32_bf16 v[46:49], v[164:167], v[196:199], v[46:49]
	v_mfma_f32_16x16x32_bf16 v[42:45], v[172:175], v[196:199], v[42:45]
	v_mfma_f32_16x16x32_bf16 v[38:41], v[164:167], v[204:207], v[38:41]
	v_mfma_f32_16x16x32_bf16 v[34:37], v[172:175], v[204:207], v[34:37]
	v_mfma_f32_16x16x32_bf16 v[30:33], v[164:167], v[212:215], v[30:33]
	v_mfma_f32_16x16x32_bf16 v[26:29], v[172:175], v[212:215], v[26:29]
	v_mfma_f32_16x16x32_bf16 v[22:25], v[164:167], v[220:223], v[22:25]
	v_mfma_f32_16x16x32_bf16 v[18:21], v[172:175], v[220:223], v[18:21]
	v_mfma_f32_16x16x32_bf16 v[14:17], v[176:179], v[192:195], v[14:17]
	v_mfma_f32_16x16x32_bf16 v[10:13], v[184:187], v[192:195], v[10:13]
	v_mfma_f32_16x16x32_bf16 v[6:9], v[176:179], v[200:203], v[6:9]
	v_mfma_f32_16x16x32_bf16 v[2:5], v[184:187], v[200:203], v[2:5]
	v_mfma_f32_16x16x32_bf16 v[114:117], v[176:179], v[208:211], v[114:117]
	v_mfma_f32_16x16x32_bf16 v[118:121], v[184:187], v[208:211], v[118:121]
	v_mfma_f32_16x16x32_bf16 v[122:125], v[176:179], v[216:219], v[122:125]
	v_mfma_f32_16x16x32_bf16 v[126:129], v[184:187], v[216:219], v[126:129]
	v_mfma_f32_16x16x32_bf16 v[14:17], v[180:183], v[196:199], v[14:17]
	v_mfma_f32_16x16x32_bf16 v[10:13], v[188:191], v[196:199], v[10:13]
	v_mfma_f32_16x16x32_bf16 v[6:9], v[180:183], v[204:207], v[6:9]
	v_mfma_f32_16x16x32_bf16 v[2:5], v[188:191], v[204:207], v[2:5]
	v_mfma_f32_16x16x32_bf16 v[114:117], v[180:183], v[212:215], v[114:117]
	v_mfma_f32_16x16x32_bf16 v[118:121], v[188:191], v[212:215], v[118:121]
	v_mfma_f32_16x16x32_bf16 v[122:125], v[180:183], v[220:223], v[122:125]
	v_mfma_f32_16x16x32_bf16 v[126:129], v[188:191], v[220:223], v[126:129]
	s_barrier
	s_add_i32 s59, s59, 2
	s_add_u32 s74, s74, 0x100
	s_addc_u32 s75, s75, 0
	s_cmp_gt_u32 s59, 13
	s_cbranch_scc0 .LBB0_538
	s_branch .Lmy_kexit_2
.LBB0_538:
	v_add_u32_e32 v154, s88, v159
	ds_read_b128 v[150:153], v154
	ds_read_b128 v[164:167], v154 offset:1024
	ds_read_b128 v[168:171], v154 offset:2048
	ds_read_b128 v[172:175], v154 offset:3072
	v_add_u32_e32 v154, s89, v159
	s_add_u32 s69, s38, s74
	ds_read_b128 v[176:179], v154
	ds_read_b128 v[180:183], v154 offset:1024
	ds_read_b128 v[184:187], v154 offset:2048
	ds_read_b128 v[188:191], v154 offset:3072
	s_addc_u32 s76, s39, s75
	s_add_u32 s69, s69, 0x100
	s_addc_u32 s76, s76, 0
	s_add_u32 s91, s54, s74
	s_addc_u32 s77, s55, s75
	s_cmpk_eq_i32 s74, 0x700
	s_cselect_b32 s79, s56, s76
	s_cselect_b32 s78, s57, s69
	s_cselect_b32 s77, s41, s77
	s_cselect_b32 s76, s58, s91
	v_lshl_add_u64 v[154:155], v[146:147], 0, s[74:75]
	s_add_i32 m0, s15, 0xc000
	ds_read_b128 v[192:195], v162
	ds_read_b128 v[196:199], v162 offset:1024
	ds_read_b128 v[200:203], v162 offset:2048
	ds_read_b128 v[204:207], v162 offset:3072
	ds_read_b128 v[208:211], v162 offset:4096
	ds_read_b128 v[212:215], v162 offset:5120
	ds_read_b128 v[216:219], v162 offset:6144
	ds_read_b128 v[220:223], v162 offset:7168
	global_load_lds_dwordx4 v[154:155], off
	v_lshl_add_u64 v[154:155], v[148:149], 0, s[74:75]
	s_add_i32 m0, s15, 0xe000
	s_nop 0
	global_load_lds_dwordx4 v[154:155], off
	s_waitcnt vmcnt(8)
	s_waitcnt lgkmcnt(0)
	s_waitcnt lgkmcnt(0)
	v_mfma_f32_16x16x32_bf16 v[110:113], v[150:153], v[192:195], v[110:113]
	v_mfma_f32_16x16x32_bf16 v[106:109], v[168:171], v[192:195], v[106:109]
	v_mfma_f32_16x16x32_bf16 v[102:105], v[150:153], v[200:203], v[102:105]
	v_mfma_f32_16x16x32_bf16 v[98:101], v[168:171], v[200:203], v[98:101]
	s_barrier
; #define PG8_STAGEA(bufoff, gbase) PG8_STAGE_(bufoff, gbase, voffA)
; #define PG8_STAGEB(bufoff, gbase) PG8_STAGE_(bufoff, gbase, voffB)
; #define PG8_LDA(dst, b, h) do { _Pragma("unroll") for (int m = 0; m < 4; ++m) _Pragma("unroll") for (int k = 0; k < 2; ++k) dst[m][k] = *(const LAS bf16x8*)(lds + PG8_SA(b, h) + aoff + m * 2048 + k * 1024); } while (0)
; #define PG8_LDB(dst, b, h) do { _Pragma("unroll") for (int n = 0; n < 2; ++n) _Pragma("unroll") for (int k = 0; k < 2; ++k) dst[n][k] = *(const LAS bf16x8*)(lds + PG8_SB(b, h) + boff + n * 2048 + k * 1024); } while (0)
; #define PG8_MMA(ai, bj, At, Bt_) do { __builtin_amdgcn_s_setprio(1); _Pragma("unroll") for (int m = 0; m < 4; ++m) _Pragma("unroll") for (int n = 0; n < 2; ++n) _Pragma("unroll") for (int k = 0; k < 2; ++k) \
;         acc[ai][bj][m][n] = __builtin_amdgcn_mfma_f32_16x16x32_bf16(Bt_[n][k], At[m][k], acc[ai][bj][m][n], 0, 0, 0); __builtin_amdgcn_s_setprio(0); } while (0)
; #define PG8_WAIT_V(n) asm volatile("s_waitcnt vmcnt(" #n ")" ::: "memory")
; #define PG8_WAIT_L(n) asm volatile("s_waitcnt lgkmcnt(" #n ")" ::: "memory")
; #define PG8_BAR __builtin_amdgcn_s_barrier()
; #define PG8_SCHED __builtin_amdgcn_sched_barrier(0)
; template <int EK, int SK = -1>
; __device__ __forceinline__ void gemm_phase(LAS unsigned char* lds, const bf16_t* A, const bf16_t* Bt, int nM, int N, int K, const EpiArgs& E) {
;     ...
;             PG8_LDB(B0, 0, 0); PG8_LDB(B1, 0, 1); PG8_SCHED; PG8_LDA(At, 0, 0); PG8_STAGEA(PG8_SA(1, 1), a1 + hstep);
;             PG8_WAIT_V(8); PG8_WAIT_L(0); PG8_BAR; PG8_MMA(0, 0, At, B0); PG8_MMA(0, 1, At, B1); PG8_BAR; PG8_SCHED;
;             PG8_LDA(At, 0, 1); PG8_STAGEB(PG8_SB(0, 0), b2); PG8_STAGEB(PG8_SB(0, 1), b2 + hstep); PG8_STAGEA(PG8_SA(0, 0), a2);
;             PG8_WAIT_V(8); PG8_WAIT_L(0); PG8_BAR; PG8_MMA(1, 0, At, B0); PG8_MMA(1, 1, At, B1); PG8_BAR; PG8_SCHED;
	v_mfma_f32_16x16x32_bf16 v[94:97], v[150:153], v[208:211], v[94:97]
	v_mfma_f32_16x16x32_bf16 v[90:93], v[168:171], v[208:211], v[90:93]
	v_mfma_f32_16x16x32_bf16 v[86:89], v[150:153], v[216:219], v[86:89]
	v_mfma_f32_16x16x32_bf16 v[82:85], v[168:171], v[216:219], v[82:85]
	v_mfma_f32_16x16x32_bf16 v[110:113], v[164:167], v[196:199], v[110:113]
	v_mfma_f32_16x16x32_bf16 v[106:109], v[172:175], v[196:199], v[106:109]
	v_mfma_f32_16x16x32_bf16 v[102:105], v[164:167], v[204:207], v[102:105]
	v_mfma_f32_16x16x32_bf16 v[98:101], v[172:175], v[204:207], v[98:101]
	v_mfma_f32_16x16x32_bf16 v[94:97], v[164:167], v[212:215], v[94:97]
	v_mfma_f32_16x16x32_bf16 v[90:93], v[172:175], v[212:215], v[90:93]
	v_mfma_f32_16x16x32_bf16 v[86:89], v[164:167], v[220:223], v[86:89]
	v_mfma_f32_16x16x32_bf16 v[82:85], v[172:175], v[220:223], v[82:85]
	v_mfma_f32_16x16x32_bf16 v[78:81], v[176:179], v[192:195], v[78:81]
	v_mfma_f32_16x16x32_bf16 v[74:77], v[184:187], v[192:195], v[74:77]
	v_mfma_f32_16x16x32_bf16 v[70:73], v[176:179], v[200:203], v[70:73]
	v_mfma_f32_16x16x32_bf16 v[66:69], v[184:187], v[200:203], v[66:69]
	v_mfma_f32_16x16x32_bf16 v[62:65], v[176:179], v[208:211], v[62:65]
	v_mfma_f32_16x16x32_bf16 v[58:61], v[184:187], v[208:211], v[58:61]
	v_mfma_f32_16x16x32_bf16 v[54:57], v[176:179], v[216:219], v[54:57]
	v_mfma_f32_16x16x32_bf16 v[50:53], v[184:187], v[216:219], v[50:53]
	v_mfma_f32_16x16x32_bf16 v[78:81], v[180:183], v[196:199], v[78:81]
	v_mfma_f32_16x16x32_bf16 v[74:77], v[188:191], v[196:199], v[74:77]
	v_mfma_f32_16x16x32_bf16 v[70:73], v[180:183], v[204:207], v[70:73]
	v_mfma_f32_16x16x32_bf16 v[66:69], v[188:191], v[204:207], v[66:69]
	v_mfma_f32_16x16x32_bf16 v[62:65], v[180:183], v[212:215], v[62:65]
	v_mfma_f32_16x16x32_bf16 v[58:61], v[188:191], v[212:215], v[58:61]
	v_mfma_f32_16x16x32_bf16 v[54:57], v[180:183], v[220:223], v[54:57]
	v_mfma_f32_16x16x32_bf16 v[50:53], v[188:191], v[220:223], v[50:53]
	s_barrier
	s_add_i32 s69, s88, s83
	v_lshl_add_u64 v[154:155], s[76:77], 0, v[132:133]
	s_mov_b32 m0, s69
	ds_read_b128 v[192:195], v162 offset:16384
	ds_read_b128 v[196:199], v162 offset:17408
	ds_read_b128 v[200:203], v162 offset:18432
	ds_read_b128 v[204:207], v162 offset:19456
	ds_read_b128 v[208:211], v162 offset:20480
	ds_read_b128 v[212:215], v162 offset:21504
	ds_read_b128 v[216:219], v162 offset:22528
	ds_read_b128 v[220:223], v162 offset:23552
	global_load_lds_dwordx4 v[154:155], off
	s_add_i32 m0, s69, 0x2000
	s_add_u32 s92, s76, 0x40000
	v_lshl_add_u64 v[224:225], s[76:77], 0, v[136:137]
	s_addc_u32 s93, s77, 0
	s_add_i32 s69, s89, s83
	global_load_lds_dwordx4 v[224:225], off
	v_lshl_add_u64 v[226:227], s[92:93], 0, v[132:133]
	s_mov_b32 m0, s69
	v_lshl_add_u64 v[228:229], s[78:79], 0, v[134:135]
	global_load_lds_dwordx4 v[226:227], off
	v_lshl_add_u64 v[226:227], s[92:93], 0, v[136:137]
	s_add_i32 m0, s69, 0x2000
	s_nop 0
	global_load_lds_dwordx4 v[226:227], off
	v_lshl_add_u64 v[226:227], s[78:79], 0, v[130:131]
	s_mov_b32 m0, s15
	s_nop 0
	global_load_lds_dwordx4 v[226:227], off
	s_mov_b32 m0, s17
	s_nop 0
	global_load_lds_dwordx4 v[228:229], off
	s_waitcnt vmcnt(8)
	s_waitcnt lgkmcnt(0)
	s_waitcnt lgkmcnt(0)
	v_mfma_f32_16x16x32_bf16 v[46:49], v[150:153], v[192:195], v[46:49]
	v_mfma_f32_16x16x32_bf16 v[42:45], v[168:171], v[192:195], v[42:45]
	v_mfma_f32_16x16x32_bf16 v[38:41], v[150:153], v[200:203], v[38:41]
	v_mfma_f32_16x16x32_bf16 v[34:37], v[168:171], v[200:203], v[34:37]
	s_barrier
	v_mfma_f32_16x16x32_bf16 v[30:33], v[150:153], v[208:211], v[30:33]
	v_mfma_f32_16x16x32_bf16 v[26:29], v[168:171], v[208:211], v[26:29]
	v_mfma_f32_16x16x32_bf16 v[22:25], v[150:153], v[216:219], v[22:25]
	v_mfma_f32_16x16x32_bf16 v[18:21], v[168:171], v[216:219], v[18:21]
	v_mfma_f32_16x16x32_bf16 v[46:49], v[164:167], v[196:199], v[46:49]
	v_mfma_f32_16x16x32_bf16 v[42:45], v[172:175], v[196:199], v[42:45]
	v_mfma_f32_16x16x32_bf16 v[38:41], v[164:167], v[204:207], v[38:41]
	v_mfma_f32_16x16x32_bf16 v[34:37], v[172:175], v[204:207], v[34:37]
	v_mfma_f32_16x16x32_bf16 v[30:33], v[164:167], v[212:215], v[30:33]
	v_mfma_f32_16x16x32_bf16 v[26:29], v[172:175], v[212:215], v[26:29]
	v_mfma_f32_16x16x32_bf16 v[22:25], v[164:167], v[220:223], v[22:25]
	v_mfma_f32_16x16x32_bf16 v[18:21], v[172:175], v[220:223], v[18:21]
	v_mfma_f32_16x16x32_bf16 v[14:17], v[176:179], v[192:195], v[14:17]
	v_mfma_f32_16x16x32_bf16 v[10:13], v[184:187], v[192:195], v[10:13]
	v_mfma_f32_16x16x32_bf16 v[6:9], v[176:179], v[200:203], v[6:9]
	v_mfma_f32_16x16x32_bf16 v[2:5], v[184:187], v[200:203], v[2:5]
	v_mfma_f32_16x16x32_bf16 v[114:117], v[176:179], v[208:211], v[114:117]
	v_mfma_f32_16x16x32_bf16 v[118:121], v[184:187], v[208:211], v[118:121]
	v_mfma_f32_16x16x32_bf16 v[122:125], v[176:179], v[216:219], v[122:125]
	v_mfma_f32_16x16x32_bf16 v[126:129], v[184:187], v[216:219], v[126:129]
	v_mfma_f32_16x16x32_bf16 v[14:17], v[180:183], v[196:199], v[14:17]
	v_mfma_f32_16x16x32_bf16 v[10:13], v[188:191], v[196:199], v[10:13]
	v_mfma_f32_16x16x32_bf16 v[6:9], v[180:183], v[204:207], v[6:9]
	v_mfma_f32_16x16x32_bf16 v[2:5], v[188:191], v[204:207], v[2:5]
	v_mfma_f32_16x16x32_bf16 v[114:117], v[180:183], v[212:215], v[114:117]
	v_mfma_f32_16x16x32_bf16 v[118:121], v[188:191], v[212:215], v[118:121]
	v_mfma_f32_16x16x32_bf16 v[122:125], v[180:183], v[220:223], v[122:125]
	v_mfma_f32_16x16x32_bf16 v[126:129], v[188:191], v[220:223], v[126:129]
	s_barrier
; #define PG8_STAGEA(bufoff, gbase) PG8_STAGE_(bufoff, gbase, voffA)
; #define PG8_STAGEB(bufoff, gbase) PG8_STAGE_(bufoff, gbase, voffB)
; #define PG8_LDA(dst, b, h) do { _Pragma("unroll") for (int m = 0; m < 4; ++m) _Pragma("unroll") for (int k = 0; k < 2; ++k) dst[m][k] = *(const LAS bf16x8*)(lds + PG8_SA(b, h) + aoff + m * 2048 + k * 1024); } while (0)
; #define PG8_LDB(dst, b, h) do { _Pragma("unroll") for (int n = 0; n < 2; ++n) _Pragma("unroll") for (int k = 0; k < 2; ++k) dst[n][k] = *(const LAS bf16x8*)(lds + PG8_SB(b, h) + boff + n * 2048 + k * 1024); } while (0)
; #define PG8_MMA(ai, bj, At, Bt_) do { __builtin_amdgcn_s_setprio(1); _Pragma("unroll") for (int m = 0; m < 4; ++m) _Pragma("unroll") for (int n = 0; n < 2; ++n) _Pragma("unroll") for (int k = 0; k < 2; ++k) \
;         acc[ai][bj][m][n] = __builtin_amdgcn_mfma_f32_16x16x32_bf16(Bt_[n][k], At[m][k], acc[ai][bj][m][n], 0, 0, 0); __builtin_amdgcn_s_setprio(0); } while (0)
; #define PG8_WAIT_V(n) asm volatile("s_waitcnt vmcnt(" #n ")" ::: "memory")
; #define PG8_WAIT_L(n) asm volatile("s_waitcnt lgkmcnt(" #n ")" ::: "memory")
; #define PG8_BAR __builtin_amdgcn_s_barrier()
; #define PG8_SCHED __builtin_amdgcn_sched_barrier(0)
; template <int EK, int SK = -1>
; __device__ __forceinline__ void gemm_phase(LAS unsigned char* lds, const bf16_t* A, const bf16_t* Bt, int nM, int N, int K, const EpiArgs& E) {
;     ...
;             PG8_LDB(B0, 1, 0); PG8_LDB(B1, 1, 1); PG8_SCHED; PG8_LDA(At, 1, 0); PG8_STAGEA(PG8_SA(0, 1), a2 + hstep);
;             PG8_WAIT_V(8); PG8_WAIT_L(0); PG8_BAR; PG8_MMA(0, 0, At, B0); PG8_MMA(0, 1, At, B1); PG8_BAR; PG8_SCHED;
;             PG8_LDA(At, 1, 1); PG8_STAGEB(PG8_SB(1, 0), b3); PG8_STAGEB(PG8_SB(1, 1), b3 + hstep); PG8_STAGEA(PG8_SA(1, 0), a3);
;             PG8_WAIT_V(8); PG8_WAIT_L(0); PG8_BAR; PG8_MMA(1, 0, At, B0); PG8_MMA(1, 1, At, B1); PG8_BAR; PG8_SCHED;
;         }
	s_add_i32 s69, 0, 0x18000
	v_add_u32_e32 v163, s69, v159
	s_add_i32 s91, 0, 0x1c000
	ds_read_b128 v[150:153], v163
	ds_read_b128 v[164:167], v163 offset:1024
	ds_read_b128 v[168:171], v163 offset:2048
	ds_read_b128 v[172:175], v163 offset:3072
	v_add_u32_e32 v163, s91, v159
	ds_read_b128 v[176:179], v163
	ds_read_b128 v[180:183], v163 offset:1024
	ds_read_b128 v[184:187], v163 offset:2048
	ds_read_b128 v[188:191], v163 offset:3072
	s_add_u32 s78, s78, 0x40000
	s_addc_u32 s79, s79, 0
	s_mov_b32 m0, s84
	v_lshl_add_u64 v[230:231], s[78:79], 0, v[130:131]
	ds_read_b128 v[192:195], v162 offset:32768
	ds_read_b128 v[196:199], v162 offset:33792
	ds_read_b128 v[200:203], v162 offset:34816
	ds_read_b128 v[204:207], v162 offset:35840
	ds_read_b128 v[208:211], v162 offset:36864
	ds_read_b128 v[212:215], v162 offset:37888
	ds_read_b128 v[216:219], v162 offset:38912
	ds_read_b128 v[220:223], v162 offset:39936
	global_load_lds_dwordx4 v[230:231], off
	v_lshl_add_u64 v[230:231], s[78:79], 0, v[134:135]
	s_mov_b32 m0, s85
	s_nop 0
	global_load_lds_dwordx4 v[230:231], off
	s_waitcnt vmcnt(8)
	s_waitcnt lgkmcnt(0)
	s_waitcnt lgkmcnt(0)
	v_mfma_f32_16x16x32_bf16 v[110:113], v[150:153], v[192:195], v[110:113]
	v_mfma_f32_16x16x32_bf16 v[106:109], v[168:171], v[192:195], v[106:109]
	v_mfma_f32_16x16x32_bf16 v[102:105], v[150:153], v[200:203], v[102:105]
	v_mfma_f32_16x16x32_bf16 v[98:101], v[168:171], v[200:203], v[98:101]
	s_barrier
	v_mfma_f32_16x16x32_bf16 v[94:97], v[150:153], v[208:211], v[94:97]
	v_mfma_f32_16x16x32_bf16 v[90:93], v[168:171], v[208:211], v[90:93]
	v_mfma_f32_16x16x32_bf16 v[86:89], v[150:153], v[216:219], v[86:89]
	v_mfma_f32_16x16x32_bf16 v[82:85], v[168:171], v[216:219], v[82:85]
	v_mfma_f32_16x16x32_bf16 v[110:113], v[164:167], v[196:199], v[110:113]
	v_mfma_f32_16x16x32_bf16 v[106:109], v[172:175], v[196:199], v[106:109]
	v_mfma_f32_16x16x32_bf16 v[102:105], v[164:167], v[204:207], v[102:105]
	v_mfma_f32_16x16x32_bf16 v[98:101], v[172:175], v[204:207], v[98:101]
	v_mfma_f32_16x16x32_bf16 v[94:97], v[164:167], v[212:215], v[94:97]
	v_mfma_f32_16x16x32_bf16 v[90:93], v[172:175], v[212:215], v[90:93]
	v_mfma_f32_16x16x32_bf16 v[86:89], v[164:167], v[220:223], v[86:89]
	v_mfma_f32_16x16x32_bf16 v[82:85], v[172:175], v[220:223], v[82:85]
	v_mfma_f32_16x16x32_bf16 v[78:81], v[176:179], v[192:195], v[78:81]
	v_mfma_f32_16x16x32_bf16 v[74:77], v[184:187], v[192:195], v[74:77]
	v_mfma_f32_16x16x32_bf16 v[70:73], v[176:179], v[200:203], v[70:73]
	v_mfma_f32_16x16x32_bf16 v[66:69], v[184:187], v[200:203], v[66:69]
	v_mfma_f32_16x16x32_bf16 v[62:65], v[176:179], v[208:211], v[62:65]
	v_mfma_f32_16x16x32_bf16 v[58:61], v[184:187], v[208:211], v[58:61]
	v_mfma_f32_16x16x32_bf16 v[54:57], v[176:179], v[216:219], v[54:57]
	v_mfma_f32_16x16x32_bf16 v[50:53], v[184:187], v[216:219], v[50:53]
	v_mfma_f32_16x16x32_bf16 v[78:81], v[180:183], v[196:199], v[78:81]
	v_mfma_f32_16x16x32_bf16 v[74:77], v[188:191], v[196:199], v[74:77]
	v_mfma_f32_16x16x32_bf16 v[70:73], v[180:183], v[204:207], v[70:73]
	v_mfma_f32_16x16x32_bf16 v[66:69], v[188:191], v[204:207], v[66:69]
	v_mfma_f32_16x16x32_bf16 v[62:65], v[180:183], v[212:215], v[62:65]
	v_mfma_f32_16x16x32_bf16 v[58:61], v[188:191], v[212:215], v[58:61]
	v_mfma_f32_16x16x32_bf16 v[54:57], v[180:183], v[220:223], v[54:57]
	v_mfma_f32_16x16x32_bf16 v[50:53], v[188:191], v[220:223], v[50:53]
	s_barrier
	s_add_i32 s69, s69, s83
	v_lshl_add_u64 v[154:155], v[154:155], 0, s[10:11]
	s_mov_b32 m0, s69
	ds_read_b128 v[192:195], v162 offset:49152
	ds_read_b128 v[196:199], v162 offset:50176
	ds_read_b128 v[200:203], v162 offset:51200
	ds_read_b128 v[204:207], v162 offset:52224
	ds_read_b128 v[208:211], v162 offset:53248
	ds_read_b128 v[212:215], v162 offset:54272
	ds_read_b128 v[216:219], v162 offset:55296
	ds_read_b128 v[220:223], v162 offset:56320
	global_load_lds_dwordx4 v[154:155], off
	s_add_i32 m0, s69, 0x2000
	s_add_u32 s76, s76, 0x40080
	v_lshl_add_u64 v[154:155], v[224:225], 0, s[10:11]
	s_addc_u32 s77, s77, 0
	s_add_i32 s69, s91, s83
	global_load_lds_dwordx4 v[154:155], off
	v_lshl_add_u64 v[154:155], s[76:77], 0, v[132:133]
	s_mov_b32 m0, s69
	s_nop 0
	global_load_lds_dwordx4 v[154:155], off
	v_lshl_add_u64 v[154:155], s[76:77], 0, v[136:137]
	s_add_i32 m0, s69, 0x2000
	s_nop 0
	global_load_lds_dwordx4 v[154:155], off
	v_lshl_add_u64 v[154:155], v[226:227], 0, s[10:11]
	s_mov_b32 m0, s86
	s_nop 0
	global_load_lds_dwordx4 v[154:155], off
	v_lshl_add_u64 v[154:155], v[228:229], 0, s[10:11]
	s_mov_b32 m0, s87
	s_nop 0
	global_load_lds_dwordx4 v[154:155], off
	s_waitcnt vmcnt(8)
	s_waitcnt lgkmcnt(0)
	s_waitcnt lgkmcnt(0)
	v_mfma_f32_16x16x32_bf16 v[46:49], v[150:153], v[192:195], v[46:49]
	v_mfma_f32_16x16x32_bf16 v[42:45], v[168:171], v[192:195], v[42:45]
	v_mfma_f32_16x16x32_bf16 v[38:41], v[150:153], v[200:203], v[38:41]
	v_mfma_f32_16x16x32_bf16 v[34:37], v[168:171], v[200:203], v[34:37]
	s_barrier
	v_mfma_f32_16x16x32_bf16 v[30:33], v[150:153], v[208:211], v[30:33]
	v_mfma_f32_16x16x32_bf16 v[26:29], v[168:171], v[208:211], v[26:29]
	v_mfma_f32_16x16x32_bf16 v[22:25], v[150:153], v[216:219], v[22:25]
	v_mfma_f32_16x16x32_bf16 v[18:21], v[168:171], v[216:219], v[18:21]
	v_mfma_f32_16x16x32_bf16 v[46:49], v[164:167], v[196:199], v[46:49]
	v_mfma_f32_16x16x32_bf16 v[42:45], v[172:175], v[196:199], v[42:45]
	v_mfma_f32_16x16x32_bf16 v[38:41], v[164:167], v[204:207], v[38:41]
	v_mfma_f32_16x16x32_bf16 v[34:37], v[172:175], v[204:207], v[34:37]
	v_mfma_f32_16x16x32_bf16 v[30:33], v[164:167], v[212:215], v[30:33]
	v_mfma_f32_16x16x32_bf16 v[26:29], v[172:175], v[212:215], v[26:29]
	v_mfma_f32_16x16x32_bf16 v[22:25], v[164:167], v[220:223], v[22:25]
	v_mfma_f32_16x16x32_bf16 v[18:21], v[172:175], v[220:223], v[18:21]
	v_mfma_f32_16x16x32_bf16 v[14:17], v[176:179], v[192:195], v[14:17]
	v_mfma_f32_16x16x32_bf16 v[10:13], v[184:187], v[192:195], v[10:13]
	v_mfma_f32_16x16x32_bf16 v[6:9], v[176:179], v[200:203], v[6:9]
	v_mfma_f32_16x16x32_bf16 v[2:5], v[184:187], v[200:203], v[2:5]
	v_mfma_f32_16x16x32_bf16 v[114:117], v[176:179], v[208:211], v[114:117]
	v_mfma_f32_16x16x32_bf16 v[118:121], v[184:187], v[208:211], v[118:121]
	v_mfma_f32_16x16x32_bf16 v[122:125], v[176:179], v[216:219], v[122:125]
	v_mfma_f32_16x16x32_bf16 v[126:129], v[184:187], v[216:219], v[126:129]
	v_mfma_f32_16x16x32_bf16 v[14:17], v[180:183], v[196:199], v[14:17]
	v_mfma_f32_16x16x32_bf16 v[10:13], v[188:191], v[196:199], v[10:13]
	v_mfma_f32_16x16x32_bf16 v[6:9], v[180:183], v[204:207], v[6:9]
	v_mfma_f32_16x16x32_bf16 v[2:5], v[188:191], v[204:207], v[2:5]
	v_mfma_f32_16x16x32_bf16 v[114:117], v[180:183], v[212:215], v[114:117]
	v_mfma_f32_16x16x32_bf16 v[118:121], v[188:191], v[212:215], v[118:121]
	v_mfma_f32_16x16x32_bf16 v[122:125], v[180:183], v[220:223], v[122:125]
	v_mfma_f32_16x16x32_bf16 v[126:129], v[188:191], v[220:223], v[126:129]
	s_barrier
	s_add_i32 s59, s59, 2
	s_add_u32 s74, s74, 0x100
	s_addc_u32 s75, s75, 0
	s_cmp_gt_u32 s59, 13
	s_cbranch_scc0 .LBB0_538

; #define PG8_STAGEA(bufoff, gbase) PG8_STAGE_(bufoff, gbase, voffA)
; #define PG8_STAGEB(bufoff, gbase) PG8_STAGE_(bufoff, gbase, voffB)
; #define PG8_LDA(dst, b, h) do { _Pragma("unroll") for (int m = 0; m < 4; ++m) _Pragma("unroll") for (int k = 0; k < 2; ++k) dst[m][k] = *(const LAS bf16x8*)(lds + PG8_SA(b, h) + aoff + m * 2048 + k * 1024); } while (0)
; #define PG8_LDB(dst, b, h) do { _Pragma("unroll") for (int n = 0; n < 2; ++n) _Pragma("unroll") for (int k = 0; k < 2; ++k) dst[n][k] = *(const LAS bf16x8*)(lds + PG8_SB(b, h) + boff + n * 2048 + k * 1024); } while (0)
; #define PG8_MMA(ai, bj, At, Bt_) do { __builtin_amdgcn_s_setprio(1); _Pragma("unroll") for (int m = 0; m < 4; ++m) _Pragma("unroll") for (int n = 0; n < 2; ++n) _Pragma("unroll") for (int k = 0; k < 2; ++k) \
;         acc[ai][bj][m][n] = __builtin_amdgcn_mfma_f32_16x16x32_bf16(Bt_[n][k], At[m][k], acc[ai][bj][m][n], 0, 0, 0); __builtin_amdgcn_s_setprio(0); } while (0)
; #define PG8_WAIT_V(n) asm volatile("s_waitcnt vmcnt(" #n ")" ::: "memory")
; #define PG8_WAIT_L(n) asm volatile("s_waitcnt lgkmcnt(" #n ")" ::: "memory")
; #define PG8_BAR __builtin_amdgcn_s_barrier()
; template <int EK, int SK = -1>
; __device__ __forceinline__ void gemm_phase(LAS unsigned char* lds, const bf16_t* A, const bf16_t* Bt, int nM, int N, int K, const EpiArgs& E) {
;     ...
;         const bool has_next = S.next(ui + 1, nxt);
;         const char* nA = has_next ? (const char*)A + (size_t)nxt.pm * tstep : cA; const char* nB = has_next ? (const char*)Bt + (size_t)nxt.pn * tstep : cB;
;         for (int t = 0; t < nt; t += 2) {
;             const bool last = (t == nt - 2);
;             const char* a1 = cA + (size_t)(t + 1) * kstep;
;             const char* a2 = last ? nA : cA + (size_t)(t + 2) * kstep; const char* b2 = last ? nB : cB + (size_t)(t + 2) * kstep;
;             const char* a3 = a2 + kstep; const char* b3 = b2 + kstep;
;             PG8_LDB(B0, 0, 0); PG8_LDB(B1, 0, 1); PG8_SCHED; PG8_LDA(At, 0, 0); PG8_STAGEA(PG8_SA(1, 1), a1 + hstep);
;             PG8_WAIT_V(8); PG8_WAIT_L(0); PG8_BAR; PG8_MMA(0, 0, At, B0); PG8_MMA(0, 1, At, B1); PG8_BAR; PG8_SCHED;
;             PG8_LDA(At, 0, 1); PG8_STAGEB(PG8_SB(0, 0), b2); PG8_STAGEB(PG8_SB(0, 1), b2 + hstep); PG8_STAGEA(PG8_SA(0, 0), a2);
;             PG8_WAIT_V(8); PG8_WAIT_L(0); PG8_BAR; PG8_MMA(1, 0, At, B0); PG8_MMA(1, 1, At, B1); PG8_BAR; PG8_SCHED;
.LBB0_792:
	s_add_u32 s77, s38, 0x100
	s_addc_u32 s78, s39, 0
	v_lshl_add_u64 v[146:147], s[14:15], 0, v[138:139]
	v_lshl_add_u64 v[148:149], s[14:15], 0, v[140:141]
	s_mov_b32 s20, -2
	s_mov_b64 s[38:39], 0
	v_add_u32_e32 v150, s71, v152
	ds_read_b128 v[156:159], v150
	ds_read_b128 v[160:163], v150 offset:1024
	ds_read_b128 v[164:167], v150 offset:2048
	ds_read_b128 v[168:171], v150 offset:3072
	v_add_u32_e32 v150, s72, v152
	s_add_u32 s40, s14, s38
	ds_read_b128 v[172:175], v150
	ds_read_b128 v[176:179], v150 offset:1024
	ds_read_b128 v[180:183], v150 offset:2048
	ds_read_b128 v[184:187], v150 offset:3072
	s_addc_u32 s41, s15, s39
	s_add_u32 s40, s40, 0x100
	s_addc_u32 s41, s41, 0
	s_add_u32 s79, s77, s38
	s_addc_u32 s80, s78, s39
	s_cmpk_eq_i32 s38, 0x1500
	s_cselect_b32 s43, s37, s41
	s_cselect_b32 s42, s36, s40
	s_cselect_b32 s41, s11, s80
	s_cselect_b32 s40, s10, s79
	v_lshl_add_u64 v[150:151], v[146:147], 0, s[38:39]
	s_add_i32 m0, s55, 0xc000
	ds_read_b128 v[188:191], v154
	ds_read_b128 v[192:195], v154 offset:1024
	ds_read_b128 v[196:199], v154 offset:2048
	ds_read_b128 v[200:203], v154 offset:3072
	ds_read_b128 v[204:207], v154 offset:4096
	ds_read_b128 v[208:211], v154 offset:5120
	ds_read_b128 v[212:215], v154 offset:6144
	ds_read_b128 v[216:219], v154 offset:7168
	global_load_lds_dwordx4 v[150:151], off
	v_lshl_add_u64 v[150:151], v[148:149], 0, s[38:39]
	s_add_i32 m0, s55, 0xe000
	s_nop 0
	global_load_lds_dwordx4 v[150:151], off
	s_waitcnt vmcnt(8)
	s_waitcnt lgkmcnt(0)
	s_waitcnt lgkmcnt(0)
	v_mfma_f32_16x16x32_bf16 v[126:129], v[156:159], v[188:191], 0
	v_mfma_f32_16x16x32_bf16 v[122:125], v[164:167], v[188:191], 0
	v_mfma_f32_16x16x32_bf16 v[118:121], v[156:159], v[196:199], 0
	v_mfma_f32_16x16x32_bf16 v[114:117], v[164:167], v[196:199], 0
	s_barrier
	v_mfma_f32_16x16x32_bf16 v[110:113], v[156:159], v[204:207], 0
	v_mfma_f32_16x16x32_bf16 v[106:109], v[164:167], v[204:207], 0
	v_mfma_f32_16x16x32_bf16 v[102:105], v[156:159], v[212:215], 0
	v_mfma_f32_16x16x32_bf16 v[98:101], v[164:167], v[212:215], 0
	v_mfma_f32_16x16x32_bf16 v[126:129], v[160:163], v[192:195], v[126:129]
	v_mfma_f32_16x16x32_bf16 v[122:125], v[168:171], v[192:195], v[122:125]
	v_mfma_f32_16x16x32_bf16 v[118:121], v[160:163], v[200:203], v[118:121]
	v_mfma_f32_16x16x32_bf16 v[114:117], v[168:171], v[200:203], v[114:117]
	v_mfma_f32_16x16x32_bf16 v[110:113], v[160:163], v[208:211], v[110:113]
	v_mfma_f32_16x16x32_bf16 v[106:109], v[168:171], v[208:211], v[106:109]
	v_mfma_f32_16x16x32_bf16 v[102:105], v[160:163], v[216:219], v[102:105]
	v_mfma_f32_16x16x32_bf16 v[98:101], v[168:171], v[216:219], v[98:101]
	v_mfma_f32_16x16x32_bf16 v[94:97], v[172:175], v[188:191], 0
	v_mfma_f32_16x16x32_bf16 v[90:93], v[180:183], v[188:191], 0
	v_mfma_f32_16x16x32_bf16 v[86:89], v[172:175], v[196:199], 0
	v_mfma_f32_16x16x32_bf16 v[82:85], v[180:183], v[196:199], 0
	v_mfma_f32_16x16x32_bf16 v[78:81], v[172:175], v[204:207], 0
	v_mfma_f32_16x16x32_bf16 v[74:77], v[180:183], v[204:207], 0
	v_mfma_f32_16x16x32_bf16 v[70:73], v[172:175], v[212:215], 0
	v_mfma_f32_16x16x32_bf16 v[66:69], v[180:183], v[212:215], 0
	v_mfma_f32_16x16x32_bf16 v[94:97], v[176:179], v[192:195], v[94:97]
	v_mfma_f32_16x16x32_bf16 v[90:93], v[184:187], v[192:195], v[90:93]
	v_mfma_f32_16x16x32_bf16 v[86:89], v[176:179], v[200:203], v[86:89]
	v_mfma_f32_16x16x32_bf16 v[82:85], v[184:187], v[200:203], v[82:85]
	v_mfma_f32_16x16x32_bf16 v[78:81], v[176:179], v[208:211], v[78:81]
	v_mfma_f32_16x16x32_bf16 v[74:77], v[184:187], v[208:211], v[74:77]
	v_mfma_f32_16x16x32_bf16 v[70:73], v[176:179], v[216:219], v[70:73]
	v_mfma_f32_16x16x32_bf16 v[66:69], v[184:187], v[216:219], v[66:69]
	s_barrier
	s_add_i32 s79, s71, s54
	v_lshl_add_u64 v[150:151], s[40:41], 0, v[132:133]
	s_mov_b32 m0, s79
	ds_read_b128 v[188:191], v154 offset:16384
	ds_read_b128 v[192:195], v154 offset:17408
	ds_read_b128 v[196:199], v154 offset:18432
	ds_read_b128 v[200:203], v154 offset:19456
	ds_read_b128 v[204:207], v154 offset:20480
	ds_read_b128 v[208:211], v154 offset:21504
	ds_read_b128 v[212:215], v154 offset:22528
	ds_read_b128 v[216:219], v154 offset:23552
	global_load_lds_dwordx4 v[150:151], off
	s_add_i32 m0, s79, 0x2000
	s_add_u32 s80, s40, 0xb0000
	v_lshl_add_u64 v[220:221], s[40:41], 0, v[136:137]
	s_addc_u32 s81, s41, 0
	s_add_i32 s79, s72, s54
	global_load_lds_dwordx4 v[220:221], off
	v_lshl_add_u64 v[222:223], s[80:81], 0, v[132:133]
	s_mov_b32 m0, s79
	v_lshl_add_u64 v[224:225], s[42:43], 0, v[134:135]
	global_load_lds_dwordx4 v[222:223], off
	v_lshl_add_u64 v[222:223], s[80:81], 0, v[136:137]
	s_add_i32 m0, s79, 0x2000
	s_nop 0
	global_load_lds_dwordx4 v[222:223], off
	v_lshl_add_u64 v[222:223], s[42:43], 0, v[130:131]
	s_mov_b32 m0, s55
	s_nop 0
	global_load_lds_dwordx4 v[222:223], off
	s_mov_b32 m0, s56
	s_nop 0
	global_load_lds_dwordx4 v[224:225], off
	s_waitcnt vmcnt(8)
	s_waitcnt lgkmcnt(0)
	s_waitcnt lgkmcnt(0)
	v_mfma_f32_16x16x32_bf16 v[62:65], v[156:159], v[188:191], 0
	v_mfma_f32_16x16x32_bf16 v[58:61], v[164:167], v[188:191], 0
	v_mfma_f32_16x16x32_bf16 v[54:57], v[156:159], v[196:199], 0
	v_mfma_f32_16x16x32_bf16 v[50:53], v[164:167], v[196:199], 0
	s_barrier
; #define PG8_STAGEA(bufoff, gbase) PG8_STAGE_(bufoff, gbase, voffA)
; #define PG8_STAGEB(bufoff, gbase) PG8_STAGE_(bufoff, gbase, voffB)
; #define PG8_LDA(dst, b, h) do { _Pragma("unroll") for (int m = 0; m < 4; ++m) _Pragma("unroll") for (int k = 0; k < 2; ++k) dst[m][k] = *(const LAS bf16x8*)(lds + PG8_SA(b, h) + aoff + m * 2048 + k * 1024); } while (0)
; #define PG8_LDB(dst, b, h) do { _Pragma("unroll") for (int n = 0; n < 2; ++n) _Pragma("unroll") for (int k = 0; k < 2; ++k) dst[n][k] = *(const LAS bf16x8*)(lds + PG8_SB(b, h) + boff + n * 2048 + k * 1024); } while (0)
; #define PG8_MMA(ai, bj, At, Bt_) do { __builtin_amdgcn_s_setprio(1); _Pragma("unroll") for (int m = 0; m < 4; ++m) _Pragma("unroll") for (int n = 0; n < 2; ++n) _Pragma("unroll") for (int k = 0; k < 2; ++k) \
;         acc[ai][bj][m][n] = __builtin_amdgcn_mfma_f32_16x16x32_bf16(Bt_[n][k], At[m][k], acc[ai][bj][m][n], 0, 0, 0); __builtin_amdgcn_s_setprio(0); } while (0)
; #define PG8_WAIT_V(n) asm volatile("s_waitcnt vmcnt(" #n ")" ::: "memory")
; #define PG8_WAIT_L(n) asm volatile("s_waitcnt lgkmcnt(" #n ")" ::: "memory")
; #define PG8_BAR __builtin_amdgcn_s_barrier()
; #define PG8_SCHED __builtin_amdgcn_sched_barrier(0)
; template <int EK, int SK = -1>
; __device__ __forceinline__ void gemm_phase(LAS unsigned char* lds, const bf16_t* A, const bf16_t* Bt, int nM, int N, int K, const EpiArgs& E) {
;     ...
;             PG8_WAIT_V(8); PG8_WAIT_L(0); PG8_BAR; PG8_MMA(1, 0, At, B0); PG8_MMA(1, 1, At, B1); PG8_BAR; PG8_SCHED;
;             PG8_LDB(B0, 1, 0); PG8_LDB(B1, 1, 1); PG8_SCHED; PG8_LDA(At, 1, 0); PG8_STAGEA(PG8_SA(0, 1), a2 + hstep);
;             PG8_WAIT_V(8); PG8_WAIT_L(0); PG8_BAR; PG8_MMA(0, 0, At, B0); PG8_MMA(0, 1, At, B1); PG8_BAR; PG8_SCHED;
;             PG8_LDA(At, 1, 1); PG8_STAGEB(PG8_SB(1, 0), b3); PG8_STAGEB(PG8_SB(1, 1), b3 + hstep); PG8_STAGEA(PG8_SA(1, 0), a3);
	v_mfma_f32_16x16x32_bf16 v[46:49], v[156:159], v[204:207], 0
	v_mfma_f32_16x16x32_bf16 v[42:45], v[164:167], v[204:207], 0
	v_mfma_f32_16x16x32_bf16 v[38:41], v[156:159], v[212:215], 0
	v_mfma_f32_16x16x32_bf16 v[34:37], v[164:167], v[212:215], 0
	v_mfma_f32_16x16x32_bf16 v[62:65], v[160:163], v[192:195], v[62:65]
	v_mfma_f32_16x16x32_bf16 v[58:61], v[168:171], v[192:195], v[58:61]
	v_mfma_f32_16x16x32_bf16 v[54:57], v[160:163], v[200:203], v[54:57]
	v_mfma_f32_16x16x32_bf16 v[50:53], v[168:171], v[200:203], v[50:53]
	v_mfma_f32_16x16x32_bf16 v[46:49], v[160:163], v[208:211], v[46:49]
	v_mfma_f32_16x16x32_bf16 v[42:45], v[168:171], v[208:211], v[42:45]
	v_mfma_f32_16x16x32_bf16 v[38:41], v[160:163], v[216:219], v[38:41]
	v_mfma_f32_16x16x32_bf16 v[34:37], v[168:171], v[216:219], v[34:37]
	v_mfma_f32_16x16x32_bf16 v[30:33], v[172:175], v[188:191], 0
	v_mfma_f32_16x16x32_bf16 v[26:29], v[180:183], v[188:191], 0
	v_mfma_f32_16x16x32_bf16 v[22:25], v[172:175], v[196:199], 0
	v_mfma_f32_16x16x32_bf16 v[18:21], v[180:183], v[196:199], 0
	v_mfma_f32_16x16x32_bf16 v[14:17], v[172:175], v[204:207], 0
	v_mfma_f32_16x16x32_bf16 v[10:13], v[180:183], v[204:207], 0
	v_mfma_f32_16x16x32_bf16 v[6:9], v[172:175], v[212:215], 0
	v_mfma_f32_16x16x32_bf16 v[2:5], v[180:183], v[212:215], 0
	v_mfma_f32_16x16x32_bf16 v[30:33], v[176:179], v[192:195], v[30:33]
	v_mfma_f32_16x16x32_bf16 v[26:29], v[184:187], v[192:195], v[26:29]
	v_mfma_f32_16x16x32_bf16 v[22:25], v[176:179], v[200:203], v[22:25]
	v_mfma_f32_16x16x32_bf16 v[18:21], v[184:187], v[200:203], v[18:21]
	v_mfma_f32_16x16x32_bf16 v[14:17], v[176:179], v[208:211], v[14:17]
	v_mfma_f32_16x16x32_bf16 v[10:13], v[184:187], v[208:211], v[10:13]
	v_mfma_f32_16x16x32_bf16 v[6:9], v[176:179], v[216:219], v[6:9]
	v_mfma_f32_16x16x32_bf16 v[2:5], v[184:187], v[216:219], v[2:5]
	s_barrier
	s_add_i32 s79, 0, 0x18000
	s_add_i32 s80, 0, 0x1c000
	v_add_u32_e32 v168, s79, v152
	v_add_u32_e32 v184, s80, v152
	ds_read_b128 v[156:159], v168
	ds_read_b128 v[160:163], v168 offset:1024
	ds_read_b128 v[164:167], v168 offset:2048
	ds_read_b128 v[168:171], v168 offset:3072
	ds_read_b128 v[172:175], v184
	ds_read_b128 v[176:179], v184 offset:1024
	ds_read_b128 v[180:183], v184 offset:2048
	ds_read_b128 v[184:187], v184 offset:3072
	s_add_u32 s42, s42, 0xb0000
	s_addc_u32 s43, s43, 0
	s_mov_b32 m0, s57
	v_lshl_add_u64 v[226:227], s[42:43], 0, v[130:131]
	ds_read_b128 v[188:191], v154 offset:32768
	ds_read_b128 v[192:195], v154 offset:33792
	ds_read_b128 v[196:199], v154 offset:34816
	ds_read_b128 v[200:203], v154 offset:35840
	ds_read_b128 v[204:207], v154 offset:36864
	ds_read_b128 v[208:211], v154 offset:37888
	ds_read_b128 v[212:215], v154 offset:38912
	ds_read_b128 v[216:219], v154 offset:39936
	global_load_lds_dwordx4 v[226:227], off
	v_lshl_add_u64 v[226:227], s[42:43], 0, v[134:135]
	s_mov_b32 m0, s58
	s_nop 0
	global_load_lds_dwordx4 v[226:227], off
	s_waitcnt vmcnt(8)
	s_waitcnt lgkmcnt(0)
	s_waitcnt lgkmcnt(0)
	v_mfma_f32_16x16x32_bf16 v[126:129], v[156:159], v[188:191], v[126:129]
	v_mfma_f32_16x16x32_bf16 v[122:125], v[164:167], v[188:191], v[122:125]
	v_mfma_f32_16x16x32_bf16 v[118:121], v[156:159], v[196:199], v[118:121]
	v_mfma_f32_16x16x32_bf16 v[114:117], v[164:167], v[196:199], v[114:117]
	s_barrier
	v_mfma_f32_16x16x32_bf16 v[110:113], v[156:159], v[204:207], v[110:113]
	v_mfma_f32_16x16x32_bf16 v[106:109], v[164:167], v[204:207], v[106:109]
	v_mfma_f32_16x16x32_bf16 v[102:105], v[156:159], v[212:215], v[102:105]
	v_mfma_f32_16x16x32_bf16 v[98:101], v[164:167], v[212:215], v[98:101]
	v_mfma_f32_16x16x32_bf16 v[126:129], v[160:163], v[192:195], v[126:129]
	v_mfma_f32_16x16x32_bf16 v[122:125], v[168:171], v[192:195], v[122:125]
	v_mfma_f32_16x16x32_bf16 v[118:121], v[160:163], v[200:203], v[118:121]
	v_mfma_f32_16x16x32_bf16 v[114:117], v[168:171], v[200:203], v[114:117]
	v_mfma_f32_16x16x32_bf16 v[110:113], v[160:163], v[208:211], v[110:113]
	v_mfma_f32_16x16x32_bf16 v[106:109], v[168:171], v[208:211], v[106:109]
	v_mfma_f32_16x16x32_bf16 v[102:105], v[160:163], v[216:219], v[102:105]
	v_mfma_f32_16x16x32_bf16 v[98:101], v[168:171], v[216:219], v[98:101]
	v_mfma_f32_16x16x32_bf16 v[94:97], v[172:175], v[188:191], v[94:97]
	v_mfma_f32_16x16x32_bf16 v[90:93], v[180:183], v[188:191], v[90:93]
	v_mfma_f32_16x16x32_bf16 v[86:89], v[172:175], v[196:199], v[86:89]
	v_mfma_f32_16x16x32_bf16 v[82:85], v[180:183], v[196:199], v[82:85]
	v_mfma_f32_16x16x32_bf16 v[78:81], v[172:175], v[204:207], v[78:81]
	v_mfma_f32_16x16x32_bf16 v[74:77], v[180:183], v[204:207], v[74:77]
	v_mfma_f32_16x16x32_bf16 v[70:73], v[172:175], v[212:215], v[70:73]
	v_mfma_f32_16x16x32_bf16 v[66:69], v[180:183], v[212:215], v[66:69]
	v_mfma_f32_16x16x32_bf16 v[94:97], v[176:179], v[192:195], v[94:97]
	v_mfma_f32_16x16x32_bf16 v[90:93], v[184:187], v[192:195], v[90:93]
	v_mfma_f32_16x16x32_bf16 v[86:89], v[176:179], v[200:203], v[86:89]
	v_mfma_f32_16x16x32_bf16 v[82:85], v[184:187], v[200:203], v[82:85]
	v_mfma_f32_16x16x32_bf16 v[78:81], v[176:179], v[208:211], v[78:81]
	v_mfma_f32_16x16x32_bf16 v[74:77], v[184:187], v[208:211], v[74:77]
	v_mfma_f32_16x16x32_bf16 v[70:73], v[176:179], v[216:219], v[70:73]
	v_mfma_f32_16x16x32_bf16 v[66:69], v[184:187], v[216:219], v[66:69]
	s_barrier
; #define PG8_STAGEA(bufoff, gbase) PG8_STAGE_(bufoff, gbase, voffA)
; #define PG8_STAGEB(bufoff, gbase) PG8_STAGE_(bufoff, gbase, voffB)
; #define PG8_LDA(dst, b, h) do { _Pragma("unroll") for (int m = 0; m < 4; ++m) _Pragma("unroll") for (int k = 0; k < 2; ++k) dst[m][k] = *(const LAS bf16x8*)(lds + PG8_SA(b, h) + aoff + m * 2048 + k * 1024); } while (0)
; #define PG8_LDB(dst, b, h) do { _Pragma("unroll") for (int n = 0; n < 2; ++n) _Pragma("unroll") for (int k = 0; k < 2; ++k) dst[n][k] = *(const LAS bf16x8*)(lds + PG8_SB(b, h) + boff + n * 2048 + k * 1024); } while (0)
; #define PG8_WAIT_V(n) asm volatile("s_waitcnt vmcnt(" #n ")" ::: "memory")
; #define PG8_WAIT_L(n) asm volatile("s_waitcnt lgkmcnt(" #n ")" ::: "memory")
; #define PG8_BAR __builtin_amdgcn_s_barrier()
; #define PG8_SCHED __builtin_amdgcn_sched_barrier(0)
; template <int EK, int SK = -1>
; __device__ __forceinline__ void gemm_phase(LAS unsigned char* lds, const bf16_t* A, const bf16_t* Bt, int nM, int N, int K, const EpiArgs& E) {
;     ...
;         for (int t = 0; t < nt; t += 2) {
;             const bool last = (t == nt - 2);
;             const char* a1 = cA + (size_t)(t + 1) * kstep;
;             const char* a2 = last ? nA : cA + (size_t)(t + 2) * kstep; const char* b2 = last ? nB : cB + (size_t)(t + 2) * kstep;
;             const char* a3 = a2 + kstep; const char* b3 = b2 + kstep;
;             PG8_LDB(B0, 0, 0); PG8_LDB(B1, 0, 1); PG8_SCHED; PG8_LDA(At, 0, 0); PG8_STAGEA(PG8_SA(1, 1), a1 + hstep);
;             PG8_WAIT_V(8); PG8_WAIT_L(0); PG8_BAR; PG8_MMA(0, 0, At, B0); PG8_MMA(0, 1, At, B1); PG8_BAR; PG8_SCHED;
;             PG8_LDA(At, 0, 1); PG8_STAGEB(PG8_SB(0, 0), b2); PG8_STAGEB(PG8_SB(0, 1), b2 + hstep); PG8_STAGEA(PG8_SA(0, 0), a2);
;             PG8_WAIT_V(8); PG8_WAIT_L(0); PG8_BAR; PG8_MMA(1, 0, At, B0); PG8_MMA(1, 1, At, B1); PG8_BAR; PG8_SCHED;
;             PG8_LDB(B0, 1, 0); PG8_LDB(B1, 1, 1); PG8_SCHED; PG8_LDA(At, 1, 0); PG8_STAGEA(PG8_SA(0, 1), a2 + hstep);
;             PG8_WAIT_V(8); PG8_WAIT_L(0); PG8_BAR; PG8_MMA(0, 0, At, B0); PG8_MMA(0, 1, At, B1); PG8_BAR; PG8_SCHED;
;             PG8_LDA(At, 1, 1); PG8_STAGEB(PG8_SB(1, 0), b3); PG8_STAGEB(PG8_SB(1, 1), b3 + hstep); PG8_STAGEA(PG8_SA(1, 0), a3);
;             PG8_WAIT_V(8); PG8_WAIT_L(0); PG8_BAR; PG8_MMA(1, 0, At, B0); PG8_MMA(1, 1, At, B1); PG8_BAR; PG8_SCHED;
	s_add_i32 s42, s79, s54
	v_lshl_add_u64 v[150:151], v[150:151], 0, s[22:23]
	s_mov_b32 m0, s42
	ds_read_b128 v[188:191], v154 offset:49152
	ds_read_b128 v[192:195], v154 offset:50176
	ds_read_b128 v[196:199], v154 offset:51200
	ds_read_b128 v[200:203], v154 offset:52224
	ds_read_b128 v[204:207], v154 offset:53248
	ds_read_b128 v[208:211], v154 offset:54272
	ds_read_b128 v[212:215], v154 offset:55296
	ds_read_b128 v[216:219], v154 offset:56320
	global_load_lds_dwordx4 v[150:151], off
	s_add_i32 m0, s42, 0x2000
	s_add_u32 s40, s40, 0xb0080
	v_lshl_add_u64 v[150:151], v[220:221], 0, s[22:23]
	s_addc_u32 s41, s41, 0
	s_add_i32 s42, s80, s54
	global_load_lds_dwordx4 v[150:151], off
	v_lshl_add_u64 v[150:151], s[40:41], 0, v[132:133]
	s_mov_b32 m0, s42
	s_nop 0
	global_load_lds_dwordx4 v[150:151], off
	v_lshl_add_u64 v[150:151], s[40:41], 0, v[136:137]
	s_add_i32 m0, s42, 0x2000
	s_nop 0
	global_load_lds_dwordx4 v[150:151], off
	v_lshl_add_u64 v[150:151], v[222:223], 0, s[22:23]
	s_mov_b32 m0, s69
	s_nop 0
	global_load_lds_dwordx4 v[150:151], off
	v_lshl_add_u64 v[150:151], v[224:225], 0, s[22:23]
	s_mov_b32 m0, s70
	s_nop 0
	global_load_lds_dwordx4 v[150:151], off
	s_waitcnt vmcnt(8)
	s_waitcnt lgkmcnt(0)
	s_waitcnt lgkmcnt(0)
	v_mfma_f32_16x16x32_bf16 v[62:65], v[156:159], v[188:191], v[62:65]
	v_mfma_f32_16x16x32_bf16 v[58:61], v[164:167], v[188:191], v[58:61]
	v_mfma_f32_16x16x32_bf16 v[54:57], v[156:159], v[196:199], v[54:57]
	v_mfma_f32_16x16x32_bf16 v[50:53], v[164:167], v[196:199], v[50:53]
	s_barrier
	v_mfma_f32_16x16x32_bf16 v[46:49], v[156:159], v[204:207], v[46:49]
	v_mfma_f32_16x16x32_bf16 v[42:45], v[164:167], v[204:207], v[42:45]
	v_mfma_f32_16x16x32_bf16 v[38:41], v[156:159], v[212:215], v[38:41]
	v_mfma_f32_16x16x32_bf16 v[34:37], v[164:167], v[212:215], v[34:37]
	v_mfma_f32_16x16x32_bf16 v[62:65], v[160:163], v[192:195], v[62:65]
	v_mfma_f32_16x16x32_bf16 v[58:61], v[168:171], v[192:195], v[58:61]
	v_mfma_f32_16x16x32_bf16 v[54:57], v[160:163], v[200:203], v[54:57]
	v_mfma_f32_16x16x32_bf16 v[50:53], v[168:171], v[200:203], v[50:53]
	v_mfma_f32_16x16x32_bf16 v[46:49], v[160:163], v[208:211], v[46:49]
	v_mfma_f32_16x16x32_bf16 v[42:45], v[168:171], v[208:211], v[42:45]
	v_mfma_f32_16x16x32_bf16 v[38:41], v[160:163], v[216:219], v[38:41]
	v_mfma_f32_16x16x32_bf16 v[34:37], v[168:171], v[216:219], v[34:37]
	v_mfma_f32_16x16x32_bf16 v[30:33], v[172:175], v[188:191], v[30:33]
	v_mfma_f32_16x16x32_bf16 v[26:29], v[180:183], v[188:191], v[26:29]
	v_mfma_f32_16x16x32_bf16 v[22:25], v[172:175], v[196:199], v[22:25]
	v_mfma_f32_16x16x32_bf16 v[18:21], v[180:183], v[196:199], v[18:21]
	v_mfma_f32_16x16x32_bf16 v[14:17], v[172:175], v[204:207], v[14:17]
	v_mfma_f32_16x16x32_bf16 v[10:13], v[180:183], v[204:207], v[10:13]
	v_mfma_f32_16x16x32_bf16 v[6:9], v[172:175], v[212:215], v[6:9]
	v_mfma_f32_16x16x32_bf16 v[2:5], v[180:183], v[212:215], v[2:5]
	v_mfma_f32_16x16x32_bf16 v[30:33], v[176:179], v[192:195], v[30:33]
	v_mfma_f32_16x16x32_bf16 v[26:29], v[184:187], v[192:195], v[26:29]
	v_mfma_f32_16x16x32_bf16 v[22:25], v[176:179], v[200:203], v[22:25]
	v_mfma_f32_16x16x32_bf16 v[18:21], v[184:187], v[200:203], v[18:21]
	v_mfma_f32_16x16x32_bf16 v[14:17], v[176:179], v[208:211], v[14:17]
	v_mfma_f32_16x16x32_bf16 v[10:13], v[184:187], v[208:211], v[10:13]
	v_mfma_f32_16x16x32_bf16 v[6:9], v[176:179], v[216:219], v[6:9]
	v_mfma_f32_16x16x32_bf16 v[2:5], v[184:187], v[216:219], v[2:5]
	s_barrier
	s_add_i32 s20, s20, 2
	s_add_u32 s38, s38, 0x100
	s_addc_u32 s39, s39, 0
	s_cmp_gt_u32 s20, 41
	s_cbranch_scc0 .LBB0_793
	s_branch .Lmy_kexit_3
.LBB0_793:
	v_add_u32_e32 v150, s71, v152
	ds_read_b128 v[156:159], v150
	ds_read_b128 v[160:163], v150 offset:1024
	ds_read_b128 v[164:167], v150 offset:2048
	ds_read_b128 v[168:171], v150 offset:3072
	v_add_u32_e32 v150, s72, v152
	s_add_u32 s40, s14, s38
	ds_read_b128 v[172:175], v150
	ds_read_b128 v[176:179], v150 offset:1024
	ds_read_b128 v[180:183], v150 offset:2048
	ds_read_b128 v[184:187], v150 offset:3072
	s_addc_u32 s41, s15, s39
	s_add_u32 s40, s40, 0x100
	s_addc_u32 s41, s41, 0
	s_add_u32 s79, s77, s38
	s_addc_u32 s80, s78, s39
	s_cmpk_eq_i32 s38, 0x1500
	s_cselect_b32 s43, s37, s41
	s_cselect_b32 s42, s36, s40
	s_cselect_b32 s41, s11, s80
	s_cselect_b32 s40, s10, s79
	v_lshl_add_u64 v[150:151], v[146:147], 0, s[38:39]
	s_add_i32 m0, s55, 0xc000
	ds_read_b128 v[188:191], v154
	ds_read_b128 v[192:195], v154 offset:1024
	ds_read_b128 v[196:199], v154 offset:2048
	ds_read_b128 v[200:203], v154 offset:3072
	ds_read_b128 v[204:207], v154 offset:4096
	ds_read_b128 v[208:211], v154 offset:5120
	ds_read_b128 v[212:215], v154 offset:6144
	ds_read_b128 v[216:219], v154 offset:7168
	global_load_lds_dwordx4 v[150:151], off
	v_lshl_add_u64 v[150:151], v[148:149], 0, s[38:39]
	s_add_i32 m0, s55, 0xe000
	s_nop 0
	global_load_lds_dwordx4 v[150:151], off
	s_waitcnt vmcnt(8)
	s_waitcnt lgkmcnt(0)
	s_waitcnt lgkmcnt(0)
	v_mfma_f32_16x16x32_bf16 v[126:129], v[156:159], v[188:191], v[126:129]
	v_mfma_f32_16x16x32_bf16 v[122:125], v[164:167], v[188:191], v[122:125]
	v_mfma_f32_16x16x32_bf16 v[118:121], v[156:159], v[196:199], v[118:121]
	v_mfma_f32_16x16x32_bf16 v[114:117], v[164:167], v[196:199], v[114:117]
	s_barrier
; #define PG8_STAGEA(bufoff, gbase) PG8_STAGE_(bufoff, gbase, voffA)
; #define PG8_STAGEB(bufoff, gbase) PG8_STAGE_(bufoff, gbase, voffB)
; #define PG8_LDA(dst, b, h) do { _Pragma("unroll") for (int m = 0; m < 4; ++m) _Pragma("unroll") for (int k = 0; k < 2; ++k) dst[m][k] = *(const LAS bf16x8*)(lds + PG8_SA(b, h) + aoff + m * 2048 + k * 1024); } while (0)
; #define PG8_MMA(ai, bj, At, Bt_) do { __builtin_amdgcn_s_setprio(1); _Pragma("unroll") for (int m = 0; m < 4; ++m) _Pragma("unroll") for (int n = 0; n < 2; ++n) _Pragma("unroll") for (int k = 0; k < 2; ++k) \
;         acc[ai][bj][m][n] = __builtin_amdgcn_mfma_f32_16x16x32_bf16(Bt_[n][k], At[m][k], acc[ai][bj][m][n], 0, 0, 0); __builtin_amdgcn_s_setprio(0); } while (0)
; #define PG8_WAIT_V(n) asm volatile("s_waitcnt vmcnt(" #n ")" ::: "memory")
; #define PG8_WAIT_L(n) asm volatile("s_waitcnt lgkmcnt(" #n ")" ::: "memory")
; #define PG8_BAR __builtin_amdgcn_s_barrier()
; #define PG8_SCHED __builtin_amdgcn_sched_barrier(0)
; template <int EK, int SK = -1>
; __device__ __forceinline__ void gemm_phase(LAS unsigned char* lds, const bf16_t* A, const bf16_t* Bt, int nM, int N, int K, const EpiArgs& E) {
;     ...
;             PG8_WAIT_V(8); PG8_WAIT_L(0); PG8_BAR; PG8_MMA(0, 0, At, B0); PG8_MMA(0, 1, At, B1); PG8_BAR; PG8_SCHED;
;             PG8_LDA(At, 0, 1); PG8_STAGEB(PG8_SB(0, 0), b2); PG8_STAGEB(PG8_SB(0, 1), b2 + hstep); PG8_STAGEA(PG8_SA(0, 0), a2);
;             PG8_WAIT_V(8); PG8_WAIT_L(0); PG8_BAR; PG8_MMA(1, 0, At, B0); PG8_MMA(1, 1, At, B1); PG8_BAR; PG8_SCHED;
	v_mfma_f32_16x16x32_bf16 v[110:113], v[156:159], v[204:207], v[110:113]
	v_mfma_f32_16x16x32_bf16 v[106:109], v[164:167], v[204:207], v[106:109]
	v_mfma_f32_16x16x32_bf16 v[102:105], v[156:159], v[212:215], v[102:105]
	v_mfma_f32_16x16x32_bf16 v[98:101], v[164:167], v[212:215], v[98:101]
	v_mfma_f32_16x16x32_bf16 v[126:129], v[160:163], v[192:195], v[126:129]
	v_mfma_f32_16x16x32_bf16 v[122:125], v[168:171], v[192:195], v[122:125]
	v_mfma_f32_16x16x32_bf16 v[118:121], v[160:163], v[200:203], v[118:121]
	v_mfma_f32_16x16x32_bf16 v[114:117], v[168:171], v[200:203], v[114:117]
	v_mfma_f32_16x16x32_bf16 v[110:113], v[160:163], v[208:211], v[110:113]
	v_mfma_f32_16x16x32_bf16 v[106:109], v[168:171], v[208:211], v[106:109]
	v_mfma_f32_16x16x32_bf16 v[102:105], v[160:163], v[216:219], v[102:105]
	v_mfma_f32_16x16x32_bf16 v[98:101], v[168:171], v[216:219], v[98:101]
	v_mfma_f32_16x16x32_bf16 v[94:97], v[172:175], v[188:191], v[94:97]
	v_mfma_f32_16x16x32_bf16 v[90:93], v[180:183], v[188:191], v[90:93]
	v_mfma_f32_16x16x32_bf16 v[86:89], v[172:175], v[196:199], v[86:89]
	v_mfma_f32_16x16x32_bf16 v[82:85], v[180:183], v[196:199], v[82:85]
	v_mfma_f32_16x16x32_bf16 v[78:81], v[172:175], v[204:207], v[78:81]
	v_mfma_f32_16x16x32_bf16 v[74:77], v[180:183], v[204:207], v[74:77]
	v_mfma_f32_16x16x32_bf16 v[70:73], v[172:175], v[212:215], v[70:73]
	v_mfma_f32_16x16x32_bf16 v[66:69], v[180:183], v[212:215], v[66:69]
	v_mfma_f32_16x16x32_bf16 v[94:97], v[176:179], v[192:195], v[94:97]
	v_mfma_f32_16x16x32_bf16 v[90:93], v[184:187], v[192:195], v[90:93]
	v_mfma_f32_16x16x32_bf16 v[86:89], v[176:179], v[200:203], v[86:89]
	v_mfma_f32_16x16x32_bf16 v[82:85], v[184:187], v[200:203], v[82:85]
	v_mfma_f32_16x16x32_bf16 v[78:81], v[176:179], v[208:211], v[78:81]
	v_mfma_f32_16x16x32_bf16 v[74:77], v[184:187], v[208:211], v[74:77]
	v_mfma_f32_16x16x32_bf16 v[70:73], v[176:179], v[216:219], v[70:73]
	v_mfma_f32_16x16x32_bf16 v[66:69], v[184:187], v[216:219], v[66:69]
	s_barrier
	s_add_i32 s79, s71, s54
	v_lshl_add_u64 v[150:151], s[40:41], 0, v[132:133]
	s_mov_b32 m0, s79
	ds_read_b128 v[188:191], v154 offset:16384
	ds_read_b128 v[192:195], v154 offset:17408
	ds_read_b128 v[196:199], v154 offset:18432
	ds_read_b128 v[200:203], v154 offset:19456
	ds_read_b128 v[204:207], v154 offset:20480
	ds_read_b128 v[208:211], v154 offset:21504
	ds_read_b128 v[212:215], v154 offset:22528
	ds_read_b128 v[216:219], v154 offset:23552
	global_load_lds_dwordx4 v[150:151], off
	s_add_i32 m0, s79, 0x2000
	s_add_u32 s80, s40, 0xb0000
	v_lshl_add_u64 v[220:221], s[40:41], 0, v[136:137]
	s_addc_u32 s81, s41, 0
	s_add_i32 s79, s72, s54
	global_load_lds_dwordx4 v[220:221], off
	v_lshl_add_u64 v[222:223], s[80:81], 0, v[132:133]
	s_mov_b32 m0, s79
	v_lshl_add_u64 v[224:225], s[42:43], 0, v[134:135]
	global_load_lds_dwordx4 v[222:223], off
	v_lshl_add_u64 v[222:223], s[80:81], 0, v[136:137]
	s_add_i32 m0, s79, 0x2000
	s_nop 0
	global_load_lds_dwordx4 v[222:223], off
	v_lshl_add_u64 v[222:223], s[42:43], 0, v[130:131]
	s_mov_b32 m0, s55
	s_nop 0
	global_load_lds_dwordx4 v[222:223], off
	s_mov_b32 m0, s56
	s_nop 0
	global_load_lds_dwordx4 v[224:225], off
	s_waitcnt vmcnt(8)
	s_waitcnt lgkmcnt(0)
	s_waitcnt lgkmcnt(0)
	v_mfma_f32_16x16x32_bf16 v[62:65], v[156:159], v[188:191], v[62:65]
	v_mfma_f32_16x16x32_bf16 v[58:61], v[164:167], v[188:191], v[58:61]
	v_mfma_f32_16x16x32_bf16 v[54:57], v[156:159], v[196:199], v[54:57]
	v_mfma_f32_16x16x32_bf16 v[50:53], v[164:167], v[196:199], v[50:53]
	s_barrier
	v_mfma_f32_16x16x32_bf16 v[46:49], v[156:159], v[204:207], v[46:49]
	v_mfma_f32_16x16x32_bf16 v[42:45], v[164:167], v[204:207], v[42:45]
	v_mfma_f32_16x16x32_bf16 v[38:41], v[156:159], v[212:215], v[38:41]
	v_mfma_f32_16x16x32_bf16 v[34:37], v[164:167], v[212:215], v[34:37]
	v_mfma_f32_16x16x32_bf16 v[62:65], v[160:163], v[192:195], v[62:65]
	v_mfma_f32_16x16x32_bf16 v[58:61], v[168:171], v[192:195], v[58:61]
	v_mfma_f32_16x16x32_bf16 v[54:57], v[160:163], v[200:203], v[54:57]
	v_mfma_f32_16x16x32_bf16 v[50:53], v[168:171], v[200:203], v[50:53]
	v_mfma_f32_16x16x32_bf16 v[46:49], v[160:163], v[208:211], v[46:49]
	v_mfma_f32_16x16x32_bf16 v[42:45], v[168:171], v[208:211], v[42:45]
	v_mfma_f32_16x16x32_bf16 v[38:41], v[160:163], v[216:219], v[38:41]
	v_mfma_f32_16x16x32_bf16 v[34:37], v[168:171], v[216:219], v[34:37]
	v_mfma_f32_16x16x32_bf16 v[30:33], v[172:175], v[188:191], v[30:33]
	v_mfma_f32_16x16x32_bf16 v[26:29], v[180:183], v[188:191], v[26:29]
	v_mfma_f32_16x16x32_bf16 v[22:25], v[172:175], v[196:199], v[22:25]
	v_mfma_f32_16x16x32_bf16 v[18:21], v[180:183], v[196:199], v[18:21]
	v_mfma_f32_16x16x32_bf16 v[14:17], v[172:175], v[204:207], v[14:17]
	v_mfma_f32_16x16x32_bf16 v[10:13], v[180:183], v[204:207], v[10:13]
	v_mfma_f32_16x16x32_bf16 v[6:9], v[172:175], v[212:215], v[6:9]
	v_mfma_f32_16x16x32_bf16 v[2:5], v[180:183], v[212:215], v[2:5]
	v_mfma_f32_16x16x32_bf16 v[30:33], v[176:179], v[192:195], v[30:33]
	v_mfma_f32_16x16x32_bf16 v[26:29], v[184:187], v[192:195], v[26:29]
	v_mfma_f32_16x16x32_bf16 v[22:25], v[176:179], v[200:203], v[22:25]
	v_mfma_f32_16x16x32_bf16 v[18:21], v[184:187], v[200:203], v[18:21]
	v_mfma_f32_16x16x32_bf16 v[14:17], v[176:179], v[208:211], v[14:17]
	v_mfma_f32_16x16x32_bf16 v[10:13], v[184:187], v[208:211], v[10:13]
	v_mfma_f32_16x16x32_bf16 v[6:9], v[176:179], v[216:219], v[6:9]
	v_mfma_f32_16x16x32_bf16 v[2:5], v[184:187], v[216:219], v[2:5]
	s_barrier
; #define PG8_STAGEA(bufoff, gbase) PG8_STAGE_(bufoff, gbase, voffA)
; #define PG8_STAGEB(bufoff, gbase) PG8_STAGE_(bufoff, gbase, voffB)
; #define PG8_LDA(dst, b, h) do { _Pragma("unroll") for (int m = 0; m < 4; ++m) _Pragma("unroll") for (int k = 0; k < 2; ++k) dst[m][k] = *(const LAS bf16x8*)(lds + PG8_SA(b, h) + aoff + m * 2048 + k * 1024); } while (0)
; #define PG8_LDB(dst, b, h) do { _Pragma("unroll") for (int n = 0; n < 2; ++n) _Pragma("unroll") for (int k = 0; k < 2; ++k) dst[n][k] = *(const LAS bf16x8*)(lds + PG8_SB(b, h) + boff + n * 2048 + k * 1024); } while (0)
; #define PG8_MMA(ai, bj, At, Bt_) do { __builtin_amdgcn_s_setprio(1); _Pragma("unroll") for (int m = 0; m < 4; ++m) _Pragma("unroll") for (int n = 0; n < 2; ++n) _Pragma("unroll") for (int k = 0; k < 2; ++k) \
;         acc[ai][bj][m][n] = __builtin_amdgcn_mfma_f32_16x16x32_bf16(Bt_[n][k], At[m][k], acc[ai][bj][m][n], 0, 0, 0); __builtin_amdgcn_s_setprio(0); } while (0)
; #define PG8_WAIT_V(n) asm volatile("s_waitcnt vmcnt(" #n ")" ::: "memory")
; #define PG8_WAIT_L(n) asm volatile("s_waitcnt lgkmcnt(" #n ")" ::: "memory")
; #define PG8_BAR __builtin_amdgcn_s_barrier()
; #define PG8_SCHED __builtin_amdgcn_sched_barrier(0)
; template <int EK, int SK = -1>
; __device__ __forceinline__ void gemm_phase(LAS unsigned char* lds, const bf16_t* A, const bf16_t* Bt, int nM, int N, int K, const EpiArgs& E) {
;     ...
;             PG8_LDB(B0, 1, 0); PG8_LDB(B1, 1, 1); PG8_SCHED; PG8_LDA(At, 1, 0); PG8_STAGEA(PG8_SA(0, 1), a2 + hstep);
;             PG8_WAIT_V(8); PG8_WAIT_L(0); PG8_BAR; PG8_MMA(0, 0, At, B0); PG8_MMA(0, 1, At, B1); PG8_BAR; PG8_SCHED;
;             PG8_LDA(At, 1, 1); PG8_STAGEB(PG8_SB(1, 0), b3); PG8_STAGEB(PG8_SB(1, 1), b3 + hstep); PG8_STAGEA(PG8_SA(1, 0), a3);
;             PG8_WAIT_V(8); PG8_WAIT_L(0); PG8_BAR; PG8_MMA(1, 0, At, B0); PG8_MMA(1, 1, At, B1); PG8_BAR; PG8_SCHED;
;         }
	s_add_i32 s79, 0, 0x18000
	s_add_i32 s80, 0, 0x1c000
	v_add_u32_e32 v168, s79, v152
	v_add_u32_e32 v184, s80, v152
	ds_read_b128 v[156:159], v168
	ds_read_b128 v[160:163], v168 offset:1024
	ds_read_b128 v[164:167], v168 offset:2048
	ds_read_b128 v[168:171], v168 offset:3072
	ds_read_b128 v[172:175], v184
	ds_read_b128 v[176:179], v184 offset:1024
	ds_read_b128 v[180:183], v184 offset:2048
	ds_read_b128 v[184:187], v184 offset:3072
	s_add_u32 s42, s42, 0xb0000
	s_addc_u32 s43, s43, 0
	s_mov_b32 m0, s57
	v_lshl_add_u64 v[226:227], s[42:43], 0, v[130:131]
	ds_read_b128 v[188:191], v154 offset:32768
	ds_read_b128 v[192:195], v154 offset:33792
	ds_read_b128 v[196:199], v154 offset:34816
	ds_read_b128 v[200:203], v154 offset:35840
	ds_read_b128 v[204:207], v154 offset:36864
	ds_read_b128 v[208:211], v154 offset:37888
	ds_read_b128 v[212:215], v154 offset:38912
	ds_read_b128 v[216:219], v154 offset:39936
	global_load_lds_dwordx4 v[226:227], off
	v_lshl_add_u64 v[226:227], s[42:43], 0, v[134:135]
	s_mov_b32 m0, s58
	s_nop 0
	global_load_lds_dwordx4 v[226:227], off
	s_waitcnt vmcnt(8)
	s_waitcnt lgkmcnt(0)
	s_waitcnt lgkmcnt(0)
	v_mfma_f32_16x16x32_bf16 v[126:129], v[156:159], v[188:191], v[126:129]
	v_mfma_f32_16x16x32_bf16 v[122:125], v[164:167], v[188:191], v[122:125]
	v_mfma_f32_16x16x32_bf16 v[118:121], v[156:159], v[196:199], v[118:121]
	v_mfma_f32_16x16x32_bf16 v[114:117], v[164:167], v[196:199], v[114:117]
	s_barrier
	v_mfma_f32_16x16x32_bf16 v[110:113], v[156:159], v[204:207], v[110:113]
	v_mfma_f32_16x16x32_bf16 v[106:109], v[164:167], v[204:207], v[106:109]
	v_mfma_f32_16x16x32_bf16 v[102:105], v[156:159], v[212:215], v[102:105]
	v_mfma_f32_16x16x32_bf16 v[98:101], v[164:167], v[212:215], v[98:101]
	v_mfma_f32_16x16x32_bf16 v[126:129], v[160:163], v[192:195], v[126:129]
	v_mfma_f32_16x16x32_bf16 v[122:125], v[168:171], v[192:195], v[122:125]
	v_mfma_f32_16x16x32_bf16 v[118:121], v[160:163], v[200:203], v[118:121]
	v_mfma_f32_16x16x32_bf16 v[114:117], v[168:171], v[200:203], v[114:117]
	v_mfma_f32_16x16x32_bf16 v[110:113], v[160:163], v[208:211], v[110:113]
	v_mfma_f32_16x16x32_bf16 v[106:109], v[168:171], v[208:211], v[106:109]
	v_mfma_f32_16x16x32_bf16 v[102:105], v[160:163], v[216:219], v[102:105]
	v_mfma_f32_16x16x32_bf16 v[98:101], v[168:171], v[216:219], v[98:101]
	v_mfma_f32_16x16x32_bf16 v[94:97], v[172:175], v[188:191], v[94:97]
	v_mfma_f32_16x16x32_bf16 v[90:93], v[180:183], v[188:191], v[90:93]
	v_mfma_f32_16x16x32_bf16 v[86:89], v[172:175], v[196:199], v[86:89]
	v_mfma_f32_16x16x32_bf16 v[82:85], v[180:183], v[196:199], v[82:85]
	v_mfma_f32_16x16x32_bf16 v[78:81], v[172:175], v[204:207], v[78:81]
	v_mfma_f32_16x16x32_bf16 v[74:77], v[180:183], v[204:207], v[74:77]
	v_mfma_f32_16x16x32_bf16 v[70:73], v[172:175], v[212:215], v[70:73]
	v_mfma_f32_16x16x32_bf16 v[66:69], v[180:183], v[212:215], v[66:69]
	v_mfma_f32_16x16x32_bf16 v[94:97], v[176:179], v[192:195], v[94:97]
	v_mfma_f32_16x16x32_bf16 v[90:93], v[184:187], v[192:195], v[90:93]
	v_mfma_f32_16x16x32_bf16 v[86:89], v[176:179], v[200:203], v[86:89]
	v_mfma_f32_16x16x32_bf16 v[82:85], v[184:187], v[200:203], v[82:85]
	v_mfma_f32_16x16x32_bf16 v[78:81], v[176:179], v[208:211], v[78:81]
	v_mfma_f32_16x16x32_bf16 v[74:77], v[184:187], v[208:211], v[74:77]
	v_mfma_f32_16x16x32_bf16 v[70:73], v[176:179], v[216:219], v[70:73]
	v_mfma_f32_16x16x32_bf16 v[66:69], v[184:187], v[216:219], v[66:69]
	s_barrier
	s_add_i32 s42, s79, s54
	v_lshl_add_u64 v[150:151], v[150:151], 0, s[22:23]
	s_mov_b32 m0, s42
	ds_read_b128 v[188:191], v154 offset:49152
	ds_read_b128 v[192:195], v154 offset:50176
	ds_read_b128 v[196:199], v154 offset:51200
	ds_read_b128 v[200:203], v154 offset:52224
	ds_read_b128 v[204:207], v154 offset:53248
	ds_read_b128 v[208:211], v154 offset:54272
	ds_read_b128 v[212:215], v154 offset:55296
	ds_read_b128 v[216:219], v154 offset:56320
	global_load_lds_dwordx4 v[150:151], off
	s_add_i32 m0, s42, 0x2000
	s_add_u32 s40, s40, 0xb0080
	v_lshl_add_u64 v[150:151], v[220:221], 0, s[22:23]
	s_addc_u32 s41, s41, 0
	s_add_i32 s42, s80, s54
	global_load_lds_dwordx4 v[150:151], off
	v_lshl_add_u64 v[150:151], s[40:41], 0, v[132:133]
	s_mov_b32 m0, s42
	s_nop 0
	global_load_lds_dwordx4 v[150:151], off
	v_lshl_add_u64 v[150:151], s[40:41], 0, v[136:137]
	s_add_i32 m0, s42, 0x2000
	s_nop 0
	global_load_lds_dwordx4 v[150:151], off
	v_lshl_add_u64 v[150:151], v[222:223], 0, s[22:23]
	s_mov_b32 m0, s69
	s_nop 0
	global_load_lds_dwordx4 v[150:151], off
	v_lshl_add_u64 v[150:151], v[224:225], 0, s[22:23]
	s_mov_b32 m0, s70
	s_nop 0
	global_load_lds_dwordx4 v[150:151], off
	s_waitcnt vmcnt(8)
	s_waitcnt lgkmcnt(0)
	s_waitcnt lgkmcnt(0)
	v_mfma_f32_16x16x32_bf16 v[62:65], v[156:159], v[188:191], v[62:65]
	v_mfma_f32_16x16x32_bf16 v[58:61], v[164:167], v[188:191], v[58:61]
	v_mfma_f32_16x16x32_bf16 v[54:57], v[156:159], v[196:199], v[54:57]
	v_mfma_f32_16x16x32_bf16 v[50:53], v[164:167], v[196:199], v[50:53]
	s_barrier
	v_mfma_f32_16x16x32_bf16 v[46:49], v[156:159], v[204:207], v[46:49]
	v_mfma_f32_16x16x32_bf16 v[42:45], v[164:167], v[204:207], v[42:45]
	v_mfma_f32_16x16x32_bf16 v[38:41], v[156:159], v[212:215], v[38:41]
	v_mfma_f32_16x16x32_bf16 v[34:37], v[164:167], v[212:215], v[34:37]
	v_mfma_f32_16x16x32_bf16 v[62:65], v[160:163], v[192:195], v[62:65]
	v_mfma_f32_16x16x32_bf16 v[58:61], v[168:171], v[192:195], v[58:61]
	v_mfma_f32_16x16x32_bf16 v[54:57], v[160:163], v[200:203], v[54:57]
	v_mfma_f32_16x16x32_bf16 v[50:53], v[168:171], v[200:203], v[50:53]
	v_mfma_f32_16x16x32_bf16 v[46:49], v[160:163], v[208:211], v[46:49]
	v_mfma_f32_16x16x32_bf16 v[42:45], v[168:171], v[208:211], v[42:45]
	v_mfma_f32_16x16x32_bf16 v[38:41], v[160:163], v[216:219], v[38:41]
	v_mfma_f32_16x16x32_bf16 v[34:37], v[168:171], v[216:219], v[34:37]
	v_mfma_f32_16x16x32_bf16 v[30:33], v[172:175], v[188:191], v[30:33]
	v_mfma_f32_16x16x32_bf16 v[26:29], v[180:183], v[188:191], v[26:29]
	v_mfma_f32_16x16x32_bf16 v[22:25], v[172:175], v[196:199], v[22:25]
	v_mfma_f32_16x16x32_bf16 v[18:21], v[180:183], v[196:199], v[18:21]
	v_mfma_f32_16x16x32_bf16 v[14:17], v[172:175], v[204:207], v[14:17]
	v_mfma_f32_16x16x32_bf16 v[10:13], v[180:183], v[204:207], v[10:13]
	v_mfma_f32_16x16x32_bf16 v[6:9], v[172:175], v[212:215], v[6:9]
	v_mfma_f32_16x16x32_bf16 v[2:5], v[180:183], v[212:215], v[2:5]
	v_mfma_f32_16x16x32_bf16 v[30:33], v[176:179], v[192:195], v[30:33]
	v_mfma_f32_16x16x32_bf16 v[26:29], v[184:187], v[192:195], v[26:29]
	v_mfma_f32_16x16x32_bf16 v[22:25], v[176:179], v[200:203], v[22:25]
	v_mfma_f32_16x16x32_bf16 v[18:21], v[184:187], v[200:203], v[18:21]
	v_mfma_f32_16x16x32_bf16 v[14:17], v[176:179], v[208:211], v[14:17]
	v_mfma_f32_16x16x32_bf16 v[10:13], v[184:187], v[208:211], v[10:13]
	v_mfma_f32_16x16x32_bf16 v[6:9], v[176:179], v[216:219], v[6:9]
	v_mfma_f32_16x16x32_bf16 v[2:5], v[184:187], v[216:219], v[2:5]
	s_barrier
	s_add_i32 s20, s20, 2
	s_add_u32 s38, s38, 0x100
	s_addc_u32 s39, s39, 0
	s_cmp_gt_u32 s20, 41
	s_cbranch_scc0 .LBB0_793

; #define PG8_STAGEA(bufoff, gbase) PG8_STAGE_(bufoff, gbase, voffA)
; #define PG8_STAGEB(bufoff, gbase) PG8_STAGE_(bufoff, gbase, voffB)
; #define PG8_LDA(dst, b, h) do { _Pragma("unroll") for (int m = 0; m < 4; ++m) _Pragma("unroll") for (int k = 0; k < 2; ++k) dst[m][k] = *(const LAS bf16x8*)(lds + PG8_SA(b, h) + aoff + m * 2048 + k * 1024); } while (0)
; #define PG8_LDB(dst, b, h) do { _Pragma("unroll") for (int n = 0; n < 2; ++n) _Pragma("unroll") for (int k = 0; k < 2; ++k) dst[n][k] = *(const LAS bf16x8*)(lds + PG8_SB(b, h) + boff + n * 2048 + k * 1024); } while (0)
; #define PG8_MMA(ai, bj, At, Bt_) do { __builtin_amdgcn_s_setprio(1); _Pragma("unroll") for (int m = 0; m < 4; ++m) _Pragma("unroll") for (int n = 0; n < 2; ++n) _Pragma("unroll") for (int k = 0; k < 2; ++k) \
;         acc[ai][bj][m][n] = __builtin_amdgcn_mfma_f32_16x16x32_bf16(Bt_[n][k], At[m][k], acc[ai][bj][m][n], 0, 0, 0); __builtin_amdgcn_s_setprio(0); } while (0)
; #define PG8_WAIT_V(n) asm volatile("s_waitcnt vmcnt(" #n ")" ::: "memory")
; #define PG8_WAIT_L(n) asm volatile("s_waitcnt lgkmcnt(" #n ")" ::: "memory")
; #define PG8_BAR __builtin_amdgcn_s_barrier()
; template <int EK, int SK = -1>
; __device__ __forceinline__ void gemm_phase(LAS unsigned char* lds, const bf16_t* A, const bf16_t* Bt, int nM, int N, int K, const EpiArgs& E) {
;     ...
;         const bool has_next = S.next(ui + 1, nxt);
;         const char* nA = has_next ? (const char*)A + (size_t)nxt.pm * tstep : cA; const char* nB = has_next ? (const char*)Bt + (size_t)nxt.pn * tstep : cB;
;         for (int t = 0; t < nt; t += 2) {
;             const bool last = (t == nt - 2);
;             const char* a1 = cA + (size_t)(t + 1) * kstep;
;             const char* a2 = last ? nA : cA + (size_t)(t + 2) * kstep; const char* b2 = last ? nB : cB + (size_t)(t + 2) * kstep;
;             const char* a3 = a2 + kstep; const char* b3 = b2 + kstep;
;             PG8_LDB(B0, 0, 0); PG8_LDB(B1, 0, 1); PG8_SCHED; PG8_LDA(At, 0, 0); PG8_STAGEA(PG8_SA(1, 1), a1 + hstep);
;             PG8_WAIT_V(8); PG8_WAIT_L(0); PG8_BAR; PG8_MMA(0, 0, At, B0); PG8_MMA(0, 1, At, B1); PG8_BAR; PG8_SCHED;
;             PG8_LDA(At, 0, 1); PG8_STAGEB(PG8_SB(0, 0), b2); PG8_STAGEB(PG8_SB(0, 1), b2 + hstep); PG8_STAGEA(PG8_SA(0, 0), a2);
;             PG8_WAIT_V(8); PG8_WAIT_L(0); PG8_BAR; PG8_MMA(1, 0, At, B0); PG8_MMA(1, 1, At, B1); PG8_BAR; PG8_SCHED;
.LBB0_928:
	s_add_u32 s86, s76, 0x100
	s_addc_u32 s87, s77, 0
	s_ashr_i32 s71, s70, 31
	s_lshl_b64 s[10:11], s[70:71], 19
	s_add_u32 s74, s62, s10
	s_addc_u32 s75, s63, s11
	s_and_b64 s[10:11], s[8:9], exec
	s_cselect_b32 s14, s75, s37
	s_cselect_b32 s71, s74, s36
	s_ashr_i32 s69, s68, 31
	s_lshl_b64 s[10:11], s[68:69], 19
	s_add_u32 s72, s43, s10
	s_addc_u32 s73, s45, s11
	s_and_b64 s[10:11], s[8:9], exec
	s_cselect_b32 s69, s73, s77
	s_cselect_b32 s88, s72, s76
	s_waitcnt lgkmcnt(0)
	v_lshl_add_u64 v[146:147], s[36:37], 0, v[138:139]
	v_lshl_add_u64 v[148:149], s[36:37], 0, v[140:141]
	s_mov_b32 s89, -2
	s_mov_b64 s[10:11], 0
	v_add_u32_e32 v158, s82, v160
	ds_read_b128 v[150:153], v158
	ds_read_b128 v[154:157], v158 offset:1024
	ds_read_b128 v[166:169], v158 offset:2048
	ds_read_b128 v[170:173], v158 offset:3072
	v_add_u32_e32 v158, s83, v160
	s_add_u32 s76, s36, s10
	ds_read_b128 v[174:177], v158
	ds_read_b128 v[178:181], v158 offset:1024
	ds_read_b128 v[182:185], v158 offset:2048
	ds_read_b128 v[186:189], v158 offset:3072
	s_addc_u32 s77, s37, s11
	s_add_u32 s76, s76, 0x100
	s_addc_u32 s77, s77, 0
	s_add_u32 s90, s86, s10
	s_addc_u32 s91, s87, s11
	s_cmpk_eq_i32 s10, 0x700
	s_cselect_b32 s79, s14, s77
	s_cselect_b32 s78, s71, s76
	s_cselect_b32 s77, s69, s91
	s_cselect_b32 s76, s88, s90
	v_lshl_add_u64 v[158:159], v[146:147], 0, s[10:11]
	s_add_i32 m0, s23, 0xc000
	ds_read_b128 v[190:193], v163
	ds_read_b128 v[194:197], v163 offset:1024
	ds_read_b128 v[198:201], v163 offset:2048
	ds_read_b128 v[202:205], v163 offset:3072
	ds_read_b128 v[206:209], v163 offset:4096
	ds_read_b128 v[210:213], v163 offset:5120
	ds_read_b128 v[214:217], v163 offset:6144
	ds_read_b128 v[218:221], v163 offset:7168
	global_load_lds_dwordx4 v[158:159], off
	v_lshl_add_u64 v[158:159], v[148:149], 0, s[10:11]
	s_add_i32 m0, s23, 0xe000
	s_nop 0
	global_load_lds_dwordx4 v[158:159], off
	s_waitcnt vmcnt(8)
	s_waitcnt lgkmcnt(0)
	s_waitcnt lgkmcnt(0)
	v_mfma_f32_16x16x32_bf16 v[110:113], v[150:153], v[190:193], 0
	v_mfma_f32_16x16x32_bf16 v[106:109], v[166:169], v[190:193], 0
	v_mfma_f32_16x16x32_bf16 v[102:105], v[150:153], v[198:201], 0
	v_mfma_f32_16x16x32_bf16 v[98:101], v[166:169], v[198:201], 0
	s_barrier
	v_mfma_f32_16x16x32_bf16 v[94:97], v[150:153], v[206:209], 0
	v_mfma_f32_16x16x32_bf16 v[90:93], v[166:169], v[206:209], 0
	v_mfma_f32_16x16x32_bf16 v[86:89], v[150:153], v[214:217], 0
	v_mfma_f32_16x16x32_bf16 v[82:85], v[166:169], v[214:217], 0
	v_mfma_f32_16x16x32_bf16 v[110:113], v[154:157], v[194:197], v[110:113]
	v_mfma_f32_16x16x32_bf16 v[106:109], v[170:173], v[194:197], v[106:109]
	v_mfma_f32_16x16x32_bf16 v[102:105], v[154:157], v[202:205], v[102:105]
	v_mfma_f32_16x16x32_bf16 v[98:101], v[170:173], v[202:205], v[98:101]
	v_mfma_f32_16x16x32_bf16 v[94:97], v[154:157], v[210:213], v[94:97]
	v_mfma_f32_16x16x32_bf16 v[90:93], v[170:173], v[210:213], v[90:93]
	v_mfma_f32_16x16x32_bf16 v[86:89], v[154:157], v[218:221], v[86:89]
	v_mfma_f32_16x16x32_bf16 v[82:85], v[170:173], v[218:221], v[82:85]
	v_mfma_f32_16x16x32_bf16 v[78:81], v[174:177], v[190:193], 0
	v_mfma_f32_16x16x32_bf16 v[74:77], v[182:185], v[190:193], 0
	v_mfma_f32_16x16x32_bf16 v[70:73], v[174:177], v[198:201], 0
	v_mfma_f32_16x16x32_bf16 v[66:69], v[182:185], v[198:201], 0
	v_mfma_f32_16x16x32_bf16 v[62:65], v[174:177], v[206:209], 0
	v_mfma_f32_16x16x32_bf16 v[58:61], v[182:185], v[206:209], 0
	v_mfma_f32_16x16x32_bf16 v[54:57], v[174:177], v[214:217], 0
	v_mfma_f32_16x16x32_bf16 v[50:53], v[182:185], v[214:217], 0
	v_mfma_f32_16x16x32_bf16 v[78:81], v[178:181], v[194:197], v[78:81]
	v_mfma_f32_16x16x32_bf16 v[74:77], v[186:189], v[194:197], v[74:77]
	v_mfma_f32_16x16x32_bf16 v[70:73], v[178:181], v[202:205], v[70:73]
	v_mfma_f32_16x16x32_bf16 v[66:69], v[186:189], v[202:205], v[66:69]
	v_mfma_f32_16x16x32_bf16 v[62:65], v[178:181], v[210:213], v[62:65]
	v_mfma_f32_16x16x32_bf16 v[58:61], v[186:189], v[210:213], v[58:61]
	v_mfma_f32_16x16x32_bf16 v[54:57], v[178:181], v[218:221], v[54:57]
	v_mfma_f32_16x16x32_bf16 v[50:53], v[186:189], v[218:221], v[50:53]
	s_barrier
	s_add_i32 s90, s82, s53
	v_lshl_add_u64 v[158:159], s[76:77], 0, v[132:133]
	s_mov_b32 m0, s90
	ds_read_b128 v[190:193], v163 offset:16384
	ds_read_b128 v[194:197], v163 offset:17408
	ds_read_b128 v[198:201], v163 offset:18432
	ds_read_b128 v[202:205], v163 offset:19456
	ds_read_b128 v[206:209], v163 offset:20480
	ds_read_b128 v[210:213], v163 offset:21504
	ds_read_b128 v[214:217], v163 offset:22528
	ds_read_b128 v[218:221], v163 offset:23552
	global_load_lds_dwordx4 v[158:159], off
	s_add_i32 m0, s90, 0x2000
	s_add_u32 s90, s76, 0x40000
	v_lshl_add_u64 v[222:223], s[76:77], 0, v[136:137]
	s_addc_u32 s91, s77, 0
	s_add_i32 s92, s83, s53
	global_load_lds_dwordx4 v[222:223], off
	v_lshl_add_u64 v[224:225], s[90:91], 0, v[132:133]
	s_mov_b32 m0, s92
	v_lshl_add_u64 v[226:227], s[78:79], 0, v[134:135]
	global_load_lds_dwordx4 v[224:225], off
	v_lshl_add_u64 v[224:225], s[90:91], 0, v[136:137]
	s_add_i32 m0, s92, 0x2000
	s_nop 0
	global_load_lds_dwordx4 v[224:225], off
	v_lshl_add_u64 v[224:225], s[78:79], 0, v[130:131]
	s_mov_b32 m0, s23
	s_nop 0
	global_load_lds_dwordx4 v[224:225], off
	s_mov_b32 m0, s27
	s_nop 0
	global_load_lds_dwordx4 v[226:227], off
	s_waitcnt vmcnt(8)
	s_waitcnt lgkmcnt(0)
	s_waitcnt lgkmcnt(0)
	v_mfma_f32_16x16x32_bf16 v[46:49], v[150:153], v[190:193], 0
	v_mfma_f32_16x16x32_bf16 v[42:45], v[166:169], v[190:193], 0
	v_mfma_f32_16x16x32_bf16 v[38:41], v[150:153], v[198:201], 0
	v_mfma_f32_16x16x32_bf16 v[34:37], v[166:169], v[198:201], 0
	s_barrier
; #define PG8_STAGEA(bufoff, gbase) PG8_STAGE_(bufoff, gbase, voffA)
; #define PG8_STAGEB(bufoff, gbase) PG8_STAGE_(bufoff, gbase, voffB)
; #define PG8_LDA(dst, b, h) do { _Pragma("unroll") for (int m = 0; m < 4; ++m) _Pragma("unroll") for (int k = 0; k < 2; ++k) dst[m][k] = *(const LAS bf16x8*)(lds + PG8_SA(b, h) + aoff + m * 2048 + k * 1024); } while (0)
; #define PG8_LDB(dst, b, h) do { _Pragma("unroll") for (int n = 0; n < 2; ++n) _Pragma("unroll") for (int k = 0; k < 2; ++k) dst[n][k] = *(const LAS bf16x8*)(lds + PG8_SB(b, h) + boff + n * 2048 + k * 1024); } while (0)
; #define PG8_MMA(ai, bj, At, Bt_) do { __builtin_amdgcn_s_setprio(1); _Pragma("unroll") for (int m = 0; m < 4; ++m) _Pragma("unroll") for (int n = 0; n < 2; ++n) _Pragma("unroll") for (int k = 0; k < 2; ++k) \
;         acc[ai][bj][m][n] = __builtin_amdgcn_mfma_f32_16x16x32_bf16(Bt_[n][k], At[m][k], acc[ai][bj][m][n], 0, 0, 0); __builtin_amdgcn_s_setprio(0); } while (0)
; #define PG8_WAIT_V(n) asm volatile("s_waitcnt vmcnt(" #n ")" ::: "memory")
; #define PG8_WAIT_L(n) asm volatile("s_waitcnt lgkmcnt(" #n ")" ::: "memory")
; #define PG8_BAR __builtin_amdgcn_s_barrier()
; #define PG8_SCHED __builtin_amdgcn_sched_barrier(0)
; template <int EK, int SK = -1>
; __device__ __forceinline__ void gemm_phase(LAS unsigned char* lds, const bf16_t* A, const bf16_t* Bt, int nM, int N, int K, const EpiArgs& E) {
;     ...
;             PG8_WAIT_V(8); PG8_WAIT_L(0); PG8_BAR; PG8_MMA(1, 0, At, B0); PG8_MMA(1, 1, At, B1); PG8_BAR; PG8_SCHED;
;             PG8_LDB(B0, 1, 0); PG8_LDB(B1, 1, 1); PG8_SCHED; PG8_LDA(At, 1, 0); PG8_STAGEA(PG8_SA(0, 1), a2 + hstep);
;             PG8_WAIT_V(8); PG8_WAIT_L(0); PG8_BAR; PG8_MMA(0, 0, At, B0); PG8_MMA(0, 1, At, B1); PG8_BAR; PG8_SCHED;
;             PG8_LDA(At, 1, 1); PG8_STAGEB(PG8_SB(1, 0), b3); PG8_STAGEB(PG8_SB(1, 1), b3 + hstep); PG8_STAGEA(PG8_SA(1, 0), a3);
	v_mfma_f32_16x16x32_bf16 v[30:33], v[150:153], v[206:209], 0
	v_mfma_f32_16x16x32_bf16 v[26:29], v[166:169], v[206:209], 0
	v_mfma_f32_16x16x32_bf16 v[22:25], v[150:153], v[214:217], 0
	v_mfma_f32_16x16x32_bf16 v[18:21], v[166:169], v[214:217], 0
	v_mfma_f32_16x16x32_bf16 v[46:49], v[154:157], v[194:197], v[46:49]
	v_mfma_f32_16x16x32_bf16 v[42:45], v[170:173], v[194:197], v[42:45]
	v_mfma_f32_16x16x32_bf16 v[38:41], v[154:157], v[202:205], v[38:41]
	v_mfma_f32_16x16x32_bf16 v[34:37], v[170:173], v[202:205], v[34:37]
	v_mfma_f32_16x16x32_bf16 v[30:33], v[154:157], v[210:213], v[30:33]
	v_mfma_f32_16x16x32_bf16 v[26:29], v[170:173], v[210:213], v[26:29]
	v_mfma_f32_16x16x32_bf16 v[22:25], v[154:157], v[218:221], v[22:25]
	v_mfma_f32_16x16x32_bf16 v[18:21], v[170:173], v[218:221], v[18:21]
	v_mfma_f32_16x16x32_bf16 v[14:17], v[174:177], v[190:193], 0
	v_mfma_f32_16x16x32_bf16 v[10:13], v[182:185], v[190:193], 0
	v_mfma_f32_16x16x32_bf16 v[6:9], v[174:177], v[198:201], 0
	v_mfma_f32_16x16x32_bf16 v[2:5], v[182:185], v[198:201], 0
	v_mfma_f32_16x16x32_bf16 v[114:117], v[174:177], v[206:209], 0
	v_mfma_f32_16x16x32_bf16 v[118:121], v[182:185], v[206:209], 0
	v_mfma_f32_16x16x32_bf16 v[122:125], v[174:177], v[214:217], 0
	v_mfma_f32_16x16x32_bf16 v[126:129], v[182:185], v[214:217], 0
	v_mfma_f32_16x16x32_bf16 v[14:17], v[178:181], v[194:197], v[14:17]
	v_mfma_f32_16x16x32_bf16 v[10:13], v[186:189], v[194:197], v[10:13]
	v_mfma_f32_16x16x32_bf16 v[6:9], v[178:181], v[202:205], v[6:9]
	v_mfma_f32_16x16x32_bf16 v[2:5], v[186:189], v[202:205], v[2:5]
	v_mfma_f32_16x16x32_bf16 v[114:117], v[178:181], v[210:213], v[114:117]
	v_mfma_f32_16x16x32_bf16 v[118:121], v[186:189], v[210:213], v[118:121]
	v_mfma_f32_16x16x32_bf16 v[122:125], v[178:181], v[218:221], v[122:125]
	v_mfma_f32_16x16x32_bf16 v[126:129], v[186:189], v[218:221], v[126:129]
	s_barrier
	s_add_i32 s90, 0, 0x18000
	v_add_u32_e32 v165, s90, v160
	s_add_i32 s91, 0, 0x1c000
	ds_read_b128 v[150:153], v165
	ds_read_b128 v[154:157], v165 offset:1024
	ds_read_b128 v[166:169], v165 offset:2048
	ds_read_b128 v[170:173], v165 offset:3072
	v_add_u32_e32 v165, s91, v160
	ds_read_b128 v[174:177], v165
	ds_read_b128 v[178:181], v165 offset:1024
	ds_read_b128 v[182:185], v165 offset:2048
	ds_read_b128 v[186:189], v165 offset:3072
	s_add_u32 s78, s78, 0x40000
	s_addc_u32 s79, s79, 0
	s_mov_b32 m0, s55
	v_lshl_add_u64 v[228:229], s[78:79], 0, v[130:131]
	ds_read_b128 v[190:193], v163 offset:32768
	ds_read_b128 v[194:197], v163 offset:33792
	ds_read_b128 v[198:201], v163 offset:34816
	ds_read_b128 v[202:205], v163 offset:35840
	ds_read_b128 v[206:209], v163 offset:36864
	ds_read_b128 v[210:213], v163 offset:37888
	ds_read_b128 v[214:217], v163 offset:38912
	ds_read_b128 v[218:221], v163 offset:39936
	global_load_lds_dwordx4 v[228:229], off
	v_lshl_add_u64 v[228:229], s[78:79], 0, v[134:135]
	s_mov_b32 m0, s57
	s_nop 0
	global_load_lds_dwordx4 v[228:229], off
	s_waitcnt vmcnt(8)
	s_waitcnt lgkmcnt(0)
	s_waitcnt lgkmcnt(0)
	v_mfma_f32_16x16x32_bf16 v[110:113], v[150:153], v[190:193], v[110:113]
	v_mfma_f32_16x16x32_bf16 v[106:109], v[166:169], v[190:193], v[106:109]
	v_mfma_f32_16x16x32_bf16 v[102:105], v[150:153], v[198:201], v[102:105]
	v_mfma_f32_16x16x32_bf16 v[98:101], v[166:169], v[198:201], v[98:101]
	s_barrier
	v_mfma_f32_16x16x32_bf16 v[94:97], v[150:153], v[206:209], v[94:97]
	v_mfma_f32_16x16x32_bf16 v[90:93], v[166:169], v[206:209], v[90:93]
	v_mfma_f32_16x16x32_bf16 v[86:89], v[150:153], v[214:217], v[86:89]
	v_mfma_f32_16x16x32_bf16 v[82:85], v[166:169], v[214:217], v[82:85]
	v_mfma_f32_16x16x32_bf16 v[110:113], v[154:157], v[194:197], v[110:113]
	v_mfma_f32_16x16x32_bf16 v[106:109], v[170:173], v[194:197], v[106:109]
	v_mfma_f32_16x16x32_bf16 v[102:105], v[154:157], v[202:205], v[102:105]
	v_mfma_f32_16x16x32_bf16 v[98:101], v[170:173], v[202:205], v[98:101]
	v_mfma_f32_16x16x32_bf16 v[94:97], v[154:157], v[210:213], v[94:97]
	v_mfma_f32_16x16x32_bf16 v[90:93], v[170:173], v[210:213], v[90:93]
	v_mfma_f32_16x16x32_bf16 v[86:89], v[154:157], v[218:221], v[86:89]
	v_mfma_f32_16x16x32_bf16 v[82:85], v[170:173], v[218:221], v[82:85]
	v_mfma_f32_16x16x32_bf16 v[78:81], v[174:177], v[190:193], v[78:81]
	v_mfma_f32_16x16x32_bf16 v[74:77], v[182:185], v[190:193], v[74:77]
	v_mfma_f32_16x16x32_bf16 v[70:73], v[174:177], v[198:201], v[70:73]
	v_mfma_f32_16x16x32_bf16 v[66:69], v[182:185], v[198:201], v[66:69]
	v_mfma_f32_16x16x32_bf16 v[62:65], v[174:177], v[206:209], v[62:65]
	v_mfma_f32_16x16x32_bf16 v[58:61], v[182:185], v[206:209], v[58:61]
	v_mfma_f32_16x16x32_bf16 v[54:57], v[174:177], v[214:217], v[54:57]
	v_mfma_f32_16x16x32_bf16 v[50:53], v[182:185], v[214:217], v[50:53]
	v_mfma_f32_16x16x32_bf16 v[78:81], v[178:181], v[194:197], v[78:81]
	v_mfma_f32_16x16x32_bf16 v[74:77], v[186:189], v[194:197], v[74:77]
	v_mfma_f32_16x16x32_bf16 v[70:73], v[178:181], v[202:205], v[70:73]
	v_mfma_f32_16x16x32_bf16 v[66:69], v[186:189], v[202:205], v[66:69]
	v_mfma_f32_16x16x32_bf16 v[62:65], v[178:181], v[210:213], v[62:65]
	v_mfma_f32_16x16x32_bf16 v[58:61], v[186:189], v[210:213], v[58:61]
	v_mfma_f32_16x16x32_bf16 v[54:57], v[178:181], v[218:221], v[54:57]
	v_mfma_f32_16x16x32_bf16 v[50:53], v[186:189], v[218:221], v[50:53]
	s_barrier
; #define PG8_STAGEA(bufoff, gbase) PG8_STAGE_(bufoff, gbase, voffA)
; #define PG8_STAGEB(bufoff, gbase) PG8_STAGE_(bufoff, gbase, voffB)
; #define PG8_LDA(dst, b, h) do { _Pragma("unroll") for (int m = 0; m < 4; ++m) _Pragma("unroll") for (int k = 0; k < 2; ++k) dst[m][k] = *(const LAS bf16x8*)(lds + PG8_SA(b, h) + aoff + m * 2048 + k * 1024); } while (0)
; #define PG8_LDB(dst, b, h) do { _Pragma("unroll") for (int n = 0; n < 2; ++n) _Pragma("unroll") for (int k = 0; k < 2; ++k) dst[n][k] = *(const LAS bf16x8*)(lds + PG8_SB(b, h) + boff + n * 2048 + k * 1024); } while (0)
; #define PG8_WAIT_V(n) asm volatile("s_waitcnt vmcnt(" #n ")" ::: "memory")
; #define PG8_WAIT_L(n) asm volatile("s_waitcnt lgkmcnt(" #n ")" ::: "memory")
; #define PG8_BAR __builtin_amdgcn_s_barrier()
; #define PG8_SCHED __builtin_amdgcn_sched_barrier(0)
; template <int EK, int SK = -1>
; __device__ __forceinline__ void gemm_phase(LAS unsigned char* lds, const bf16_t* A, const bf16_t* Bt, int nM, int N, int K, const EpiArgs& E) {
;     ...
;         for (int t = 0; t < nt; t += 2) {
;             const bool last = (t == nt - 2);
;             const char* a1 = cA + (size_t)(t + 1) * kstep;
;             const char* a2 = last ? nA : cA + (size_t)(t + 2) * kstep; const char* b2 = last ? nB : cB + (size_t)(t + 2) * kstep;
;             const char* a3 = a2 + kstep; const char* b3 = b2 + kstep;
;             PG8_LDB(B0, 0, 0); PG8_LDB(B1, 0, 1); PG8_SCHED; PG8_LDA(At, 0, 0); PG8_STAGEA(PG8_SA(1, 1), a1 + hstep);
;             PG8_WAIT_V(8); PG8_WAIT_L(0); PG8_BAR; PG8_MMA(0, 0, At, B0); PG8_MMA(0, 1, At, B1); PG8_BAR; PG8_SCHED;
;             PG8_LDA(At, 0, 1); PG8_STAGEB(PG8_SB(0, 0), b2); PG8_STAGEB(PG8_SB(0, 1), b2 + hstep); PG8_STAGEA(PG8_SA(0, 0), a2);
;             PG8_WAIT_V(8); PG8_WAIT_L(0); PG8_BAR; PG8_MMA(1, 0, At, B0); PG8_MMA(1, 1, At, B1); PG8_BAR; PG8_SCHED;
;             PG8_LDB(B0, 1, 0); PG8_LDB(B1, 1, 1); PG8_SCHED; PG8_LDA(At, 1, 0); PG8_STAGEA(PG8_SA(0, 1), a2 + hstep);
;             PG8_WAIT_V(8); PG8_WAIT_L(0); PG8_BAR; PG8_MMA(0, 0, At, B0); PG8_MMA(0, 1, At, B1); PG8_BAR; PG8_SCHED;
;             PG8_LDA(At, 1, 1); PG8_STAGEB(PG8_SB(1, 0), b3); PG8_STAGEB(PG8_SB(1, 1), b3 + hstep); PG8_STAGEA(PG8_SA(1, 0), a3);
;             PG8_WAIT_V(8); PG8_WAIT_L(0); PG8_BAR; PG8_MMA(1, 0, At, B0); PG8_MMA(1, 1, At, B1); PG8_BAR; PG8_SCHED;
	s_add_i32 s78, s90, s53
	v_lshl_add_u64 v[158:159], v[158:159], 0, s[16:17]
	s_mov_b32 m0, s78
	ds_read_b128 v[190:193], v163 offset:49152
	ds_read_b128 v[194:197], v163 offset:50176
	ds_read_b128 v[198:201], v163 offset:51200
	ds_read_b128 v[202:205], v163 offset:52224
	ds_read_b128 v[206:209], v163 offset:53248
	ds_read_b128 v[210:213], v163 offset:54272
	ds_read_b128 v[214:217], v163 offset:55296
	ds_read_b128 v[218:221], v163 offset:56320
	global_load_lds_dwordx4 v[158:159], off
	s_add_i32 m0, s78, 0x2000
	s_add_u32 s76, s76, 0x40080
	v_lshl_add_u64 v[158:159], v[222:223], 0, s[16:17]
	s_addc_u32 s77, s77, 0
	s_add_i32 s78, s91, s53
	global_load_lds_dwordx4 v[158:159], off
	v_lshl_add_u64 v[158:159], s[76:77], 0, v[132:133]
	s_mov_b32 m0, s78
	s_nop 0
	global_load_lds_dwordx4 v[158:159], off
	v_lshl_add_u64 v[158:159], s[76:77], 0, v[136:137]
	s_add_i32 m0, s78, 0x2000
	s_nop 0
	global_load_lds_dwordx4 v[158:159], off
	v_lshl_add_u64 v[158:159], v[224:225], 0, s[16:17]
	s_mov_b32 m0, s80
	s_nop 0
	global_load_lds_dwordx4 v[158:159], off
	v_lshl_add_u64 v[158:159], v[226:227], 0, s[16:17]
	s_mov_b32 m0, s81
	s_nop 0
	global_load_lds_dwordx4 v[158:159], off
	s_waitcnt vmcnt(8)
	s_waitcnt lgkmcnt(0)
	s_waitcnt lgkmcnt(0)
	v_mfma_f32_16x16x32_bf16 v[46:49], v[150:153], v[190:193], v[46:49]
	v_mfma_f32_16x16x32_bf16 v[42:45], v[166:169], v[190:193], v[42:45]
	v_mfma_f32_16x16x32_bf16 v[38:41], v[150:153], v[198:201], v[38:41]
	v_mfma_f32_16x16x32_bf16 v[34:37], v[166:169], v[198:201], v[34:37]
	s_barrier
	v_mfma_f32_16x16x32_bf16 v[30:33], v[150:153], v[206:209], v[30:33]
	v_mfma_f32_16x16x32_bf16 v[26:29], v[166:169], v[206:209], v[26:29]
	v_mfma_f32_16x16x32_bf16 v[22:25], v[150:153], v[214:217], v[22:25]
	v_mfma_f32_16x16x32_bf16 v[18:21], v[166:169], v[214:217], v[18:21]
	v_mfma_f32_16x16x32_bf16 v[46:49], v[154:157], v[194:197], v[46:49]
	v_mfma_f32_16x16x32_bf16 v[42:45], v[170:173], v[194:197], v[42:45]
	v_mfma_f32_16x16x32_bf16 v[38:41], v[154:157], v[202:205], v[38:41]
	v_mfma_f32_16x16x32_bf16 v[34:37], v[170:173], v[202:205], v[34:37]
	v_mfma_f32_16x16x32_bf16 v[30:33], v[154:157], v[210:213], v[30:33]
	v_mfma_f32_16x16x32_bf16 v[26:29], v[170:173], v[210:213], v[26:29]
	v_mfma_f32_16x16x32_bf16 v[22:25], v[154:157], v[218:221], v[22:25]
	v_mfma_f32_16x16x32_bf16 v[18:21], v[170:173], v[218:221], v[18:21]
	v_mfma_f32_16x16x32_bf16 v[14:17], v[174:177], v[190:193], v[14:17]
	v_mfma_f32_16x16x32_bf16 v[10:13], v[182:185], v[190:193], v[10:13]
	v_mfma_f32_16x16x32_bf16 v[6:9], v[174:177], v[198:201], v[6:9]
	v_mfma_f32_16x16x32_bf16 v[2:5], v[182:185], v[198:201], v[2:5]
	v_mfma_f32_16x16x32_bf16 v[114:117], v[174:177], v[206:209], v[114:117]
	v_mfma_f32_16x16x32_bf16 v[118:121], v[182:185], v[206:209], v[118:121]
	v_mfma_f32_16x16x32_bf16 v[122:125], v[174:177], v[214:217], v[122:125]
	v_mfma_f32_16x16x32_bf16 v[126:129], v[182:185], v[214:217], v[126:129]
	v_mfma_f32_16x16x32_bf16 v[14:17], v[178:181], v[194:197], v[14:17]
	v_mfma_f32_16x16x32_bf16 v[10:13], v[186:189], v[194:197], v[10:13]
	v_mfma_f32_16x16x32_bf16 v[6:9], v[178:181], v[202:205], v[6:9]
	v_mfma_f32_16x16x32_bf16 v[2:5], v[186:189], v[202:205], v[2:5]
	v_mfma_f32_16x16x32_bf16 v[114:117], v[178:181], v[210:213], v[114:117]
	v_mfma_f32_16x16x32_bf16 v[118:121], v[186:189], v[210:213], v[118:121]
	v_mfma_f32_16x16x32_bf16 v[122:125], v[178:181], v[218:221], v[122:125]
	v_mfma_f32_16x16x32_bf16 v[126:129], v[186:189], v[218:221], v[126:129]
	s_barrier
	s_add_i32 s89, s89, 2
	s_add_u32 s10, s10, 0x100
	s_addc_u32 s11, s11, 0
	s_cmp_gt_u32 s89, 13
	s_cbranch_scc0 .LBB0_929
	s_branch .Lmy_kexit_4
.LBB0_929:
	v_add_u32_e32 v158, s82, v160
	ds_read_b128 v[150:153], v158
	ds_read_b128 v[154:157], v158 offset:1024
	ds_read_b128 v[166:169], v158 offset:2048
	ds_read_b128 v[170:173], v158 offset:3072
	v_add_u32_e32 v158, s83, v160
	s_add_u32 s76, s36, s10
	ds_read_b128 v[174:177], v158
	ds_read_b128 v[178:181], v158 offset:1024
	ds_read_b128 v[182:185], v158 offset:2048
	ds_read_b128 v[186:189], v158 offset:3072
	s_addc_u32 s77, s37, s11
	s_add_u32 s76, s76, 0x100
	s_addc_u32 s77, s77, 0
	s_add_u32 s90, s86, s10
	s_addc_u32 s91, s87, s11
	s_cmpk_eq_i32 s10, 0x700
	s_cselect_b32 s79, s14, s77
	s_cselect_b32 s78, s71, s76
	s_cselect_b32 s77, s69, s91
	s_cselect_b32 s76, s88, s90
	v_lshl_add_u64 v[158:159], v[146:147], 0, s[10:11]
	s_add_i32 m0, s23, 0xc000
	ds_read_b128 v[190:193], v163
	ds_read_b128 v[194:197], v163 offset:1024
	ds_read_b128 v[198:201], v163 offset:2048
	ds_read_b128 v[202:205], v163 offset:3072
	ds_read_b128 v[206:209], v163 offset:4096
	ds_read_b128 v[210:213], v163 offset:5120
	ds_read_b128 v[214:217], v163 offset:6144
	ds_read_b128 v[218:221], v163 offset:7168
	global_load_lds_dwordx4 v[158:159], off
	v_lshl_add_u64 v[158:159], v[148:149], 0, s[10:11]
	s_add_i32 m0, s23, 0xe000
	s_nop 0
	global_load_lds_dwordx4 v[158:159], off
	s_waitcnt vmcnt(8)
	s_waitcnt lgkmcnt(0)
	s_waitcnt lgkmcnt(0)
	v_mfma_f32_16x16x32_bf16 v[110:113], v[150:153], v[190:193], v[110:113]
	v_mfma_f32_16x16x32_bf16 v[106:109], v[166:169], v[190:193], v[106:109]
	v_mfma_f32_16x16x32_bf16 v[102:105], v[150:153], v[198:201], v[102:105]
	v_mfma_f32_16x16x32_bf16 v[98:101], v[166:169], v[198:201], v[98:101]
	s_barrier
; #define PG8_STAGEA(bufoff, gbase) PG8_STAGE_(bufoff, gbase, voffA)
; #define PG8_STAGEB(bufoff, gbase) PG8_STAGE_(bufoff, gbase, voffB)
; #define PG8_LDA(dst, b, h) do { _Pragma("unroll") for (int m = 0; m < 4; ++m) _Pragma("unroll") for (int k = 0; k < 2; ++k) dst[m][k] = *(const LAS bf16x8*)(lds + PG8_SA(b, h) + aoff + m * 2048 + k * 1024); } while (0)
; #define PG8_MMA(ai, bj, At, Bt_) do { __builtin_amdgcn_s_setprio(1); _Pragma("unroll") for (int m = 0; m < 4; ++m) _Pragma("unroll") for (int n = 0; n < 2; ++n) _Pragma("unroll") for (int k = 0; k < 2; ++k) \
;         acc[ai][bj][m][n] = __builtin_amdgcn_mfma_f32_16x16x32_bf16(Bt_[n][k], At[m][k], acc[ai][bj][m][n], 0, 0, 0); __builtin_amdgcn_s_setprio(0); } while (0)
; #define PG8_WAIT_V(n) asm volatile("s_waitcnt vmcnt(" #n ")" ::: "memory")
; #define PG8_WAIT_L(n) asm volatile("s_waitcnt lgkmcnt(" #n ")" ::: "memory")
; #define PG8_BAR __builtin_amdgcn_s_barrier()
; #define PG8_SCHED __builtin_amdgcn_sched_barrier(0)
; template <int EK, int SK = -1>
; __device__ __forceinline__ void gemm_phase(LAS unsigned char* lds, const bf16_t* A, const bf16_t* Bt, int nM, int N, int K, const EpiArgs& E) {
;     ...
;             PG8_WAIT_V(8); PG8_WAIT_L(0); PG8_BAR; PG8_MMA(0, 0, At, B0); PG8_MMA(0, 1, At, B1); PG8_BAR; PG8_SCHED;
;             PG8_LDA(At, 0, 1); PG8_STAGEB(PG8_SB(0, 0), b2); PG8_STAGEB(PG8_SB(0, 1), b2 + hstep); PG8_STAGEA(PG8_SA(0, 0), a2);
;             PG8_WAIT_V(8); PG8_WAIT_L(0); PG8_BAR; PG8_MMA(1, 0, At, B0); PG8_MMA(1, 1, At, B1); PG8_BAR; PG8_SCHED;
	v_mfma_f32_16x16x32_bf16 v[94:97], v[150:153], v[206:209], v[94:97]
	v_mfma_f32_16x16x32_bf16 v[90:93], v[166:169], v[206:209], v[90:93]
	v_mfma_f32_16x16x32_bf16 v[86:89], v[150:153], v[214:217], v[86:89]
	v_mfma_f32_16x16x32_bf16 v[82:85], v[166:169], v[214:217], v[82:85]
	v_mfma_f32_16x16x32_bf16 v[110:113], v[154:157], v[194:197], v[110:113]
	v_mfma_f32_16x16x32_bf16 v[106:109], v[170:173], v[194:197], v[106:109]
	v_mfma_f32_16x16x32_bf16 v[102:105], v[154:157], v[202:205], v[102:105]
	v_mfma_f32_16x16x32_bf16 v[98:101], v[170:173], v[202:205], v[98:101]
	v_mfma_f32_16x16x32_bf16 v[94:97], v[154:157], v[210:213], v[94:97]
	v_mfma_f32_16x16x32_bf16 v[90:93], v[170:173], v[210:213], v[90:93]
	v_mfma_f32_16x16x32_bf16 v[86:89], v[154:157], v[218:221], v[86:89]
	v_mfma_f32_16x16x32_bf16 v[82:85], v[170:173], v[218:221], v[82:85]
	v_mfma_f32_16x16x32_bf16 v[78:81], v[174:177], v[190:193], v[78:81]
	v_mfma_f32_16x16x32_bf16 v[74:77], v[182:185], v[190:193], v[74:77]
	v_mfma_f32_16x16x32_bf16 v[70:73], v[174:177], v[198:201], v[70:73]
	v_mfma_f32_16x16x32_bf16 v[66:69], v[182:185], v[198:201], v[66:69]
	v_mfma_f32_16x16x32_bf16 v[62:65], v[174:177], v[206:209], v[62:65]
	v_mfma_f32_16x16x32_bf16 v[58:61], v[182:185], v[206:209], v[58:61]
	v_mfma_f32_16x16x32_bf16 v[54:57], v[174:177], v[214:217], v[54:57]
	v_mfma_f32_16x16x32_bf16 v[50:53], v[182:185], v[214:217], v[50:53]
	v_mfma_f32_16x16x32_bf16 v[78:81], v[178:181], v[194:197], v[78:81]
	v_mfma_f32_16x16x32_bf16 v[74:77], v[186:189], v[194:197], v[74:77]
	v_mfma_f32_16x16x32_bf16 v[70:73], v[178:181], v[202:205], v[70:73]
	v_mfma_f32_16x16x32_bf16 v[66:69], v[186:189], v[202:205], v[66:69]
	v_mfma_f32_16x16x32_bf16 v[62:65], v[178:181], v[210:213], v[62:65]
	v_mfma_f32_16x16x32_bf16 v[58:61], v[186:189], v[210:213], v[58:61]
	v_mfma_f32_16x16x32_bf16 v[54:57], v[178:181], v[218:221], v[54:57]
	v_mfma_f32_16x16x32_bf16 v[50:53], v[186:189], v[218:221], v[50:53]
	s_barrier
	s_add_i32 s90, s82, s53
	v_lshl_add_u64 v[158:159], s[76:77], 0, v[132:133]
	s_mov_b32 m0, s90
	ds_read_b128 v[190:193], v163 offset:16384
	ds_read_b128 v[194:197], v163 offset:17408
	ds_read_b128 v[198:201], v163 offset:18432
	ds_read_b128 v[202:205], v163 offset:19456
	ds_read_b128 v[206:209], v163 offset:20480
	ds_read_b128 v[210:213], v163 offset:21504
	ds_read_b128 v[214:217], v163 offset:22528
	ds_read_b128 v[218:221], v163 offset:23552
	global_load_lds_dwordx4 v[158:159], off
	s_add_i32 m0, s90, 0x2000
	s_add_u32 s90, s76, 0x40000
	v_lshl_add_u64 v[222:223], s[76:77], 0, v[136:137]
	s_addc_u32 s91, s77, 0
	s_add_i32 s92, s83, s53
	global_load_lds_dwordx4 v[222:223], off
	v_lshl_add_u64 v[224:225], s[90:91], 0, v[132:133]
	s_mov_b32 m0, s92
	v_lshl_add_u64 v[226:227], s[78:79], 0, v[134:135]
	global_load_lds_dwordx4 v[224:225], off
	v_lshl_add_u64 v[224:225], s[90:91], 0, v[136:137]
	s_add_i32 m0, s92, 0x2000
	s_nop 0
	global_load_lds_dwordx4 v[224:225], off
	v_lshl_add_u64 v[224:225], s[78:79], 0, v[130:131]
	s_mov_b32 m0, s23
	s_nop 0
	global_load_lds_dwordx4 v[224:225], off
	s_mov_b32 m0, s27
	s_nop 0
	global_load_lds_dwordx4 v[226:227], off
	s_waitcnt vmcnt(8)
	s_waitcnt lgkmcnt(0)
	s_waitcnt lgkmcnt(0)
	v_mfma_f32_16x16x32_bf16 v[46:49], v[150:153], v[190:193], v[46:49]
	v_mfma_f32_16x16x32_bf16 v[42:45], v[166:169], v[190:193], v[42:45]
	v_mfma_f32_16x16x32_bf16 v[38:41], v[150:153], v[198:201], v[38:41]
	v_mfma_f32_16x16x32_bf16 v[34:37], v[166:169], v[198:201], v[34:37]
	s_barrier
	v_mfma_f32_16x16x32_bf16 v[30:33], v[150:153], v[206:209], v[30:33]
	v_mfma_f32_16x16x32_bf16 v[26:29], v[166:169], v[206:209], v[26:29]
	v_mfma_f32_16x16x32_bf16 v[22:25], v[150:153], v[214:217], v[22:25]
	v_mfma_f32_16x16x32_bf16 v[18:21], v[166:169], v[214:217], v[18:21]
	v_mfma_f32_16x16x32_bf16 v[46:49], v[154:157], v[194:197], v[46:49]
	v_mfma_f32_16x16x32_bf16 v[42:45], v[170:173], v[194:197], v[42:45]
	v_mfma_f32_16x16x32_bf16 v[38:41], v[154:157], v[202:205], v[38:41]
	v_mfma_f32_16x16x32_bf16 v[34:37], v[170:173], v[202:205], v[34:37]
	v_mfma_f32_16x16x32_bf16 v[30:33], v[154:157], v[210:213], v[30:33]
	v_mfma_f32_16x16x32_bf16 v[26:29], v[170:173], v[210:213], v[26:29]
	v_mfma_f32_16x16x32_bf16 v[22:25], v[154:157], v[218:221], v[22:25]
	v_mfma_f32_16x16x32_bf16 v[18:21], v[170:173], v[218:221], v[18:21]
	v_mfma_f32_16x16x32_bf16 v[14:17], v[174:177], v[190:193], v[14:17]
	v_mfma_f32_16x16x32_bf16 v[10:13], v[182:185], v[190:193], v[10:13]
	v_mfma_f32_16x16x32_bf16 v[6:9], v[174:177], v[198:201], v[6:9]
	v_mfma_f32_16x16x32_bf16 v[2:5], v[182:185], v[198:201], v[2:5]
	v_mfma_f32_16x16x32_bf16 v[114:117], v[174:177], v[206:209], v[114:117]
	v_mfma_f32_16x16x32_bf16 v[118:121], v[182:185], v[206:209], v[118:121]
	v_mfma_f32_16x16x32_bf16 v[122:125], v[174:177], v[214:217], v[122:125]
	v_mfma_f32_16x16x32_bf16 v[126:129], v[182:185], v[214:217], v[126:129]
	v_mfma_f32_16x16x32_bf16 v[14:17], v[178:181], v[194:197], v[14:17]
	v_mfma_f32_16x16x32_bf16 v[10:13], v[186:189], v[194:197], v[10:13]
	v_mfma_f32_16x16x32_bf16 v[6:9], v[178:181], v[202:205], v[6:9]
	v_mfma_f32_16x16x32_bf16 v[2:5], v[186:189], v[202:205], v[2:5]
	v_mfma_f32_16x16x32_bf16 v[114:117], v[178:181], v[210:213], v[114:117]
	v_mfma_f32_16x16x32_bf16 v[118:121], v[186:189], v[210:213], v[118:121]
	v_mfma_f32_16x16x32_bf16 v[122:125], v[178:181], v[218:221], v[122:125]
	v_mfma_f32_16x16x32_bf16 v[126:129], v[186:189], v[218:221], v[126:129]
	s_barrier
; #define PG8_STAGEA(bufoff, gbase) PG8_STAGE_(bufoff, gbase, voffA)
; #define PG8_STAGEB(bufoff, gbase) PG8_STAGE_(bufoff, gbase, voffB)
; #define PG8_LDA(dst, b, h) do { _Pragma("unroll") for (int m = 0; m < 4; ++m) _Pragma("unroll") for (int k = 0; k < 2; ++k) dst[m][k] = *(const LAS bf16x8*)(lds + PG8_SA(b, h) + aoff + m * 2048 + k * 1024); } while (0)
; #define PG8_LDB(dst, b, h) do { _Pragma("unroll") for (int n = 0; n < 2; ++n) _Pragma("unroll") for (int k = 0; k < 2; ++k) dst[n][k] = *(const LAS bf16x8*)(lds + PG8_SB(b, h) + boff + n * 2048 + k * 1024); } while (0)
; #define PG8_MMA(ai, bj, At, Bt_) do { __builtin_amdgcn_s_setprio(1); _Pragma("unroll") for (int m = 0; m < 4; ++m) _Pragma("unroll") for (int n = 0; n < 2; ++n) _Pragma("unroll") for (int k = 0; k < 2; ++k) \
;         acc[ai][bj][m][n] = __builtin_amdgcn_mfma_f32_16x16x32_bf16(Bt_[n][k], At[m][k], acc[ai][bj][m][n], 0, 0, 0); __builtin_amdgcn_s_setprio(0); } while (0)
; #define PG8_WAIT_V(n) asm volatile("s_waitcnt vmcnt(" #n ")" ::: "memory")
; #define PG8_WAIT_L(n) asm volatile("s_waitcnt lgkmcnt(" #n ")" ::: "memory")
; #define PG8_BAR __builtin_amdgcn_s_barrier()
; #define PG8_SCHED __builtin_amdgcn_sched_barrier(0)
; template <int EK, int SK = -1>
; __device__ __forceinline__ void gemm_phase(LAS unsigned char* lds, const bf16_t* A, const bf16_t* Bt, int nM, int N, int K, const EpiArgs& E) {
;     ...
;             PG8_LDB(B0, 1, 0); PG8_LDB(B1, 1, 1); PG8_SCHED; PG8_LDA(At, 1, 0); PG8_STAGEA(PG8_SA(0, 1), a2 + hstep);
;             PG8_WAIT_V(8); PG8_WAIT_L(0); PG8_BAR; PG8_MMA(0, 0, At, B0); PG8_MMA(0, 1, At, B1); PG8_BAR; PG8_SCHED;
;             PG8_LDA(At, 1, 1); PG8_STAGEB(PG8_SB(1, 0), b3); PG8_STAGEB(PG8_SB(1, 1), b3 + hstep); PG8_STAGEA(PG8_SA(1, 0), a3);
;             PG8_WAIT_V(8); PG8_WAIT_L(0); PG8_BAR; PG8_MMA(1, 0, At, B0); PG8_MMA(1, 1, At, B1); PG8_BAR; PG8_SCHED;
;         }
	s_add_i32 s90, 0, 0x18000
	v_add_u32_e32 v165, s90, v160
	s_add_i32 s91, 0, 0x1c000
	ds_read_b128 v[150:153], v165
	ds_read_b128 v[154:157], v165 offset:1024
	ds_read_b128 v[166:169], v165 offset:2048
	ds_read_b128 v[170:173], v165 offset:3072
	v_add_u32_e32 v165, s91, v160
	ds_read_b128 v[174:177], v165
	ds_read_b128 v[178:181], v165 offset:1024
	ds_read_b128 v[182:185], v165 offset:2048
	ds_read_b128 v[186:189], v165 offset:3072
	s_add_u32 s78, s78, 0x40000
	s_addc_u32 s79, s79, 0
	s_mov_b32 m0, s55
	v_lshl_add_u64 v[228:229], s[78:79], 0, v[130:131]
	ds_read_b128 v[190:193], v163 offset:32768
	ds_read_b128 v[194:197], v163 offset:33792
	ds_read_b128 v[198:201], v163 offset:34816
	ds_read_b128 v[202:205], v163 offset:35840
	ds_read_b128 v[206:209], v163 offset:36864
	ds_read_b128 v[210:213], v163 offset:37888
	ds_read_b128 v[214:217], v163 offset:38912
	ds_read_b128 v[218:221], v163 offset:39936
	global_load_lds_dwordx4 v[228:229], off
	v_lshl_add_u64 v[228:229], s[78:79], 0, v[134:135]
	s_mov_b32 m0, s57
	s_nop 0
	global_load_lds_dwordx4 v[228:229], off
	s_waitcnt vmcnt(8)
	s_waitcnt lgkmcnt(0)
	s_waitcnt lgkmcnt(0)
	v_mfma_f32_16x16x32_bf16 v[110:113], v[150:153], v[190:193], v[110:113]
	v_mfma_f32_16x16x32_bf16 v[106:109], v[166:169], v[190:193], v[106:109]
	v_mfma_f32_16x16x32_bf16 v[102:105], v[150:153], v[198:201], v[102:105]
	v_mfma_f32_16x16x32_bf16 v[98:101], v[166:169], v[198:201], v[98:101]
	s_barrier
	v_mfma_f32_16x16x32_bf16 v[94:97], v[150:153], v[206:209], v[94:97]
	v_mfma_f32_16x16x32_bf16 v[90:93], v[166:169], v[206:209], v[90:93]
	v_mfma_f32_16x16x32_bf16 v[86:89], v[150:153], v[214:217], v[86:89]
	v_mfma_f32_16x16x32_bf16 v[82:85], v[166:169], v[214:217], v[82:85]
	v_mfma_f32_16x16x32_bf16 v[110:113], v[154:157], v[194:197], v[110:113]
	v_mfma_f32_16x16x32_bf16 v[106:109], v[170:173], v[194:197], v[106:109]
	v_mfma_f32_16x16x32_bf16 v[102:105], v[154:157], v[202:205], v[102:105]
	v_mfma_f32_16x16x32_bf16 v[98:101], v[170:173], v[202:205], v[98:101]
	v_mfma_f32_16x16x32_bf16 v[94:97], v[154:157], v[210:213], v[94:97]
	v_mfma_f32_16x16x32_bf16 v[90:93], v[170:173], v[210:213], v[90:93]
	v_mfma_f32_16x16x32_bf16 v[86:89], v[154:157], v[218:221], v[86:89]
	v_mfma_f32_16x16x32_bf16 v[82:85], v[170:173], v[218:221], v[82:85]
	v_mfma_f32_16x16x32_bf16 v[78:81], v[174:177], v[190:193], v[78:81]
	v_mfma_f32_16x16x32_bf16 v[74:77], v[182:185], v[190:193], v[74:77]
	v_mfma_f32_16x16x32_bf16 v[70:73], v[174:177], v[198:201], v[70:73]
	v_mfma_f32_16x16x32_bf16 v[66:69], v[182:185], v[198:201], v[66:69]
	v_mfma_f32_16x16x32_bf16 v[62:65], v[174:177], v[206:209], v[62:65]
	v_mfma_f32_16x16x32_bf16 v[58:61], v[182:185], v[206:209], v[58:61]
	v_mfma_f32_16x16x32_bf16 v[54:57], v[174:177], v[214:217], v[54:57]
	v_mfma_f32_16x16x32_bf16 v[50:53], v[182:185], v[214:217], v[50:53]
	v_mfma_f32_16x16x32_bf16 v[78:81], v[178:181], v[194:197], v[78:81]
	v_mfma_f32_16x16x32_bf16 v[74:77], v[186:189], v[194:197], v[74:77]
	v_mfma_f32_16x16x32_bf16 v[70:73], v[178:181], v[202:205], v[70:73]
	v_mfma_f32_16x16x32_bf16 v[66:69], v[186:189], v[202:205], v[66:69]
	v_mfma_f32_16x16x32_bf16 v[62:65], v[178:181], v[210:213], v[62:65]
	v_mfma_f32_16x16x32_bf16 v[58:61], v[186:189], v[210:213], v[58:61]
	v_mfma_f32_16x16x32_bf16 v[54:57], v[178:181], v[218:221], v[54:57]
	v_mfma_f32_16x16x32_bf16 v[50:53], v[186:189], v[218:221], v[50:53]
	s_barrier
	s_add_i32 s78, s90, s53
	v_lshl_add_u64 v[158:159], v[158:159], 0, s[16:17]
	s_mov_b32 m0, s78
	ds_read_b128 v[190:193], v163 offset:49152
	ds_read_b128 v[194:197], v163 offset:50176
	ds_read_b128 v[198:201], v163 offset:51200
	ds_read_b128 v[202:205], v163 offset:52224
	ds_read_b128 v[206:209], v163 offset:53248
	ds_read_b128 v[210:213], v163 offset:54272
	ds_read_b128 v[214:217], v163 offset:55296
	ds_read_b128 v[218:221], v163 offset:56320
	global_load_lds_dwordx4 v[158:159], off
	s_add_i32 m0, s78, 0x2000
	s_add_u32 s76, s76, 0x40080
	v_lshl_add_u64 v[158:159], v[222:223], 0, s[16:17]
	s_addc_u32 s77, s77, 0
	s_add_i32 s78, s91, s53
	global_load_lds_dwordx4 v[158:159], off
	v_lshl_add_u64 v[158:159], s[76:77], 0, v[132:133]
	s_mov_b32 m0, s78
	s_nop 0
	global_load_lds_dwordx4 v[158:159], off
	v_lshl_add_u64 v[158:159], s[76:77], 0, v[136:137]
	s_add_i32 m0, s78, 0x2000
	s_nop 0
	global_load_lds_dwordx4 v[158:159], off
	v_lshl_add_u64 v[158:159], v[224:225], 0, s[16:17]
	s_mov_b32 m0, s80
	s_nop 0
	global_load_lds_dwordx4 v[158:159], off
	v_lshl_add_u64 v[158:159], v[226:227], 0, s[16:17]
	s_mov_b32 m0, s81
	s_nop 0
	global_load_lds_dwordx4 v[158:159], off
	s_waitcnt vmcnt(8)
	s_waitcnt lgkmcnt(0)
	s_waitcnt lgkmcnt(0)
	v_mfma_f32_16x16x32_bf16 v[46:49], v[150:153], v[190:193], v[46:49]
	v_mfma_f32_16x16x32_bf16 v[42:45], v[166:169], v[190:193], v[42:45]
	v_mfma_f32_16x16x32_bf16 v[38:41], v[150:153], v[198:201], v[38:41]
	v_mfma_f32_16x16x32_bf16 v[34:37], v[166:169], v[198:201], v[34:37]
	s_barrier
	v_mfma_f32_16x16x32_bf16 v[30:33], v[150:153], v[206:209], v[30:33]
	v_mfma_f32_16x16x32_bf16 v[26:29], v[166:169], v[206:209], v[26:29]
	v_mfma_f32_16x16x32_bf16 v[22:25], v[150:153], v[214:217], v[22:25]
	v_mfma_f32_16x16x32_bf16 v[18:21], v[166:169], v[214:217], v[18:21]
	v_mfma_f32_16x16x32_bf16 v[46:49], v[154:157], v[194:197], v[46:49]
	v_mfma_f32_16x16x32_bf16 v[42:45], v[170:173], v[194:197], v[42:45]
	v_mfma_f32_16x16x32_bf16 v[38:41], v[154:157], v[202:205], v[38:41]
	v_mfma_f32_16x16x32_bf16 v[34:37], v[170:173], v[202:205], v[34:37]
	v_mfma_f32_16x16x32_bf16 v[30:33], v[154:157], v[210:213], v[30:33]
	v_mfma_f32_16x16x32_bf16 v[26:29], v[170:173], v[210:213], v[26:29]
	v_mfma_f32_16x16x32_bf16 v[22:25], v[154:157], v[218:221], v[22:25]
	v_mfma_f32_16x16x32_bf16 v[18:21], v[170:173], v[218:221], v[18:21]
	v_mfma_f32_16x16x32_bf16 v[14:17], v[174:177], v[190:193], v[14:17]
	v_mfma_f32_16x16x32_bf16 v[10:13], v[182:185], v[190:193], v[10:13]
	v_mfma_f32_16x16x32_bf16 v[6:9], v[174:177], v[198:201], v[6:9]
	v_mfma_f32_16x16x32_bf16 v[2:5], v[182:185], v[198:201], v[2:5]
	v_mfma_f32_16x16x32_bf16 v[114:117], v[174:177], v[206:209], v[114:117]
	v_mfma_f32_16x16x32_bf16 v[118:121], v[182:185], v[206:209], v[118:121]
	v_mfma_f32_16x16x32_bf16 v[122:125], v[174:177], v[214:217], v[122:125]
	v_mfma_f32_16x16x32_bf16 v[126:129], v[182:185], v[214:217], v[126:129]
	v_mfma_f32_16x16x32_bf16 v[14:17], v[178:181], v[194:197], v[14:17]
	v_mfma_f32_16x16x32_bf16 v[10:13], v[186:189], v[194:197], v[10:13]
	v_mfma_f32_16x16x32_bf16 v[6:9], v[178:181], v[202:205], v[6:9]
	v_mfma_f32_16x16x32_bf16 v[2:5], v[186:189], v[202:205], v[2:5]
	v_mfma_f32_16x16x32_bf16 v[114:117], v[178:181], v[210:213], v[114:117]
	v_mfma_f32_16x16x32_bf16 v[118:121], v[186:189], v[210:213], v[118:121]
	v_mfma_f32_16x16x32_bf16 v[122:125], v[178:181], v[218:221], v[122:125]
	v_mfma_f32_16x16x32_bf16 v[126:129], v[186:189], v[218:221], v[126:129]
	s_barrier
	s_add_i32 s89, s89, 2
	s_add_u32 s10, s10, 0x100
	s_addc_u32 s11, s11, 0
	s_cmp_gt_u32 s89, 13
	s_cbranch_scc0 .LBB0_929

; #define PG8_STAGEA(bufoff, gbase) PG8_STAGE_(bufoff, gbase, voffA)
; #define PG8_STAGEB(bufoff, gbase) PG8_STAGE_(bufoff, gbase, voffB)
; #define PG8_LDA(dst, b, h) do { _Pragma("unroll") for (int m = 0; m < 4; ++m) _Pragma("unroll") for (int k = 0; k < 2; ++k) dst[m][k] = *(const LAS bf16x8*)(lds + PG8_SA(b, h) + aoff + m * 2048 + k * 1024); } while (0)
; #define PG8_LDB(dst, b, h) do { _Pragma("unroll") for (int n = 0; n < 2; ++n) _Pragma("unroll") for (int k = 0; k < 2; ++k) dst[n][k] = *(const LAS bf16x8*)(lds + PG8_SB(b, h) + boff + n * 2048 + k * 1024); } while (0)
; #define PG8_MMA(ai, bj, At, Bt_) do { __builtin_amdgcn_s_setprio(1); _Pragma("unroll") for (int m = 0; m < 4; ++m) _Pragma("unroll") for (int n = 0; n < 2; ++n) _Pragma("unroll") for (int k = 0; k < 2; ++k) \
;         acc[ai][bj][m][n] = __builtin_amdgcn_mfma_f32_16x16x32_bf16(Bt_[n][k], At[m][k], acc[ai][bj][m][n], 0, 0, 0); __builtin_amdgcn_s_setprio(0); } while (0)
; #define PG8_WAIT_V(n) asm volatile("s_waitcnt vmcnt(" #n ")" ::: "memory")
; #define PG8_WAIT_L(n) asm volatile("s_waitcnt lgkmcnt(" #n ")" ::: "memory")
; #define PG8_BAR __builtin_amdgcn_s_barrier()
; template <int EK, int SK = -1>
; __device__ __forceinline__ void gemm_phase(LAS unsigned char* lds, const bf16_t* A, const bf16_t* Bt, int nM, int N, int K, const EpiArgs& E) {
;     ...
;         const bool has_next = S.next(ui + 1, nxt);
;         const char* nA = has_next ? (const char*)A + (size_t)nxt.pm * tstep : cA; const char* nB = has_next ? (const char*)Bt + (size_t)nxt.pn * tstep : cB;
;         for (int t = 0; t < nt; t += 2) {
;             const bool last = (t == nt - 2);
;             const char* a1 = cA + (size_t)(t + 1) * kstep;
;             const char* a2 = last ? nA : cA + (size_t)(t + 2) * kstep; const char* b2 = last ? nB : cB + (size_t)(t + 2) * kstep;
;             const char* a3 = a2 + kstep; const char* b3 = b2 + kstep;
;             PG8_LDB(B0, 0, 0); PG8_LDB(B1, 0, 1); PG8_SCHED; PG8_LDA(At, 0, 0); PG8_STAGEA(PG8_SA(1, 1), a1 + hstep);
;             PG8_WAIT_V(8); PG8_WAIT_L(0); PG8_BAR; PG8_MMA(0, 0, At, B0); PG8_MMA(0, 1, At, B1); PG8_BAR; PG8_SCHED;
;             PG8_LDA(At, 0, 1); PG8_STAGEB(PG8_SB(0, 0), b2); PG8_STAGEB(PG8_SB(0, 1), b2 + hstep); PG8_STAGEA(PG8_SA(0, 0), a2);
;             PG8_WAIT_V(8); PG8_WAIT_L(0); PG8_BAR; PG8_MMA(1, 0, At, B0); PG8_MMA(1, 1, At, B1); PG8_BAR; PG8_SCHED;
.LBB0_1119:
	s_add_u32 s73, s46, 0x100
	s_addc_u32 s74, s47, 0
	s_ashr_i32 s41, s40, 31
	s_lshl_b64 s[42:43], s[40:41], 19
	s_add_u32 s44, s66, s42
	s_addc_u32 s45, s67, s43
	s_and_b64 s[42:43], s[8:9], exec
	s_cselect_b32 s22, s45, s19
	s_cselect_b32 s41, s44, s18
	s_ashr_i32 s39, s38, 31
	s_lshl_b64 s[42:43], s[38:39], 19
	s_add_u32 s42, s52, s42
	s_addc_u32 s43, s53, s43
	s_and_b64 s[48:49], s[8:9], exec
	s_cselect_b32 s39, s43, s47
	s_cselect_b32 s75, s42, s46
	v_lshl_add_u64 v[146:147], s[18:19], 0, v[138:139]
	v_lshl_add_u64 v[148:149], s[18:19], 0, v[140:141]
	s_mov_b32 s76, -2
	s_mov_b64 s[46:47], 0
	v_add_u32_e32 v150, s69, v152
	ds_read_b128 v[156:159], v150
	ds_read_b128 v[160:163], v150 offset:1024
	ds_read_b128 v[164:167], v150 offset:2048
	ds_read_b128 v[168:171], v150 offset:3072
	v_add_u32_e32 v150, s70, v152
	s_add_u32 s48, s18, s46
	ds_read_b128 v[172:175], v150
	ds_read_b128 v[176:179], v150 offset:1024
	ds_read_b128 v[180:183], v150 offset:2048
	ds_read_b128 v[184:187], v150 offset:3072
	s_addc_u32 s49, s19, s47
	s_add_u32 s48, s48, 0x100
	s_addc_u32 s49, s49, 0
	s_add_u32 s77, s73, s46
	s_addc_u32 s78, s74, s47
	s_cmpk_eq_i32 s46, 0x700
	s_cselect_b32 s51, s22, s49
	s_cselect_b32 s50, s41, s48
	s_cselect_b32 s49, s39, s78
	s_cselect_b32 s48, s75, s77
	v_lshl_add_u64 v[150:151], v[146:147], 0, s[46:47]
	s_add_i32 m0, s15, 0xc000
	ds_read_b128 v[188:191], v154
	ds_read_b128 v[192:195], v154 offset:1024
	ds_read_b128 v[196:199], v154 offset:2048
	ds_read_b128 v[200:203], v154 offset:3072
	ds_read_b128 v[204:207], v154 offset:4096
	ds_read_b128 v[208:211], v154 offset:5120
	ds_read_b128 v[212:215], v154 offset:6144
	ds_read_b128 v[216:219], v154 offset:7168
	global_load_lds_dwordx4 v[150:151], off
	v_lshl_add_u64 v[150:151], v[148:149], 0, s[46:47]
	s_add_i32 m0, s15, 0xe000
	s_nop 0
	global_load_lds_dwordx4 v[150:151], off
	s_waitcnt vmcnt(8)
	s_waitcnt lgkmcnt(0)
	s_waitcnt lgkmcnt(0)
	v_mfma_f32_16x16x32_bf16 v[126:129], v[156:159], v[188:191], 0
	v_mfma_f32_16x16x32_bf16 v[122:125], v[164:167], v[188:191], 0
	v_mfma_f32_16x16x32_bf16 v[118:121], v[156:159], v[196:199], 0
	v_mfma_f32_16x16x32_bf16 v[114:117], v[164:167], v[196:199], 0
	s_barrier
	v_mfma_f32_16x16x32_bf16 v[110:113], v[156:159], v[204:207], 0
	v_mfma_f32_16x16x32_bf16 v[106:109], v[164:167], v[204:207], 0
	v_mfma_f32_16x16x32_bf16 v[102:105], v[156:159], v[212:215], 0
	v_mfma_f32_16x16x32_bf16 v[98:101], v[164:167], v[212:215], 0
	v_mfma_f32_16x16x32_bf16 v[126:129], v[160:163], v[192:195], v[126:129]
	v_mfma_f32_16x16x32_bf16 v[122:125], v[168:171], v[192:195], v[122:125]
	v_mfma_f32_16x16x32_bf16 v[118:121], v[160:163], v[200:203], v[118:121]
	v_mfma_f32_16x16x32_bf16 v[114:117], v[168:171], v[200:203], v[114:117]
	v_mfma_f32_16x16x32_bf16 v[110:113], v[160:163], v[208:211], v[110:113]
	v_mfma_f32_16x16x32_bf16 v[106:109], v[168:171], v[208:211], v[106:109]
	v_mfma_f32_16x16x32_bf16 v[102:105], v[160:163], v[216:219], v[102:105]
	v_mfma_f32_16x16x32_bf16 v[98:101], v[168:171], v[216:219], v[98:101]
	v_mfma_f32_16x16x32_bf16 v[94:97], v[172:175], v[188:191], 0
	v_mfma_f32_16x16x32_bf16 v[90:93], v[180:183], v[188:191], 0
	v_mfma_f32_16x16x32_bf16 v[86:89], v[172:175], v[196:199], 0
	v_mfma_f32_16x16x32_bf16 v[82:85], v[180:183], v[196:199], 0
	v_mfma_f32_16x16x32_bf16 v[78:81], v[172:175], v[204:207], 0
	v_mfma_f32_16x16x32_bf16 v[74:77], v[180:183], v[204:207], 0
	v_mfma_f32_16x16x32_bf16 v[70:73], v[172:175], v[212:215], 0
	v_mfma_f32_16x16x32_bf16 v[66:69], v[180:183], v[212:215], 0
	v_mfma_f32_16x16x32_bf16 v[94:97], v[176:179], v[192:195], v[94:97]
	v_mfma_f32_16x16x32_bf16 v[90:93], v[184:187], v[192:195], v[90:93]
	v_mfma_f32_16x16x32_bf16 v[86:89], v[176:179], v[200:203], v[86:89]
	v_mfma_f32_16x16x32_bf16 v[82:85], v[184:187], v[200:203], v[82:85]
	v_mfma_f32_16x16x32_bf16 v[78:81], v[176:179], v[208:211], v[78:81]
	v_mfma_f32_16x16x32_bf16 v[74:77], v[184:187], v[208:211], v[74:77]
	v_mfma_f32_16x16x32_bf16 v[70:73], v[176:179], v[216:219], v[70:73]
	v_mfma_f32_16x16x32_bf16 v[66:69], v[184:187], v[216:219], v[66:69]
	s_barrier
	s_add_i32 s77, s69, s54
	v_lshl_add_u64 v[150:151], s[48:49], 0, v[132:133]
	s_mov_b32 m0, s77
	ds_read_b128 v[188:191], v154 offset:16384
	ds_read_b128 v[192:195], v154 offset:17408
	ds_read_b128 v[196:199], v154 offset:18432
	ds_read_b128 v[200:203], v154 offset:19456
	ds_read_b128 v[204:207], v154 offset:20480
	ds_read_b128 v[208:211], v154 offset:21504
	ds_read_b128 v[212:215], v154 offset:22528
	ds_read_b128 v[216:219], v154 offset:23552
	global_load_lds_dwordx4 v[150:151], off
	s_add_i32 m0, s77, 0x2000
	s_add_u32 s78, s48, 0x40000
	v_lshl_add_u64 v[220:221], s[48:49], 0, v[136:137]
	s_addc_u32 s79, s49, 0
	s_add_i32 s77, s70, s54
	global_load_lds_dwordx4 v[220:221], off
	v_lshl_add_u64 v[222:223], s[78:79], 0, v[132:133]
	s_mov_b32 m0, s77
	v_lshl_add_u64 v[224:225], s[50:51], 0, v[134:135]
	global_load_lds_dwordx4 v[222:223], off
	v_lshl_add_u64 v[222:223], s[78:79], 0, v[136:137]
	s_add_i32 m0, s77, 0x2000
	s_nop 0
	global_load_lds_dwordx4 v[222:223], off
	v_lshl_add_u64 v[222:223], s[50:51], 0, v[130:131]
	s_mov_b32 m0, s15
	s_nop 0
	global_load_lds_dwordx4 v[222:223], off
	s_mov_b32 m0, s17
	s_nop 0
	global_load_lds_dwordx4 v[224:225], off
	s_waitcnt vmcnt(8)
	s_waitcnt lgkmcnt(0)
	s_waitcnt lgkmcnt(0)
	v_mfma_f32_16x16x32_bf16 v[62:65], v[156:159], v[188:191], 0
	v_mfma_f32_16x16x32_bf16 v[58:61], v[164:167], v[188:191], 0
	v_mfma_f32_16x16x32_bf16 v[54:57], v[156:159], v[196:199], 0
	v_mfma_f32_16x16x32_bf16 v[50:53], v[164:167], v[196:199], 0
	s_barrier
; #define PG8_STAGEA(bufoff, gbase) PG8_STAGE_(bufoff, gbase, voffA)
; #define PG8_STAGEB(bufoff, gbase) PG8_STAGE_(bufoff, gbase, voffB)
; #define PG8_LDA(dst, b, h) do { _Pragma("unroll") for (int m = 0; m < 4; ++m) _Pragma("unroll") for (int k = 0; k < 2; ++k) dst[m][k] = *(const LAS bf16x8*)(lds + PG8_SA(b, h) + aoff + m * 2048 + k * 1024); } while (0)
; #define PG8_LDB(dst, b, h) do { _Pragma("unroll") for (int n = 0; n < 2; ++n) _Pragma("unroll") for (int k = 0; k < 2; ++k) dst[n][k] = *(const LAS bf16x8*)(lds + PG8_SB(b, h) + boff + n * 2048 + k * 1024); } while (0)
; #define PG8_MMA(ai, bj, At, Bt_) do { __builtin_amdgcn_s_setprio(1); _Pragma("unroll") for (int m = 0; m < 4; ++m) _Pragma("unroll") for (int n = 0; n < 2; ++n) _Pragma("unroll") for (int k = 0; k < 2; ++k) \
;         acc[ai][bj][m][n] = __builtin_amdgcn_mfma_f32_16x16x32_bf16(Bt_[n][k], At[m][k], acc[ai][bj][m][n], 0, 0, 0); __builtin_amdgcn_s_setprio(0); } while (0)
; #define PG8_WAIT_V(n) asm volatile("s_waitcnt vmcnt(" #n ")" ::: "memory")
; #define PG8_WAIT_L(n) asm volatile("s_waitcnt lgkmcnt(" #n ")" ::: "memory")
; #define PG8_BAR __builtin_amdgcn_s_barrier()
; #define PG8_SCHED __builtin_amdgcn_sched_barrier(0)
; template <int EK, int SK = -1>
; __device__ __forceinline__ void gemm_phase(LAS unsigned char* lds, const bf16_t* A, const bf16_t* Bt, int nM, int N, int K, const EpiArgs& E) {
;     ...
;             PG8_WAIT_V(8); PG8_WAIT_L(0); PG8_BAR; PG8_MMA(1, 0, At, B0); PG8_MMA(1, 1, At, B1); PG8_BAR; PG8_SCHED;
;             PG8_LDB(B0, 1, 0); PG8_LDB(B1, 1, 1); PG8_SCHED; PG8_LDA(At, 1, 0); PG8_STAGEA(PG8_SA(0, 1), a2 + hstep);
;             PG8_WAIT_V(8); PG8_WAIT_L(0); PG8_BAR; PG8_MMA(0, 0, At, B0); PG8_MMA(0, 1, At, B1); PG8_BAR; PG8_SCHED;
;             PG8_LDA(At, 1, 1); PG8_STAGEB(PG8_SB(1, 0), b3); PG8_STAGEB(PG8_SB(1, 1), b3 + hstep); PG8_STAGEA(PG8_SA(1, 0), a3);
	v_mfma_f32_16x16x32_bf16 v[46:49], v[156:159], v[204:207], 0
	v_mfma_f32_16x16x32_bf16 v[42:45], v[164:167], v[204:207], 0
	v_mfma_f32_16x16x32_bf16 v[38:41], v[156:159], v[212:215], 0
	v_mfma_f32_16x16x32_bf16 v[34:37], v[164:167], v[212:215], 0
	v_mfma_f32_16x16x32_bf16 v[62:65], v[160:163], v[192:195], v[62:65]
	v_mfma_f32_16x16x32_bf16 v[58:61], v[168:171], v[192:195], v[58:61]
	v_mfma_f32_16x16x32_bf16 v[54:57], v[160:163], v[200:203], v[54:57]
	v_mfma_f32_16x16x32_bf16 v[50:53], v[168:171], v[200:203], v[50:53]
	v_mfma_f32_16x16x32_bf16 v[46:49], v[160:163], v[208:211], v[46:49]
	v_mfma_f32_16x16x32_bf16 v[42:45], v[168:171], v[208:211], v[42:45]
	v_mfma_f32_16x16x32_bf16 v[38:41], v[160:163], v[216:219], v[38:41]
	v_mfma_f32_16x16x32_bf16 v[34:37], v[168:171], v[216:219], v[34:37]
	v_mfma_f32_16x16x32_bf16 v[30:33], v[172:175], v[188:191], 0
	v_mfma_f32_16x16x32_bf16 v[26:29], v[180:183], v[188:191], 0
	v_mfma_f32_16x16x32_bf16 v[22:25], v[172:175], v[196:199], 0
	v_mfma_f32_16x16x32_bf16 v[18:21], v[180:183], v[196:199], 0
	v_mfma_f32_16x16x32_bf16 v[14:17], v[172:175], v[204:207], 0
	v_mfma_f32_16x16x32_bf16 v[10:13], v[180:183], v[204:207], 0
	v_mfma_f32_16x16x32_bf16 v[6:9], v[172:175], v[212:215], 0
	v_mfma_f32_16x16x32_bf16 v[2:5], v[180:183], v[212:215], 0
	v_mfma_f32_16x16x32_bf16 v[30:33], v[176:179], v[192:195], v[30:33]
	v_mfma_f32_16x16x32_bf16 v[26:29], v[184:187], v[192:195], v[26:29]
	v_mfma_f32_16x16x32_bf16 v[22:25], v[176:179], v[200:203], v[22:25]
	v_mfma_f32_16x16x32_bf16 v[18:21], v[184:187], v[200:203], v[18:21]
	v_mfma_f32_16x16x32_bf16 v[14:17], v[176:179], v[208:211], v[14:17]
	v_mfma_f32_16x16x32_bf16 v[10:13], v[184:187], v[208:211], v[10:13]
	v_mfma_f32_16x16x32_bf16 v[6:9], v[176:179], v[216:219], v[6:9]
	v_mfma_f32_16x16x32_bf16 v[2:5], v[184:187], v[216:219], v[2:5]
	s_barrier
	s_add_i32 s77, 0, 0x18000
	s_add_i32 s78, 0, 0x1c000
	v_add_u32_e32 v168, s77, v152
	v_add_u32_e32 v184, s78, v152
	ds_read_b128 v[156:159], v168
	ds_read_b128 v[160:163], v168 offset:1024
	ds_read_b128 v[164:167], v168 offset:2048
	ds_read_b128 v[168:171], v168 offset:3072
	ds_read_b128 v[172:175], v184
	ds_read_b128 v[176:179], v184 offset:1024
	ds_read_b128 v[180:183], v184 offset:2048
	ds_read_b128 v[184:187], v184 offset:3072
	s_add_u32 s50, s50, 0x40000
	s_addc_u32 s51, s51, 0
	s_mov_b32 m0, s55
	v_lshl_add_u64 v[226:227], s[50:51], 0, v[130:131]
	ds_read_b128 v[188:191], v154 offset:32768
	ds_read_b128 v[192:195], v154 offset:33792
	ds_read_b128 v[196:199], v154 offset:34816
	ds_read_b128 v[200:203], v154 offset:35840
	ds_read_b128 v[204:207], v154 offset:36864
	ds_read_b128 v[208:211], v154 offset:37888
	ds_read_b128 v[212:215], v154 offset:38912
	ds_read_b128 v[216:219], v154 offset:39936
	global_load_lds_dwordx4 v[226:227], off
	v_lshl_add_u64 v[226:227], s[50:51], 0, v[134:135]
	s_mov_b32 m0, s56
	s_nop 0
	global_load_lds_dwordx4 v[226:227], off
	s_waitcnt vmcnt(8)
	s_waitcnt lgkmcnt(0)
	s_waitcnt lgkmcnt(0)
	v_mfma_f32_16x16x32_bf16 v[126:129], v[156:159], v[188:191], v[126:129]
	v_mfma_f32_16x16x32_bf16 v[122:125], v[164:167], v[188:191], v[122:125]
	v_mfma_f32_16x16x32_bf16 v[118:121], v[156:159], v[196:199], v[118:121]
	v_mfma_f32_16x16x32_bf16 v[114:117], v[164:167], v[196:199], v[114:117]
	s_barrier
	v_mfma_f32_16x16x32_bf16 v[110:113], v[156:159], v[204:207], v[110:113]
	v_mfma_f32_16x16x32_bf16 v[106:109], v[164:167], v[204:207], v[106:109]
	v_mfma_f32_16x16x32_bf16 v[102:105], v[156:159], v[212:215], v[102:105]
	v_mfma_f32_16x16x32_bf16 v[98:101], v[164:167], v[212:215], v[98:101]
	v_mfma_f32_16x16x32_bf16 v[126:129], v[160:163], v[192:195], v[126:129]
	v_mfma_f32_16x16x32_bf16 v[122:125], v[168:171], v[192:195], v[122:125]
	v_mfma_f32_16x16x32_bf16 v[118:121], v[160:163], v[200:203], v[118:121]
	v_mfma_f32_16x16x32_bf16 v[114:117], v[168:171], v[200:203], v[114:117]
	v_mfma_f32_16x16x32_bf16 v[110:113], v[160:163], v[208:211], v[110:113]
	v_mfma_f32_16x16x32_bf16 v[106:109], v[168:171], v[208:211], v[106:109]
	v_mfma_f32_16x16x32_bf16 v[102:105], v[160:163], v[216:219], v[102:105]
	v_mfma_f32_16x16x32_bf16 v[98:101], v[168:171], v[216:219], v[98:101]
	v_mfma_f32_16x16x32_bf16 v[94:97], v[172:175], v[188:191], v[94:97]
	v_mfma_f32_16x16x32_bf16 v[90:93], v[180:183], v[188:191], v[90:93]
	v_mfma_f32_16x16x32_bf16 v[86:89], v[172:175], v[196:199], v[86:89]
	v_mfma_f32_16x16x32_bf16 v[82:85], v[180:183], v[196:199], v[82:85]
	v_mfma_f32_16x16x32_bf16 v[78:81], v[172:175], v[204:207], v[78:81]
	v_mfma_f32_16x16x32_bf16 v[74:77], v[180:183], v[204:207], v[74:77]
	v_mfma_f32_16x16x32_bf16 v[70:73], v[172:175], v[212:215], v[70:73]
	v_mfma_f32_16x16x32_bf16 v[66:69], v[180:183], v[212:215], v[66:69]
	v_mfma_f32_16x16x32_bf16 v[94:97], v[176:179], v[192:195], v[94:97]
	v_mfma_f32_16x16x32_bf16 v[90:93], v[184:187], v[192:195], v[90:93]
	v_mfma_f32_16x16x32_bf16 v[86:89], v[176:179], v[200:203], v[86:89]
	v_mfma_f32_16x16x32_bf16 v[82:85], v[184:187], v[200:203], v[82:85]
	v_mfma_f32_16x16x32_bf16 v[78:81], v[176:179], v[208:211], v[78:81]
	v_mfma_f32_16x16x32_bf16 v[74:77], v[184:187], v[208:211], v[74:77]
	v_mfma_f32_16x16x32_bf16 v[70:73], v[176:179], v[216:219], v[70:73]
	v_mfma_f32_16x16x32_bf16 v[66:69], v[184:187], v[216:219], v[66:69]
	s_barrier
; #define PG8_STAGEA(bufoff, gbase) PG8_STAGE_(bufoff, gbase, voffA)
; #define PG8_STAGEB(bufoff, gbase) PG8_STAGE_(bufoff, gbase, voffB)
; #define PG8_LDA(dst, b, h) do { _Pragma("unroll") for (int m = 0; m < 4; ++m) _Pragma("unroll") for (int k = 0; k < 2; ++k) dst[m][k] = *(const LAS bf16x8*)(lds + PG8_SA(b, h) + aoff + m * 2048 + k * 1024); } while (0)
; #define PG8_LDB(dst, b, h) do { _Pragma("unroll") for (int n = 0; n < 2; ++n) _Pragma("unroll") for (int k = 0; k < 2; ++k) dst[n][k] = *(const LAS bf16x8*)(lds + PG8_SB(b, h) + boff + n * 2048 + k * 1024); } while (0)
; #define PG8_WAIT_V(n) asm volatile("s_waitcnt vmcnt(" #n ")" ::: "memory")
; #define PG8_WAIT_L(n) asm volatile("s_waitcnt lgkmcnt(" #n ")" ::: "memory")
; #define PG8_BAR __builtin_amdgcn_s_barrier()
; #define PG8_SCHED __builtin_amdgcn_sched_barrier(0)
; template <int EK, int SK = -1>
; __device__ __forceinline__ void gemm_phase(LAS unsigned char* lds, const bf16_t* A, const bf16_t* Bt, int nM, int N, int K, const EpiArgs& E) {
;     ...
;         for (int t = 0; t < nt; t += 2) {
;             const bool last = (t == nt - 2);
;             const char* a1 = cA + (size_t)(t + 1) * kstep;
;             const char* a2 = last ? nA : cA + (size_t)(t + 2) * kstep; const char* b2 = last ? nB : cB + (size_t)(t + 2) * kstep;
;             const char* a3 = a2 + kstep; const char* b3 = b2 + kstep;
;             PG8_LDB(B0, 0, 0); PG8_LDB(B1, 0, 1); PG8_SCHED; PG8_LDA(At, 0, 0); PG8_STAGEA(PG8_SA(1, 1), a1 + hstep);
;             PG8_WAIT_V(8); PG8_WAIT_L(0); PG8_BAR; PG8_MMA(0, 0, At, B0); PG8_MMA(0, 1, At, B1); PG8_BAR; PG8_SCHED;
;             PG8_LDA(At, 0, 1); PG8_STAGEB(PG8_SB(0, 0), b2); PG8_STAGEB(PG8_SB(0, 1), b2 + hstep); PG8_STAGEA(PG8_SA(0, 0), a2);
;             PG8_WAIT_V(8); PG8_WAIT_L(0); PG8_BAR; PG8_MMA(1, 0, At, B0); PG8_MMA(1, 1, At, B1); PG8_BAR; PG8_SCHED;
;             PG8_LDB(B0, 1, 0); PG8_LDB(B1, 1, 1); PG8_SCHED; PG8_LDA(At, 1, 0); PG8_STAGEA(PG8_SA(0, 1), a2 + hstep);
;             PG8_WAIT_V(8); PG8_WAIT_L(0); PG8_BAR; PG8_MMA(0, 0, At, B0); PG8_MMA(0, 1, At, B1); PG8_BAR; PG8_SCHED;
;             PG8_LDA(At, 1, 1); PG8_STAGEB(PG8_SB(1, 0), b3); PG8_STAGEB(PG8_SB(1, 1), b3 + hstep); PG8_STAGEA(PG8_SA(1, 0), a3);
;             PG8_WAIT_V(8); PG8_WAIT_L(0); PG8_BAR; PG8_MMA(1, 0, At, B0); PG8_MMA(1, 1, At, B1); PG8_BAR; PG8_SCHED;
	s_add_i32 s50, s77, s54
	v_lshl_add_u64 v[150:151], v[150:151], 0, s[26:27]
	s_mov_b32 m0, s50
	ds_read_b128 v[188:191], v154 offset:49152
	ds_read_b128 v[192:195], v154 offset:50176
	ds_read_b128 v[196:199], v154 offset:51200
	ds_read_b128 v[200:203], v154 offset:52224
	ds_read_b128 v[204:207], v154 offset:53248
	ds_read_b128 v[208:211], v154 offset:54272
	ds_read_b128 v[212:215], v154 offset:55296
	ds_read_b128 v[216:219], v154 offset:56320
	global_load_lds_dwordx4 v[150:151], off
	s_add_i32 m0, s50, 0x2000
	s_add_u32 s48, s48, 0x40080
	v_lshl_add_u64 v[150:151], v[220:221], 0, s[26:27]
	s_addc_u32 s49, s49, 0
	s_add_i32 s50, s78, s54
	global_load_lds_dwordx4 v[150:151], off
	v_lshl_add_u64 v[150:151], s[48:49], 0, v[132:133]
	s_mov_b32 m0, s50
	s_nop 0
	global_load_lds_dwordx4 v[150:151], off
	v_lshl_add_u64 v[150:151], s[48:49], 0, v[136:137]
	s_add_i32 m0, s50, 0x2000
	s_nop 0
	global_load_lds_dwordx4 v[150:151], off
	v_lshl_add_u64 v[150:151], v[222:223], 0, s[26:27]
	s_mov_b32 m0, s59
	s_nop 0
	global_load_lds_dwordx4 v[150:151], off
	v_lshl_add_u64 v[150:151], v[224:225], 0, s[26:27]
	s_mov_b32 m0, s68
	s_nop 0
	global_load_lds_dwordx4 v[150:151], off
	s_waitcnt vmcnt(8)
	s_waitcnt lgkmcnt(0)
	s_waitcnt lgkmcnt(0)
	v_mfma_f32_16x16x32_bf16 v[62:65], v[156:159], v[188:191], v[62:65]
	v_mfma_f32_16x16x32_bf16 v[58:61], v[164:167], v[188:191], v[58:61]
	v_mfma_f32_16x16x32_bf16 v[54:57], v[156:159], v[196:199], v[54:57]
	v_mfma_f32_16x16x32_bf16 v[50:53], v[164:167], v[196:199], v[50:53]
	s_barrier
	v_mfma_f32_16x16x32_bf16 v[46:49], v[156:159], v[204:207], v[46:49]
	v_mfma_f32_16x16x32_bf16 v[42:45], v[164:167], v[204:207], v[42:45]
	v_mfma_f32_16x16x32_bf16 v[38:41], v[156:159], v[212:215], v[38:41]
	v_mfma_f32_16x16x32_bf16 v[34:37], v[164:167], v[212:215], v[34:37]
	v_mfma_f32_16x16x32_bf16 v[62:65], v[160:163], v[192:195], v[62:65]
	v_mfma_f32_16x16x32_bf16 v[58:61], v[168:171], v[192:195], v[58:61]
	v_mfma_f32_16x16x32_bf16 v[54:57], v[160:163], v[200:203], v[54:57]
	v_mfma_f32_16x16x32_bf16 v[50:53], v[168:171], v[200:203], v[50:53]
	v_mfma_f32_16x16x32_bf16 v[46:49], v[160:163], v[208:211], v[46:49]
	v_mfma_f32_16x16x32_bf16 v[42:45], v[168:171], v[208:211], v[42:45]
	v_mfma_f32_16x16x32_bf16 v[38:41], v[160:163], v[216:219], v[38:41]
	v_mfma_f32_16x16x32_bf16 v[34:37], v[168:171], v[216:219], v[34:37]
	v_mfma_f32_16x16x32_bf16 v[30:33], v[172:175], v[188:191], v[30:33]
	v_mfma_f32_16x16x32_bf16 v[26:29], v[180:183], v[188:191], v[26:29]
	v_mfma_f32_16x16x32_bf16 v[22:25], v[172:175], v[196:199], v[22:25]
	v_mfma_f32_16x16x32_bf16 v[18:21], v[180:183], v[196:199], v[18:21]
	v_mfma_f32_16x16x32_bf16 v[14:17], v[172:175], v[204:207], v[14:17]
	v_mfma_f32_16x16x32_bf16 v[10:13], v[180:183], v[204:207], v[10:13]
	v_mfma_f32_16x16x32_bf16 v[6:9], v[172:175], v[212:215], v[6:9]
	v_mfma_f32_16x16x32_bf16 v[2:5], v[180:183], v[212:215], v[2:5]
	v_mfma_f32_16x16x32_bf16 v[30:33], v[176:179], v[192:195], v[30:33]
	v_mfma_f32_16x16x32_bf16 v[26:29], v[184:187], v[192:195], v[26:29]
	v_mfma_f32_16x16x32_bf16 v[22:25], v[176:179], v[200:203], v[22:25]
	v_mfma_f32_16x16x32_bf16 v[18:21], v[184:187], v[200:203], v[18:21]
	v_mfma_f32_16x16x32_bf16 v[14:17], v[176:179], v[208:211], v[14:17]
	v_mfma_f32_16x16x32_bf16 v[10:13], v[184:187], v[208:211], v[10:13]
	v_mfma_f32_16x16x32_bf16 v[6:9], v[176:179], v[216:219], v[6:9]
	v_mfma_f32_16x16x32_bf16 v[2:5], v[184:187], v[216:219], v[2:5]
	s_barrier
	s_add_i32 s76, s76, 2
	s_add_u32 s46, s46, 0x100
	s_addc_u32 s47, s47, 0
	s_cmp_gt_u32 s76, 13
	s_cbranch_scc0 .LBB0_1120
	s_branch .Lmy_kexit_5
.LBB0_1120:
	v_add_u32_e32 v150, s69, v152
	ds_read_b128 v[156:159], v150
	ds_read_b128 v[160:163], v150 offset:1024
	ds_read_b128 v[164:167], v150 offset:2048
	ds_read_b128 v[168:171], v150 offset:3072
	v_add_u32_e32 v150, s70, v152
	s_add_u32 s48, s18, s46
	ds_read_b128 v[172:175], v150
	ds_read_b128 v[176:179], v150 offset:1024
	ds_read_b128 v[180:183], v150 offset:2048
	ds_read_b128 v[184:187], v150 offset:3072
	s_addc_u32 s49, s19, s47
	s_add_u32 s48, s48, 0x100
	s_addc_u32 s49, s49, 0
	s_add_u32 s77, s73, s46
	s_addc_u32 s78, s74, s47
	s_cmpk_eq_i32 s46, 0x700
	s_cselect_b32 s51, s22, s49
	s_cselect_b32 s50, s41, s48
	s_cselect_b32 s49, s39, s78
	s_cselect_b32 s48, s75, s77
	v_lshl_add_u64 v[150:151], v[146:147], 0, s[46:47]
	s_add_i32 m0, s15, 0xc000
	ds_read_b128 v[188:191], v154
	ds_read_b128 v[192:195], v154 offset:1024
	ds_read_b128 v[196:199], v154 offset:2048
	ds_read_b128 v[200:203], v154 offset:3072
	ds_read_b128 v[204:207], v154 offset:4096
	ds_read_b128 v[208:211], v154 offset:5120
	ds_read_b128 v[212:215], v154 offset:6144
	ds_read_b128 v[216:219], v154 offset:7168
	global_load_lds_dwordx4 v[150:151], off
	v_lshl_add_u64 v[150:151], v[148:149], 0, s[46:47]
	s_add_i32 m0, s15, 0xe000
	s_nop 0
	global_load_lds_dwordx4 v[150:151], off
	s_waitcnt vmcnt(8)
	s_waitcnt lgkmcnt(0)
	s_waitcnt lgkmcnt(0)
	v_mfma_f32_16x16x32_bf16 v[126:129], v[156:159], v[188:191], v[126:129]
	v_mfma_f32_16x16x32_bf16 v[122:125], v[164:167], v[188:191], v[122:125]
	v_mfma_f32_16x16x32_bf16 v[118:121], v[156:159], v[196:199], v[118:121]
	v_mfma_f32_16x16x32_bf16 v[114:117], v[164:167], v[196:199], v[114:117]
	s_barrier
; #define PG8_STAGEA(bufoff, gbase) PG8_STAGE_(bufoff, gbase, voffA)
; #define PG8_STAGEB(bufoff, gbase) PG8_STAGE_(bufoff, gbase, voffB)
; #define PG8_LDA(dst, b, h) do { _Pragma("unroll") for (int m = 0; m < 4; ++m) _Pragma("unroll") for (int k = 0; k < 2; ++k) dst[m][k] = *(const LAS bf16x8*)(lds + PG8_SA(b, h) + aoff + m * 2048 + k * 1024); } while (0)
; #define PG8_MMA(ai, bj, At, Bt_) do { __builtin_amdgcn_s_setprio(1); _Pragma("unroll") for (int m = 0; m < 4; ++m) _Pragma("unroll") for (int n = 0; n < 2; ++n) _Pragma("unroll") for (int k = 0; k < 2; ++k) \
;         acc[ai][bj][m][n] = __builtin_amdgcn_mfma_f32_16x16x32_bf16(Bt_[n][k], At[m][k], acc[ai][bj][m][n], 0, 0, 0); __builtin_amdgcn_s_setprio(0); } while (0)
; #define PG8_WAIT_V(n) asm volatile("s_waitcnt vmcnt(" #n ")" ::: "memory")
; #define PG8_WAIT_L(n) asm volatile("s_waitcnt lgkmcnt(" #n ")" ::: "memory")
; #define PG8_BAR __builtin_amdgcn_s_barrier()
; #define PG8_SCHED __builtin_amdgcn_sched_barrier(0)
; template <int EK, int SK = -1>
; __device__ __forceinline__ void gemm_phase(LAS unsigned char* lds, const bf16_t* A, const bf16_t* Bt, int nM, int N, int K, const EpiArgs& E) {
;     ...
;             PG8_WAIT_V(8); PG8_WAIT_L(0); PG8_BAR; PG8_MMA(0, 0, At, B0); PG8_MMA(0, 1, At, B1); PG8_BAR; PG8_SCHED;
;             PG8_LDA(At, 0, 1); PG8_STAGEB(PG8_SB(0, 0), b2); PG8_STAGEB(PG8_SB(0, 1), b2 + hstep); PG8_STAGEA(PG8_SA(0, 0), a2);
;             PG8_WAIT_V(8); PG8_WAIT_L(0); PG8_BAR; PG8_MMA(1, 0, At, B0); PG8_MMA(1, 1, At, B1); PG8_BAR; PG8_SCHED;
	v_mfma_f32_16x16x32_bf16 v[110:113], v[156:159], v[204:207], v[110:113]
	v_mfma_f32_16x16x32_bf16 v[106:109], v[164:167], v[204:207], v[106:109]
	v_mfma_f32_16x16x32_bf16 v[102:105], v[156:159], v[212:215], v[102:105]
	v_mfma_f32_16x16x32_bf16 v[98:101], v[164:167], v[212:215], v[98:101]
	v_mfma_f32_16x16x32_bf16 v[126:129], v[160:163], v[192:195], v[126:129]
	v_mfma_f32_16x16x32_bf16 v[122:125], v[168:171], v[192:195], v[122:125]
	v_mfma_f32_16x16x32_bf16 v[118:121], v[160:163], v[200:203], v[118:121]
	v_mfma_f32_16x16x32_bf16 v[114:117], v[168:171], v[200:203], v[114:117]
	v_mfma_f32_16x16x32_bf16 v[110:113], v[160:163], v[208:211], v[110:113]
	v_mfma_f32_16x16x32_bf16 v[106:109], v[168:171], v[208:211], v[106:109]
	v_mfma_f32_16x16x32_bf16 v[102:105], v[160:163], v[216:219], v[102:105]
	v_mfma_f32_16x16x32_bf16 v[98:101], v[168:171], v[216:219], v[98:101]
	v_mfma_f32_16x16x32_bf16 v[94:97], v[172:175], v[188:191], v[94:97]
	v_mfma_f32_16x16x32_bf16 v[90:93], v[180:183], v[188:191], v[90:93]
	v_mfma_f32_16x16x32_bf16 v[86:89], v[172:175], v[196:199], v[86:89]
	v_mfma_f32_16x16x32_bf16 v[82:85], v[180:183], v[196:199], v[82:85]
	v_mfma_f32_16x16x32_bf16 v[78:81], v[172:175], v[204:207], v[78:81]
	v_mfma_f32_16x16x32_bf16 v[74:77], v[180:183], v[204:207], v[74:77]
	v_mfma_f32_16x16x32_bf16 v[70:73], v[172:175], v[212:215], v[70:73]
	v_mfma_f32_16x16x32_bf16 v[66:69], v[180:183], v[212:215], v[66:69]
	v_mfma_f32_16x16x32_bf16 v[94:97], v[176:179], v[192:195], v[94:97]
	v_mfma_f32_16x16x32_bf16 v[90:93], v[184:187], v[192:195], v[90:93]
	v_mfma_f32_16x16x32_bf16 v[86:89], v[176:179], v[200:203], v[86:89]
	v_mfma_f32_16x16x32_bf16 v[82:85], v[184:187], v[200:203], v[82:85]
	v_mfma_f32_16x16x32_bf16 v[78:81], v[176:179], v[208:211], v[78:81]
	v_mfma_f32_16x16x32_bf16 v[74:77], v[184:187], v[208:211], v[74:77]
	v_mfma_f32_16x16x32_bf16 v[70:73], v[176:179], v[216:219], v[70:73]
	v_mfma_f32_16x16x32_bf16 v[66:69], v[184:187], v[216:219], v[66:69]
	s_barrier
	s_add_i32 s77, s69, s54
	v_lshl_add_u64 v[150:151], s[48:49], 0, v[132:133]
	s_mov_b32 m0, s77
	ds_read_b128 v[188:191], v154 offset:16384
	ds_read_b128 v[192:195], v154 offset:17408
	ds_read_b128 v[196:199], v154 offset:18432
	ds_read_b128 v[200:203], v154 offset:19456
	ds_read_b128 v[204:207], v154 offset:20480
	ds_read_b128 v[208:211], v154 offset:21504
	ds_read_b128 v[212:215], v154 offset:22528
	ds_read_b128 v[216:219], v154 offset:23552
	global_load_lds_dwordx4 v[150:151], off
	s_add_i32 m0, s77, 0x2000
	s_add_u32 s78, s48, 0x40000
	v_lshl_add_u64 v[220:221], s[48:49], 0, v[136:137]
	s_addc_u32 s79, s49, 0
	s_add_i32 s77, s70, s54
	global_load_lds_dwordx4 v[220:221], off
	v_lshl_add_u64 v[222:223], s[78:79], 0, v[132:133]
	s_mov_b32 m0, s77
	v_lshl_add_u64 v[224:225], s[50:51], 0, v[134:135]
	global_load_lds_dwordx4 v[222:223], off
	v_lshl_add_u64 v[222:223], s[78:79], 0, v[136:137]
	s_add_i32 m0, s77, 0x2000
	s_nop 0
	global_load_lds_dwordx4 v[222:223], off
	v_lshl_add_u64 v[222:223], s[50:51], 0, v[130:131]
	s_mov_b32 m0, s15
	s_nop 0
	global_load_lds_dwordx4 v[222:223], off
	s_mov_b32 m0, s17
	s_nop 0
	global_load_lds_dwordx4 v[224:225], off
	s_waitcnt vmcnt(8)
	s_waitcnt lgkmcnt(0)
	s_waitcnt lgkmcnt(0)
	v_mfma_f32_16x16x32_bf16 v[62:65], v[156:159], v[188:191], v[62:65]
	v_mfma_f32_16x16x32_bf16 v[58:61], v[164:167], v[188:191], v[58:61]
	v_mfma_f32_16x16x32_bf16 v[54:57], v[156:159], v[196:199], v[54:57]
	v_mfma_f32_16x16x32_bf16 v[50:53], v[164:167], v[196:199], v[50:53]
	s_barrier
	v_mfma_f32_16x16x32_bf16 v[46:49], v[156:159], v[204:207], v[46:49]
	v_mfma_f32_16x16x32_bf16 v[42:45], v[164:167], v[204:207], v[42:45]
	v_mfma_f32_16x16x32_bf16 v[38:41], v[156:159], v[212:215], v[38:41]
	v_mfma_f32_16x16x32_bf16 v[34:37], v[164:167], v[212:215], v[34:37]
	v_mfma_f32_16x16x32_bf16 v[62:65], v[160:163], v[192:195], v[62:65]
	v_mfma_f32_16x16x32_bf16 v[58:61], v[168:171], v[192:195], v[58:61]
	v_mfma_f32_16x16x32_bf16 v[54:57], v[160:163], v[200:203], v[54:57]
	v_mfma_f32_16x16x32_bf16 v[50:53], v[168:171], v[200:203], v[50:53]
	v_mfma_f32_16x16x32_bf16 v[46:49], v[160:163], v[208:211], v[46:49]
	v_mfma_f32_16x16x32_bf16 v[42:45], v[168:171], v[208:211], v[42:45]
	v_mfma_f32_16x16x32_bf16 v[38:41], v[160:163], v[216:219], v[38:41]
	v_mfma_f32_16x16x32_bf16 v[34:37], v[168:171], v[216:219], v[34:37]
	v_mfma_f32_16x16x32_bf16 v[30:33], v[172:175], v[188:191], v[30:33]
	v_mfma_f32_16x16x32_bf16 v[26:29], v[180:183], v[188:191], v[26:29]
	v_mfma_f32_16x16x32_bf16 v[22:25], v[172:175], v[196:199], v[22:25]
	v_mfma_f32_16x16x32_bf16 v[18:21], v[180:183], v[196:199], v[18:21]
	v_mfma_f32_16x16x32_bf16 v[14:17], v[172:175], v[204:207], v[14:17]
	v_mfma_f32_16x16x32_bf16 v[10:13], v[180:183], v[204:207], v[10:13]
	v_mfma_f32_16x16x32_bf16 v[6:9], v[172:175], v[212:215], v[6:9]
	v_mfma_f32_16x16x32_bf16 v[2:5], v[180:183], v[212:215], v[2:5]
	v_mfma_f32_16x16x32_bf16 v[30:33], v[176:179], v[192:195], v[30:33]
	v_mfma_f32_16x16x32_bf16 v[26:29], v[184:187], v[192:195], v[26:29]
	v_mfma_f32_16x16x32_bf16 v[22:25], v[176:179], v[200:203], v[22:25]
	v_mfma_f32_16x16x32_bf16 v[18:21], v[184:187], v[200:203], v[18:21]
	v_mfma_f32_16x16x32_bf16 v[14:17], v[176:179], v[208:211], v[14:17]
	v_mfma_f32_16x16x32_bf16 v[10:13], v[184:187], v[208:211], v[10:13]
	v_mfma_f32_16x16x32_bf16 v[6:9], v[176:179], v[216:219], v[6:9]
	v_mfma_f32_16x16x32_bf16 v[2:5], v[184:187], v[216:219], v[2:5]
	s_barrier
; #define PG8_STAGEA(bufoff, gbase) PG8_STAGE_(bufoff, gbase, voffA)
; #define PG8_STAGEB(bufoff, gbase) PG8_STAGE_(bufoff, gbase, voffB)
; #define PG8_LDA(dst, b, h) do { _Pragma("unroll") for (int m = 0; m < 4; ++m) _Pragma("unroll") for (int k = 0; k < 2; ++k) dst[m][k] = *(const LAS bf16x8*)(lds + PG8_SA(b, h) + aoff + m * 2048 + k * 1024); } while (0)
; #define PG8_LDB(dst, b, h) do { _Pragma("unroll") for (int n = 0; n < 2; ++n) _Pragma("unroll") for (int k = 0; k < 2; ++k) dst[n][k] = *(const LAS bf16x8*)(lds + PG8_SB(b, h) + boff + n * 2048 + k * 1024); } while (0)
; #define PG8_MMA(ai, bj, At, Bt_) do { __builtin_amdgcn_s_setprio(1); _Pragma("unroll") for (int m = 0; m < 4; ++m) _Pragma("unroll") for (int n = 0; n < 2; ++n) _Pragma("unroll") for (int k = 0; k < 2; ++k) \
;         acc[ai][bj][m][n] = __builtin_amdgcn_mfma_f32_16x16x32_bf16(Bt_[n][k], At[m][k], acc[ai][bj][m][n], 0, 0, 0); __builtin_amdgcn_s_setprio(0); } while (0)
; #define PG8_WAIT_V(n) asm volatile("s_waitcnt vmcnt(" #n ")" ::: "memory")
; #define PG8_WAIT_L(n) asm volatile("s_waitcnt lgkmcnt(" #n ")" ::: "memory")
; #define PG8_BAR __builtin_amdgcn_s_barrier()
; #define PG8_SCHED __builtin_amdgcn_sched_barrier(0)
; template <int EK, int SK = -1>
; __device__ __forceinline__ void gemm_phase(LAS unsigned char* lds, const bf16_t* A, const bf16_t* Bt, int nM, int N, int K, const EpiArgs& E) {
;     ...
;             PG8_LDB(B0, 1, 0); PG8_LDB(B1, 1, 1); PG8_SCHED; PG8_LDA(At, 1, 0); PG8_STAGEA(PG8_SA(0, 1), a2 + hstep);
;             PG8_WAIT_V(8); PG8_WAIT_L(0); PG8_BAR; PG8_MMA(0, 0, At, B0); PG8_MMA(0, 1, At, B1); PG8_BAR; PG8_SCHED;
;             PG8_LDA(At, 1, 1); PG8_STAGEB(PG8_SB(1, 0), b3); PG8_STAGEB(PG8_SB(1, 1), b3 + hstep); PG8_STAGEA(PG8_SA(1, 0), a3);
;             PG8_WAIT_V(8); PG8_WAIT_L(0); PG8_BAR; PG8_MMA(1, 0, At, B0); PG8_MMA(1, 1, At, B1); PG8_BAR; PG8_SCHED;
;         }
	s_add_i32 s77, 0, 0x18000
	s_add_i32 s78, 0, 0x1c000
	v_add_u32_e32 v168, s77, v152
	v_add_u32_e32 v184, s78, v152
	ds_read_b128 v[156:159], v168
	ds_read_b128 v[160:163], v168 offset:1024
	ds_read_b128 v[164:167], v168 offset:2048
	ds_read_b128 v[168:171], v168 offset:3072
	ds_read_b128 v[172:175], v184
	ds_read_b128 v[176:179], v184 offset:1024
	ds_read_b128 v[180:183], v184 offset:2048
	ds_read_b128 v[184:187], v184 offset:3072
	s_add_u32 s50, s50, 0x40000
	s_addc_u32 s51, s51, 0
	s_mov_b32 m0, s55
	v_lshl_add_u64 v[226:227], s[50:51], 0, v[130:131]
	ds_read_b128 v[188:191], v154 offset:32768
	ds_read_b128 v[192:195], v154 offset:33792
	ds_read_b128 v[196:199], v154 offset:34816
	ds_read_b128 v[200:203], v154 offset:35840
	ds_read_b128 v[204:207], v154 offset:36864
	ds_read_b128 v[208:211], v154 offset:37888
	ds_read_b128 v[212:215], v154 offset:38912
	ds_read_b128 v[216:219], v154 offset:39936
	global_load_lds_dwordx4 v[226:227], off
	v_lshl_add_u64 v[226:227], s[50:51], 0, v[134:135]
	s_mov_b32 m0, s56
	s_nop 0
	global_load_lds_dwordx4 v[226:227], off
	s_waitcnt vmcnt(8)
	s_waitcnt lgkmcnt(0)
	s_waitcnt lgkmcnt(0)
	v_mfma_f32_16x16x32_bf16 v[126:129], v[156:159], v[188:191], v[126:129]
	v_mfma_f32_16x16x32_bf16 v[122:125], v[164:167], v[188:191], v[122:125]
	v_mfma_f32_16x16x32_bf16 v[118:121], v[156:159], v[196:199], v[118:121]
	v_mfma_f32_16x16x32_bf16 v[114:117], v[164:167], v[196:199], v[114:117]
	s_barrier
	v_mfma_f32_16x16x32_bf16 v[110:113], v[156:159], v[204:207], v[110:113]
	v_mfma_f32_16x16x32_bf16 v[106:109], v[164:167], v[204:207], v[106:109]
	v_mfma_f32_16x16x32_bf16 v[102:105], v[156:159], v[212:215], v[102:105]
	v_mfma_f32_16x16x32_bf16 v[98:101], v[164:167], v[212:215], v[98:101]
	v_mfma_f32_16x16x32_bf16 v[126:129], v[160:163], v[192:195], v[126:129]
	v_mfma_f32_16x16x32_bf16 v[122:125], v[168:171], v[192:195], v[122:125]
	v_mfma_f32_16x16x32_bf16 v[118:121], v[160:163], v[200:203], v[118:121]
	v_mfma_f32_16x16x32_bf16 v[114:117], v[168:171], v[200:203], v[114:117]
	v_mfma_f32_16x16x32_bf16 v[110:113], v[160:163], v[208:211], v[110:113]
	v_mfma_f32_16x16x32_bf16 v[106:109], v[168:171], v[208:211], v[106:109]
	v_mfma_f32_16x16x32_bf16 v[102:105], v[160:163], v[216:219], v[102:105]
	v_mfma_f32_16x16x32_bf16 v[98:101], v[168:171], v[216:219], v[98:101]
	v_mfma_f32_16x16x32_bf16 v[94:97], v[172:175], v[188:191], v[94:97]
	v_mfma_f32_16x16x32_bf16 v[90:93], v[180:183], v[188:191], v[90:93]
	v_mfma_f32_16x16x32_bf16 v[86:89], v[172:175], v[196:199], v[86:89]
	v_mfma_f32_16x16x32_bf16 v[82:85], v[180:183], v[196:199], v[82:85]
	v_mfma_f32_16x16x32_bf16 v[78:81], v[172:175], v[204:207], v[78:81]
	v_mfma_f32_16x16x32_bf16 v[74:77], v[180:183], v[204:207], v[74:77]
	v_mfma_f32_16x16x32_bf16 v[70:73], v[172:175], v[212:215], v[70:73]
	v_mfma_f32_16x16x32_bf16 v[66:69], v[180:183], v[212:215], v[66:69]
	v_mfma_f32_16x16x32_bf16 v[94:97], v[176:179], v[192:195], v[94:97]
	v_mfma_f32_16x16x32_bf16 v[90:93], v[184:187], v[192:195], v[90:93]
	v_mfma_f32_16x16x32_bf16 v[86:89], v[176:179], v[200:203], v[86:89]
	v_mfma_f32_16x16x32_bf16 v[82:85], v[184:187], v[200:203], v[82:85]
	v_mfma_f32_16x16x32_bf16 v[78:81], v[176:179], v[208:211], v[78:81]
	v_mfma_f32_16x16x32_bf16 v[74:77], v[184:187], v[208:211], v[74:77]
	v_mfma_f32_16x16x32_bf16 v[70:73], v[176:179], v[216:219], v[70:73]
	v_mfma_f32_16x16x32_bf16 v[66:69], v[184:187], v[216:219], v[66:69]
	s_barrier
	s_add_i32 s50, s77, s54
	v_lshl_add_u64 v[150:151], v[150:151], 0, s[26:27]
	s_mov_b32 m0, s50
	ds_read_b128 v[188:191], v154 offset:49152
	ds_read_b128 v[192:195], v154 offset:50176
	ds_read_b128 v[196:199], v154 offset:51200
	ds_read_b128 v[200:203], v154 offset:52224
	ds_read_b128 v[204:207], v154 offset:53248
	ds_read_b128 v[208:211], v154 offset:54272
	ds_read_b128 v[212:215], v154 offset:55296
	ds_read_b128 v[216:219], v154 offset:56320
	global_load_lds_dwordx4 v[150:151], off
	s_add_i32 m0, s50, 0x2000
	s_add_u32 s48, s48, 0x40080
	v_lshl_add_u64 v[150:151], v[220:221], 0, s[26:27]
	s_addc_u32 s49, s49, 0
	s_add_i32 s50, s78, s54
	global_load_lds_dwordx4 v[150:151], off
	v_lshl_add_u64 v[150:151], s[48:49], 0, v[132:133]
	s_mov_b32 m0, s50
	s_nop 0
	global_load_lds_dwordx4 v[150:151], off
	v_lshl_add_u64 v[150:151], s[48:49], 0, v[136:137]
	s_add_i32 m0, s50, 0x2000
	s_nop 0
	global_load_lds_dwordx4 v[150:151], off
	v_lshl_add_u64 v[150:151], v[222:223], 0, s[26:27]
	s_mov_b32 m0, s59
	s_nop 0
	global_load_lds_dwordx4 v[150:151], off
	v_lshl_add_u64 v[150:151], v[224:225], 0, s[26:27]
	s_mov_b32 m0, s68
	s_nop 0
	global_load_lds_dwordx4 v[150:151], off
	s_waitcnt vmcnt(8)
	s_waitcnt lgkmcnt(0)
	s_waitcnt lgkmcnt(0)
	v_mfma_f32_16x16x32_bf16 v[62:65], v[156:159], v[188:191], v[62:65]
	v_mfma_f32_16x16x32_bf16 v[58:61], v[164:167], v[188:191], v[58:61]
	v_mfma_f32_16x16x32_bf16 v[54:57], v[156:159], v[196:199], v[54:57]
	v_mfma_f32_16x16x32_bf16 v[50:53], v[164:167], v[196:199], v[50:53]
	s_barrier
	v_mfma_f32_16x16x32_bf16 v[46:49], v[156:159], v[204:207], v[46:49]
	v_mfma_f32_16x16x32_bf16 v[42:45], v[164:167], v[204:207], v[42:45]
	v_mfma_f32_16x16x32_bf16 v[38:41], v[156:159], v[212:215], v[38:41]
	v_mfma_f32_16x16x32_bf16 v[34:37], v[164:167], v[212:215], v[34:37]
	v_mfma_f32_16x16x32_bf16 v[62:65], v[160:163], v[192:195], v[62:65]
	v_mfma_f32_16x16x32_bf16 v[58:61], v[168:171], v[192:195], v[58:61]
	v_mfma_f32_16x16x32_bf16 v[54:57], v[160:163], v[200:203], v[54:57]
	v_mfma_f32_16x16x32_bf16 v[50:53], v[168:171], v[200:203], v[50:53]
	v_mfma_f32_16x16x32_bf16 v[46:49], v[160:163], v[208:211], v[46:49]
	v_mfma_f32_16x16x32_bf16 v[42:45], v[168:171], v[208:211], v[42:45]
	v_mfma_f32_16x16x32_bf16 v[38:41], v[160:163], v[216:219], v[38:41]
	v_mfma_f32_16x16x32_bf16 v[34:37], v[168:171], v[216:219], v[34:37]
	v_mfma_f32_16x16x32_bf16 v[30:33], v[172:175], v[188:191], v[30:33]
	v_mfma_f32_16x16x32_bf16 v[26:29], v[180:183], v[188:191], v[26:29]
	v_mfma_f32_16x16x32_bf16 v[22:25], v[172:175], v[196:199], v[22:25]
	v_mfma_f32_16x16x32_bf16 v[18:21], v[180:183], v[196:199], v[18:21]
	v_mfma_f32_16x16x32_bf16 v[14:17], v[172:175], v[204:207], v[14:17]
	v_mfma_f32_16x16x32_bf16 v[10:13], v[180:183], v[204:207], v[10:13]
	v_mfma_f32_16x16x32_bf16 v[6:9], v[172:175], v[212:215], v[6:9]
	v_mfma_f32_16x16x32_bf16 v[2:5], v[180:183], v[212:215], v[2:5]
	v_mfma_f32_16x16x32_bf16 v[30:33], v[176:179], v[192:195], v[30:33]
	v_mfma_f32_16x16x32_bf16 v[26:29], v[184:187], v[192:195], v[26:29]
	v_mfma_f32_16x16x32_bf16 v[22:25], v[176:179], v[200:203], v[22:25]
	v_mfma_f32_16x16x32_bf16 v[18:21], v[184:187], v[200:203], v[18:21]
	v_mfma_f32_16x16x32_bf16 v[14:17], v[176:179], v[208:211], v[14:17]
	v_mfma_f32_16x16x32_bf16 v[10:13], v[184:187], v[208:211], v[10:13]
	v_mfma_f32_16x16x32_bf16 v[6:9], v[176:179], v[216:219], v[6:9]
	v_mfma_f32_16x16x32_bf16 v[2:5], v[184:187], v[216:219], v[2:5]
	s_barrier
	s_add_i32 s76, s76, 2
	s_add_u32 s46, s46, 0x100
	s_addc_u32 s47, s47, 0
	s_cmp_gt_u32 s76, 13
	s_cbranch_scc0 .LBB0_1120

; #define PG8_STAGEA(bufoff, gbase) PG8_STAGE_(bufoff, gbase, voffA)
; #define PG8_STAGEB(bufoff, gbase) PG8_STAGE_(bufoff, gbase, voffB)
; #define PG8_LDA(dst, b, h) do { _Pragma("unroll") for (int m = 0; m < 4; ++m) _Pragma("unroll") for (int k = 0; k < 2; ++k) dst[m][k] = *(const LAS bf16x8*)(lds + PG8_SA(b, h) + aoff + m * 2048 + k * 1024); } while (0)
; #define PG8_LDB(dst, b, h) do { _Pragma("unroll") for (int n = 0; n < 2; ++n) _Pragma("unroll") for (int k = 0; k < 2; ++k) dst[n][k] = *(const LAS bf16x8*)(lds + PG8_SB(b, h) + boff + n * 2048 + k * 1024); } while (0)
; #define PG8_MMA(ai, bj, At, Bt_) do { __builtin_amdgcn_s_setprio(1); _Pragma("unroll") for (int m = 0; m < 4; ++m) _Pragma("unroll") for (int n = 0; n < 2; ++n) _Pragma("unroll") for (int k = 0; k < 2; ++k) \
;         acc[ai][bj][m][n] = __builtin_amdgcn_mfma_f32_16x16x32_bf16(Bt_[n][k], At[m][k], acc[ai][bj][m][n], 0, 0, 0); __builtin_amdgcn_s_setprio(0); } while (0)
; #define PG8_WAIT_V(n) asm volatile("s_waitcnt vmcnt(" #n ")" ::: "memory")
; #define PG8_WAIT_L(n) asm volatile("s_waitcnt lgkmcnt(" #n ")" ::: "memory")
; #define PG8_BAR __builtin_amdgcn_s_barrier()
; template <int EK, int SK = -1>
; __device__ __forceinline__ void gemm_phase(LAS unsigned char* lds, const bf16_t* A, const bf16_t* Bt, int nM, int N, int K, const EpiArgs& E) {
;     ...
;         const bool has_next = S.next(ui + 1, nxt);
;         const char* nA = has_next ? (const char*)A + (size_t)nxt.pm * tstep : cA; const char* nB = has_next ? (const char*)Bt + (size_t)nxt.pn * tstep : cB;
;         for (int t = 0; t < nt; t += 2) {
;             const bool last = (t == nt - 2);
;             const char* a1 = cA + (size_t)(t + 1) * kstep;
;             const char* a2 = last ? nA : cA + (size_t)(t + 2) * kstep; const char* b2 = last ? nB : cB + (size_t)(t + 2) * kstep;
;             const char* a3 = a2 + kstep; const char* b3 = b2 + kstep;
;             PG8_LDB(B0, 0, 0); PG8_LDB(B1, 0, 1); PG8_SCHED; PG8_LDA(At, 0, 0); PG8_STAGEA(PG8_SA(1, 1), a1 + hstep);
;             PG8_WAIT_V(8); PG8_WAIT_L(0); PG8_BAR; PG8_MMA(0, 0, At, B0); PG8_MMA(0, 1, At, B1); PG8_BAR; PG8_SCHED;
;             PG8_LDA(At, 0, 1); PG8_STAGEB(PG8_SB(0, 0), b2); PG8_STAGEB(PG8_SB(0, 1), b2 + hstep); PG8_STAGEA(PG8_SA(0, 0), a2);
;             PG8_WAIT_V(8); PG8_WAIT_L(0); PG8_BAR; PG8_MMA(1, 0, At, B0); PG8_MMA(1, 1, At, B1); PG8_BAR; PG8_SCHED;
.LBB0_1244:
	s_add_u32 s59, s40, 0x100
	s_addc_u32 s66, s41, 0
	s_ashr_i32 s27, s26, 31
	s_lshl_b64 s[36:37], s[26:27], 19
	s_add_u32 s38, s62, s36
	s_addc_u32 s39, s63, s37
	s_and_b64 s[36:37], s[6:7], exec
	s_cselect_b32 s27, s39, s21
	s_cselect_b32 s67, s38, s20
	s_ashr_i32 s23, s22, 31
	s_lshl_b64 s[36:37], s[22:23], 19
	s_add_u32 s36, s47, s36
	s_addc_u32 s37, s48, s37
	s_and_b64 s[42:43], s[6:7], exec
	s_cselect_b32 s23, s37, s41
	s_cselect_b32 s68, s36, s40
	v_lshl_add_u64 v[146:147], s[20:21], 0, v[138:139]
	v_lshl_add_u64 v[148:149], s[20:21], 0, v[140:141]
	s_mov_b32 s69, -2
	s_mov_b64 s[40:41], 0
	v_add_u32_e32 v154, s54, v156
	ds_read_b128 v[150:153], v154
	ds_read_b128 v[160:163], v154 offset:1024
	ds_read_b128 v[164:167], v154 offset:2048
	ds_read_b128 v[168:171], v154 offset:3072
	v_add_u32_e32 v154, s55, v156
	s_add_u32 s42, s20, s40
	ds_read_b128 v[172:175], v154
	ds_read_b128 v[176:179], v154 offset:1024
	ds_read_b128 v[180:183], v154 offset:2048
	ds_read_b128 v[184:187], v154 offset:3072
	s_addc_u32 s43, s21, s41
	s_add_u32 s42, s42, 0x100
	s_addc_u32 s43, s43, 0
	s_add_u32 s70, s59, s40
	s_addc_u32 s71, s66, s41
	s_cmpk_eq_i32 s40, 0x700
	s_cselect_b32 s45, s27, s43
	s_cselect_b32 s44, s67, s42
	s_cselect_b32 s43, s23, s71
	s_cselect_b32 s42, s68, s70
	v_lshl_add_u64 v[154:155], v[146:147], 0, s[40:41]
	s_add_i32 m0, s17, 0xc000
	ds_read_b128 v[188:191], v159
	ds_read_b128 v[192:195], v159 offset:1024
	ds_read_b128 v[196:199], v159 offset:2048
	ds_read_b128 v[200:203], v159 offset:3072
	ds_read_b128 v[204:207], v159 offset:4096
	ds_read_b128 v[208:211], v159 offset:5120
	ds_read_b128 v[212:215], v159 offset:6144
	ds_read_b128 v[216:219], v159 offset:7168
	global_load_lds_dwordx4 v[154:155], off
	v_lshl_add_u64 v[154:155], v[148:149], 0, s[40:41]
	s_add_i32 m0, s17, 0xe000
	s_nop 0
	global_load_lds_dwordx4 v[154:155], off
	s_waitcnt vmcnt(8)
	s_waitcnt lgkmcnt(0)
	s_waitcnt lgkmcnt(0)
	v_mfma_f32_16x16x32_bf16 v[110:113], v[150:153], v[188:191], 0
	v_mfma_f32_16x16x32_bf16 v[106:109], v[164:167], v[188:191], 0
	v_mfma_f32_16x16x32_bf16 v[102:105], v[150:153], v[196:199], 0
	v_mfma_f32_16x16x32_bf16 v[98:101], v[164:167], v[196:199], 0
	s_barrier
	v_mfma_f32_16x16x32_bf16 v[94:97], v[150:153], v[204:207], 0
	v_mfma_f32_16x16x32_bf16 v[90:93], v[164:167], v[204:207], 0
	v_mfma_f32_16x16x32_bf16 v[86:89], v[150:153], v[212:215], 0
	v_mfma_f32_16x16x32_bf16 v[82:85], v[164:167], v[212:215], 0
	v_mfma_f32_16x16x32_bf16 v[110:113], v[160:163], v[192:195], v[110:113]
	v_mfma_f32_16x16x32_bf16 v[106:109], v[168:171], v[192:195], v[106:109]
	v_mfma_f32_16x16x32_bf16 v[102:105], v[160:163], v[200:203], v[102:105]
	v_mfma_f32_16x16x32_bf16 v[98:101], v[168:171], v[200:203], v[98:101]
	v_mfma_f32_16x16x32_bf16 v[94:97], v[160:163], v[208:211], v[94:97]
	v_mfma_f32_16x16x32_bf16 v[90:93], v[168:171], v[208:211], v[90:93]
	v_mfma_f32_16x16x32_bf16 v[86:89], v[160:163], v[216:219], v[86:89]
	v_mfma_f32_16x16x32_bf16 v[82:85], v[168:171], v[216:219], v[82:85]
	v_mfma_f32_16x16x32_bf16 v[78:81], v[172:175], v[188:191], 0
	v_mfma_f32_16x16x32_bf16 v[74:77], v[180:183], v[188:191], 0
	v_mfma_f32_16x16x32_bf16 v[70:73], v[172:175], v[196:199], 0
	v_mfma_f32_16x16x32_bf16 v[66:69], v[180:183], v[196:199], 0
	v_mfma_f32_16x16x32_bf16 v[62:65], v[172:175], v[204:207], 0
	v_mfma_f32_16x16x32_bf16 v[58:61], v[180:183], v[204:207], 0
	v_mfma_f32_16x16x32_bf16 v[54:57], v[172:175], v[212:215], 0
	v_mfma_f32_16x16x32_bf16 v[50:53], v[180:183], v[212:215], 0
	v_mfma_f32_16x16x32_bf16 v[78:81], v[176:179], v[192:195], v[78:81]
	v_mfma_f32_16x16x32_bf16 v[74:77], v[184:187], v[192:195], v[74:77]
	v_mfma_f32_16x16x32_bf16 v[70:73], v[176:179], v[200:203], v[70:73]
	v_mfma_f32_16x16x32_bf16 v[66:69], v[184:187], v[200:203], v[66:69]
	v_mfma_f32_16x16x32_bf16 v[62:65], v[176:179], v[208:211], v[62:65]
	v_mfma_f32_16x16x32_bf16 v[58:61], v[184:187], v[208:211], v[58:61]
	v_mfma_f32_16x16x32_bf16 v[54:57], v[176:179], v[216:219], v[54:57]
	v_mfma_f32_16x16x32_bf16 v[50:53], v[184:187], v[216:219], v[50:53]
	s_barrier
	s_add_i32 s70, s54, s49
	v_lshl_add_u64 v[154:155], s[42:43], 0, v[132:133]
	s_mov_b32 m0, s70
	ds_read_b128 v[188:191], v159 offset:16384
	ds_read_b128 v[192:195], v159 offset:17408
	ds_read_b128 v[196:199], v159 offset:18432
	ds_read_b128 v[200:203], v159 offset:19456
	ds_read_b128 v[204:207], v159 offset:20480
	ds_read_b128 v[208:211], v159 offset:21504
	ds_read_b128 v[212:215], v159 offset:22528
	ds_read_b128 v[216:219], v159 offset:23552
	global_load_lds_dwordx4 v[154:155], off
	s_add_i32 m0, s70, 0x2000
	s_add_u32 s70, s42, 0x40000
	v_lshl_add_u64 v[220:221], s[42:43], 0, v[136:137]
	s_addc_u32 s71, s43, 0
	s_add_i32 s72, s55, s49
	global_load_lds_dwordx4 v[220:221], off
	v_lshl_add_u64 v[222:223], s[70:71], 0, v[132:133]
	s_mov_b32 m0, s72
	v_lshl_add_u64 v[224:225], s[44:45], 0, v[134:135]
	global_load_lds_dwordx4 v[222:223], off
	v_lshl_add_u64 v[222:223], s[70:71], 0, v[136:137]
	s_add_i32 m0, s72, 0x2000
	s_nop 0
	global_load_lds_dwordx4 v[222:223], off
	v_lshl_add_u64 v[222:223], s[44:45], 0, v[130:131]
	s_mov_b32 m0, s17
	s_nop 0
	global_load_lds_dwordx4 v[222:223], off
	s_mov_b32 m0, s19
	s_nop 0
	global_load_lds_dwordx4 v[224:225], off
	s_waitcnt vmcnt(8)
	s_waitcnt lgkmcnt(0)
	s_waitcnt lgkmcnt(0)
	v_mfma_f32_16x16x32_bf16 v[46:49], v[150:153], v[188:191], 0
	v_mfma_f32_16x16x32_bf16 v[42:45], v[164:167], v[188:191], 0
	v_mfma_f32_16x16x32_bf16 v[38:41], v[150:153], v[196:199], 0
	v_mfma_f32_16x16x32_bf16 v[34:37], v[164:167], v[196:199], 0
	s_barrier
; #define PG8_STAGEA(bufoff, gbase) PG8_STAGE_(bufoff, gbase, voffA)
; #define PG8_STAGEB(bufoff, gbase) PG8_STAGE_(bufoff, gbase, voffB)
; #define PG8_LDA(dst, b, h) do { _Pragma("unroll") for (int m = 0; m < 4; ++m) _Pragma("unroll") for (int k = 0; k < 2; ++k) dst[m][k] = *(const LAS bf16x8*)(lds + PG8_SA(b, h) + aoff + m * 2048 + k * 1024); } while (0)
; #define PG8_LDB(dst, b, h) do { _Pragma("unroll") for (int n = 0; n < 2; ++n) _Pragma("unroll") for (int k = 0; k < 2; ++k) dst[n][k] = *(const LAS bf16x8*)(lds + PG8_SB(b, h) + boff + n * 2048 + k * 1024); } while (0)
; #define PG8_MMA(ai, bj, At, Bt_) do { __builtin_amdgcn_s_setprio(1); _Pragma("unroll") for (int m = 0; m < 4; ++m) _Pragma("unroll") for (int n = 0; n < 2; ++n) _Pragma("unroll") for (int k = 0; k < 2; ++k) \
;         acc[ai][bj][m][n] = __builtin_amdgcn_mfma_f32_16x16x32_bf16(Bt_[n][k], At[m][k], acc[ai][bj][m][n], 0, 0, 0); __builtin_amdgcn_s_setprio(0); } while (0)
; #define PG8_WAIT_V(n) asm volatile("s_waitcnt vmcnt(" #n ")" ::: "memory")
; #define PG8_WAIT_L(n) asm volatile("s_waitcnt lgkmcnt(" #n ")" ::: "memory")
; #define PG8_BAR __builtin_amdgcn_s_barrier()
; #define PG8_SCHED __builtin_amdgcn_sched_barrier(0)
; template <int EK, int SK = -1>
; __device__ __forceinline__ void gemm_phase(LAS unsigned char* lds, const bf16_t* A, const bf16_t* Bt, int nM, int N, int K, const EpiArgs& E) {
;     ...
;             PG8_WAIT_V(8); PG8_WAIT_L(0); PG8_BAR; PG8_MMA(1, 0, At, B0); PG8_MMA(1, 1, At, B1); PG8_BAR; PG8_SCHED;
;             PG8_LDB(B0, 1, 0); PG8_LDB(B1, 1, 1); PG8_SCHED; PG8_LDA(At, 1, 0); PG8_STAGEA(PG8_SA(0, 1), a2 + hstep);
;             PG8_WAIT_V(8); PG8_WAIT_L(0); PG8_BAR; PG8_MMA(0, 0, At, B0); PG8_MMA(0, 1, At, B1); PG8_BAR; PG8_SCHED;
;             PG8_LDA(At, 1, 1); PG8_STAGEB(PG8_SB(1, 0), b3); PG8_STAGEB(PG8_SB(1, 1), b3 + hstep); PG8_STAGEA(PG8_SA(1, 0), a3);
	v_mfma_f32_16x16x32_bf16 v[30:33], v[150:153], v[204:207], 0
	v_mfma_f32_16x16x32_bf16 v[26:29], v[164:167], v[204:207], 0
	v_mfma_f32_16x16x32_bf16 v[22:25], v[150:153], v[212:215], 0
	v_mfma_f32_16x16x32_bf16 v[18:21], v[164:167], v[212:215], 0
	v_mfma_f32_16x16x32_bf16 v[46:49], v[160:163], v[192:195], v[46:49]
	v_mfma_f32_16x16x32_bf16 v[42:45], v[168:171], v[192:195], v[42:45]
	v_mfma_f32_16x16x32_bf16 v[38:41], v[160:163], v[200:203], v[38:41]
	v_mfma_f32_16x16x32_bf16 v[34:37], v[168:171], v[200:203], v[34:37]
	v_mfma_f32_16x16x32_bf16 v[30:33], v[160:163], v[208:211], v[30:33]
	v_mfma_f32_16x16x32_bf16 v[26:29], v[168:171], v[208:211], v[26:29]
	v_mfma_f32_16x16x32_bf16 v[22:25], v[160:163], v[216:219], v[22:25]
	v_mfma_f32_16x16x32_bf16 v[18:21], v[168:171], v[216:219], v[18:21]
	v_mfma_f32_16x16x32_bf16 v[14:17], v[172:175], v[188:191], 0
	v_mfma_f32_16x16x32_bf16 v[10:13], v[180:183], v[188:191], 0
	v_mfma_f32_16x16x32_bf16 v[6:9], v[172:175], v[196:199], 0
	v_mfma_f32_16x16x32_bf16 v[2:5], v[180:183], v[196:199], 0
	v_mfma_f32_16x16x32_bf16 v[114:117], v[172:175], v[204:207], 0
	v_mfma_f32_16x16x32_bf16 v[118:121], v[180:183], v[204:207], 0
	v_mfma_f32_16x16x32_bf16 v[122:125], v[172:175], v[212:215], 0
	v_mfma_f32_16x16x32_bf16 v[126:129], v[180:183], v[212:215], 0
	v_mfma_f32_16x16x32_bf16 v[14:17], v[176:179], v[192:195], v[14:17]
	v_mfma_f32_16x16x32_bf16 v[10:13], v[184:187], v[192:195], v[10:13]
	v_mfma_f32_16x16x32_bf16 v[6:9], v[176:179], v[200:203], v[6:9]
	v_mfma_f32_16x16x32_bf16 v[2:5], v[184:187], v[200:203], v[2:5]
	v_mfma_f32_16x16x32_bf16 v[114:117], v[176:179], v[208:211], v[114:117]
	v_mfma_f32_16x16x32_bf16 v[118:121], v[184:187], v[208:211], v[118:121]
	v_mfma_f32_16x16x32_bf16 v[122:125], v[176:179], v[216:219], v[122:125]
	v_mfma_f32_16x16x32_bf16 v[126:129], v[184:187], v[216:219], v[126:129]
	s_barrier
	s_add_i32 s70, 0, 0x18000
	s_add_i32 s71, 0, 0x1c000
	v_add_u32_e32 v168, s70, v156
	v_add_u32_e32 v184, s71, v156
	ds_read_b128 v[150:153], v168
	ds_read_b128 v[160:163], v168 offset:1024
	ds_read_b128 v[164:167], v168 offset:2048
	ds_read_b128 v[168:171], v168 offset:3072
	ds_read_b128 v[172:175], v184
	ds_read_b128 v[176:179], v184 offset:1024
	ds_read_b128 v[180:183], v184 offset:2048
	ds_read_b128 v[184:187], v184 offset:3072
	s_add_u32 s44, s44, 0x40000
	s_addc_u32 s45, s45, 0
	s_mov_b32 m0, s50
	v_lshl_add_u64 v[226:227], s[44:45], 0, v[130:131]
	ds_read_b128 v[188:191], v159 offset:32768
	ds_read_b128 v[192:195], v159 offset:33792
	ds_read_b128 v[196:199], v159 offset:34816
	ds_read_b128 v[200:203], v159 offset:35840
	ds_read_b128 v[204:207], v159 offset:36864
	ds_read_b128 v[208:211], v159 offset:37888
	ds_read_b128 v[212:215], v159 offset:38912
	ds_read_b128 v[216:219], v159 offset:39936
	global_load_lds_dwordx4 v[226:227], off
	v_lshl_add_u64 v[226:227], s[44:45], 0, v[134:135]
	s_mov_b32 m0, s51
	s_nop 0
	global_load_lds_dwordx4 v[226:227], off
	s_waitcnt vmcnt(8)
	s_waitcnt lgkmcnt(0)
	s_waitcnt lgkmcnt(0)
	v_mfma_f32_16x16x32_bf16 v[110:113], v[150:153], v[188:191], v[110:113]
	v_mfma_f32_16x16x32_bf16 v[106:109], v[164:167], v[188:191], v[106:109]
	v_mfma_f32_16x16x32_bf16 v[102:105], v[150:153], v[196:199], v[102:105]
	v_mfma_f32_16x16x32_bf16 v[98:101], v[164:167], v[196:199], v[98:101]
	s_barrier
	v_mfma_f32_16x16x32_bf16 v[94:97], v[150:153], v[204:207], v[94:97]
	v_mfma_f32_16x16x32_bf16 v[90:93], v[164:167], v[204:207], v[90:93]
	v_mfma_f32_16x16x32_bf16 v[86:89], v[150:153], v[212:215], v[86:89]
	v_mfma_f32_16x16x32_bf16 v[82:85], v[164:167], v[212:215], v[82:85]
	v_mfma_f32_16x16x32_bf16 v[110:113], v[160:163], v[192:195], v[110:113]
	v_mfma_f32_16x16x32_bf16 v[106:109], v[168:171], v[192:195], v[106:109]
	v_mfma_f32_16x16x32_bf16 v[102:105], v[160:163], v[200:203], v[102:105]
	v_mfma_f32_16x16x32_bf16 v[98:101], v[168:171], v[200:203], v[98:101]
	v_mfma_f32_16x16x32_bf16 v[94:97], v[160:163], v[208:211], v[94:97]
	v_mfma_f32_16x16x32_bf16 v[90:93], v[168:171], v[208:211], v[90:93]
	v_mfma_f32_16x16x32_bf16 v[86:89], v[160:163], v[216:219], v[86:89]
	v_mfma_f32_16x16x32_bf16 v[82:85], v[168:171], v[216:219], v[82:85]
	v_mfma_f32_16x16x32_bf16 v[78:81], v[172:175], v[188:191], v[78:81]
	v_mfma_f32_16x16x32_bf16 v[74:77], v[180:183], v[188:191], v[74:77]
	v_mfma_f32_16x16x32_bf16 v[70:73], v[172:175], v[196:199], v[70:73]
	v_mfma_f32_16x16x32_bf16 v[66:69], v[180:183], v[196:199], v[66:69]
	v_mfma_f32_16x16x32_bf16 v[62:65], v[172:175], v[204:207], v[62:65]
	v_mfma_f32_16x16x32_bf16 v[58:61], v[180:183], v[204:207], v[58:61]
	v_mfma_f32_16x16x32_bf16 v[54:57], v[172:175], v[212:215], v[54:57]
	v_mfma_f32_16x16x32_bf16 v[50:53], v[180:183], v[212:215], v[50:53]
	v_mfma_f32_16x16x32_bf16 v[78:81], v[176:179], v[192:195], v[78:81]
	v_mfma_f32_16x16x32_bf16 v[74:77], v[184:187], v[192:195], v[74:77]
	v_mfma_f32_16x16x32_bf16 v[70:73], v[176:179], v[200:203], v[70:73]
	v_mfma_f32_16x16x32_bf16 v[66:69], v[184:187], v[200:203], v[66:69]
	v_mfma_f32_16x16x32_bf16 v[62:65], v[176:179], v[208:211], v[62:65]
	v_mfma_f32_16x16x32_bf16 v[58:61], v[184:187], v[208:211], v[58:61]
	v_mfma_f32_16x16x32_bf16 v[54:57], v[176:179], v[216:219], v[54:57]
	v_mfma_f32_16x16x32_bf16 v[50:53], v[184:187], v[216:219], v[50:53]
	s_barrier
; #define PG8_STAGEA(bufoff, gbase) PG8_STAGE_(bufoff, gbase, voffA)
; #define PG8_STAGEB(bufoff, gbase) PG8_STAGE_(bufoff, gbase, voffB)
; #define PG8_LDA(dst, b, h) do { _Pragma("unroll") for (int m = 0; m < 4; ++m) _Pragma("unroll") for (int k = 0; k < 2; ++k) dst[m][k] = *(const LAS bf16x8*)(lds + PG8_SA(b, h) + aoff + m * 2048 + k * 1024); } while (0)
; #define PG8_LDB(dst, b, h) do { _Pragma("unroll") for (int n = 0; n < 2; ++n) _Pragma("unroll") for (int k = 0; k < 2; ++k) dst[n][k] = *(const LAS bf16x8*)(lds + PG8_SB(b, h) + boff + n * 2048 + k * 1024); } while (0)
; #define PG8_WAIT_V(n) asm volatile("s_waitcnt vmcnt(" #n ")" ::: "memory")
; #define PG8_WAIT_L(n) asm volatile("s_waitcnt lgkmcnt(" #n ")" ::: "memory")
; #define PG8_BAR __builtin_amdgcn_s_barrier()
; #define PG8_SCHED __builtin_amdgcn_sched_barrier(0)
; template <int EK, int SK = -1>
; __device__ __forceinline__ void gemm_phase(LAS unsigned char* lds, const bf16_t* A, const bf16_t* Bt, int nM, int N, int K, const EpiArgs& E) {
;     ...
;         for (int t = 0; t < nt; t += 2) {
;             const bool last = (t == nt - 2);
;             const char* a1 = cA + (size_t)(t + 1) * kstep;
;             const char* a2 = last ? nA : cA + (size_t)(t + 2) * kstep; const char* b2 = last ? nB : cB + (size_t)(t + 2) * kstep;
;             const char* a3 = a2 + kstep; const char* b3 = b2 + kstep;
;             PG8_LDB(B0, 0, 0); PG8_LDB(B1, 0, 1); PG8_SCHED; PG8_LDA(At, 0, 0); PG8_STAGEA(PG8_SA(1, 1), a1 + hstep);
;             PG8_WAIT_V(8); PG8_WAIT_L(0); PG8_BAR; PG8_MMA(0, 0, At, B0); PG8_MMA(0, 1, At, B1); PG8_BAR; PG8_SCHED;
;             PG8_LDA(At, 0, 1); PG8_STAGEB(PG8_SB(0, 0), b2); PG8_STAGEB(PG8_SB(0, 1), b2 + hstep); PG8_STAGEA(PG8_SA(0, 0), a2);
;             PG8_WAIT_V(8); PG8_WAIT_L(0); PG8_BAR; PG8_MMA(1, 0, At, B0); PG8_MMA(1, 1, At, B1); PG8_BAR; PG8_SCHED;
;             PG8_LDB(B0, 1, 0); PG8_LDB(B1, 1, 1); PG8_SCHED; PG8_LDA(At, 1, 0); PG8_STAGEA(PG8_SA(0, 1), a2 + hstep);
;             PG8_WAIT_V(8); PG8_WAIT_L(0); PG8_BAR; PG8_MMA(0, 0, At, B0); PG8_MMA(0, 1, At, B1); PG8_BAR; PG8_SCHED;
;             PG8_LDA(At, 1, 1); PG8_STAGEB(PG8_SB(1, 0), b3); PG8_STAGEB(PG8_SB(1, 1), b3 + hstep); PG8_STAGEA(PG8_SA(1, 0), a3);
;             PG8_WAIT_V(8); PG8_WAIT_L(0); PG8_BAR; PG8_MMA(1, 0, At, B0); PG8_MMA(1, 1, At, B1); PG8_BAR; PG8_SCHED;
;         }
	s_add_i32 s44, s70, s49
	v_lshl_add_u64 v[154:155], v[154:155], 0, s[10:11]
	s_mov_b32 m0, s44
	ds_read_b128 v[188:191], v159 offset:49152
	ds_read_b128 v[192:195], v159 offset:50176
	ds_read_b128 v[196:199], v159 offset:51200
	ds_read_b128 v[200:203], v159 offset:52224
	ds_read_b128 v[204:207], v159 offset:53248
	ds_read_b128 v[208:211], v159 offset:54272
	ds_read_b128 v[212:215], v159 offset:55296
	ds_read_b128 v[216:219], v159 offset:56320
	global_load_lds_dwordx4 v[154:155], off
	s_add_i32 m0, s44, 0x2000
	s_add_u32 s42, s42, 0x40080
	v_lshl_add_u64 v[154:155], v[220:221], 0, s[10:11]
	s_addc_u32 s43, s43, 0
	s_add_i32 s44, s71, s49
	global_load_lds_dwordx4 v[154:155], off
	v_lshl_add_u64 v[154:155], s[42:43], 0, v[132:133]
	s_mov_b32 m0, s44
	s_nop 0
	global_load_lds_dwordx4 v[154:155], off
	v_lshl_add_u64 v[154:155], s[42:43], 0, v[136:137]
	s_add_i32 m0, s44, 0x2000
	s_nop 0
	global_load_lds_dwordx4 v[154:155], off
	v_lshl_add_u64 v[154:155], v[222:223], 0, s[10:11]
	s_mov_b32 m0, s52
	s_nop 0
	global_load_lds_dwordx4 v[154:155], off
	v_lshl_add_u64 v[154:155], v[224:225], 0, s[10:11]
	s_mov_b32 m0, s53
	s_nop 0
	global_load_lds_dwordx4 v[154:155], off
	s_waitcnt vmcnt(8)
	s_waitcnt lgkmcnt(0)
	s_waitcnt lgkmcnt(0)
	v_mfma_f32_16x16x32_bf16 v[46:49], v[150:153], v[188:191], v[46:49]
	v_mfma_f32_16x16x32_bf16 v[42:45], v[164:167], v[188:191], v[42:45]
	v_mfma_f32_16x16x32_bf16 v[38:41], v[150:153], v[196:199], v[38:41]
	v_mfma_f32_16x16x32_bf16 v[34:37], v[164:167], v[196:199], v[34:37]
	s_barrier
	v_mfma_f32_16x16x32_bf16 v[30:33], v[150:153], v[204:207], v[30:33]
	v_mfma_f32_16x16x32_bf16 v[26:29], v[164:167], v[204:207], v[26:29]
	v_mfma_f32_16x16x32_bf16 v[22:25], v[150:153], v[212:215], v[22:25]
	v_mfma_f32_16x16x32_bf16 v[18:21], v[164:167], v[212:215], v[18:21]
	v_mfma_f32_16x16x32_bf16 v[46:49], v[160:163], v[192:195], v[46:49]
	v_mfma_f32_16x16x32_bf16 v[42:45], v[168:171], v[192:195], v[42:45]
	v_mfma_f32_16x16x32_bf16 v[38:41], v[160:163], v[200:203], v[38:41]
	v_mfma_f32_16x16x32_bf16 v[34:37], v[168:171], v[200:203], v[34:37]
	v_mfma_f32_16x16x32_bf16 v[30:33], v[160:163], v[208:211], v[30:33]
	v_mfma_f32_16x16x32_bf16 v[26:29], v[168:171], v[208:211], v[26:29]
	v_mfma_f32_16x16x32_bf16 v[22:25], v[160:163], v[216:219], v[22:25]
	v_mfma_f32_16x16x32_bf16 v[18:21], v[168:171], v[216:219], v[18:21]
	v_mfma_f32_16x16x32_bf16 v[14:17], v[172:175], v[188:191], v[14:17]
	v_mfma_f32_16x16x32_bf16 v[10:13], v[180:183], v[188:191], v[10:13]
	v_mfma_f32_16x16x32_bf16 v[6:9], v[172:175], v[196:199], v[6:9]
	v_mfma_f32_16x16x32_bf16 v[2:5], v[180:183], v[196:199], v[2:5]
	v_mfma_f32_16x16x32_bf16 v[114:117], v[172:175], v[204:207], v[114:117]
	v_mfma_f32_16x16x32_bf16 v[118:121], v[180:183], v[204:207], v[118:121]
	v_mfma_f32_16x16x32_bf16 v[122:125], v[172:175], v[212:215], v[122:125]
	v_mfma_f32_16x16x32_bf16 v[126:129], v[180:183], v[212:215], v[126:129]
	v_mfma_f32_16x16x32_bf16 v[14:17], v[176:179], v[192:195], v[14:17]
	v_mfma_f32_16x16x32_bf16 v[10:13], v[184:187], v[192:195], v[10:13]
	v_mfma_f32_16x16x32_bf16 v[6:9], v[176:179], v[200:203], v[6:9]
	v_mfma_f32_16x16x32_bf16 v[2:5], v[184:187], v[200:203], v[2:5]
	v_mfma_f32_16x16x32_bf16 v[114:117], v[176:179], v[208:211], v[114:117]
	v_mfma_f32_16x16x32_bf16 v[118:121], v[184:187], v[208:211], v[118:121]
	v_mfma_f32_16x16x32_bf16 v[122:125], v[176:179], v[216:219], v[122:125]
	v_mfma_f32_16x16x32_bf16 v[126:129], v[184:187], v[216:219], v[126:129]
	s_barrier
	s_add_i32 s69, s69, 2
	s_add_u32 s40, s40, 0x100
	s_addc_u32 s41, s41, 0
	s_cmp_gt_u32 s69, 13
	s_cbranch_scc0 .LBB0_1245
	s_branch .Lmy_kexit_6
.LBB0_1245:
	v_add_u32_e32 v154, s54, v156
	ds_read_b128 v[150:153], v154
	ds_read_b128 v[160:163], v154 offset:1024
	ds_read_b128 v[164:167], v154 offset:2048
	ds_read_b128 v[168:171], v154 offset:3072
	v_add_u32_e32 v154, s55, v156
	s_add_u32 s42, s20, s40
	ds_read_b128 v[172:175], v154
	ds_read_b128 v[176:179], v154 offset:1024
	ds_read_b128 v[180:183], v154 offset:2048
	ds_read_b128 v[184:187], v154 offset:3072
	s_addc_u32 s43, s21, s41
	s_add_u32 s42, s42, 0x100
	s_addc_u32 s43, s43, 0
	s_add_u32 s70, s59, s40
	s_addc_u32 s71, s66, s41
	s_cmpk_eq_i32 s40, 0x700
	s_cselect_b32 s45, s27, s43
	s_cselect_b32 s44, s67, s42
	s_cselect_b32 s43, s23, s71
	s_cselect_b32 s42, s68, s70
	v_lshl_add_u64 v[154:155], v[146:147], 0, s[40:41]
	s_add_i32 m0, s17, 0xc000
	ds_read_b128 v[188:191], v159
	ds_read_b128 v[192:195], v159 offset:1024
	ds_read_b128 v[196:199], v159 offset:2048
	ds_read_b128 v[200:203], v159 offset:3072
	ds_read_b128 v[204:207], v159 offset:4096
	ds_read_b128 v[208:211], v159 offset:5120
	ds_read_b128 v[212:215], v159 offset:6144
	ds_read_b128 v[216:219], v159 offset:7168
	global_load_lds_dwordx4 v[154:155], off
	v_lshl_add_u64 v[154:155], v[148:149], 0, s[40:41]
	s_add_i32 m0, s17, 0xe000
	s_nop 0
	global_load_lds_dwordx4 v[154:155], off
	s_waitcnt vmcnt(8)
	s_waitcnt lgkmcnt(0)
	s_waitcnt lgkmcnt(0)
	v_mfma_f32_16x16x32_bf16 v[110:113], v[150:153], v[188:191], v[110:113]
	v_mfma_f32_16x16x32_bf16 v[106:109], v[164:167], v[188:191], v[106:109]
	v_mfma_f32_16x16x32_bf16 v[102:105], v[150:153], v[196:199], v[102:105]
	v_mfma_f32_16x16x32_bf16 v[98:101], v[164:167], v[196:199], v[98:101]
	s_barrier
; #define PG8_STAGEA(bufoff, gbase) PG8_STAGE_(bufoff, gbase, voffA)
; #define PG8_STAGEB(bufoff, gbase) PG8_STAGE_(bufoff, gbase, voffB)
; #define PG8_LDA(dst, b, h) do { _Pragma("unroll") for (int m = 0; m < 4; ++m) _Pragma("unroll") for (int k = 0; k < 2; ++k) dst[m][k] = *(const LAS bf16x8*)(lds + PG8_SA(b, h) + aoff + m * 2048 + k * 1024); } while (0)
; #define PG8_LDB(dst, b, h) do { _Pragma("unroll") for (int n = 0; n < 2; ++n) _Pragma("unroll") for (int k = 0; k < 2; ++k) dst[n][k] = *(const LAS bf16x8*)(lds + PG8_SB(b, h) + boff + n * 2048 + k * 1024); } while (0)
; #define PG8_MMA(ai, bj, At, Bt_) do { __builtin_amdgcn_s_setprio(1); _Pragma("unroll") for (int m = 0; m < 4; ++m) _Pragma("unroll") for (int n = 0; n < 2; ++n) _Pragma("unroll") for (int k = 0; k < 2; ++k) \
;         acc[ai][bj][m][n] = __builtin_amdgcn_mfma_f32_16x16x32_bf16(Bt_[n][k], At[m][k], acc[ai][bj][m][n], 0, 0, 0); __builtin_amdgcn_s_setprio(0); } while (0)
; #define PG8_WAIT_V(n) asm volatile("s_waitcnt vmcnt(" #n ")" ::: "memory")
; #define PG8_WAIT_L(n) asm volatile("s_waitcnt lgkmcnt(" #n ")" ::: "memory")
; #define PG8_BAR __builtin_amdgcn_s_barrier()
; #define PG8_SCHED __builtin_amdgcn_sched_barrier(0)
; template <int EK, int SK = -1>
; __device__ __forceinline__ void gemm_phase(LAS unsigned char* lds, const bf16_t* A, const bf16_t* Bt, int nM, int N, int K, const EpiArgs& E) {
;     ...
;             PG8_LDB(B0, 0, 0); PG8_LDB(B1, 0, 1); PG8_SCHED; PG8_LDA(At, 0, 0); PG8_STAGEA(PG8_SA(1, 1), a1 + hstep);
;             PG8_WAIT_V(8); PG8_WAIT_L(0); PG8_BAR; PG8_MMA(0, 0, At, B0); PG8_MMA(0, 1, At, B1); PG8_BAR; PG8_SCHED;
;             PG8_LDA(At, 0, 1); PG8_STAGEB(PG8_SB(0, 0), b2); PG8_STAGEB(PG8_SB(0, 1), b2 + hstep); PG8_STAGEA(PG8_SA(0, 0), a2);
;             PG8_WAIT_V(8); PG8_WAIT_L(0); PG8_BAR; PG8_MMA(1, 0, At, B0); PG8_MMA(1, 1, At, B1); PG8_BAR; PG8_SCHED;
	v_mfma_f32_16x16x32_bf16 v[94:97], v[150:153], v[204:207], v[94:97]
	v_mfma_f32_16x16x32_bf16 v[90:93], v[164:167], v[204:207], v[90:93]
	v_mfma_f32_16x16x32_bf16 v[86:89], v[150:153], v[212:215], v[86:89]
	v_mfma_f32_16x16x32_bf16 v[82:85], v[164:167], v[212:215], v[82:85]
	v_mfma_f32_16x16x32_bf16 v[110:113], v[160:163], v[192:195], v[110:113]
	v_mfma_f32_16x16x32_bf16 v[106:109], v[168:171], v[192:195], v[106:109]
	v_mfma_f32_16x16x32_bf16 v[102:105], v[160:163], v[200:203], v[102:105]
	v_mfma_f32_16x16x32_bf16 v[98:101], v[168:171], v[200:203], v[98:101]
	v_mfma_f32_16x16x32_bf16 v[94:97], v[160:163], v[208:211], v[94:97]
	v_mfma_f32_16x16x32_bf16 v[90:93], v[168:171], v[208:211], v[90:93]
	v_mfma_f32_16x16x32_bf16 v[86:89], v[160:163], v[216:219], v[86:89]
	v_mfma_f32_16x16x32_bf16 v[82:85], v[168:171], v[216:219], v[82:85]
	v_mfma_f32_16x16x32_bf16 v[78:81], v[172:175], v[188:191], v[78:81]
	v_mfma_f32_16x16x32_bf16 v[74:77], v[180:183], v[188:191], v[74:77]
	v_mfma_f32_16x16x32_bf16 v[70:73], v[172:175], v[196:199], v[70:73]
	v_mfma_f32_16x16x32_bf16 v[66:69], v[180:183], v[196:199], v[66:69]
	v_mfma_f32_16x16x32_bf16 v[62:65], v[172:175], v[204:207], v[62:65]
	v_mfma_f32_16x16x32_bf16 v[58:61], v[180:183], v[204:207], v[58:61]
	v_mfma_f32_16x16x32_bf16 v[54:57], v[172:175], v[212:215], v[54:57]
	v_mfma_f32_16x16x32_bf16 v[50:53], v[180:183], v[212:215], v[50:53]
	v_mfma_f32_16x16x32_bf16 v[78:81], v[176:179], v[192:195], v[78:81]
	v_mfma_f32_16x16x32_bf16 v[74:77], v[184:187], v[192:195], v[74:77]
	v_mfma_f32_16x16x32_bf16 v[70:73], v[176:179], v[200:203], v[70:73]
	v_mfma_f32_16x16x32_bf16 v[66:69], v[184:187], v[200:203], v[66:69]
	v_mfma_f32_16x16x32_bf16 v[62:65], v[176:179], v[208:211], v[62:65]
	v_mfma_f32_16x16x32_bf16 v[58:61], v[184:187], v[208:211], v[58:61]
	v_mfma_f32_16x16x32_bf16 v[54:57], v[176:179], v[216:219], v[54:57]
	v_mfma_f32_16x16x32_bf16 v[50:53], v[184:187], v[216:219], v[50:53]
	s_barrier
	s_add_i32 s70, s54, s49
	v_lshl_add_u64 v[154:155], s[42:43], 0, v[132:133]
	s_mov_b32 m0, s70
	ds_read_b128 v[188:191], v159 offset:16384
	ds_read_b128 v[192:195], v159 offset:17408
	ds_read_b128 v[196:199], v159 offset:18432
	ds_read_b128 v[200:203], v159 offset:19456
	ds_read_b128 v[204:207], v159 offset:20480
	ds_read_b128 v[208:211], v159 offset:21504
	ds_read_b128 v[212:215], v159 offset:22528
	ds_read_b128 v[216:219], v159 offset:23552
	global_load_lds_dwordx4 v[154:155], off
	s_add_i32 m0, s70, 0x2000
	s_add_u32 s70, s42, 0x40000
	v_lshl_add_u64 v[220:221], s[42:43], 0, v[136:137]
	s_addc_u32 s71, s43, 0
	s_add_i32 s72, s55, s49
	global_load_lds_dwordx4 v[220:221], off
	v_lshl_add_u64 v[222:223], s[70:71], 0, v[132:133]
	s_mov_b32 m0, s72
	v_lshl_add_u64 v[224:225], s[44:45], 0, v[134:135]
	global_load_lds_dwordx4 v[222:223], off
	v_lshl_add_u64 v[222:223], s[70:71], 0, v[136:137]
	s_add_i32 m0, s72, 0x2000
	s_nop 0
	global_load_lds_dwordx4 v[222:223], off
	v_lshl_add_u64 v[222:223], s[44:45], 0, v[130:131]
	s_mov_b32 m0, s17
	s_nop 0
	global_load_lds_dwordx4 v[222:223], off
	s_mov_b32 m0, s19
	s_nop 0
	global_load_lds_dwordx4 v[224:225], off
	s_waitcnt vmcnt(8)
	s_waitcnt lgkmcnt(0)
	s_waitcnt lgkmcnt(0)
	v_mfma_f32_16x16x32_bf16 v[46:49], v[150:153], v[188:191], v[46:49]
	v_mfma_f32_16x16x32_bf16 v[42:45], v[164:167], v[188:191], v[42:45]
	v_mfma_f32_16x16x32_bf16 v[38:41], v[150:153], v[196:199], v[38:41]
	v_mfma_f32_16x16x32_bf16 v[34:37], v[164:167], v[196:199], v[34:37]
	s_barrier
	v_mfma_f32_16x16x32_bf16 v[30:33], v[150:153], v[204:207], v[30:33]
	v_mfma_f32_16x16x32_bf16 v[26:29], v[164:167], v[204:207], v[26:29]
	v_mfma_f32_16x16x32_bf16 v[22:25], v[150:153], v[212:215], v[22:25]
	v_mfma_f32_16x16x32_bf16 v[18:21], v[164:167], v[212:215], v[18:21]
	v_mfma_f32_16x16x32_bf16 v[46:49], v[160:163], v[192:195], v[46:49]
	v_mfma_f32_16x16x32_bf16 v[42:45], v[168:171], v[192:195], v[42:45]
	v_mfma_f32_16x16x32_bf16 v[38:41], v[160:163], v[200:203], v[38:41]
	v_mfma_f32_16x16x32_bf16 v[34:37], v[168:171], v[200:203], v[34:37]
	v_mfma_f32_16x16x32_bf16 v[30:33], v[160:163], v[208:211], v[30:33]
	v_mfma_f32_16x16x32_bf16 v[26:29], v[168:171], v[208:211], v[26:29]
	v_mfma_f32_16x16x32_bf16 v[22:25], v[160:163], v[216:219], v[22:25]
	v_mfma_f32_16x16x32_bf16 v[18:21], v[168:171], v[216:219], v[18:21]
	v_mfma_f32_16x16x32_bf16 v[14:17], v[172:175], v[188:191], v[14:17]
	v_mfma_f32_16x16x32_bf16 v[10:13], v[180:183], v[188:191], v[10:13]
	v_mfma_f32_16x16x32_bf16 v[6:9], v[172:175], v[196:199], v[6:9]
	v_mfma_f32_16x16x32_bf16 v[2:5], v[180:183], v[196:199], v[2:5]
	v_mfma_f32_16x16x32_bf16 v[114:117], v[172:175], v[204:207], v[114:117]
	v_mfma_f32_16x16x32_bf16 v[118:121], v[180:183], v[204:207], v[118:121]
	v_mfma_f32_16x16x32_bf16 v[122:125], v[172:175], v[212:215], v[122:125]
	v_mfma_f32_16x16x32_bf16 v[126:129], v[180:183], v[212:215], v[126:129]
	v_mfma_f32_16x16x32_bf16 v[14:17], v[176:179], v[192:195], v[14:17]
	v_mfma_f32_16x16x32_bf16 v[10:13], v[184:187], v[192:195], v[10:13]
	v_mfma_f32_16x16x32_bf16 v[6:9], v[176:179], v[200:203], v[6:9]
	v_mfma_f32_16x16x32_bf16 v[2:5], v[184:187], v[200:203], v[2:5]
	v_mfma_f32_16x16x32_bf16 v[114:117], v[176:179], v[208:211], v[114:117]
	v_mfma_f32_16x16x32_bf16 v[118:121], v[184:187], v[208:211], v[118:121]
	v_mfma_f32_16x16x32_bf16 v[122:125], v[176:179], v[216:219], v[122:125]
	v_mfma_f32_16x16x32_bf16 v[126:129], v[184:187], v[216:219], v[126:129]
	s_barrier
; #define PG8_STAGEA(bufoff, gbase) PG8_STAGE_(bufoff, gbase, voffA)
; #define PG8_STAGEB(bufoff, gbase) PG8_STAGE_(bufoff, gbase, voffB)
; #define PG8_LDA(dst, b, h) do { _Pragma("unroll") for (int m = 0; m < 4; ++m) _Pragma("unroll") for (int k = 0; k < 2; ++k) dst[m][k] = *(const LAS bf16x8*)(lds + PG8_SA(b, h) + aoff + m * 2048 + k * 1024); } while (0)
; #define PG8_LDB(dst, b, h) do { _Pragma("unroll") for (int n = 0; n < 2; ++n) _Pragma("unroll") for (int k = 0; k < 2; ++k) dst[n][k] = *(const LAS bf16x8*)(lds + PG8_SB(b, h) + boff + n * 2048 + k * 1024); } while (0)
; #define PG8_MMA(ai, bj, At, Bt_) do { __builtin_amdgcn_s_setprio(1); _Pragma("unroll") for (int m = 0; m < 4; ++m) _Pragma("unroll") for (int n = 0; n < 2; ++n) _Pragma("unroll") for (int k = 0; k < 2; ++k) \
;         acc[ai][bj][m][n] = __builtin_amdgcn_mfma_f32_16x16x32_bf16(Bt_[n][k], At[m][k], acc[ai][bj][m][n], 0, 0, 0); __builtin_amdgcn_s_setprio(0); } while (0)
; #define PG8_WAIT_V(n) asm volatile("s_waitcnt vmcnt(" #n ")" ::: "memory")
; #define PG8_WAIT_L(n) asm volatile("s_waitcnt lgkmcnt(" #n ")" ::: "memory")
; #define PG8_BAR __builtin_amdgcn_s_barrier()
; #define PG8_SCHED __builtin_amdgcn_sched_barrier(0)
; template <int EK, int SK = -1>
; __device__ __forceinline__ void gemm_phase(LAS unsigned char* lds, const bf16_t* A, const bf16_t* Bt, int nM, int N, int K, const EpiArgs& E) {
;     ...
;             PG8_LDB(B0, 1, 0); PG8_LDB(B1, 1, 1); PG8_SCHED; PG8_LDA(At, 1, 0); PG8_STAGEA(PG8_SA(0, 1), a2 + hstep);
;             PG8_WAIT_V(8); PG8_WAIT_L(0); PG8_BAR; PG8_MMA(0, 0, At, B0); PG8_MMA(0, 1, At, B1); PG8_BAR; PG8_SCHED;
;             PG8_LDA(At, 1, 1); PG8_STAGEB(PG8_SB(1, 0), b3); PG8_STAGEB(PG8_SB(1, 1), b3 + hstep); PG8_STAGEA(PG8_SA(1, 0), a3);
;             PG8_WAIT_V(8); PG8_WAIT_L(0); PG8_BAR; PG8_MMA(1, 0, At, B0); PG8_MMA(1, 1, At, B1); PG8_BAR; PG8_SCHED;
;         }
	s_add_i32 s70, 0, 0x18000
	s_add_i32 s71, 0, 0x1c000
	v_add_u32_e32 v168, s70, v156
	v_add_u32_e32 v184, s71, v156
	ds_read_b128 v[150:153], v168
	ds_read_b128 v[160:163], v168 offset:1024
	ds_read_b128 v[164:167], v168 offset:2048
	ds_read_b128 v[168:171], v168 offset:3072
	ds_read_b128 v[172:175], v184
	ds_read_b128 v[176:179], v184 offset:1024
	ds_read_b128 v[180:183], v184 offset:2048
	ds_read_b128 v[184:187], v184 offset:3072
	s_add_u32 s44, s44, 0x40000
	s_addc_u32 s45, s45, 0
	s_mov_b32 m0, s50
	v_lshl_add_u64 v[226:227], s[44:45], 0, v[130:131]
	ds_read_b128 v[188:191], v159 offset:32768
	ds_read_b128 v[192:195], v159 offset:33792
	ds_read_b128 v[196:199], v159 offset:34816
	ds_read_b128 v[200:203], v159 offset:35840
	ds_read_b128 v[204:207], v159 offset:36864
	ds_read_b128 v[208:211], v159 offset:37888
	ds_read_b128 v[212:215], v159 offset:38912
	ds_read_b128 v[216:219], v159 offset:39936
	global_load_lds_dwordx4 v[226:227], off
	v_lshl_add_u64 v[226:227], s[44:45], 0, v[134:135]
	s_mov_b32 m0, s51
	s_nop 0
	global_load_lds_dwordx4 v[226:227], off
	s_waitcnt vmcnt(8)
	s_waitcnt lgkmcnt(0)
	s_waitcnt lgkmcnt(0)
	v_mfma_f32_16x16x32_bf16 v[110:113], v[150:153], v[188:191], v[110:113]
	v_mfma_f32_16x16x32_bf16 v[106:109], v[164:167], v[188:191], v[106:109]
	v_mfma_f32_16x16x32_bf16 v[102:105], v[150:153], v[196:199], v[102:105]
	v_mfma_f32_16x16x32_bf16 v[98:101], v[164:167], v[196:199], v[98:101]
	s_barrier
	v_mfma_f32_16x16x32_bf16 v[94:97], v[150:153], v[204:207], v[94:97]
	v_mfma_f32_16x16x32_bf16 v[90:93], v[164:167], v[204:207], v[90:93]
	v_mfma_f32_16x16x32_bf16 v[86:89], v[150:153], v[212:215], v[86:89]
	v_mfma_f32_16x16x32_bf16 v[82:85], v[164:167], v[212:215], v[82:85]
	v_mfma_f32_16x16x32_bf16 v[110:113], v[160:163], v[192:195], v[110:113]
	v_mfma_f32_16x16x32_bf16 v[106:109], v[168:171], v[192:195], v[106:109]
	v_mfma_f32_16x16x32_bf16 v[102:105], v[160:163], v[200:203], v[102:105]
	v_mfma_f32_16x16x32_bf16 v[98:101], v[168:171], v[200:203], v[98:101]
	v_mfma_f32_16x16x32_bf16 v[94:97], v[160:163], v[208:211], v[94:97]
	v_mfma_f32_16x16x32_bf16 v[90:93], v[168:171], v[208:211], v[90:93]
	v_mfma_f32_16x16x32_bf16 v[86:89], v[160:163], v[216:219], v[86:89]
	v_mfma_f32_16x16x32_bf16 v[82:85], v[168:171], v[216:219], v[82:85]
	v_mfma_f32_16x16x32_bf16 v[78:81], v[172:175], v[188:191], v[78:81]
	v_mfma_f32_16x16x32_bf16 v[74:77], v[180:183], v[188:191], v[74:77]
	v_mfma_f32_16x16x32_bf16 v[70:73], v[172:175], v[196:199], v[70:73]
	v_mfma_f32_16x16x32_bf16 v[66:69], v[180:183], v[196:199], v[66:69]
	v_mfma_f32_16x16x32_bf16 v[62:65], v[172:175], v[204:207], v[62:65]
	v_mfma_f32_16x16x32_bf16 v[58:61], v[180:183], v[204:207], v[58:61]
	v_mfma_f32_16x16x32_bf16 v[54:57], v[172:175], v[212:215], v[54:57]
	v_mfma_f32_16x16x32_bf16 v[50:53], v[180:183], v[212:215], v[50:53]
	v_mfma_f32_16x16x32_bf16 v[78:81], v[176:179], v[192:195], v[78:81]
	v_mfma_f32_16x16x32_bf16 v[74:77], v[184:187], v[192:195], v[74:77]
	v_mfma_f32_16x16x32_bf16 v[70:73], v[176:179], v[200:203], v[70:73]
	v_mfma_f32_16x16x32_bf16 v[66:69], v[184:187], v[200:203], v[66:69]
	v_mfma_f32_16x16x32_bf16 v[62:65], v[176:179], v[208:211], v[62:65]
	v_mfma_f32_16x16x32_bf16 v[58:61], v[184:187], v[208:211], v[58:61]
	v_mfma_f32_16x16x32_bf16 v[54:57], v[176:179], v[216:219], v[54:57]
	v_mfma_f32_16x16x32_bf16 v[50:53], v[184:187], v[216:219], v[50:53]
	s_barrier
	s_add_i32 s44, s70, s49
	v_lshl_add_u64 v[154:155], v[154:155], 0, s[10:11]
	s_mov_b32 m0, s44
	ds_read_b128 v[188:191], v159 offset:49152
	ds_read_b128 v[192:195], v159 offset:50176
	ds_read_b128 v[196:199], v159 offset:51200
	ds_read_b128 v[200:203], v159 offset:52224
	ds_read_b128 v[204:207], v159 offset:53248
	ds_read_b128 v[208:211], v159 offset:54272
	ds_read_b128 v[212:215], v159 offset:55296
	ds_read_b128 v[216:219], v159 offset:56320
	global_load_lds_dwordx4 v[154:155], off
	s_add_i32 m0, s44, 0x2000
	s_add_u32 s42, s42, 0x40080
	v_lshl_add_u64 v[154:155], v[220:221], 0, s[10:11]
	s_addc_u32 s43, s43, 0
	s_add_i32 s44, s71, s49
	global_load_lds_dwordx4 v[154:155], off
	v_lshl_add_u64 v[154:155], s[42:43], 0, v[132:133]
	s_mov_b32 m0, s44
	s_nop 0
	global_load_lds_dwordx4 v[154:155], off
	v_lshl_add_u64 v[154:155], s[42:43], 0, v[136:137]
	s_add_i32 m0, s44, 0x2000
	s_nop 0
	global_load_lds_dwordx4 v[154:155], off
	v_lshl_add_u64 v[154:155], v[222:223], 0, s[10:11]
	s_mov_b32 m0, s52
	s_nop 0
	global_load_lds_dwordx4 v[154:155], off
	v_lshl_add_u64 v[154:155], v[224:225], 0, s[10:11]
	s_mov_b32 m0, s53
	s_nop 0
	global_load_lds_dwordx4 v[154:155], off
	s_waitcnt vmcnt(8)
	s_waitcnt lgkmcnt(0)
	s_waitcnt lgkmcnt(0)
	v_mfma_f32_16x16x32_bf16 v[46:49], v[150:153], v[188:191], v[46:49]
	v_mfma_f32_16x16x32_bf16 v[42:45], v[164:167], v[188:191], v[42:45]
	v_mfma_f32_16x16x32_bf16 v[38:41], v[150:153], v[196:199], v[38:41]
	v_mfma_f32_16x16x32_bf16 v[34:37], v[164:167], v[196:199], v[34:37]
	s_barrier
	v_mfma_f32_16x16x32_bf16 v[30:33], v[150:153], v[204:207], v[30:33]
	v_mfma_f32_16x16x32_bf16 v[26:29], v[164:167], v[204:207], v[26:29]
	v_mfma_f32_16x16x32_bf16 v[22:25], v[150:153], v[212:215], v[22:25]
	v_mfma_f32_16x16x32_bf16 v[18:21], v[164:167], v[212:215], v[18:21]
	v_mfma_f32_16x16x32_bf16 v[46:49], v[160:163], v[192:195], v[46:49]
	v_mfma_f32_16x16x32_bf16 v[42:45], v[168:171], v[192:195], v[42:45]
	v_mfma_f32_16x16x32_bf16 v[38:41], v[160:163], v[200:203], v[38:41]
	v_mfma_f32_16x16x32_bf16 v[34:37], v[168:171], v[200:203], v[34:37]
	v_mfma_f32_16x16x32_bf16 v[30:33], v[160:163], v[208:211], v[30:33]
	v_mfma_f32_16x16x32_bf16 v[26:29], v[168:171], v[208:211], v[26:29]
	v_mfma_f32_16x16x32_bf16 v[22:25], v[160:163], v[216:219], v[22:25]
	v_mfma_f32_16x16x32_bf16 v[18:21], v[168:171], v[216:219], v[18:21]
	v_mfma_f32_16x16x32_bf16 v[14:17], v[172:175], v[188:191], v[14:17]
	v_mfma_f32_16x16x32_bf16 v[10:13], v[180:183], v[188:191], v[10:13]
	v_mfma_f32_16x16x32_bf16 v[6:9], v[172:175], v[196:199], v[6:9]
	v_mfma_f32_16x16x32_bf16 v[2:5], v[180:183], v[196:199], v[2:5]
	v_mfma_f32_16x16x32_bf16 v[114:117], v[172:175], v[204:207], v[114:117]
	v_mfma_f32_16x16x32_bf16 v[118:121], v[180:183], v[204:207], v[118:121]
	v_mfma_f32_16x16x32_bf16 v[122:125], v[172:175], v[212:215], v[122:125]
	v_mfma_f32_16x16x32_bf16 v[126:129], v[180:183], v[212:215], v[126:129]
	v_mfma_f32_16x16x32_bf16 v[14:17], v[176:179], v[192:195], v[14:17]
	v_mfma_f32_16x16x32_bf16 v[10:13], v[184:187], v[192:195], v[10:13]
	v_mfma_f32_16x16x32_bf16 v[6:9], v[176:179], v[200:203], v[6:9]
	v_mfma_f32_16x16x32_bf16 v[2:5], v[184:187], v[200:203], v[2:5]
	v_mfma_f32_16x16x32_bf16 v[114:117], v[176:179], v[208:211], v[114:117]
	v_mfma_f32_16x16x32_bf16 v[118:121], v[184:187], v[208:211], v[118:121]
	v_mfma_f32_16x16x32_bf16 v[122:125], v[176:179], v[216:219], v[122:125]
	v_mfma_f32_16x16x32_bf16 v[126:129], v[184:187], v[216:219], v[126:129]
	s_barrier
	s_add_i32 s69, s69, 2
	s_add_u32 s40, s40, 0x100
	s_addc_u32 s41, s41, 0
	s_cmp_gt_u32 s69, 13
	s_cbranch_scc0 .LBB0_1245

; #define PG8_STAGEA(bufoff, gbase) PG8_STAGE_(bufoff, gbase, voffA)
; #define PG8_STAGEB(bufoff, gbase) PG8_STAGE_(bufoff, gbase, voffB)
; #define PG8_LDA(dst, b, h) do { _Pragma("unroll") for (int m = 0; m < 4; ++m) _Pragma("unroll") for (int k = 0; k < 2; ++k) dst[m][k] = *(const LAS bf16x8*)(lds + PG8_SA(b, h) + aoff + m * 2048 + k * 1024); } while (0)
; #define PG8_LDB(dst, b, h) do { _Pragma("unroll") for (int n = 0; n < 2; ++n) _Pragma("unroll") for (int k = 0; k < 2; ++k) dst[n][k] = *(const LAS bf16x8*)(lds + PG8_SB(b, h) + boff + n * 2048 + k * 1024); } while (0)
; #define PG8_MMA(ai, bj, At, Bt_) do { __builtin_amdgcn_s_setprio(1); _Pragma("unroll") for (int m = 0; m < 4; ++m) _Pragma("unroll") for (int n = 0; n < 2; ++n) _Pragma("unroll") for (int k = 0; k < 2; ++k) \
;         acc[ai][bj][m][n] = __builtin_amdgcn_mfma_f32_16x16x32_bf16(Bt_[n][k], At[m][k], acc[ai][bj][m][n], 0, 0, 0); __builtin_amdgcn_s_setprio(0); } while (0)
; #define PG8_WAIT_V(n) asm volatile("s_waitcnt vmcnt(" #n ")" ::: "memory")
; #define PG8_WAIT_L(n) asm volatile("s_waitcnt lgkmcnt(" #n ")" ::: "memory")
; #define PG8_BAR __builtin_amdgcn_s_barrier()
; #define PG8_SCHED __builtin_amdgcn_sched_barrier(0)
; template <int EK, int SK = -1>
; __device__ __forceinline__ void gemm_phase(LAS unsigned char* lds, const bf16_t* A, const bf16_t* Bt, int nM, int N, int K, const EpiArgs& E) {
;     ...
;         for (int t = 0; t < nt; t += 2) {
;             const bool last = (t == nt - 2);
;             const char* a1 = cA + (size_t)(t + 1) * kstep;
;             const char* a2 = last ? nA : cA + (size_t)(t + 2) * kstep; const char* b2 = last ? nB : cB + (size_t)(t + 2) * kstep;
;             const char* a3 = a2 + kstep; const char* b3 = b2 + kstep;
;             PG8_LDB(B0, 0, 0); PG8_LDB(B1, 0, 1); PG8_SCHED; PG8_LDA(At, 0, 0); PG8_STAGEA(PG8_SA(1, 1), a1 + hstep);
;             PG8_WAIT_V(8); PG8_WAIT_L(0); PG8_BAR; PG8_MMA(0, 0, At, B0); PG8_MMA(0, 1, At, B1); PG8_BAR; PG8_SCHED;
;             PG8_LDA(At, 0, 1); PG8_STAGEB(PG8_SB(0, 0), b2); PG8_STAGEB(PG8_SB(0, 1), b2 + hstep); PG8_STAGEA(PG8_SA(0, 0), a2);
;             PG8_WAIT_V(8); PG8_WAIT_L(0); PG8_BAR; PG8_MMA(1, 0, At, B0); PG8_MMA(1, 1, At, B1); PG8_BAR; PG8_SCHED;
.LBB0_1401:
	v_add_u32_e32 v168, s66, v154
	v_add_u32_e32 v184, s67, v154
	s_add_u32 s42, s20, s40
	ds_read_b128 v[156:159], v168
	ds_read_b128 v[160:163], v168 offset:1024
	ds_read_b128 v[164:167], v168 offset:2048
	ds_read_b128 v[168:171], v168 offset:3072
	ds_read_b128 v[172:175], v184
	ds_read_b128 v[176:179], v184 offset:1024
	ds_read_b128 v[180:183], v184 offset:2048
	ds_read_b128 v[184:187], v184 offset:3072
	s_addc_u32 s43, s21, s41
	s_add_u32 s42, s42, 0x100
	s_addc_u32 s43, s43, 0
	s_add_u32 s73, s37, s40
	s_addc_u32 s74, s71, s41
	s_cmpk_eq_i32 s40, 0x1500
	s_cselect_b32 s45, s7, s43
	s_cselect_b32 s44, s6, s42
	s_cselect_b32 s43, s39, s74
	s_cselect_b32 s42, s38, s73
	v_lshl_add_u64 v[220:221], v[146:147], 0, s[40:41]
	s_add_i32 m0, s53, 0xc000
	ds_read_b128 v[188:191], v155
	ds_read_b128 v[192:195], v155 offset:1024
	ds_read_b128 v[196:199], v155 offset:2048
	ds_read_b128 v[200:203], v155 offset:3072
	ds_read_b128 v[204:207], v155 offset:4096
	ds_read_b128 v[208:211], v155 offset:5120
	ds_read_b128 v[212:215], v155 offset:6144
	ds_read_b128 v[216:219], v155 offset:7168
	global_load_lds_dwordx4 v[220:221], off
	v_lshl_add_u64 v[220:221], v[148:149], 0, s[40:41]
	s_add_i32 m0, s53, 0xe000
	s_nop 0
	global_load_lds_dwordx4 v[220:221], off
	s_waitcnt vmcnt(8)
	s_waitcnt lgkmcnt(0)
	s_waitcnt lgkmcnt(0)
	v_mfma_f32_16x16x32_bf16 v[126:129], v[156:159], v[188:191], v[126:129]
	v_mfma_f32_16x16x32_bf16 v[122:125], v[164:167], v[188:191], v[122:125]
	v_mfma_f32_16x16x32_bf16 v[110:113], v[156:159], v[196:199], v[110:113]
	v_mfma_f32_16x16x32_bf16 v[106:109], v[164:167], v[196:199], v[106:109]
	s_barrier
	v_mfma_f32_16x16x32_bf16 v[94:97], v[156:159], v[204:207], v[94:97]
	v_mfma_f32_16x16x32_bf16 v[90:93], v[164:167], v[204:207], v[90:93]
	v_mfma_f32_16x16x32_bf16 v[78:81], v[156:159], v[212:215], v[78:81]
	v_mfma_f32_16x16x32_bf16 v[74:77], v[164:167], v[212:215], v[74:77]
	v_mfma_f32_16x16x32_bf16 v[126:129], v[160:163], v[192:195], v[126:129]
	v_mfma_f32_16x16x32_bf16 v[122:125], v[168:171], v[192:195], v[122:125]
	v_mfma_f32_16x16x32_bf16 v[110:113], v[160:163], v[200:203], v[110:113]
	v_mfma_f32_16x16x32_bf16 v[106:109], v[168:171], v[200:203], v[106:109]
	v_mfma_f32_16x16x32_bf16 v[94:97], v[160:163], v[208:211], v[94:97]
	v_mfma_f32_16x16x32_bf16 v[90:93], v[168:171], v[208:211], v[90:93]
	v_mfma_f32_16x16x32_bf16 v[78:81], v[160:163], v[216:219], v[78:81]
	v_mfma_f32_16x16x32_bf16 v[74:77], v[168:171], v[216:219], v[74:77]
	v_mfma_f32_16x16x32_bf16 v[118:121], v[172:175], v[188:191], v[118:121]
	v_mfma_f32_16x16x32_bf16 v[114:117], v[180:183], v[188:191], v[114:117]
	v_mfma_f32_16x16x32_bf16 v[102:105], v[172:175], v[196:199], v[102:105]
	v_mfma_f32_16x16x32_bf16 v[98:101], v[180:183], v[196:199], v[98:101]
	v_mfma_f32_16x16x32_bf16 v[86:89], v[172:175], v[204:207], v[86:89]
	v_mfma_f32_16x16x32_bf16 v[82:85], v[180:183], v[204:207], v[82:85]
	v_mfma_f32_16x16x32_bf16 v[70:73], v[172:175], v[212:215], v[70:73]
	v_mfma_f32_16x16x32_bf16 v[66:69], v[180:183], v[212:215], v[66:69]
	v_mfma_f32_16x16x32_bf16 v[118:121], v[176:179], v[192:195], v[118:121]
	v_mfma_f32_16x16x32_bf16 v[114:117], v[184:187], v[192:195], v[114:117]
	v_mfma_f32_16x16x32_bf16 v[102:105], v[176:179], v[200:203], v[102:105]
	v_mfma_f32_16x16x32_bf16 v[98:101], v[184:187], v[200:203], v[98:101]
	v_mfma_f32_16x16x32_bf16 v[86:89], v[176:179], v[208:211], v[86:89]
	v_mfma_f32_16x16x32_bf16 v[82:85], v[184:187], v[208:211], v[82:85]
	v_mfma_f32_16x16x32_bf16 v[70:73], v[176:179], v[216:219], v[70:73]
	v_mfma_f32_16x16x32_bf16 v[66:69], v[184:187], v[216:219], v[66:69]
	s_barrier
	s_add_i32 s73, s66, s52
	v_lshl_add_u64 v[220:221], s[42:43], 0, v[132:133]
	s_mov_b32 m0, s73
	ds_read_b128 v[188:191], v155 offset:16384
	ds_read_b128 v[192:195], v155 offset:17408
	ds_read_b128 v[196:199], v155 offset:18432
	ds_read_b128 v[200:203], v155 offset:19456
	ds_read_b128 v[204:207], v155 offset:20480
	ds_read_b128 v[208:211], v155 offset:21504
	ds_read_b128 v[212:215], v155 offset:22528
	ds_read_b128 v[216:219], v155 offset:23552
	global_load_lds_dwordx4 v[220:221], off
	s_add_i32 m0, s73, 0x2000
	s_add_u32 s74, s42, 0xb0000
	v_lshl_add_u64 v[222:223], s[42:43], 0, v[136:137]
	s_addc_u32 s75, s43, 0
	s_add_i32 s73, s67, s52
	global_load_lds_dwordx4 v[222:223], off
	v_lshl_add_u64 v[224:225], s[74:75], 0, v[132:133]
	s_mov_b32 m0, s73
	v_lshl_add_u64 v[226:227], s[44:45], 0, v[134:135]
	global_load_lds_dwordx4 v[224:225], off
	v_lshl_add_u64 v[224:225], s[74:75], 0, v[136:137]
	s_add_i32 m0, s73, 0x2000
	s_nop 0
	global_load_lds_dwordx4 v[224:225], off
	v_lshl_add_u64 v[224:225], s[44:45], 0, v[130:131]
	s_mov_b32 m0, s53
	s_nop 0
	global_load_lds_dwordx4 v[224:225], off
	s_mov_b32 m0, s54
	s_nop 0
	global_load_lds_dwordx4 v[226:227], off
	s_waitcnt vmcnt(8)
	s_waitcnt lgkmcnt(0)
	s_waitcnt lgkmcnt(0)
	v_mfma_f32_16x16x32_bf16 v[62:65], v[156:159], v[188:191], v[62:65]
	v_mfma_f32_16x16x32_bf16 v[58:61], v[164:167], v[188:191], v[58:61]
	v_mfma_f32_16x16x32_bf16 v[46:49], v[156:159], v[196:199], v[46:49]
	v_mfma_f32_16x16x32_bf16 v[42:45], v[164:167], v[196:199], v[42:45]
	s_barrier
; #define PG8_STAGEA(bufoff, gbase) PG8_STAGE_(bufoff, gbase, voffA)
; #define PG8_LDA(dst, b, h) do { _Pragma("unroll") for (int m = 0; m < 4; ++m) _Pragma("unroll") for (int k = 0; k < 2; ++k) dst[m][k] = *(const LAS bf16x8*)(lds + PG8_SA(b, h) + aoff + m * 2048 + k * 1024); } while (0)
; #define PG8_LDB(dst, b, h) do { _Pragma("unroll") for (int n = 0; n < 2; ++n) _Pragma("unroll") for (int k = 0; k < 2; ++k) dst[n][k] = *(const LAS bf16x8*)(lds + PG8_SB(b, h) + boff + n * 2048 + k * 1024); } while (0)
; #define PG8_MMA(ai, bj, At, Bt_) do { __builtin_amdgcn_s_setprio(1); _Pragma("unroll") for (int m = 0; m < 4; ++m) _Pragma("unroll") for (int n = 0; n < 2; ++n) _Pragma("unroll") for (int k = 0; k < 2; ++k) \
;         acc[ai][bj][m][n] = __builtin_amdgcn_mfma_f32_16x16x32_bf16(Bt_[n][k], At[m][k], acc[ai][bj][m][n], 0, 0, 0); __builtin_amdgcn_s_setprio(0); } while (0)
; #define PG8_WAIT_V(n) asm volatile("s_waitcnt vmcnt(" #n ")" ::: "memory")
; #define PG8_WAIT_L(n) asm volatile("s_waitcnt lgkmcnt(" #n ")" ::: "memory")
; #define PG8_BAR __builtin_amdgcn_s_barrier()
; #define PG8_SCHED __builtin_amdgcn_sched_barrier(0)
; template <int EK, int SK = -1>
; __device__ __forceinline__ void gemm_phase(LAS unsigned char* lds, const bf16_t* A, const bf16_t* Bt, int nM, int N, int K, const EpiArgs& E) {
;     ...
;             PG8_WAIT_V(8); PG8_WAIT_L(0); PG8_BAR; PG8_MMA(1, 0, At, B0); PG8_MMA(1, 1, At, B1); PG8_BAR; PG8_SCHED;
;             PG8_LDB(B0, 1, 0); PG8_LDB(B1, 1, 1); PG8_SCHED; PG8_LDA(At, 1, 0); PG8_STAGEA(PG8_SA(0, 1), a2 + hstep);
;             PG8_WAIT_V(8); PG8_WAIT_L(0); PG8_BAR; PG8_MMA(0, 0, At, B0); PG8_MMA(0, 1, At, B1); PG8_BAR; PG8_SCHED;
	v_mfma_f32_16x16x32_bf16 v[30:33], v[156:159], v[204:207], v[30:33]
	v_mfma_f32_16x16x32_bf16 v[26:29], v[164:167], v[204:207], v[26:29]
	v_mfma_f32_16x16x32_bf16 v[14:17], v[156:159], v[212:215], v[14:17]
	v_mfma_f32_16x16x32_bf16 v[10:13], v[164:167], v[212:215], v[10:13]
	v_mfma_f32_16x16x32_bf16 v[62:65], v[160:163], v[192:195], v[62:65]
	v_mfma_f32_16x16x32_bf16 v[58:61], v[168:171], v[192:195], v[58:61]
	v_mfma_f32_16x16x32_bf16 v[46:49], v[160:163], v[200:203], v[46:49]
	v_mfma_f32_16x16x32_bf16 v[42:45], v[168:171], v[200:203], v[42:45]
	v_mfma_f32_16x16x32_bf16 v[30:33], v[160:163], v[208:211], v[30:33]
	v_mfma_f32_16x16x32_bf16 v[26:29], v[168:171], v[208:211], v[26:29]
	v_mfma_f32_16x16x32_bf16 v[14:17], v[160:163], v[216:219], v[14:17]
	v_mfma_f32_16x16x32_bf16 v[10:13], v[168:171], v[216:219], v[10:13]
	v_mfma_f32_16x16x32_bf16 v[54:57], v[172:175], v[188:191], v[54:57]
	v_mfma_f32_16x16x32_bf16 v[50:53], v[180:183], v[188:191], v[50:53]
	v_mfma_f32_16x16x32_bf16 v[38:41], v[172:175], v[196:199], v[38:41]
	v_mfma_f32_16x16x32_bf16 v[34:37], v[180:183], v[196:199], v[34:37]
	v_mfma_f32_16x16x32_bf16 v[22:25], v[172:175], v[204:207], v[22:25]
	v_mfma_f32_16x16x32_bf16 v[18:21], v[180:183], v[204:207], v[18:21]
	v_mfma_f32_16x16x32_bf16 v[6:9], v[172:175], v[212:215], v[6:9]
	v_mfma_f32_16x16x32_bf16 v[2:5], v[180:183], v[212:215], v[2:5]
	v_mfma_f32_16x16x32_bf16 v[54:57], v[176:179], v[192:195], v[54:57]
	v_mfma_f32_16x16x32_bf16 v[50:53], v[184:187], v[192:195], v[50:53]
	v_mfma_f32_16x16x32_bf16 v[38:41], v[176:179], v[200:203], v[38:41]
	v_mfma_f32_16x16x32_bf16 v[34:37], v[184:187], v[200:203], v[34:37]
	v_mfma_f32_16x16x32_bf16 v[22:25], v[176:179], v[208:211], v[22:25]
	v_mfma_f32_16x16x32_bf16 v[18:21], v[184:187], v[208:211], v[18:21]
	v_mfma_f32_16x16x32_bf16 v[6:9], v[176:179], v[216:219], v[6:9]
	v_mfma_f32_16x16x32_bf16 v[2:5], v[184:187], v[216:219], v[2:5]
	s_barrier
	s_add_i32 s73, 0, 0x18000
	s_add_i32 s74, 0, 0x1c000
	v_add_u32_e32 v168, s73, v154
	v_add_u32_e32 v184, s74, v154
	ds_read_b128 v[156:159], v168
	ds_read_b128 v[160:163], v168 offset:1024
	ds_read_b128 v[164:167], v168 offset:2048
	ds_read_b128 v[168:171], v168 offset:3072
	ds_read_b128 v[172:175], v184
	ds_read_b128 v[176:179], v184 offset:1024
	ds_read_b128 v[180:183], v184 offset:2048
	ds_read_b128 v[184:187], v184 offset:3072
	s_add_u32 s44, s44, 0xb0000
	s_addc_u32 s45, s45, 0
	s_mov_b32 m0, s55
	v_lshl_add_u64 v[228:229], s[44:45], 0, v[130:131]
	ds_read_b128 v[188:191], v155 offset:32768
	ds_read_b128 v[192:195], v155 offset:33792
	ds_read_b128 v[196:199], v155 offset:34816
	ds_read_b128 v[200:203], v155 offset:35840
	ds_read_b128 v[204:207], v155 offset:36864
	ds_read_b128 v[208:211], v155 offset:37888
	ds_read_b128 v[212:215], v155 offset:38912
	ds_read_b128 v[216:219], v155 offset:39936
	global_load_lds_dwordx4 v[228:229], off
	v_lshl_add_u64 v[228:229], s[44:45], 0, v[134:135]
	s_mov_b32 m0, s56
	s_nop 0
	global_load_lds_dwordx4 v[228:229], off
	s_waitcnt vmcnt(8)
	s_waitcnt lgkmcnt(0)
	s_waitcnt lgkmcnt(0)
	v_mfma_f32_16x16x32_bf16 v[126:129], v[156:159], v[188:191], v[126:129]
	v_mfma_f32_16x16x32_bf16 v[122:125], v[164:167], v[188:191], v[122:125]
	v_mfma_f32_16x16x32_bf16 v[110:113], v[156:159], v[196:199], v[110:113]
	v_mfma_f32_16x16x32_bf16 v[106:109], v[164:167], v[196:199], v[106:109]
	s_barrier
	v_mfma_f32_16x16x32_bf16 v[94:97], v[156:159], v[204:207], v[94:97]
	v_mfma_f32_16x16x32_bf16 v[90:93], v[164:167], v[204:207], v[90:93]
	v_mfma_f32_16x16x32_bf16 v[78:81], v[156:159], v[212:215], v[78:81]
	v_mfma_f32_16x16x32_bf16 v[74:77], v[164:167], v[212:215], v[74:77]
	v_mfma_f32_16x16x32_bf16 v[126:129], v[160:163], v[192:195], v[126:129]
	v_mfma_f32_16x16x32_bf16 v[122:125], v[168:171], v[192:195], v[122:125]
	v_mfma_f32_16x16x32_bf16 v[110:113], v[160:163], v[200:203], v[110:113]
	v_mfma_f32_16x16x32_bf16 v[106:109], v[168:171], v[200:203], v[106:109]
	v_mfma_f32_16x16x32_bf16 v[94:97], v[160:163], v[208:211], v[94:97]
	v_mfma_f32_16x16x32_bf16 v[90:93], v[168:171], v[208:211], v[90:93]
	v_mfma_f32_16x16x32_bf16 v[78:81], v[160:163], v[216:219], v[78:81]
	v_mfma_f32_16x16x32_bf16 v[74:77], v[168:171], v[216:219], v[74:77]
	v_mfma_f32_16x16x32_bf16 v[118:121], v[172:175], v[188:191], v[118:121]
	v_mfma_f32_16x16x32_bf16 v[114:117], v[180:183], v[188:191], v[114:117]
	v_mfma_f32_16x16x32_bf16 v[102:105], v[172:175], v[196:199], v[102:105]
	v_mfma_f32_16x16x32_bf16 v[98:101], v[180:183], v[196:199], v[98:101]
	v_mfma_f32_16x16x32_bf16 v[86:89], v[172:175], v[204:207], v[86:89]
	v_mfma_f32_16x16x32_bf16 v[82:85], v[180:183], v[204:207], v[82:85]
	v_mfma_f32_16x16x32_bf16 v[70:73], v[172:175], v[212:215], v[70:73]
	v_mfma_f32_16x16x32_bf16 v[66:69], v[180:183], v[212:215], v[66:69]
	v_mfma_f32_16x16x32_bf16 v[118:121], v[176:179], v[192:195], v[118:121]
	v_mfma_f32_16x16x32_bf16 v[114:117], v[184:187], v[192:195], v[114:117]
	v_mfma_f32_16x16x32_bf16 v[102:105], v[176:179], v[200:203], v[102:105]
	v_mfma_f32_16x16x32_bf16 v[98:101], v[184:187], v[200:203], v[98:101]
	v_mfma_f32_16x16x32_bf16 v[86:89], v[176:179], v[208:211], v[86:89]
	v_mfma_f32_16x16x32_bf16 v[82:85], v[184:187], v[208:211], v[82:85]
	v_mfma_f32_16x16x32_bf16 v[70:73], v[176:179], v[216:219], v[70:73]
	v_mfma_f32_16x16x32_bf16 v[66:69], v[184:187], v[216:219], v[66:69]
	s_barrier
; #define PG8_STAGEA(bufoff, gbase) PG8_STAGE_(bufoff, gbase, voffA)
; #define PG8_STAGEB(bufoff, gbase) PG8_STAGE_(bufoff, gbase, voffB)
; #define PG8_LDA(dst, b, h) do { _Pragma("unroll") for (int m = 0; m < 4; ++m) _Pragma("unroll") for (int k = 0; k < 2; ++k) dst[m][k] = *(const LAS bf16x8*)(lds + PG8_SA(b, h) + aoff + m * 2048 + k * 1024); } while (0)
; #define PG8_MMA(ai, bj, At, Bt_) do { __builtin_amdgcn_s_setprio(1); _Pragma("unroll") for (int m = 0; m < 4; ++m) _Pragma("unroll") for (int n = 0; n < 2; ++n) _Pragma("unroll") for (int k = 0; k < 2; ++k) \
;         acc[ai][bj][m][n] = __builtin_amdgcn_mfma_f32_16x16x32_bf16(Bt_[n][k], At[m][k], acc[ai][bj][m][n], 0, 0, 0); __builtin_amdgcn_s_setprio(0); } while (0)
; #define PG8_WAIT_V(n) asm volatile("s_waitcnt vmcnt(" #n ")" ::: "memory")
; #define PG8_WAIT_L(n) asm volatile("s_waitcnt lgkmcnt(" #n ")" ::: "memory")
; #define PG8_BAR __builtin_amdgcn_s_barrier()
; #define PG8_SCHED __builtin_amdgcn_sched_barrier(0)
; template <int EK, int SK = -1>
; __device__ __forceinline__ void gemm_phase(LAS unsigned char* lds, const bf16_t* A, const bf16_t* Bt, int nM, int N, int K, const EpiArgs& E) {
;     ...
;             PG8_LDA(At, 1, 1); PG8_STAGEB(PG8_SB(1, 0), b3); PG8_STAGEB(PG8_SB(1, 1), b3 + hstep); PG8_STAGEA(PG8_SA(1, 0), a3);
;             PG8_WAIT_V(8); PG8_WAIT_L(0); PG8_BAR; PG8_MMA(1, 0, At, B0); PG8_MMA(1, 1, At, B1); PG8_BAR; PG8_SCHED;
;         }
;         if (wr == 0) PG8_BAR;
	s_add_i32 s44, s73, s52
	v_lshl_add_u64 v[220:221], v[220:221], 0, s[22:23]
	s_mov_b32 m0, s44
	ds_read_b128 v[188:191], v155 offset:49152
	ds_read_b128 v[192:195], v155 offset:50176
	ds_read_b128 v[196:199], v155 offset:51200
	ds_read_b128 v[200:203], v155 offset:52224
	ds_read_b128 v[204:207], v155 offset:53248
	ds_read_b128 v[208:211], v155 offset:54272
	ds_read_b128 v[212:215], v155 offset:55296
	ds_read_b128 v[216:219], v155 offset:56320
	global_load_lds_dwordx4 v[220:221], off
	s_add_i32 m0, s44, 0x2000
	s_add_u32 s42, s42, 0xb0080
	v_lshl_add_u64 v[220:221], v[222:223], 0, s[22:23]
	s_addc_u32 s43, s43, 0
	s_add_i32 s44, s74, s52
	global_load_lds_dwordx4 v[220:221], off
	v_lshl_add_u64 v[220:221], s[42:43], 0, v[132:133]
	s_mov_b32 m0, s44
	s_nop 0
	global_load_lds_dwordx4 v[220:221], off
	v_lshl_add_u64 v[220:221], s[42:43], 0, v[136:137]
	s_add_i32 m0, s44, 0x2000
	s_nop 0
	global_load_lds_dwordx4 v[220:221], off
	v_lshl_add_u64 v[220:221], v[224:225], 0, s[22:23]
	s_mov_b32 m0, s58
	s_nop 0
	global_load_lds_dwordx4 v[220:221], off
	v_lshl_add_u64 v[220:221], v[226:227], 0, s[22:23]
	s_mov_b32 m0, s59
	s_nop 0
	global_load_lds_dwordx4 v[220:221], off
	s_waitcnt vmcnt(8)
	s_waitcnt lgkmcnt(0)
	s_waitcnt lgkmcnt(0)
	v_mfma_f32_16x16x32_bf16 v[62:65], v[156:159], v[188:191], v[62:65]
	v_mfma_f32_16x16x32_bf16 v[58:61], v[164:167], v[188:191], v[58:61]
	v_mfma_f32_16x16x32_bf16 v[46:49], v[156:159], v[196:199], v[46:49]
	v_mfma_f32_16x16x32_bf16 v[42:45], v[164:167], v[196:199], v[42:45]
	s_barrier
	v_mfma_f32_16x16x32_bf16 v[30:33], v[156:159], v[204:207], v[30:33]
	v_mfma_f32_16x16x32_bf16 v[26:29], v[164:167], v[204:207], v[26:29]
	v_mfma_f32_16x16x32_bf16 v[14:17], v[156:159], v[212:215], v[14:17]
	v_mfma_f32_16x16x32_bf16 v[10:13], v[164:167], v[212:215], v[10:13]
	v_mfma_f32_16x16x32_bf16 v[62:65], v[160:163], v[192:195], v[62:65]
	v_mfma_f32_16x16x32_bf16 v[58:61], v[168:171], v[192:195], v[58:61]
	v_mfma_f32_16x16x32_bf16 v[46:49], v[160:163], v[200:203], v[46:49]
	v_mfma_f32_16x16x32_bf16 v[42:45], v[168:171], v[200:203], v[42:45]
	v_mfma_f32_16x16x32_bf16 v[30:33], v[160:163], v[208:211], v[30:33]
	v_mfma_f32_16x16x32_bf16 v[26:29], v[168:171], v[208:211], v[26:29]
	v_mfma_f32_16x16x32_bf16 v[14:17], v[160:163], v[216:219], v[14:17]
	v_mfma_f32_16x16x32_bf16 v[10:13], v[168:171], v[216:219], v[10:13]
	v_mfma_f32_16x16x32_bf16 v[54:57], v[172:175], v[188:191], v[54:57]
	v_mfma_f32_16x16x32_bf16 v[50:53], v[180:183], v[188:191], v[50:53]
	v_mfma_f32_16x16x32_bf16 v[38:41], v[172:175], v[196:199], v[38:41]
	v_mfma_f32_16x16x32_bf16 v[34:37], v[180:183], v[196:199], v[34:37]
	v_mfma_f32_16x16x32_bf16 v[22:25], v[172:175], v[204:207], v[22:25]
	v_mfma_f32_16x16x32_bf16 v[18:21], v[180:183], v[204:207], v[18:21]
	v_mfma_f32_16x16x32_bf16 v[6:9], v[172:175], v[212:215], v[6:9]
	v_mfma_f32_16x16x32_bf16 v[2:5], v[180:183], v[212:215], v[2:5]
	v_mfma_f32_16x16x32_bf16 v[54:57], v[176:179], v[192:195], v[54:57]
	v_mfma_f32_16x16x32_bf16 v[50:53], v[184:187], v[192:195], v[50:53]
	v_mfma_f32_16x16x32_bf16 v[38:41], v[176:179], v[200:203], v[38:41]
	v_mfma_f32_16x16x32_bf16 v[34:37], v[184:187], v[200:203], v[34:37]
	v_mfma_f32_16x16x32_bf16 v[22:25], v[176:179], v[208:211], v[22:25]
	v_mfma_f32_16x16x32_bf16 v[18:21], v[184:187], v[208:211], v[18:21]
	v_mfma_f32_16x16x32_bf16 v[6:9], v[176:179], v[216:219], v[6:9]
	v_mfma_f32_16x16x32_bf16 v[2:5], v[184:187], v[216:219], v[2:5]
	s_barrier
	s_add_i32 s72, s72, 2
	s_add_u32 s40, s40, 0x100
	s_addc_u32 s41, s41, 0
	s_cmp_gt_u32 s72, 41
	s_cbranch_scc0 .LBB0_1401
	s_and_b64 vcc, exec, s[26:27]
	s_cbranch_vccz .LBB0_1404
	s_barrier
